# K-loops without per-segment s_setprio flips + hand-written conv LayerNorm tail (4 rows per wave processed together)
# baseline (speedup 1.0000x reference)
; #define PG8_STAGE(bufoff, gbase, voff) do { _Pragma("unroll") for (int _i = 0; _i < 2; ++_i) \
;         __builtin_amdgcn_global_load_lds((const unsigned*)((const char*)(gbase) + (voff)[_i]), (LAS unsigned*)(lds + (bufoff) + ldsw + _i * 8192), 16, 0, 0); } while (0)
; #define PG8_LDA(dst, b, h) do { _Pragma("unroll") for (int m = 0; m < 4; ++m) _Pragma("unroll") for (int k = 0; k < 2; ++k) dst[m][k] = *(const LAS bf16x8*)(lds + PG8_SA(b, h) + aoff + m * 2048 + k * 1024); } while (0)
; #define PG8_LDB(dst, b, h) do { _Pragma("unroll") for (int n = 0; n < 2; ++n) _Pragma("unroll") for (int k = 0; k < 2; ++k) dst[n][k] = *(const LAS bf16x8*)(lds + PG8_SB(b, h) + boff + n * 2048 + k * 1024); } while (0)
; #define PG8_MMA(ai, bj, At, Bt) do { __builtin_amdgcn_s_setprio(1); _Pragma("unroll") for (int m = 0; m < 4; ++m) _Pragma("unroll") for (int n = 0; n < 2; ++n) _Pragma("unroll") for (int k = 0; k < 2; ++k) \
;         acc[ai][bj][m][n] = __builtin_amdgcn_mfma_f32_16x16x32_bf16(Bt[n][k], At[m][k], acc[ai][bj][m][n], 0, 0, 0); __builtin_amdgcn_s_setprio(0); } while (0)
; #define PG8_WAIT_V(n) asm volatile("s_waitcnt vmcnt(" #n ")" ::: "memory")
; #define PG8_WAIT_L(n) asm volatile("s_waitcnt lgkmcnt(" #n ")" ::: "memory")
; #define PG8_BAR __builtin_amdgcn_s_barrier()
; #define PG8_SCHED __builtin_amdgcn_sched_barrier(0)
; template <class Epi, class Sched, bool ALIGN_EPI>
; __device__ __forceinline__ void gemm_phase(LAS unsigned char* lds, const Gemm g, const Sched& S, const Epi& E) {
;     ...
;         for (int t = 0; t < nt; t += 2) {
;             const bool last = (t == nt - 2);
;             const char* a1 = cA + (size_t)(t + 1) * kstep;
;             const char* a2 = last ? nA : cA + (size_t)(t + 2) * kstep; const char* b2 = last ? nB : cB + (size_t)(t + 2) * kstep;
;             const char* a3 = a2 + kstep; const char* b3 = b2 + kstep;
;             PG8_LDB(B0, 0, 0); PG8_LDB(B1, 0, 1); PG8_SCHED; PG8_LDA(At, 0, 0); PG8_STAGE(PG8_SA(1, 1), a1 + hA, voffA);
;             PG8_WAIT_V(8); PG8_WAIT_L(0); PG8_BAR; PG8_MMA(0, 0, At, B0); PG8_MMA(0, 1, At, B1); PG8_BAR; PG8_SCHED;
;             PG8_LDA(At, 0, 1); PG8_STAGE(PG8_SB(0, 0), b2, voffB); PG8_STAGE(PG8_SB(0, 1), b2 + hB, voffB); PG8_STAGE(PG8_SA(0, 0), a2, voffA);
;             PG8_WAIT_V(8); PG8_WAIT_L(0); PG8_BAR; PG8_MMA(1, 0, At, B0); PG8_MMA(1, 1, At, B1); PG8_BAR; PG8_SCHED;
.LBB0_242:
	ds_read_b128 v[140:143], v137
	ds_read_b128 v[152:155], v137 offset:1024
	ds_read_b128 v[156:159], v137 offset:2048
	ds_read_b128 v[160:163], v137 offset:3072
	ds_read_b128 v[164:167], v138
	ds_read_b128 v[168:171], v138 offset:1024
	ds_read_b128 v[172:175], v138 offset:2048
	ds_read_b128 v[176:179], v138 offset:3072
	s_add_u32 s18, s66, 0xfff80080
	s_addc_u32 s19, s67, -1
	s_cmp_eq_u32 s72, 28
	s_cselect_b32 s71, vcc_lo, s19
	s_cselect_b32 s70, vcc_hi, s18
	s_cselect_b32 s69, s41, s45
	s_cselect_b32 s68, s87, s44
	v_lshl_add_u64 v[132:133], s[66:67], 0, v[128:129]
	s_add_i32 m0, s81, 0xc000
	ds_read_b128 v[192:195], v139
	ds_read_b128 v[196:199], v139 offset:1024
	ds_read_b128 v[200:203], v139 offset:2048
	ds_read_b128 v[204:207], v139 offset:3072
	ds_read_b128 v[208:211], v139 offset:4096
	ds_read_b128 v[212:215], v139 offset:5120
	ds_read_b128 v[216:219], v139 offset:6144
	ds_read_b128 v[222:225], v139 offset:7168
	global_load_lds_dwordx4 v[132:133], off
	v_lshl_add_u64 v[132:133], s[66:67], 0, v[130:131]
	s_add_i32 m0, s81, 0xe000
	s_nop 0
	global_load_lds_dwordx4 v[132:133], off
	s_waitcnt vmcnt(8)
	s_waitcnt lgkmcnt(0)
	s_barrier
	s_waitcnt lgkmcnt(0)
	v_mfma_f32_16x16x32_bf16 v[124:127], v[140:143], v[192:195], v[124:127]
	v_mfma_f32_16x16x32_bf16 v[120:123], v[156:159], v[192:195], v[120:123]
	v_mfma_f32_16x16x32_bf16 v[112:115], v[140:143], v[200:203], v[112:115]
	v_mfma_f32_16x16x32_bf16 v[104:107], v[156:159], v[200:203], v[104:107]
	v_mfma_f32_16x16x32_bf16 v[96:99], v[140:143], v[208:211], v[96:99]
	v_mfma_f32_16x16x32_bf16 v[88:91], v[156:159], v[208:211], v[88:91]
	v_mfma_f32_16x16x32_bf16 v[80:83], v[140:143], v[216:219], v[80:83]
	v_mfma_f32_16x16x32_bf16 v[72:75], v[156:159], v[216:219], v[72:75]
	v_mfma_f32_16x16x32_bf16 v[124:127], v[152:155], v[196:199], v[124:127]
	v_mfma_f32_16x16x32_bf16 v[120:123], v[160:163], v[196:199], v[120:123]
	v_mfma_f32_16x16x32_bf16 v[112:115], v[152:155], v[204:207], v[112:115]
	v_mfma_f32_16x16x32_bf16 v[104:107], v[160:163], v[204:207], v[104:107]
	v_mfma_f32_16x16x32_bf16 v[96:99], v[152:155], v[212:215], v[96:99]
	v_mfma_f32_16x16x32_bf16 v[88:91], v[160:163], v[212:215], v[88:91]
	v_mfma_f32_16x16x32_bf16 v[80:83], v[152:155], v[222:225], v[80:83]
	v_mfma_f32_16x16x32_bf16 v[72:75], v[160:163], v[222:225], v[72:75]
	v_mfma_f32_16x16x32_bf16 v[116:119], v[164:167], v[192:195], v[116:119]
	v_mfma_f32_16x16x32_bf16 v[108:111], v[172:175], v[192:195], v[108:111]
	v_mfma_f32_16x16x32_bf16 v[100:103], v[164:167], v[200:203], v[100:103]
	v_mfma_f32_16x16x32_bf16 v[92:95], v[172:175], v[200:203], v[92:95]
	v_mfma_f32_16x16x32_bf16 v[84:87], v[164:167], v[208:211], v[84:87]
	v_mfma_f32_16x16x32_bf16 v[76:79], v[172:175], v[208:211], v[76:79]
	v_mfma_f32_16x16x32_bf16 v[68:71], v[164:167], v[216:219], v[68:71]
	v_mfma_f32_16x16x32_bf16 v[64:67], v[172:175], v[216:219], v[64:67]
	v_mfma_f32_16x16x32_bf16 v[116:119], v[168:171], v[196:199], v[116:119]
	v_mfma_f32_16x16x32_bf16 v[108:111], v[176:179], v[196:199], v[108:111]
	v_mfma_f32_16x16x32_bf16 v[100:103], v[168:171], v[204:207], v[100:103]
	v_mfma_f32_16x16x32_bf16 v[92:95], v[176:179], v[204:207], v[92:95]
	v_mfma_f32_16x16x32_bf16 v[84:87], v[168:171], v[212:215], v[84:87]
	v_mfma_f32_16x16x32_bf16 v[76:79], v[176:179], v[212:215], v[76:79]
	v_mfma_f32_16x16x32_bf16 v[68:71], v[168:171], v[222:225], v[68:71]
	v_mfma_f32_16x16x32_bf16 v[64:67], v[176:179], v[222:225], v[64:67]
	s_barrier
	s_add_i32 s18, s92, s78
	v_lshl_add_u64 v[132:133], s[68:69], 0, v[144:145]
	s_mov_b32 m0, s18
	ds_read_b128 v[192:195], v139 offset:16384
	ds_read_b128 v[196:199], v139 offset:17408
	ds_read_b128 v[200:203], v139 offset:18432
	ds_read_b128 v[204:207], v139 offset:19456
	ds_read_b128 v[208:211], v139 offset:20480
	ds_read_b128 v[212:215], v139 offset:21504
	ds_read_b128 v[216:219], v139 offset:22528
	ds_read_b128 v[222:225], v139 offset:23552
	global_load_lds_dwordx4 v[132:133], off
	s_add_i32 m0, s18, 0x2000
	s_add_u32 s46, s68, 0x80000
	v_lshl_add_u64 v[226:227], s[68:69], 0, v[146:147]
	s_addc_u32 s47, s69, 0
	s_add_i32 s18, s93, s78
	global_load_lds_dwordx4 v[226:227], off
	v_lshl_add_u64 v[228:229], s[46:47], 0, v[144:145]
	s_mov_b32 m0, s18
	v_lshl_add_u64 v[230:231], s[70:71], 0, v[150:151]
	global_load_lds_dwordx4 v[228:229], off
	v_lshl_add_u64 v[228:229], s[46:47], 0, v[146:147]
	s_add_i32 m0, s18, 0x2000
	s_nop 0
	global_load_lds_dwordx4 v[228:229], off
	v_lshl_add_u64 v[228:229], s[70:71], 0, v[148:149]
	s_mov_b32 m0, s81
	s_nop 0
	global_load_lds_dwordx4 v[228:229], off
	s_mov_b32 m0, s82
	s_nop 0
	global_load_lds_dwordx4 v[230:231], off
	s_waitcnt vmcnt(8)
	s_waitcnt lgkmcnt(0)
	s_barrier
; #define PG8_STAGE(bufoff, gbase, voff) do { _Pragma("unroll") for (int _i = 0; _i < 2; ++_i) \
;         __builtin_amdgcn_global_load_lds((const unsigned*)((const char*)(gbase) + (voff)[_i]), (LAS unsigned*)(lds + (bufoff) + ldsw + _i * 8192), 16, 0, 0); } while (0)
; #define PG8_LDA(dst, b, h) do { _Pragma("unroll") for (int m = 0; m < 4; ++m) _Pragma("unroll") for (int k = 0; k < 2; ++k) dst[m][k] = *(const LAS bf16x8*)(lds + PG8_SA(b, h) + aoff + m * 2048 + k * 1024); } while (0)
; #define PG8_LDB(dst, b, h) do { _Pragma("unroll") for (int n = 0; n < 2; ++n) _Pragma("unroll") for (int k = 0; k < 2; ++k) dst[n][k] = *(const LAS bf16x8*)(lds + PG8_SB(b, h) + boff + n * 2048 + k * 1024); } while (0)
; #define PG8_MMA(ai, bj, At, Bt) do { __builtin_amdgcn_s_setprio(1); _Pragma("unroll") for (int m = 0; m < 4; ++m) _Pragma("unroll") for (int n = 0; n < 2; ++n) _Pragma("unroll") for (int k = 0; k < 2; ++k) \
;         acc[ai][bj][m][n] = __builtin_amdgcn_mfma_f32_16x16x32_bf16(Bt[n][k], At[m][k], acc[ai][bj][m][n], 0, 0, 0); __builtin_amdgcn_s_setprio(0); } while (0)
; #define PG8_WAIT_V(n) asm volatile("s_waitcnt vmcnt(" #n ")" ::: "memory")
; #define PG8_WAIT_L(n) asm volatile("s_waitcnt lgkmcnt(" #n ")" ::: "memory")
; #define PG8_BAR __builtin_amdgcn_s_barrier()
; #define PG8_SCHED __builtin_amdgcn_sched_barrier(0)
; template <class Epi, class Sched, bool ALIGN_EPI>
; __device__ __forceinline__ void gemm_phase(LAS unsigned char* lds, const Gemm g, const Sched& S, const Epi& E) {
;     ...
;             PG8_WAIT_V(8); PG8_WAIT_L(0); PG8_BAR; PG8_MMA(1, 0, At, B0); PG8_MMA(1, 1, At, B1); PG8_BAR; PG8_SCHED;
;             PG8_LDB(B0, 1, 0); PG8_LDB(B1, 1, 1); PG8_SCHED; PG8_LDA(At, 1, 0); PG8_STAGE(PG8_SA(0, 1), a2 + hA, voffA);
;             PG8_WAIT_V(8); PG8_WAIT_L(0); PG8_BAR; PG8_MMA(0, 0, At, B0); PG8_MMA(0, 1, At, B1); PG8_BAR; PG8_SCHED;
;             PG8_LDA(At, 1, 1); PG8_STAGE(PG8_SB(1, 0), b3, voffB); PG8_STAGE(PG8_SB(1, 1), b3 + hB, voffB); PG8_STAGE(PG8_SA(1, 0), a3, voffA);
	s_waitcnt lgkmcnt(0)
	v_mfma_f32_16x16x32_bf16 v[60:63], v[140:143], v[192:195], v[60:63]
	v_mfma_f32_16x16x32_bf16 v[56:59], v[156:159], v[192:195], v[56:59]
	v_mfma_f32_16x16x32_bf16 v[52:55], v[140:143], v[200:203], v[52:55]
	v_mfma_f32_16x16x32_bf16 v[44:47], v[156:159], v[200:203], v[44:47]
	v_mfma_f32_16x16x32_bf16 v[36:39], v[140:143], v[208:211], v[36:39]
	v_mfma_f32_16x16x32_bf16 v[28:31], v[156:159], v[208:211], v[28:31]
	v_mfma_f32_16x16x32_bf16 v[20:23], v[140:143], v[216:219], v[20:23]
	v_mfma_f32_16x16x32_bf16 v[12:15], v[156:159], v[216:219], v[12:15]
	v_mfma_f32_16x16x32_bf16 v[60:63], v[152:155], v[196:199], v[60:63]
	v_mfma_f32_16x16x32_bf16 v[56:59], v[160:163], v[196:199], v[56:59]
	v_mfma_f32_16x16x32_bf16 v[52:55], v[152:155], v[204:207], v[52:55]
	v_mfma_f32_16x16x32_bf16 v[44:47], v[160:163], v[204:207], v[44:47]
	v_mfma_f32_16x16x32_bf16 v[36:39], v[152:155], v[212:215], v[36:39]
	v_mfma_f32_16x16x32_bf16 v[28:31], v[160:163], v[212:215], v[28:31]
	v_mfma_f32_16x16x32_bf16 v[20:23], v[152:155], v[222:225], v[20:23]
	v_mfma_f32_16x16x32_bf16 v[12:15], v[160:163], v[222:225], v[12:15]
	v_mfma_f32_16x16x32_bf16 v[48:51], v[164:167], v[192:195], v[48:51]
	v_mfma_f32_16x16x32_bf16 v[40:43], v[172:175], v[192:195], v[40:43]
	v_mfma_f32_16x16x32_bf16 v[32:35], v[164:167], v[200:203], v[32:35]
	v_mfma_f32_16x16x32_bf16 v[24:27], v[172:175], v[200:203], v[24:27]
	v_mfma_f32_16x16x32_bf16 v[16:19], v[164:167], v[208:211], v[16:19]
	v_mfma_f32_16x16x32_bf16 v[8:11], v[172:175], v[208:211], v[8:11]
	v_mfma_f32_16x16x32_bf16 v[4:7], v[164:167], v[216:219], v[4:7]
	v_mfma_f32_16x16x32_bf16 v[0:3], v[172:175], v[216:219], v[0:3]
	v_mfma_f32_16x16x32_bf16 v[48:51], v[168:171], v[196:199], v[48:51]
	v_mfma_f32_16x16x32_bf16 v[40:43], v[176:179], v[196:199], v[40:43]
	v_mfma_f32_16x16x32_bf16 v[32:35], v[168:171], v[204:207], v[32:35]
	v_mfma_f32_16x16x32_bf16 v[24:27], v[176:179], v[204:207], v[24:27]
	v_mfma_f32_16x16x32_bf16 v[16:19], v[168:171], v[212:215], v[16:19]
	v_mfma_f32_16x16x32_bf16 v[8:11], v[176:179], v[212:215], v[8:11]
	v_mfma_f32_16x16x32_bf16 v[4:7], v[168:171], v[222:225], v[4:7]
	v_mfma_f32_16x16x32_bf16 v[0:3], v[176:179], v[222:225], v[0:3]
	s_barrier
	s_add_i32 s18, 0, 0x18000
	s_add_i32 s19, 0, 0x1c000
	v_add_u32_e32 v160, s18, v135
	v_add_u32_e32 v176, s19, v135
	ds_read_b128 v[140:143], v160
	ds_read_b128 v[152:155], v160 offset:1024
	ds_read_b128 v[156:159], v160 offset:2048
	ds_read_b128 v[160:163], v160 offset:3072
	ds_read_b128 v[164:167], v176
	ds_read_b128 v[168:171], v176 offset:1024
	ds_read_b128 v[172:175], v176 offset:2048
	ds_read_b128 v[176:179], v176 offset:3072
	s_add_u32 s46, s70, 0x80000
	s_addc_u32 s47, s71, 0
	s_mov_b32 m0, s83
	v_lshl_add_u64 v[232:233], s[46:47], 0, v[148:149]
	ds_read_b128 v[192:195], v139 offset:32768
	ds_read_b128 v[196:199], v139 offset:33792
	ds_read_b128 v[200:203], v139 offset:34816
	ds_read_b128 v[204:207], v139 offset:35840
	ds_read_b128 v[208:211], v139 offset:36864
	ds_read_b128 v[212:215], v139 offset:37888
	ds_read_b128 v[216:219], v139 offset:38912
	ds_read_b128 v[222:225], v139 offset:39936
	global_load_lds_dwordx4 v[232:233], off
	v_lshl_add_u64 v[232:233], s[46:47], 0, v[150:151]
	s_mov_b32 m0, s84
	s_nop 0
	global_load_lds_dwordx4 v[232:233], off
	s_waitcnt vmcnt(8)
	s_waitcnt lgkmcnt(0)
	s_barrier
	s_waitcnt lgkmcnt(0)
	v_mfma_f32_16x16x32_bf16 v[124:127], v[140:143], v[192:195], v[124:127]
	v_mfma_f32_16x16x32_bf16 v[120:123], v[156:159], v[192:195], v[120:123]
	v_mfma_f32_16x16x32_bf16 v[112:115], v[140:143], v[200:203], v[112:115]
	v_mfma_f32_16x16x32_bf16 v[104:107], v[156:159], v[200:203], v[104:107]
	v_mfma_f32_16x16x32_bf16 v[96:99], v[140:143], v[208:211], v[96:99]
	v_mfma_f32_16x16x32_bf16 v[88:91], v[156:159], v[208:211], v[88:91]
	v_mfma_f32_16x16x32_bf16 v[80:83], v[140:143], v[216:219], v[80:83]
	v_mfma_f32_16x16x32_bf16 v[72:75], v[156:159], v[216:219], v[72:75]
	v_mfma_f32_16x16x32_bf16 v[124:127], v[152:155], v[196:199], v[124:127]
	v_mfma_f32_16x16x32_bf16 v[120:123], v[160:163], v[196:199], v[120:123]
	v_mfma_f32_16x16x32_bf16 v[112:115], v[152:155], v[204:207], v[112:115]
	v_mfma_f32_16x16x32_bf16 v[104:107], v[160:163], v[204:207], v[104:107]
	v_mfma_f32_16x16x32_bf16 v[96:99], v[152:155], v[212:215], v[96:99]
	v_mfma_f32_16x16x32_bf16 v[88:91], v[160:163], v[212:215], v[88:91]
	v_mfma_f32_16x16x32_bf16 v[80:83], v[152:155], v[222:225], v[80:83]
	v_mfma_f32_16x16x32_bf16 v[72:75], v[160:163], v[222:225], v[72:75]
	v_mfma_f32_16x16x32_bf16 v[116:119], v[164:167], v[192:195], v[116:119]
	v_mfma_f32_16x16x32_bf16 v[108:111], v[172:175], v[192:195], v[108:111]
	v_mfma_f32_16x16x32_bf16 v[100:103], v[164:167], v[200:203], v[100:103]
	v_mfma_f32_16x16x32_bf16 v[92:95], v[172:175], v[200:203], v[92:95]
	v_mfma_f32_16x16x32_bf16 v[84:87], v[164:167], v[208:211], v[84:87]
	v_mfma_f32_16x16x32_bf16 v[76:79], v[172:175], v[208:211], v[76:79]
	v_mfma_f32_16x16x32_bf16 v[68:71], v[164:167], v[216:219], v[68:71]
	v_mfma_f32_16x16x32_bf16 v[64:67], v[172:175], v[216:219], v[64:67]
	v_mfma_f32_16x16x32_bf16 v[116:119], v[168:171], v[196:199], v[116:119]
	v_mfma_f32_16x16x32_bf16 v[108:111], v[176:179], v[196:199], v[108:111]
	v_mfma_f32_16x16x32_bf16 v[100:103], v[168:171], v[204:207], v[100:103]
	v_mfma_f32_16x16x32_bf16 v[92:95], v[176:179], v[204:207], v[92:95]
	v_mfma_f32_16x16x32_bf16 v[84:87], v[168:171], v[212:215], v[84:87]
	v_mfma_f32_16x16x32_bf16 v[76:79], v[176:179], v[212:215], v[76:79]
	v_mfma_f32_16x16x32_bf16 v[68:71], v[168:171], v[222:225], v[68:71]
	v_mfma_f32_16x16x32_bf16 v[64:67], v[176:179], v[222:225], v[64:67]
	s_barrier
; #define PG8_STAGE(bufoff, gbase, voff) do { _Pragma("unroll") for (int _i = 0; _i < 2; ++_i) \
;         __builtin_amdgcn_global_load_lds((const unsigned*)((const char*)(gbase) + (voff)[_i]), (LAS unsigned*)(lds + (bufoff) + ldsw + _i * 8192), 16, 0, 0); } while (0)
; #define PG8_LDA(dst, b, h) do { _Pragma("unroll") for (int m = 0; m < 4; ++m) _Pragma("unroll") for (int k = 0; k < 2; ++k) dst[m][k] = *(const LAS bf16x8*)(lds + PG8_SA(b, h) + aoff + m * 2048 + k * 1024); } while (0)
; #define PG8_MMA(ai, bj, At, Bt) do { __builtin_amdgcn_s_setprio(1); _Pragma("unroll") for (int m = 0; m < 4; ++m) _Pragma("unroll") for (int n = 0; n < 2; ++n) _Pragma("unroll") for (int k = 0; k < 2; ++k) \
;         acc[ai][bj][m][n] = __builtin_amdgcn_mfma_f32_16x16x32_bf16(Bt[n][k], At[m][k], acc[ai][bj][m][n], 0, 0, 0); __builtin_amdgcn_s_setprio(0); } while (0)
; #define PG8_WAIT_V(n) asm volatile("s_waitcnt vmcnt(" #n ")" ::: "memory")
; #define PG8_WAIT_L(n) asm volatile("s_waitcnt lgkmcnt(" #n ")" ::: "memory")
; #define PG8_BAR __builtin_amdgcn_s_barrier()
; #define PG8_SCHED __builtin_amdgcn_sched_barrier(0)
; template <class Epi, class Sched, bool ALIGN_EPI>
; __device__ __forceinline__ void gemm_phase(LAS unsigned char* lds, const Gemm g, const Sched& S, const Epi& E) {
;     ...
;             PG8_LDA(At, 1, 1); PG8_STAGE(PG8_SB(1, 0), b3, voffB); PG8_STAGE(PG8_SB(1, 1), b3 + hB, voffB); PG8_STAGE(PG8_SA(1, 0), a3, voffA);
;             PG8_WAIT_V(8); PG8_WAIT_L(0); PG8_BAR; PG8_MMA(1, 0, At, B0); PG8_MMA(1, 1, At, B1); PG8_BAR; PG8_SCHED;
;         }
	s_add_i32 s18, s18, s78
	v_lshl_add_u64 v[132:133], v[132:133], 0, s[24:25]
	s_mov_b32 m0, s18
	ds_read_b128 v[192:195], v139 offset:49152
	ds_read_b128 v[196:199], v139 offset:50176
	ds_read_b128 v[200:203], v139 offset:51200
	ds_read_b128 v[204:207], v139 offset:52224
	ds_read_b128 v[208:211], v139 offset:53248
	ds_read_b128 v[212:215], v139 offset:54272
	ds_read_b128 v[216:219], v139 offset:55296
	ds_read_b128 v[222:225], v139 offset:56320
	global_load_lds_dwordx4 v[132:133], off
	s_add_i32 m0, s18, 0x2000
	s_add_u32 s46, s68, 0x80080
	v_lshl_add_u64 v[132:133], v[226:227], 0, s[24:25]
	s_addc_u32 s47, s69, 0
	s_add_i32 s18, s19, s78
	global_load_lds_dwordx4 v[132:133], off
	v_lshl_add_u64 v[132:133], s[46:47], 0, v[144:145]
	s_mov_b32 m0, s18
	s_nop 0
	global_load_lds_dwordx4 v[132:133], off
	v_lshl_add_u64 v[132:133], s[46:47], 0, v[146:147]
	s_add_i32 m0, s18, 0x2000
	s_nop 0
	global_load_lds_dwordx4 v[132:133], off
	v_lshl_add_u64 v[132:133], v[228:229], 0, s[24:25]
	s_mov_b32 m0, s88
	s_nop 0
	global_load_lds_dwordx4 v[132:133], off
	v_lshl_add_u64 v[132:133], v[230:231], 0, s[24:25]
	s_mov_b32 m0, s89
	s_nop 0
	global_load_lds_dwordx4 v[132:133], off
	s_waitcnt vmcnt(8)
	s_waitcnt lgkmcnt(0)
	s_barrier
	s_waitcnt lgkmcnt(0)
	v_mfma_f32_16x16x32_bf16 v[60:63], v[140:143], v[192:195], v[60:63]
	v_mfma_f32_16x16x32_bf16 v[56:59], v[156:159], v[192:195], v[56:59]
	v_mfma_f32_16x16x32_bf16 v[52:55], v[140:143], v[200:203], v[52:55]
	v_mfma_f32_16x16x32_bf16 v[44:47], v[156:159], v[200:203], v[44:47]
	v_mfma_f32_16x16x32_bf16 v[36:39], v[140:143], v[208:211], v[36:39]
	v_mfma_f32_16x16x32_bf16 v[28:31], v[156:159], v[208:211], v[28:31]
	v_mfma_f32_16x16x32_bf16 v[20:23], v[140:143], v[216:219], v[20:23]
	v_mfma_f32_16x16x32_bf16 v[12:15], v[156:159], v[216:219], v[12:15]
	v_mfma_f32_16x16x32_bf16 v[60:63], v[152:155], v[196:199], v[60:63]
	v_mfma_f32_16x16x32_bf16 v[56:59], v[160:163], v[196:199], v[56:59]
	v_mfma_f32_16x16x32_bf16 v[52:55], v[152:155], v[204:207], v[52:55]
	v_mfma_f32_16x16x32_bf16 v[44:47], v[160:163], v[204:207], v[44:47]
	v_mfma_f32_16x16x32_bf16 v[36:39], v[152:155], v[212:215], v[36:39]
	v_mfma_f32_16x16x32_bf16 v[28:31], v[160:163], v[212:215], v[28:31]
	v_mfma_f32_16x16x32_bf16 v[20:23], v[152:155], v[222:225], v[20:23]
	v_mfma_f32_16x16x32_bf16 v[12:15], v[160:163], v[222:225], v[12:15]
	v_mfma_f32_16x16x32_bf16 v[48:51], v[164:167], v[192:195], v[48:51]
	v_mfma_f32_16x16x32_bf16 v[40:43], v[172:175], v[192:195], v[40:43]
	v_mfma_f32_16x16x32_bf16 v[32:35], v[164:167], v[200:203], v[32:35]
	v_mfma_f32_16x16x32_bf16 v[24:27], v[172:175], v[200:203], v[24:27]
	v_mfma_f32_16x16x32_bf16 v[16:19], v[164:167], v[208:211], v[16:19]
	v_mfma_f32_16x16x32_bf16 v[8:11], v[172:175], v[208:211], v[8:11]
	v_mfma_f32_16x16x32_bf16 v[4:7], v[164:167], v[216:219], v[4:7]
	v_mfma_f32_16x16x32_bf16 v[0:3], v[172:175], v[216:219], v[0:3]
	v_mfma_f32_16x16x32_bf16 v[48:51], v[168:171], v[196:199], v[48:51]
	v_mfma_f32_16x16x32_bf16 v[40:43], v[176:179], v[196:199], v[40:43]
	v_mfma_f32_16x16x32_bf16 v[32:35], v[168:171], v[204:207], v[32:35]
	v_mfma_f32_16x16x32_bf16 v[24:27], v[176:179], v[204:207], v[24:27]
	v_mfma_f32_16x16x32_bf16 v[16:19], v[168:171], v[212:215], v[16:19]
	v_mfma_f32_16x16x32_bf16 v[8:11], v[176:179], v[212:215], v[8:11]
	v_mfma_f32_16x16x32_bf16 v[4:7], v[168:171], v[222:225], v[4:7]
	v_mfma_f32_16x16x32_bf16 v[0:3], v[176:179], v[222:225], v[0:3]
	s_barrier
	s_add_i32 s72, s72, 2
	s_add_u32 s66, s66, 0x100
	s_addc_u32 s67, s67, 0
	s_add_u32 s44, s44, 0x100
	s_addc_u32 s45, s45, 0
	s_cmp_gt_u32 s72, 29
	s_cbranch_scc0 .LBB0_242
	s_and_b64 vcc, exec, s[26:27]
	s_cbranch_vccz .LBB0_245
	s_barrier

; #define PG8_STAGE(bufoff, gbase, voff) do { _Pragma("unroll") for (int _i = 0; _i < 2; ++_i) \
;         __builtin_amdgcn_global_load_lds((const unsigned*)((const char*)(gbase) + (voff)[_i]), (LAS unsigned*)(lds + (bufoff) + ldsw + _i * 8192), 16, 0, 0); } while (0)
; #define PG8_LDA(dst, b, h) do { _Pragma("unroll") for (int m = 0; m < 4; ++m) _Pragma("unroll") for (int k = 0; k < 2; ++k) dst[m][k] = *(const LAS bf16x8*)(lds + PG8_SA(b, h) + aoff + m * 2048 + k * 1024); } while (0)
; #define PG8_LDB(dst, b, h) do { _Pragma("unroll") for (int n = 0; n < 2; ++n) _Pragma("unroll") for (int k = 0; k < 2; ++k) dst[n][k] = *(const LAS bf16x8*)(lds + PG8_SB(b, h) + boff + n * 2048 + k * 1024); } while (0)
; #define PG8_MMA(ai, bj, At, Bt) do { __builtin_amdgcn_s_setprio(1); _Pragma("unroll") for (int m = 0; m < 4; ++m) _Pragma("unroll") for (int n = 0; n < 2; ++n) _Pragma("unroll") for (int k = 0; k < 2; ++k) \
;         acc[ai][bj][m][n] = __builtin_amdgcn_mfma_f32_16x16x32_bf16(Bt[n][k], At[m][k], acc[ai][bj][m][n], 0, 0, 0); __builtin_amdgcn_s_setprio(0); } while (0)
; #define PG8_WAIT_V(n) asm volatile("s_waitcnt vmcnt(" #n ")" ::: "memory")
; #define PG8_WAIT_L(n) asm volatile("s_waitcnt lgkmcnt(" #n ")" ::: "memory")
; #define PG8_BAR __builtin_amdgcn_s_barrier()
; #define PG8_SCHED __builtin_amdgcn_sched_barrier(0)
; template <class Epi, class Sched, bool ALIGN_EPI>
; __device__ __forceinline__ void gemm_phase(LAS unsigned char* lds, const Gemm g, const Sched& S, const Epi& E) {
;     ...
;         for (int t = 0; t < nt; t += 2) {
;             const bool last = (t == nt - 2);
;             const char* a1 = cA + (size_t)(t + 1) * kstep;
;             const char* a2 = last ? nA : cA + (size_t)(t + 2) * kstep; const char* b2 = last ? nB : cB + (size_t)(t + 2) * kstep;
;             const char* a3 = a2 + kstep; const char* b3 = b2 + kstep;
;             PG8_LDB(B0, 0, 0); PG8_LDB(B1, 0, 1); PG8_SCHED; PG8_LDA(At, 0, 0); PG8_STAGE(PG8_SA(1, 1), a1 + hA, voffA);
;             PG8_WAIT_V(8); PG8_WAIT_L(0); PG8_BAR; PG8_MMA(0, 0, At, B0); PG8_MMA(0, 1, At, B1); PG8_BAR; PG8_SCHED;
;             PG8_LDA(At, 0, 1); PG8_STAGE(PG8_SB(0, 0), b2, voffB); PG8_STAGE(PG8_SB(0, 1), b2 + hB, voffB); PG8_STAGE(PG8_SA(0, 0), a2, voffA);
;             PG8_WAIT_V(8); PG8_WAIT_L(0); PG8_BAR; PG8_MMA(1, 0, At, B0); PG8_MMA(1, 1, At, B1); PG8_BAR; PG8_SCHED;
.LBB0_261:
	ds_read_b128 v[128:131], v195
	ds_read_b128 v[132:135], v195 offset:1024
	ds_read_b128 v[136:139], v195 offset:2048
	ds_read_b128 v[140:143], v195 offset:3072
	ds_read_b128 v[162:165], v196
	ds_read_b128 v[166:169], v196 offset:1024
	ds_read_b128 v[170:173], v196 offset:2048
	ds_read_b128 v[174:177], v196 offset:3072
	s_add_u32 s6, s4, 0xfff80080
	s_addc_u32 s7, s5, -1
	s_cmp_eq_u32 s72, 28
	s_cselect_b32 s67, s93, s7
	s_cselect_b32 s66, s94, s6
	s_cselect_b32 s7, s43, s45
	s_cselect_b32 s6, s87, s44
	v_lshl_add_u64 v[178:179], s[4:5], 0, v[154:155]
	s_add_i32 m0, s70, 0xc000
	ds_read_b128 v[200:203], v197
	ds_read_b128 v[204:207], v197 offset:1024
	ds_read_b128 v[208:211], v197 offset:2048
	ds_read_b128 v[212:215], v197 offset:3072
	ds_read_b128 v[216:219], v197 offset:4096
	ds_read_b128 v[222:225], v197 offset:5120
	ds_read_b128 v[226:229], v197 offset:6144
	ds_read_b128 v[230:233], v197 offset:7168
	global_load_lds_dwordx4 v[178:179], off
	v_lshl_add_u64 v[178:179], s[4:5], 0, v[156:157]
	s_add_i32 m0, s70, 0xe000
	s_nop 0
	global_load_lds_dwordx4 v[178:179], off
	s_waitcnt vmcnt(8)
	s_waitcnt lgkmcnt(0)
	s_barrier
	s_waitcnt lgkmcnt(0)
	v_mfma_f32_16x16x32_bf16 v[124:127], v[128:131], v[200:203], v[124:127]
	v_mfma_f32_16x16x32_bf16 v[116:119], v[136:139], v[200:203], v[116:119]
	v_mfma_f32_16x16x32_bf16 v[108:111], v[128:131], v[208:211], v[108:111]
	v_mfma_f32_16x16x32_bf16 v[100:103], v[136:139], v[208:211], v[100:103]
	v_mfma_f32_16x16x32_bf16 v[92:95], v[128:131], v[216:219], v[92:95]
	v_mfma_f32_16x16x32_bf16 v[84:87], v[136:139], v[216:219], v[84:87]
	v_mfma_f32_16x16x32_bf16 v[76:79], v[128:131], v[226:229], v[76:79]
	v_mfma_f32_16x16x32_bf16 v[68:71], v[136:139], v[226:229], v[68:71]
	v_mfma_f32_16x16x32_bf16 v[124:127], v[132:135], v[204:207], v[124:127]
	v_mfma_f32_16x16x32_bf16 v[116:119], v[140:143], v[204:207], v[116:119]
	v_mfma_f32_16x16x32_bf16 v[108:111], v[132:135], v[212:215], v[108:111]
	v_mfma_f32_16x16x32_bf16 v[100:103], v[140:143], v[212:215], v[100:103]
	v_mfma_f32_16x16x32_bf16 v[92:95], v[132:135], v[222:225], v[92:95]
	v_mfma_f32_16x16x32_bf16 v[84:87], v[140:143], v[222:225], v[84:87]
	v_mfma_f32_16x16x32_bf16 v[76:79], v[132:135], v[230:233], v[76:79]
	v_mfma_f32_16x16x32_bf16 v[68:71], v[140:143], v[230:233], v[68:71]
	v_mfma_f32_16x16x32_bf16 v[120:123], v[162:165], v[200:203], v[120:123]
	v_mfma_f32_16x16x32_bf16 v[112:115], v[170:173], v[200:203], v[112:115]
	v_mfma_f32_16x16x32_bf16 v[104:107], v[162:165], v[208:211], v[104:107]
	v_mfma_f32_16x16x32_bf16 v[96:99], v[170:173], v[208:211], v[96:99]
	v_mfma_f32_16x16x32_bf16 v[88:91], v[162:165], v[216:219], v[88:91]
	v_mfma_f32_16x16x32_bf16 v[80:83], v[170:173], v[216:219], v[80:83]
	v_mfma_f32_16x16x32_bf16 v[72:75], v[162:165], v[226:229], v[72:75]
	v_mfma_f32_16x16x32_bf16 v[64:67], v[170:173], v[226:229], v[64:67]
	v_mfma_f32_16x16x32_bf16 v[120:123], v[166:169], v[204:207], v[120:123]
	v_mfma_f32_16x16x32_bf16 v[112:115], v[174:177], v[204:207], v[112:115]
	v_mfma_f32_16x16x32_bf16 v[104:107], v[166:169], v[212:215], v[104:107]
	v_mfma_f32_16x16x32_bf16 v[96:99], v[174:177], v[212:215], v[96:99]
	v_mfma_f32_16x16x32_bf16 v[88:91], v[166:169], v[222:225], v[88:91]
	v_mfma_f32_16x16x32_bf16 v[80:83], v[174:177], v[222:225], v[80:83]
	v_mfma_f32_16x16x32_bf16 v[72:75], v[166:169], v[230:233], v[72:75]
	v_mfma_f32_16x16x32_bf16 v[64:67], v[174:177], v[230:233], v[64:67]
	s_barrier
	s_add_i32 s18, s82, s41
	v_lshl_add_u64 v[178:179], s[6:7], 0, v[144:145]
	s_mov_b32 m0, s18
	ds_read_b128 v[200:203], v197 offset:16384
	ds_read_b128 v[204:207], v197 offset:17408
	ds_read_b128 v[208:211], v197 offset:18432
	ds_read_b128 v[212:215], v197 offset:19456
	ds_read_b128 v[216:219], v197 offset:20480
	ds_read_b128 v[222:225], v197 offset:21504
	ds_read_b128 v[226:229], v197 offset:22528
	ds_read_b128 v[230:233], v197 offset:23552
	global_load_lds_dwordx4 v[178:179], off
	s_add_i32 m0, s18, 0x2000
	s_add_u32 s46, s6, 0x80000
	v_lshl_add_u64 v[234:235], s[6:7], 0, v[146:147]
	s_addc_u32 s47, s7, 0
	s_add_i32 s18, s83, s41
	global_load_lds_dwordx4 v[234:235], off
	v_lshl_add_u64 v[236:237], s[46:47], 0, v[144:145]
	s_mov_b32 m0, s18
	v_lshl_add_u64 v[238:239], s[66:67], 0, v[150:151]
	global_load_lds_dwordx4 v[236:237], off
	v_lshl_add_u64 v[236:237], s[46:47], 0, v[146:147]
	s_add_i32 m0, s18, 0x2000
	s_nop 0
	global_load_lds_dwordx4 v[236:237], off
	v_lshl_add_u64 v[236:237], s[66:67], 0, v[148:149]
	s_mov_b32 m0, s70
	s_nop 0
	global_load_lds_dwordx4 v[236:237], off
	s_mov_b32 m0, s71
	s_nop 0
	global_load_lds_dwordx4 v[238:239], off
	s_waitcnt vmcnt(8)
	s_waitcnt lgkmcnt(0)
	s_barrier
; #define PG8_STAGE(bufoff, gbase, voff) do { _Pragma("unroll") for (int _i = 0; _i < 2; ++_i) \
;         __builtin_amdgcn_global_load_lds((const unsigned*)((const char*)(gbase) + (voff)[_i]), (LAS unsigned*)(lds + (bufoff) + ldsw + _i * 8192), 16, 0, 0); } while (0)
; #define PG8_LDA(dst, b, h) do { _Pragma("unroll") for (int m = 0; m < 4; ++m) _Pragma("unroll") for (int k = 0; k < 2; ++k) dst[m][k] = *(const LAS bf16x8*)(lds + PG8_SA(b, h) + aoff + m * 2048 + k * 1024); } while (0)
; #define PG8_LDB(dst, b, h) do { _Pragma("unroll") for (int n = 0; n < 2; ++n) _Pragma("unroll") for (int k = 0; k < 2; ++k) dst[n][k] = *(const LAS bf16x8*)(lds + PG8_SB(b, h) + boff + n * 2048 + k * 1024); } while (0)
; #define PG8_MMA(ai, bj, At, Bt) do { __builtin_amdgcn_s_setprio(1); _Pragma("unroll") for (int m = 0; m < 4; ++m) _Pragma("unroll") for (int n = 0; n < 2; ++n) _Pragma("unroll") for (int k = 0; k < 2; ++k) \
;         acc[ai][bj][m][n] = __builtin_amdgcn_mfma_f32_16x16x32_bf16(Bt[n][k], At[m][k], acc[ai][bj][m][n], 0, 0, 0); __builtin_amdgcn_s_setprio(0); } while (0)
; #define PG8_WAIT_V(n) asm volatile("s_waitcnt vmcnt(" #n ")" ::: "memory")
; #define PG8_WAIT_L(n) asm volatile("s_waitcnt lgkmcnt(" #n ")" ::: "memory")
; #define PG8_BAR __builtin_amdgcn_s_barrier()
; #define PG8_SCHED __builtin_amdgcn_sched_barrier(0)
; template <class Epi, class Sched, bool ALIGN_EPI>
; __device__ __forceinline__ void gemm_phase(LAS unsigned char* lds, const Gemm g, const Sched& S, const Epi& E) {
;     ...
;             PG8_WAIT_V(8); PG8_WAIT_L(0); PG8_BAR; PG8_MMA(1, 0, At, B0); PG8_MMA(1, 1, At, B1); PG8_BAR; PG8_SCHED;
;             PG8_LDB(B0, 1, 0); PG8_LDB(B1, 1, 1); PG8_SCHED; PG8_LDA(At, 1, 0); PG8_STAGE(PG8_SA(0, 1), a2 + hA, voffA);
;             PG8_WAIT_V(8); PG8_WAIT_L(0); PG8_BAR; PG8_MMA(0, 0, At, B0); PG8_MMA(0, 1, At, B1); PG8_BAR; PG8_SCHED;
;             PG8_LDA(At, 1, 1); PG8_STAGE(PG8_SB(1, 0), b3, voffB); PG8_STAGE(PG8_SB(1, 1), b3 + hB, voffB); PG8_STAGE(PG8_SA(1, 0), a3, voffA);
	s_waitcnt lgkmcnt(0)
	v_mfma_f32_16x16x32_bf16 v[60:63], v[128:131], v[200:203], v[60:63]
	v_mfma_f32_16x16x32_bf16 v[52:55], v[136:139], v[200:203], v[52:55]
	v_mfma_f32_16x16x32_bf16 v[44:47], v[128:131], v[208:211], v[44:47]
	v_mfma_f32_16x16x32_bf16 v[36:39], v[136:139], v[208:211], v[36:39]
	v_mfma_f32_16x16x32_bf16 v[28:31], v[128:131], v[216:219], v[28:31]
	v_mfma_f32_16x16x32_bf16 v[20:23], v[136:139], v[216:219], v[20:23]
	v_mfma_f32_16x16x32_bf16 v[12:15], v[128:131], v[226:229], v[12:15]
	v_mfma_f32_16x16x32_bf16 v[4:7], v[136:139], v[226:229], v[4:7]
	v_mfma_f32_16x16x32_bf16 v[60:63], v[132:135], v[204:207], v[60:63]
	v_mfma_f32_16x16x32_bf16 v[52:55], v[140:143], v[204:207], v[52:55]
	v_mfma_f32_16x16x32_bf16 v[44:47], v[132:135], v[212:215], v[44:47]
	v_mfma_f32_16x16x32_bf16 v[36:39], v[140:143], v[212:215], v[36:39]
	v_mfma_f32_16x16x32_bf16 v[28:31], v[132:135], v[222:225], v[28:31]
	v_mfma_f32_16x16x32_bf16 v[20:23], v[140:143], v[222:225], v[20:23]
	v_mfma_f32_16x16x32_bf16 v[12:15], v[132:135], v[230:233], v[12:15]
	v_mfma_f32_16x16x32_bf16 v[4:7], v[140:143], v[230:233], v[4:7]
	v_mfma_f32_16x16x32_bf16 v[56:59], v[162:165], v[200:203], v[56:59]
	v_mfma_f32_16x16x32_bf16 v[48:51], v[170:173], v[200:203], v[48:51]
	v_mfma_f32_16x16x32_bf16 v[40:43], v[162:165], v[208:211], v[40:43]
	v_mfma_f32_16x16x32_bf16 v[32:35], v[170:173], v[208:211], v[32:35]
	v_mfma_f32_16x16x32_bf16 v[24:27], v[162:165], v[216:219], v[24:27]
	v_mfma_f32_16x16x32_bf16 v[16:19], v[170:173], v[216:219], v[16:19]
	v_mfma_f32_16x16x32_bf16 v[8:11], v[162:165], v[226:229], v[8:11]
	v_mfma_f32_16x16x32_bf16 v[0:3], v[170:173], v[226:229], v[0:3]
	v_mfma_f32_16x16x32_bf16 v[56:59], v[166:169], v[204:207], v[56:59]
	v_mfma_f32_16x16x32_bf16 v[48:51], v[174:177], v[204:207], v[48:51]
	v_mfma_f32_16x16x32_bf16 v[40:43], v[166:169], v[212:215], v[40:43]
	v_mfma_f32_16x16x32_bf16 v[32:35], v[174:177], v[212:215], v[32:35]
	v_mfma_f32_16x16x32_bf16 v[24:27], v[166:169], v[222:225], v[24:27]
	v_mfma_f32_16x16x32_bf16 v[16:19], v[174:177], v[222:225], v[16:19]
	v_mfma_f32_16x16x32_bf16 v[8:11], v[166:169], v[230:233], v[8:11]
	v_mfma_f32_16x16x32_bf16 v[0:3], v[174:177], v[230:233], v[0:3]
	s_barrier
	s_add_i32 s18, 0, 0x18000
	s_add_i32 s19, 0, 0x1c000
	v_add_u32_e32 v140, s18, v193
	v_add_u32_e32 v174, s19, v193
	ds_read_b128 v[128:131], v140
	ds_read_b128 v[132:135], v140 offset:1024
	ds_read_b128 v[136:139], v140 offset:2048
	ds_read_b128 v[140:143], v140 offset:3072
	ds_read_b128 v[162:165], v174
	ds_read_b128 v[166:169], v174 offset:1024
	ds_read_b128 v[170:173], v174 offset:2048
	ds_read_b128 v[174:177], v174 offset:3072
	s_add_u32 s46, s66, 0x80000
	s_addc_u32 s47, s67, 0
	s_mov_b32 m0, s76
	v_lshl_add_u64 v[240:241], s[46:47], 0, v[148:149]
	ds_read_b128 v[200:203], v197 offset:32768
	ds_read_b128 v[204:207], v197 offset:33792
	ds_read_b128 v[208:211], v197 offset:34816
	ds_read_b128 v[212:215], v197 offset:35840
	ds_read_b128 v[216:219], v197 offset:36864
	ds_read_b128 v[222:225], v197 offset:37888
	ds_read_b128 v[226:229], v197 offset:38912
	ds_read_b128 v[230:233], v197 offset:39936
	global_load_lds_dwordx4 v[240:241], off
	v_lshl_add_u64 v[240:241], s[46:47], 0, v[150:151]
	s_mov_b32 m0, s77
	s_nop 0
	global_load_lds_dwordx4 v[240:241], off
	s_waitcnt vmcnt(8)
	s_waitcnt lgkmcnt(0)
	s_barrier
	s_waitcnt lgkmcnt(0)
	v_mfma_f32_16x16x32_bf16 v[124:127], v[128:131], v[200:203], v[124:127]
	v_mfma_f32_16x16x32_bf16 v[116:119], v[136:139], v[200:203], v[116:119]
	v_mfma_f32_16x16x32_bf16 v[108:111], v[128:131], v[208:211], v[108:111]
	v_mfma_f32_16x16x32_bf16 v[100:103], v[136:139], v[208:211], v[100:103]
	v_mfma_f32_16x16x32_bf16 v[92:95], v[128:131], v[216:219], v[92:95]
	v_mfma_f32_16x16x32_bf16 v[84:87], v[136:139], v[216:219], v[84:87]
	v_mfma_f32_16x16x32_bf16 v[76:79], v[128:131], v[226:229], v[76:79]
	v_mfma_f32_16x16x32_bf16 v[68:71], v[136:139], v[226:229], v[68:71]
	v_mfma_f32_16x16x32_bf16 v[124:127], v[132:135], v[204:207], v[124:127]
	v_mfma_f32_16x16x32_bf16 v[116:119], v[140:143], v[204:207], v[116:119]
	v_mfma_f32_16x16x32_bf16 v[108:111], v[132:135], v[212:215], v[108:111]
	v_mfma_f32_16x16x32_bf16 v[100:103], v[140:143], v[212:215], v[100:103]
	v_mfma_f32_16x16x32_bf16 v[92:95], v[132:135], v[222:225], v[92:95]
	v_mfma_f32_16x16x32_bf16 v[84:87], v[140:143], v[222:225], v[84:87]
	v_mfma_f32_16x16x32_bf16 v[76:79], v[132:135], v[230:233], v[76:79]
	v_mfma_f32_16x16x32_bf16 v[68:71], v[140:143], v[230:233], v[68:71]
	v_mfma_f32_16x16x32_bf16 v[120:123], v[162:165], v[200:203], v[120:123]
	v_mfma_f32_16x16x32_bf16 v[112:115], v[170:173], v[200:203], v[112:115]
	v_mfma_f32_16x16x32_bf16 v[104:107], v[162:165], v[208:211], v[104:107]
	v_mfma_f32_16x16x32_bf16 v[96:99], v[170:173], v[208:211], v[96:99]
	v_mfma_f32_16x16x32_bf16 v[88:91], v[162:165], v[216:219], v[88:91]
	v_mfma_f32_16x16x32_bf16 v[80:83], v[170:173], v[216:219], v[80:83]
	v_mfma_f32_16x16x32_bf16 v[72:75], v[162:165], v[226:229], v[72:75]
	v_mfma_f32_16x16x32_bf16 v[64:67], v[170:173], v[226:229], v[64:67]
	v_mfma_f32_16x16x32_bf16 v[120:123], v[166:169], v[204:207], v[120:123]
	v_mfma_f32_16x16x32_bf16 v[112:115], v[174:177], v[204:207], v[112:115]
	v_mfma_f32_16x16x32_bf16 v[104:107], v[166:169], v[212:215], v[104:107]
	v_mfma_f32_16x16x32_bf16 v[96:99], v[174:177], v[212:215], v[96:99]
	v_mfma_f32_16x16x32_bf16 v[88:91], v[166:169], v[222:225], v[88:91]
	v_mfma_f32_16x16x32_bf16 v[80:83], v[174:177], v[222:225], v[80:83]
	v_mfma_f32_16x16x32_bf16 v[72:75], v[166:169], v[230:233], v[72:75]
	v_mfma_f32_16x16x32_bf16 v[64:67], v[174:177], v[230:233], v[64:67]
	s_barrier
; #define PG8_STAGE(bufoff, gbase, voff) do { _Pragma("unroll") for (int _i = 0; _i < 2; ++_i) \
;         __builtin_amdgcn_global_load_lds((const unsigned*)((const char*)(gbase) + (voff)[_i]), (LAS unsigned*)(lds + (bufoff) + ldsw + _i * 8192), 16, 0, 0); } while (0)
; #define PG8_LDA(dst, b, h) do { _Pragma("unroll") for (int m = 0; m < 4; ++m) _Pragma("unroll") for (int k = 0; k < 2; ++k) dst[m][k] = *(const LAS bf16x8*)(lds + PG8_SA(b, h) + aoff + m * 2048 + k * 1024); } while (0)
; #define PG8_MMA(ai, bj, At, Bt) do { __builtin_amdgcn_s_setprio(1); _Pragma("unroll") for (int m = 0; m < 4; ++m) _Pragma("unroll") for (int n = 0; n < 2; ++n) _Pragma("unroll") for (int k = 0; k < 2; ++k) \
;         acc[ai][bj][m][n] = __builtin_amdgcn_mfma_f32_16x16x32_bf16(Bt[n][k], At[m][k], acc[ai][bj][m][n], 0, 0, 0); __builtin_amdgcn_s_setprio(0); } while (0)
; #define PG8_WAIT_V(n) asm volatile("s_waitcnt vmcnt(" #n ")" ::: "memory")
; #define PG8_WAIT_L(n) asm volatile("s_waitcnt lgkmcnt(" #n ")" ::: "memory")
; #define PG8_BAR __builtin_amdgcn_s_barrier()
; #define PG8_SCHED __builtin_amdgcn_sched_barrier(0)
; template <class Epi, class Sched, bool ALIGN_EPI>
; __device__ __forceinline__ void gemm_phase(LAS unsigned char* lds, const Gemm g, const Sched& S, const Epi& E) {
;     ...
;             PG8_LDA(At, 1, 1); PG8_STAGE(PG8_SB(1, 0), b3, voffB); PG8_STAGE(PG8_SB(1, 1), b3 + hB, voffB); PG8_STAGE(PG8_SA(1, 0), a3, voffA);
;             PG8_WAIT_V(8); PG8_WAIT_L(0); PG8_BAR; PG8_MMA(1, 0, At, B0); PG8_MMA(1, 1, At, B1); PG8_BAR; PG8_SCHED;
;         }
	s_add_i32 s18, s18, s41
	v_lshl_add_u64 v[178:179], v[178:179], 0, s[36:37]
	s_mov_b32 m0, s18
	ds_read_b128 v[200:203], v197 offset:49152
	ds_read_b128 v[204:207], v197 offset:50176
	ds_read_b128 v[208:211], v197 offset:51200
	ds_read_b128 v[212:215], v197 offset:52224
	ds_read_b128 v[216:219], v197 offset:53248
	ds_read_b128 v[222:225], v197 offset:54272
	ds_read_b128 v[226:229], v197 offset:55296
	ds_read_b128 v[230:233], v197 offset:56320
	global_load_lds_dwordx4 v[178:179], off
	s_add_i32 m0, s18, 0x2000
	s_add_u32 s6, s6, 0x80080
	v_lshl_add_u64 v[178:179], v[234:235], 0, s[36:37]
	s_addc_u32 s7, s7, 0
	s_add_i32 s18, s19, s41
	global_load_lds_dwordx4 v[178:179], off
	v_lshl_add_u64 v[178:179], s[6:7], 0, v[144:145]
	s_mov_b32 m0, s18
	s_nop 0
	global_load_lds_dwordx4 v[178:179], off
	v_lshl_add_u64 v[178:179], s[6:7], 0, v[146:147]
	s_add_i32 m0, s18, 0x2000
	s_nop 0
	global_load_lds_dwordx4 v[178:179], off
	v_lshl_add_u64 v[178:179], v[236:237], 0, s[36:37]
	s_mov_b32 m0, s78
	s_nop 0
	global_load_lds_dwordx4 v[178:179], off
	v_lshl_add_u64 v[178:179], v[238:239], 0, s[36:37]
	s_mov_b32 m0, s79
	s_nop 0
	global_load_lds_dwordx4 v[178:179], off
	s_waitcnt vmcnt(8)
	s_waitcnt lgkmcnt(0)
	s_barrier
	s_waitcnt lgkmcnt(0)
	v_mfma_f32_16x16x32_bf16 v[60:63], v[128:131], v[200:203], v[60:63]
	v_mfma_f32_16x16x32_bf16 v[52:55], v[136:139], v[200:203], v[52:55]
	v_mfma_f32_16x16x32_bf16 v[44:47], v[128:131], v[208:211], v[44:47]
	v_mfma_f32_16x16x32_bf16 v[36:39], v[136:139], v[208:211], v[36:39]
	v_mfma_f32_16x16x32_bf16 v[28:31], v[128:131], v[216:219], v[28:31]
	v_mfma_f32_16x16x32_bf16 v[20:23], v[136:139], v[216:219], v[20:23]
	v_mfma_f32_16x16x32_bf16 v[12:15], v[128:131], v[226:229], v[12:15]
	v_mfma_f32_16x16x32_bf16 v[4:7], v[136:139], v[226:229], v[4:7]
	v_mfma_f32_16x16x32_bf16 v[60:63], v[132:135], v[204:207], v[60:63]
	v_mfma_f32_16x16x32_bf16 v[52:55], v[140:143], v[204:207], v[52:55]
	v_mfma_f32_16x16x32_bf16 v[44:47], v[132:135], v[212:215], v[44:47]
	v_mfma_f32_16x16x32_bf16 v[36:39], v[140:143], v[212:215], v[36:39]
	v_mfma_f32_16x16x32_bf16 v[28:31], v[132:135], v[222:225], v[28:31]
	v_mfma_f32_16x16x32_bf16 v[20:23], v[140:143], v[222:225], v[20:23]
	v_mfma_f32_16x16x32_bf16 v[12:15], v[132:135], v[230:233], v[12:15]
	v_mfma_f32_16x16x32_bf16 v[4:7], v[140:143], v[230:233], v[4:7]
	v_mfma_f32_16x16x32_bf16 v[56:59], v[162:165], v[200:203], v[56:59]
	v_mfma_f32_16x16x32_bf16 v[48:51], v[170:173], v[200:203], v[48:51]
	v_mfma_f32_16x16x32_bf16 v[40:43], v[162:165], v[208:211], v[40:43]
	v_mfma_f32_16x16x32_bf16 v[32:35], v[170:173], v[208:211], v[32:35]
	v_mfma_f32_16x16x32_bf16 v[24:27], v[162:165], v[216:219], v[24:27]
	v_mfma_f32_16x16x32_bf16 v[16:19], v[170:173], v[216:219], v[16:19]
	v_mfma_f32_16x16x32_bf16 v[8:11], v[162:165], v[226:229], v[8:11]
	v_mfma_f32_16x16x32_bf16 v[0:3], v[170:173], v[226:229], v[0:3]
	v_mfma_f32_16x16x32_bf16 v[56:59], v[166:169], v[204:207], v[56:59]
	v_mfma_f32_16x16x32_bf16 v[48:51], v[174:177], v[204:207], v[48:51]
	v_mfma_f32_16x16x32_bf16 v[40:43], v[166:169], v[212:215], v[40:43]
	v_mfma_f32_16x16x32_bf16 v[32:35], v[174:177], v[212:215], v[32:35]
	v_mfma_f32_16x16x32_bf16 v[24:27], v[166:169], v[222:225], v[24:27]
	v_mfma_f32_16x16x32_bf16 v[16:19], v[174:177], v[222:225], v[16:19]
	v_mfma_f32_16x16x32_bf16 v[8:11], v[166:169], v[230:233], v[8:11]
	v_mfma_f32_16x16x32_bf16 v[0:3], v[174:177], v[230:233], v[0:3]
	s_barrier
	s_add_i32 s72, s72, 2
	s_add_u32 s4, s4, 0x100
	s_addc_u32 s5, s5, 0
	s_add_u32 s44, s44, 0x100
	s_addc_u32 s45, s45, 0
	s_cmp_gt_u32 s72, 29
	s_cbranch_scc0 .LBB0_261
	s_and_b64 vcc, exec, s[38:39]
	s_cbranch_vccz .LBB0_264
	s_barrier

; #define PG8_STAGE(bufoff, gbase, voff) do { _Pragma("unroll") for (int _i = 0; _i < 2; ++_i) \
;         __builtin_amdgcn_global_load_lds((const unsigned*)((const char*)(gbase) + (voff)[_i]), (LAS unsigned*)(lds + (bufoff) + ldsw + _i * 8192), 16, 0, 0); } while (0)
; #define PG8_LDA(dst, b, h) do { _Pragma("unroll") for (int m = 0; m < 4; ++m) _Pragma("unroll") for (int k = 0; k < 2; ++k) dst[m][k] = *(const LAS bf16x8*)(lds + PG8_SA(b, h) + aoff + m * 2048 + k * 1024); } while (0)
; #define PG8_LDB(dst, b, h) do { _Pragma("unroll") for (int n = 0; n < 2; ++n) _Pragma("unroll") for (int k = 0; k < 2; ++k) dst[n][k] = *(const LAS bf16x8*)(lds + PG8_SB(b, h) + boff + n * 2048 + k * 1024); } while (0)
; #define PG8_MMA(ai, bj, At, Bt) do { __builtin_amdgcn_s_setprio(1); _Pragma("unroll") for (int m = 0; m < 4; ++m) _Pragma("unroll") for (int n = 0; n < 2; ++n) _Pragma("unroll") for (int k = 0; k < 2; ++k) \
;         acc[ai][bj][m][n] = __builtin_amdgcn_mfma_f32_16x16x32_bf16(Bt[n][k], At[m][k], acc[ai][bj][m][n], 0, 0, 0); __builtin_amdgcn_s_setprio(0); } while (0)
; #define PG8_WAIT_V(n) asm volatile("s_waitcnt vmcnt(" #n ")" ::: "memory")
; #define PG8_WAIT_L(n) asm volatile("s_waitcnt lgkmcnt(" #n ")" ::: "memory")
; #define PG8_BAR __builtin_amdgcn_s_barrier()
; #define PG8_SCHED __builtin_amdgcn_sched_barrier(0)
; template <class Epi, class Sched, bool ALIGN_EPI>
; __device__ __forceinline__ void gemm_phase(LAS unsigned char* lds, const Gemm g, const Sched& S, const Epi& E) {
;     ...
;         for (int t = 0; t < nt; t += 2) {
;             const bool last = (t == nt - 2);
;             const char* a1 = cA + (size_t)(t + 1) * kstep;
;             const char* a2 = last ? nA : cA + (size_t)(t + 2) * kstep; const char* b2 = last ? nB : cB + (size_t)(t + 2) * kstep;
;             const char* a3 = a2 + kstep; const char* b3 = b2 + kstep;
;             PG8_LDB(B0, 0, 0); PG8_LDB(B1, 0, 1); PG8_SCHED; PG8_LDA(At, 0, 0); PG8_STAGE(PG8_SA(1, 1), a1 + hA, voffA);
;             PG8_WAIT_V(8); PG8_WAIT_L(0); PG8_BAR; PG8_MMA(0, 0, At, B0); PG8_MMA(0, 1, At, B1); PG8_BAR; PG8_SCHED;
;             PG8_LDA(At, 0, 1); PG8_STAGE(PG8_SB(0, 0), b2, voffB); PG8_STAGE(PG8_SB(0, 1), b2 + hB, voffB); PG8_STAGE(PG8_SA(0, 0), a2, voffA);
;             PG8_WAIT_V(8); PG8_WAIT_L(0); PG8_BAR; PG8_MMA(1, 0, At, B0); PG8_MMA(1, 1, At, B1); PG8_BAR; PG8_SCHED;
.LBB0_280:
	ds_read_b128 v[150:153], v148
	ds_read_b128 v[154:157], v148 offset:1024
	ds_read_b128 v[158:161], v148 offset:2048
	ds_read_b128 v[162:165], v148 offset:3072
	ds_read_b128 v[166:169], v149
	ds_read_b128 v[170:173], v149 offset:1024
	ds_read_b128 v[174:177], v149 offset:2048
	ds_read_b128 v[186:189], v149 offset:3072
	s_add_i32 s80, s42, 2
	s_add_u32 s18, s40, 0xf4000080
	s_addc_u32 s19, s41, -1
	s_cmp_lg_u32 s66, s42
	s_cselect_b32 s18, s18, 0
	s_cselect_b32 s19, s19, 0
	s_add_u32 s62, s38, s18
	s_addc_u32 s63, s39, s19
	s_add_u32 s42, s36, s18
	s_addc_u32 s43, s37, s19
	s_mov_b32 m0, s6
	v_lshl_add_u64 v[178:179], v[138:139], 0, s[40:41]
	ds_read_b128 v[190:193], v143
	ds_read_b128 v[194:197], v143 offset:1024
	ds_read_b128 v[198:201], v143 offset:2048
	ds_read_b128 v[202:205], v143 offset:3072
	ds_read_b128 v[206:209], v143 offset:4096
	ds_read_b128 v[210:213], v143 offset:5120
	ds_read_b128 v[214:217], v143 offset:6144
	ds_read_b128 v[222:225], v143 offset:7168
	global_load_lds_dwordx4 v[178:179], off
	v_lshl_add_u64 v[178:179], v[140:141], 0, s[40:41]
	s_mov_b32 m0, s44
	s_nop 0
	global_load_lds_dwordx4 v[178:179], off
	s_waitcnt vmcnt(8)
	s_waitcnt lgkmcnt(0)
	s_barrier
	s_waitcnt lgkmcnt(0)
	v_mfma_f32_16x16x32_bf16 v[124:127], v[150:153], v[190:193], v[124:127]
	v_mfma_f32_16x16x32_bf16 v[120:123], v[158:161], v[190:193], v[120:123]
	v_mfma_f32_16x16x32_bf16 v[108:111], v[150:153], v[198:201], v[108:111]
	v_mfma_f32_16x16x32_bf16 v[104:107], v[158:161], v[198:201], v[104:107]
	v_mfma_f32_16x16x32_bf16 v[92:95], v[150:153], v[206:209], v[92:95]
	v_mfma_f32_16x16x32_bf16 v[88:91], v[158:161], v[206:209], v[88:91]
	v_mfma_f32_16x16x32_bf16 v[76:79], v[150:153], v[214:217], v[76:79]
	v_mfma_f32_16x16x32_bf16 v[72:75], v[158:161], v[214:217], v[72:75]
	v_mfma_f32_16x16x32_bf16 v[124:127], v[154:157], v[194:197], v[124:127]
	v_mfma_f32_16x16x32_bf16 v[120:123], v[162:165], v[194:197], v[120:123]
	v_mfma_f32_16x16x32_bf16 v[108:111], v[154:157], v[202:205], v[108:111]
	v_mfma_f32_16x16x32_bf16 v[104:107], v[162:165], v[202:205], v[104:107]
	v_mfma_f32_16x16x32_bf16 v[92:95], v[154:157], v[210:213], v[92:95]
	v_mfma_f32_16x16x32_bf16 v[88:91], v[162:165], v[210:213], v[88:91]
	v_mfma_f32_16x16x32_bf16 v[76:79], v[154:157], v[222:225], v[76:79]
	v_mfma_f32_16x16x32_bf16 v[72:75], v[162:165], v[222:225], v[72:75]
	v_mfma_f32_16x16x32_bf16 v[116:119], v[166:169], v[190:193], v[116:119]
	v_mfma_f32_16x16x32_bf16 v[112:115], v[174:177], v[190:193], v[112:115]
	v_mfma_f32_16x16x32_bf16 v[100:103], v[166:169], v[198:201], v[100:103]
	v_mfma_f32_16x16x32_bf16 v[96:99], v[174:177], v[198:201], v[96:99]
	v_mfma_f32_16x16x32_bf16 v[84:87], v[166:169], v[206:209], v[84:87]
	v_mfma_f32_16x16x32_bf16 v[80:83], v[174:177], v[206:209], v[80:83]
	v_mfma_f32_16x16x32_bf16 v[68:71], v[166:169], v[214:217], v[68:71]
	v_mfma_f32_16x16x32_bf16 v[64:67], v[174:177], v[214:217], v[64:67]
	v_mfma_f32_16x16x32_bf16 v[116:119], v[170:173], v[194:197], v[116:119]
	v_mfma_f32_16x16x32_bf16 v[112:115], v[186:189], v[194:197], v[112:115]
	v_mfma_f32_16x16x32_bf16 v[100:103], v[170:173], v[202:205], v[100:103]
	v_mfma_f32_16x16x32_bf16 v[96:99], v[186:189], v[202:205], v[96:99]
	v_mfma_f32_16x16x32_bf16 v[84:87], v[170:173], v[210:213], v[84:87]
	v_mfma_f32_16x16x32_bf16 v[80:83], v[186:189], v[210:213], v[80:83]
	v_mfma_f32_16x16x32_bf16 v[68:71], v[170:173], v[222:225], v[68:71]
	v_mfma_f32_16x16x32_bf16 v[64:67], v[186:189], v[222:225], v[64:67]
	s_barrier
	s_mov_b32 m0, s45
	v_lshl_add_u64 v[178:179], s[42:43], 0, v[144:145]
	s_add_u32 s82, s42, 0x80000
	ds_read_b128 v[190:193], v143 offset:16384
	ds_read_b128 v[194:197], v143 offset:17408
	ds_read_b128 v[198:201], v143 offset:18432
	ds_read_b128 v[202:205], v143 offset:19456
	ds_read_b128 v[206:209], v143 offset:20480
	ds_read_b128 v[210:213], v143 offset:21504
	ds_read_b128 v[214:217], v143 offset:22528
	ds_read_b128 v[222:225], v143 offset:23552
	global_load_lds_dwordx4 v[178:179], off
	v_lshl_add_u64 v[218:219], s[42:43], 0, v[146:147]
	s_mov_b32 m0, s46
	s_addc_u32 s83, s43, 0
	global_load_lds_dwordx4 v[218:219], off
	v_lshl_add_u64 v[226:227], s[82:83], 0, v[144:145]
	s_mov_b32 m0, s47
	v_lshl_add_u64 v[228:229], s[62:63], 0, v[130:131]
	global_load_lds_dwordx4 v[226:227], off
	v_lshl_add_u64 v[226:227], s[82:83], 0, v[146:147]
	s_mov_b32 m0, s72
	s_nop 0
	global_load_lds_dwordx4 v[226:227], off
	v_lshl_add_u64 v[226:227], s[62:63], 0, v[128:129]
	s_mov_b32 m0, s27
	s_nop 0
	global_load_lds_dwordx4 v[226:227], off
	s_mov_b32 m0, s75
	s_nop 0
	global_load_lds_dwordx4 v[228:229], off
	s_waitcnt vmcnt(8)
	s_waitcnt lgkmcnt(0)
	s_barrier
; #define PG8_STAGE(bufoff, gbase, voff) do { _Pragma("unroll") for (int _i = 0; _i < 2; ++_i) \
;         __builtin_amdgcn_global_load_lds((const unsigned*)((const char*)(gbase) + (voff)[_i]), (LAS unsigned*)(lds + (bufoff) + ldsw + _i * 8192), 16, 0, 0); } while (0)
; #define PG8_LDA(dst, b, h) do { _Pragma("unroll") for (int m = 0; m < 4; ++m) _Pragma("unroll") for (int k = 0; k < 2; ++k) dst[m][k] = *(const LAS bf16x8*)(lds + PG8_SA(b, h) + aoff + m * 2048 + k * 1024); } while (0)
; #define PG8_LDB(dst, b, h) do { _Pragma("unroll") for (int n = 0; n < 2; ++n) _Pragma("unroll") for (int k = 0; k < 2; ++k) dst[n][k] = *(const LAS bf16x8*)(lds + PG8_SB(b, h) + boff + n * 2048 + k * 1024); } while (0)
; #define PG8_MMA(ai, bj, At, Bt) do { __builtin_amdgcn_s_setprio(1); _Pragma("unroll") for (int m = 0; m < 4; ++m) _Pragma("unroll") for (int n = 0; n < 2; ++n) _Pragma("unroll") for (int k = 0; k < 2; ++k) \
;         acc[ai][bj][m][n] = __builtin_amdgcn_mfma_f32_16x16x32_bf16(Bt[n][k], At[m][k], acc[ai][bj][m][n], 0, 0, 0); __builtin_amdgcn_s_setprio(0); } while (0)
; #define PG8_WAIT_V(n) asm volatile("s_waitcnt vmcnt(" #n ")" ::: "memory")
; #define PG8_WAIT_L(n) asm volatile("s_waitcnt lgkmcnt(" #n ")" ::: "memory")
; #define PG8_BAR __builtin_amdgcn_s_barrier()
; #define PG8_SCHED __builtin_amdgcn_sched_barrier(0)
; template <class Epi, class Sched, bool ALIGN_EPI>
; __device__ __forceinline__ void gemm_phase(LAS unsigned char* lds, const Gemm g, const Sched& S, const Epi& E) {
;     ...
;             PG8_WAIT_V(8); PG8_WAIT_L(0); PG8_BAR; PG8_MMA(1, 0, At, B0); PG8_MMA(1, 1, At, B1); PG8_BAR; PG8_SCHED;
;             PG8_LDB(B0, 1, 0); PG8_LDB(B1, 1, 1); PG8_SCHED; PG8_LDA(At, 1, 0); PG8_STAGE(PG8_SA(0, 1), a2 + hA, voffA);
;             PG8_WAIT_V(8); PG8_WAIT_L(0); PG8_BAR; PG8_MMA(0, 0, At, B0); PG8_MMA(0, 1, At, B1); PG8_BAR; PG8_SCHED;
;             PG8_LDA(At, 1, 1); PG8_STAGE(PG8_SB(1, 0), b3, voffB); PG8_STAGE(PG8_SB(1, 1), b3 + hB, voffB); PG8_STAGE(PG8_SA(1, 0), a3, voffA);
	s_waitcnt lgkmcnt(0)
	v_mfma_f32_16x16x32_bf16 v[60:63], v[150:153], v[190:193], v[60:63]
	v_mfma_f32_16x16x32_bf16 v[56:59], v[158:161], v[190:193], v[56:59]
	v_mfma_f32_16x16x32_bf16 v[44:47], v[150:153], v[198:201], v[44:47]
	v_mfma_f32_16x16x32_bf16 v[40:43], v[158:161], v[198:201], v[40:43]
	v_mfma_f32_16x16x32_bf16 v[28:31], v[150:153], v[206:209], v[28:31]
	v_mfma_f32_16x16x32_bf16 v[24:27], v[158:161], v[206:209], v[24:27]
	v_mfma_f32_16x16x32_bf16 v[12:15], v[150:153], v[214:217], v[12:15]
	v_mfma_f32_16x16x32_bf16 v[8:11], v[158:161], v[214:217], v[8:11]
	v_mfma_f32_16x16x32_bf16 v[60:63], v[154:157], v[194:197], v[60:63]
	v_mfma_f32_16x16x32_bf16 v[56:59], v[162:165], v[194:197], v[56:59]
	v_mfma_f32_16x16x32_bf16 v[44:47], v[154:157], v[202:205], v[44:47]
	v_mfma_f32_16x16x32_bf16 v[40:43], v[162:165], v[202:205], v[40:43]
	v_mfma_f32_16x16x32_bf16 v[28:31], v[154:157], v[210:213], v[28:31]
	v_mfma_f32_16x16x32_bf16 v[24:27], v[162:165], v[210:213], v[24:27]
	v_mfma_f32_16x16x32_bf16 v[12:15], v[154:157], v[222:225], v[12:15]
	v_mfma_f32_16x16x32_bf16 v[8:11], v[162:165], v[222:225], v[8:11]
	v_mfma_f32_16x16x32_bf16 v[52:55], v[166:169], v[190:193], v[52:55]
	v_mfma_f32_16x16x32_bf16 v[48:51], v[174:177], v[190:193], v[48:51]
	v_mfma_f32_16x16x32_bf16 v[36:39], v[166:169], v[198:201], v[36:39]
	v_mfma_f32_16x16x32_bf16 v[32:35], v[174:177], v[198:201], v[32:35]
	v_mfma_f32_16x16x32_bf16 v[20:23], v[166:169], v[206:209], v[20:23]
	v_mfma_f32_16x16x32_bf16 v[16:19], v[174:177], v[206:209], v[16:19]
	v_mfma_f32_16x16x32_bf16 v[4:7], v[166:169], v[214:217], v[4:7]
	v_mfma_f32_16x16x32_bf16 v[0:3], v[174:177], v[214:217], v[0:3]
	v_mfma_f32_16x16x32_bf16 v[52:55], v[170:173], v[194:197], v[52:55]
	v_mfma_f32_16x16x32_bf16 v[48:51], v[186:189], v[194:197], v[48:51]
	v_mfma_f32_16x16x32_bf16 v[36:39], v[170:173], v[202:205], v[36:39]
	v_mfma_f32_16x16x32_bf16 v[32:35], v[186:189], v[202:205], v[32:35]
	v_mfma_f32_16x16x32_bf16 v[20:23], v[170:173], v[210:213], v[20:23]
	v_mfma_f32_16x16x32_bf16 v[16:19], v[186:189], v[210:213], v[16:19]
	v_mfma_f32_16x16x32_bf16 v[4:7], v[170:173], v[222:225], v[4:7]
	v_mfma_f32_16x16x32_bf16 v[0:3], v[186:189], v[222:225], v[0:3]
	s_barrier
	s_add_i32 s18, 0, 0x18000
	s_add_i32 s19, 0, 0x1c000
	v_add_u32_e32 v162, s18, v142
	v_add_u32_e32 v185, s19, v142
	ds_read_b128 v[150:153], v162
	ds_read_b128 v[154:157], v162 offset:1024
	ds_read_b128 v[158:161], v162 offset:2048
	ds_read_b128 v[162:165], v162 offset:3072
	ds_read_b128 v[166:169], v185
	ds_read_b128 v[170:173], v185 offset:1024
	ds_read_b128 v[174:177], v185 offset:2048
	ds_read_b128 v[186:189], v185 offset:3072
	s_add_u32 s62, s62, 0x100000
	s_addc_u32 s63, s63, 0
	s_mov_b32 m0, s76
	v_lshl_add_u64 v[230:231], s[62:63], 0, v[128:129]
	ds_read_b128 v[190:193], v143 offset:32768
	ds_read_b128 v[194:197], v143 offset:33792
	ds_read_b128 v[198:201], v143 offset:34816
	ds_read_b128 v[202:205], v143 offset:35840
	ds_read_b128 v[206:209], v143 offset:36864
	ds_read_b128 v[210:213], v143 offset:37888
	ds_read_b128 v[214:217], v143 offset:38912
	ds_read_b128 v[222:225], v143 offset:39936
	global_load_lds_dwordx4 v[230:231], off
	v_lshl_add_u64 v[230:231], s[62:63], 0, v[130:131]
	s_mov_b32 m0, s77
	s_nop 0
	global_load_lds_dwordx4 v[230:231], off
	s_waitcnt vmcnt(8)
	s_waitcnt lgkmcnt(0)
	s_barrier
	s_waitcnt lgkmcnt(0)
	v_mfma_f32_16x16x32_bf16 v[124:127], v[150:153], v[190:193], v[124:127]
	v_mfma_f32_16x16x32_bf16 v[120:123], v[158:161], v[190:193], v[120:123]
	v_mfma_f32_16x16x32_bf16 v[108:111], v[150:153], v[198:201], v[108:111]
	v_mfma_f32_16x16x32_bf16 v[104:107], v[158:161], v[198:201], v[104:107]
	v_mfma_f32_16x16x32_bf16 v[92:95], v[150:153], v[206:209], v[92:95]
	v_mfma_f32_16x16x32_bf16 v[88:91], v[158:161], v[206:209], v[88:91]
	v_mfma_f32_16x16x32_bf16 v[76:79], v[150:153], v[214:217], v[76:79]
	v_mfma_f32_16x16x32_bf16 v[72:75], v[158:161], v[214:217], v[72:75]
	v_mfma_f32_16x16x32_bf16 v[124:127], v[154:157], v[194:197], v[124:127]
	v_mfma_f32_16x16x32_bf16 v[120:123], v[162:165], v[194:197], v[120:123]
	v_mfma_f32_16x16x32_bf16 v[108:111], v[154:157], v[202:205], v[108:111]
	v_mfma_f32_16x16x32_bf16 v[104:107], v[162:165], v[202:205], v[104:107]
	v_mfma_f32_16x16x32_bf16 v[92:95], v[154:157], v[210:213], v[92:95]
	v_mfma_f32_16x16x32_bf16 v[88:91], v[162:165], v[210:213], v[88:91]
	v_mfma_f32_16x16x32_bf16 v[76:79], v[154:157], v[222:225], v[76:79]
	v_mfma_f32_16x16x32_bf16 v[72:75], v[162:165], v[222:225], v[72:75]
	v_mfma_f32_16x16x32_bf16 v[116:119], v[166:169], v[190:193], v[116:119]
	v_mfma_f32_16x16x32_bf16 v[112:115], v[174:177], v[190:193], v[112:115]
	v_mfma_f32_16x16x32_bf16 v[100:103], v[166:169], v[198:201], v[100:103]
	v_mfma_f32_16x16x32_bf16 v[96:99], v[174:177], v[198:201], v[96:99]
	v_mfma_f32_16x16x32_bf16 v[84:87], v[166:169], v[206:209], v[84:87]
	v_mfma_f32_16x16x32_bf16 v[80:83], v[174:177], v[206:209], v[80:83]
	v_mfma_f32_16x16x32_bf16 v[68:71], v[166:169], v[214:217], v[68:71]
	v_mfma_f32_16x16x32_bf16 v[64:67], v[174:177], v[214:217], v[64:67]
	v_mfma_f32_16x16x32_bf16 v[116:119], v[170:173], v[194:197], v[116:119]
	v_mfma_f32_16x16x32_bf16 v[112:115], v[186:189], v[194:197], v[112:115]
	v_mfma_f32_16x16x32_bf16 v[100:103], v[170:173], v[202:205], v[100:103]
	v_mfma_f32_16x16x32_bf16 v[96:99], v[186:189], v[202:205], v[96:99]
	v_mfma_f32_16x16x32_bf16 v[84:87], v[170:173], v[210:213], v[84:87]
	v_mfma_f32_16x16x32_bf16 v[80:83], v[186:189], v[210:213], v[80:83]
	v_mfma_f32_16x16x32_bf16 v[68:71], v[170:173], v[222:225], v[68:71]
	v_mfma_f32_16x16x32_bf16 v[64:67], v[186:189], v[222:225], v[64:67]
	s_barrier
; #define PG8_STAGE(bufoff, gbase, voff) do { _Pragma("unroll") for (int _i = 0; _i < 2; ++_i) \
;         __builtin_amdgcn_global_load_lds((const unsigned*)((const char*)(gbase) + (voff)[_i]), (LAS unsigned*)(lds + (bufoff) + ldsw + _i * 8192), 16, 0, 0); } while (0)
; #define PG8_LDA(dst, b, h) do { _Pragma("unroll") for (int m = 0; m < 4; ++m) _Pragma("unroll") for (int k = 0; k < 2; ++k) dst[m][k] = *(const LAS bf16x8*)(lds + PG8_SA(b, h) + aoff + m * 2048 + k * 1024); } while (0)
; #define PG8_MMA(ai, bj, At, Bt) do { __builtin_amdgcn_s_setprio(1); _Pragma("unroll") for (int m = 0; m < 4; ++m) _Pragma("unroll") for (int n = 0; n < 2; ++n) _Pragma("unroll") for (int k = 0; k < 2; ++k) \
;         acc[ai][bj][m][n] = __builtin_amdgcn_mfma_f32_16x16x32_bf16(Bt[n][k], At[m][k], acc[ai][bj][m][n], 0, 0, 0); __builtin_amdgcn_s_setprio(0); } while (0)
; #define PG8_WAIT_V(n) asm volatile("s_waitcnt vmcnt(" #n ")" ::: "memory")
; #define PG8_WAIT_L(n) asm volatile("s_waitcnt lgkmcnt(" #n ")" ::: "memory")
; #define PG8_BAR __builtin_amdgcn_s_barrier()
; #define PG8_SCHED __builtin_amdgcn_sched_barrier(0)
; template <class Epi, class Sched, bool ALIGN_EPI>
; __device__ __forceinline__ void gemm_phase(LAS unsigned char* lds, const Gemm g, const Sched& S, const Epi& E) {
;     ...
;             PG8_LDA(At, 1, 1); PG8_STAGE(PG8_SB(1, 0), b3, voffB); PG8_STAGE(PG8_SB(1, 1), b3 + hB, voffB); PG8_STAGE(PG8_SA(1, 0), a3, voffA);
;             PG8_WAIT_V(8); PG8_WAIT_L(0); PG8_BAR; PG8_MMA(1, 0, At, B0); PG8_MMA(1, 1, At, B1); PG8_BAR; PG8_SCHED;
;         }
	s_add_i32 s18, s18, s11
	v_lshl_add_u64 v[178:179], v[178:179], 0, s[24:25]
	s_mov_b32 m0, s18
	ds_read_b128 v[190:193], v143 offset:49152
	ds_read_b128 v[194:197], v143 offset:50176
	ds_read_b128 v[198:201], v143 offset:51200
	ds_read_b128 v[202:205], v143 offset:52224
	ds_read_b128 v[206:209], v143 offset:53248
	ds_read_b128 v[210:213], v143 offset:54272
	ds_read_b128 v[214:217], v143 offset:55296
	ds_read_b128 v[222:225], v143 offset:56320
	global_load_lds_dwordx4 v[178:179], off
	s_add_i32 m0, s18, 0x2000
	s_add_u32 s42, s42, 0x80080
	v_lshl_add_u64 v[178:179], v[218:219], 0, s[24:25]
	s_addc_u32 s43, s43, 0
	s_add_i32 s18, s19, s11
	global_load_lds_dwordx4 v[178:179], off
	v_lshl_add_u64 v[178:179], s[42:43], 0, v[144:145]
	s_mov_b32 m0, s18
	s_nop 0
	global_load_lds_dwordx4 v[178:179], off
	v_lshl_add_u64 v[178:179], s[42:43], 0, v[146:147]
	s_add_i32 m0, s18, 0x2000
	s_nop 0
	global_load_lds_dwordx4 v[178:179], off
	v_lshl_add_u64 v[178:179], v[226:227], 0, s[24:25]
	s_mov_b32 m0, s78
	s_nop 0
	global_load_lds_dwordx4 v[178:179], off
	v_lshl_add_u64 v[178:179], v[228:229], 0, s[24:25]
	s_mov_b32 m0, s79
	s_nop 0
	global_load_lds_dwordx4 v[178:179], off
	s_waitcnt vmcnt(8)
	s_waitcnt lgkmcnt(0)
	s_barrier
	s_waitcnt lgkmcnt(0)
	v_mfma_f32_16x16x32_bf16 v[60:63], v[150:153], v[190:193], v[60:63]
	v_mfma_f32_16x16x32_bf16 v[56:59], v[158:161], v[190:193], v[56:59]
	v_mfma_f32_16x16x32_bf16 v[44:47], v[150:153], v[198:201], v[44:47]
	v_mfma_f32_16x16x32_bf16 v[40:43], v[158:161], v[198:201], v[40:43]
	v_mfma_f32_16x16x32_bf16 v[28:31], v[150:153], v[206:209], v[28:31]
	v_mfma_f32_16x16x32_bf16 v[24:27], v[158:161], v[206:209], v[24:27]
	v_mfma_f32_16x16x32_bf16 v[12:15], v[150:153], v[214:217], v[12:15]
	v_mfma_f32_16x16x32_bf16 v[8:11], v[158:161], v[214:217], v[8:11]
	v_mfma_f32_16x16x32_bf16 v[60:63], v[154:157], v[194:197], v[60:63]
	v_mfma_f32_16x16x32_bf16 v[56:59], v[162:165], v[194:197], v[56:59]
	v_mfma_f32_16x16x32_bf16 v[44:47], v[154:157], v[202:205], v[44:47]
	v_mfma_f32_16x16x32_bf16 v[40:43], v[162:165], v[202:205], v[40:43]
	v_mfma_f32_16x16x32_bf16 v[28:31], v[154:157], v[210:213], v[28:31]
	v_mfma_f32_16x16x32_bf16 v[24:27], v[162:165], v[210:213], v[24:27]
	v_mfma_f32_16x16x32_bf16 v[12:15], v[154:157], v[222:225], v[12:15]
	v_mfma_f32_16x16x32_bf16 v[8:11], v[162:165], v[222:225], v[8:11]
	v_mfma_f32_16x16x32_bf16 v[52:55], v[166:169], v[190:193], v[52:55]
	v_mfma_f32_16x16x32_bf16 v[48:51], v[174:177], v[190:193], v[48:51]
	v_mfma_f32_16x16x32_bf16 v[36:39], v[166:169], v[198:201], v[36:39]
	v_mfma_f32_16x16x32_bf16 v[32:35], v[174:177], v[198:201], v[32:35]
	v_mfma_f32_16x16x32_bf16 v[20:23], v[166:169], v[206:209], v[20:23]
	v_mfma_f32_16x16x32_bf16 v[16:19], v[174:177], v[206:209], v[16:19]
	v_mfma_f32_16x16x32_bf16 v[4:7], v[166:169], v[214:217], v[4:7]
	v_mfma_f32_16x16x32_bf16 v[0:3], v[174:177], v[214:217], v[0:3]
	v_mfma_f32_16x16x32_bf16 v[52:55], v[170:173], v[194:197], v[52:55]
	v_mfma_f32_16x16x32_bf16 v[48:51], v[186:189], v[194:197], v[48:51]
	v_mfma_f32_16x16x32_bf16 v[36:39], v[170:173], v[202:205], v[36:39]
	v_mfma_f32_16x16x32_bf16 v[32:35], v[186:189], v[202:205], v[32:35]
	v_mfma_f32_16x16x32_bf16 v[20:23], v[170:173], v[210:213], v[20:23]
	v_mfma_f32_16x16x32_bf16 v[16:19], v[186:189], v[210:213], v[16:19]
	v_mfma_f32_16x16x32_bf16 v[4:7], v[170:173], v[222:225], v[4:7]
	v_mfma_f32_16x16x32_bf16 v[0:3], v[186:189], v[222:225], v[0:3]
	s_barrier
	s_add_u32 s40, s40, 0x100
	s_addc_u32 s41, s41, 0
	s_cmp_ge_i32 s80, s65
	s_mov_b32 s42, s80
	s_cbranch_scc0 .LBB0_280

; #define PG8_STAGE(bufoff, gbase, voff) do { _Pragma("unroll") for (int _i = 0; _i < 2; ++_i) \
;         __builtin_amdgcn_global_load_lds((const unsigned*)((const char*)(gbase) + (voff)[_i]), (LAS unsigned*)(lds + (bufoff) + ldsw + _i * 8192), 16, 0, 0); } while (0)
; #define PG8_LDA(dst, b, h) do { _Pragma("unroll") for (int m = 0; m < 4; ++m) _Pragma("unroll") for (int k = 0; k < 2; ++k) dst[m][k] = *(const LAS bf16x8*)(lds + PG8_SA(b, h) + aoff + m * 2048 + k * 1024); } while (0)
; #define PG8_LDB(dst, b, h) do { _Pragma("unroll") for (int n = 0; n < 2; ++n) _Pragma("unroll") for (int k = 0; k < 2; ++k) dst[n][k] = *(const LAS bf16x8*)(lds + PG8_SB(b, h) + boff + n * 2048 + k * 1024); } while (0)
; #define PG8_MMA(ai, bj, At, Bt) do { __builtin_amdgcn_s_setprio(1); _Pragma("unroll") for (int m = 0; m < 4; ++m) _Pragma("unroll") for (int n = 0; n < 2; ++n) _Pragma("unroll") for (int k = 0; k < 2; ++k) \
;         acc[ai][bj][m][n] = __builtin_amdgcn_mfma_f32_16x16x32_bf16(Bt[n][k], At[m][k], acc[ai][bj][m][n], 0, 0, 0); __builtin_amdgcn_s_setprio(0); } while (0)
; #define PG8_WAIT_V(n) asm volatile("s_waitcnt vmcnt(" #n ")" ::: "memory")
; #define PG8_WAIT_L(n) asm volatile("s_waitcnt lgkmcnt(" #n ")" ::: "memory")
; #define PG8_BAR __builtin_amdgcn_s_barrier()
; #define PG8_SCHED __builtin_amdgcn_sched_barrier(0)
; template <class Epi, class Sched, bool ALIGN_EPI>
; __device__ __forceinline__ void gemm_phase(LAS unsigned char* lds, const Gemm g, const Sched& S, const Epi& E) {
;     ...
;         for (int t = 0; t < nt; t += 2) {
;             const bool last = (t == nt - 2);
;             const char* a1 = cA + (size_t)(t + 1) * kstep;
;             const char* a2 = last ? nA : cA + (size_t)(t + 2) * kstep; const char* b2 = last ? nB : cB + (size_t)(t + 2) * kstep;
;             const char* a3 = a2 + kstep; const char* b3 = b2 + kstep;
;             PG8_LDB(B0, 0, 0); PG8_LDB(B1, 0, 1); PG8_SCHED; PG8_LDA(At, 0, 0); PG8_STAGE(PG8_SA(1, 1), a1 + hA, voffA);
;             PG8_WAIT_V(8); PG8_WAIT_L(0); PG8_BAR; PG8_MMA(0, 0, At, B0); PG8_MMA(0, 1, At, B1); PG8_BAR; PG8_SCHED;
;             PG8_LDA(At, 0, 1); PG8_STAGE(PG8_SB(0, 0), b2, voffB); PG8_STAGE(PG8_SB(0, 1), b2 + hB, voffB); PG8_STAGE(PG8_SA(0, 0), a2, voffA);
;             PG8_WAIT_V(8); PG8_WAIT_L(0); PG8_BAR; PG8_MMA(1, 0, At, B0); PG8_MMA(1, 1, At, B1); PG8_BAR; PG8_SCHED;
.LBB0_361:
	ds_read_b128 v[144:147], v151
	ds_read_b128 v[156:159], v151 offset:1024
	ds_read_b128 v[160:163], v151 offset:2048
	ds_read_b128 v[164:167], v151 offset:3072
	ds_read_b128 v[168:171], v152
	ds_read_b128 v[172:175], v152 offset:1024
	ds_read_b128 v[176:179], v152 offset:2048
	ds_read_b128 v[180:183], v152 offset:3072
	s_add_u32 s18, s42, 0xffea0080
	s_addc_u32 s19, s43, -1
	s_cmpk_eq_i32 s84, 0x54
	s_cselect_b32 s63, s81, s19
	s_cselect_b32 s62, s82, s18
	s_cselect_b32 s61, s37, s45
	s_cselect_b32 s60, s83, s44
	v_lshl_add_u64 v[216:217], s[42:43], 0, v[136:137]
	s_add_i32 m0, s66, 0xc000
	ds_read_b128 v[184:187], v153
	ds_read_b128 v[188:191], v153 offset:1024
	ds_read_b128 v[192:195], v153 offset:2048
	ds_read_b128 v[196:199], v153 offset:3072
	ds_read_b128 v[200:203], v153 offset:4096
	ds_read_b128 v[204:207], v153 offset:5120
	ds_read_b128 v[208:211], v153 offset:6144
	ds_read_b128 v[212:215], v153 offset:7168
	global_load_lds_dwordx4 v[216:217], off
	v_lshl_add_u64 v[216:217], s[42:43], 0, v[138:139]
	s_add_i32 m0, s66, 0xe000
	s_nop 0
	global_load_lds_dwordx4 v[216:217], off
	s_waitcnt vmcnt(8)
	s_waitcnt lgkmcnt(0)
	s_barrier
	s_waitcnt lgkmcnt(0)
	v_mfma_f32_16x16x32_bf16 v[124:127], v[144:147], v[184:187], v[124:127]
	v_mfma_f32_16x16x32_bf16 v[120:123], v[160:163], v[184:187], v[120:123]
	v_mfma_f32_16x16x32_bf16 v[108:111], v[144:147], v[192:195], v[108:111]
	v_mfma_f32_16x16x32_bf16 v[104:107], v[160:163], v[192:195], v[104:107]
	v_mfma_f32_16x16x32_bf16 v[92:95], v[144:147], v[200:203], v[92:95]
	v_mfma_f32_16x16x32_bf16 v[88:91], v[160:163], v[200:203], v[88:91]
	v_mfma_f32_16x16x32_bf16 v[76:79], v[144:147], v[208:211], v[76:79]
	v_mfma_f32_16x16x32_bf16 v[72:75], v[160:163], v[208:211], v[72:75]
	v_mfma_f32_16x16x32_bf16 v[124:127], v[156:159], v[188:191], v[124:127]
	v_mfma_f32_16x16x32_bf16 v[120:123], v[164:167], v[188:191], v[120:123]
	v_mfma_f32_16x16x32_bf16 v[108:111], v[156:159], v[196:199], v[108:111]
	v_mfma_f32_16x16x32_bf16 v[104:107], v[164:167], v[196:199], v[104:107]
	v_mfma_f32_16x16x32_bf16 v[92:95], v[156:159], v[204:207], v[92:95]
	v_mfma_f32_16x16x32_bf16 v[88:91], v[164:167], v[204:207], v[88:91]
	v_mfma_f32_16x16x32_bf16 v[76:79], v[156:159], v[212:215], v[76:79]
	v_mfma_f32_16x16x32_bf16 v[72:75], v[164:167], v[212:215], v[72:75]
	v_mfma_f32_16x16x32_bf16 v[116:119], v[168:171], v[184:187], v[116:119]
	v_mfma_f32_16x16x32_bf16 v[112:115], v[176:179], v[184:187], v[112:115]
	v_mfma_f32_16x16x32_bf16 v[100:103], v[168:171], v[192:195], v[100:103]
	v_mfma_f32_16x16x32_bf16 v[96:99], v[176:179], v[192:195], v[96:99]
	v_mfma_f32_16x16x32_bf16 v[84:87], v[168:171], v[200:203], v[84:87]
	v_mfma_f32_16x16x32_bf16 v[80:83], v[176:179], v[200:203], v[80:83]
	v_mfma_f32_16x16x32_bf16 v[68:71], v[168:171], v[208:211], v[68:71]
	v_mfma_f32_16x16x32_bf16 v[64:67], v[176:179], v[208:211], v[64:67]
	v_mfma_f32_16x16x32_bf16 v[116:119], v[172:175], v[188:191], v[116:119]
	v_mfma_f32_16x16x32_bf16 v[112:115], v[180:183], v[188:191], v[112:115]
	v_mfma_f32_16x16x32_bf16 v[100:103], v[172:175], v[196:199], v[100:103]
	v_mfma_f32_16x16x32_bf16 v[96:99], v[180:183], v[196:199], v[96:99]
	v_mfma_f32_16x16x32_bf16 v[84:87], v[172:175], v[204:207], v[84:87]
	v_mfma_f32_16x16x32_bf16 v[80:83], v[180:183], v[204:207], v[80:83]
	v_mfma_f32_16x16x32_bf16 v[68:71], v[172:175], v[212:215], v[68:71]
	v_mfma_f32_16x16x32_bf16 v[64:67], v[180:183], v[212:215], v[64:67]
	s_barrier
	s_add_i32 s18, s76, s65
	v_lshl_add_u64 v[216:217], s[60:61], 0, v[130:131]
	s_mov_b32 m0, s18
	ds_read_b128 v[184:187], v153 offset:16384
	ds_read_b128 v[188:191], v153 offset:17408
	ds_read_b128 v[192:195], v153 offset:18432
	ds_read_b128 v[196:199], v153 offset:19456
	ds_read_b128 v[200:203], v153 offset:20480
	ds_read_b128 v[204:207], v153 offset:21504
	ds_read_b128 v[208:211], v153 offset:22528
	ds_read_b128 v[212:215], v153 offset:23552
	global_load_lds_dwordx4 v[216:217], off
	s_add_i32 m0, s18, 0x2000
	s_add_u32 s46, s60, 0x160000
	v_lshl_add_u64 v[218:219], s[60:61], 0, v[134:135]
	s_addc_u32 s47, s61, 0
	s_add_i32 s18, s77, s65
	global_load_lds_dwordx4 v[218:219], off
	v_lshl_add_u64 v[222:223], s[46:47], 0, v[130:131]
	s_mov_b32 m0, s18
	v_lshl_add_u64 v[224:225], s[62:63], 0, v[132:133]
	global_load_lds_dwordx4 v[222:223], off
	v_lshl_add_u64 v[222:223], s[46:47], 0, v[134:135]
	s_add_i32 m0, s18, 0x2000
	s_nop 0
	global_load_lds_dwordx4 v[222:223], off
	v_lshl_add_u64 v[222:223], s[62:63], 0, v[128:129]
	s_mov_b32 m0, s66
	s_nop 0
	global_load_lds_dwordx4 v[222:223], off
	s_mov_b32 m0, s67
	s_nop 0
	global_load_lds_dwordx4 v[224:225], off
	s_waitcnt vmcnt(8)
	s_waitcnt lgkmcnt(0)
	s_barrier
; #define PG8_STAGE(bufoff, gbase, voff) do { _Pragma("unroll") for (int _i = 0; _i < 2; ++_i) \
;         __builtin_amdgcn_global_load_lds((const unsigned*)((const char*)(gbase) + (voff)[_i]), (LAS unsigned*)(lds + (bufoff) + ldsw + _i * 8192), 16, 0, 0); } while (0)
; #define PG8_LDA(dst, b, h) do { _Pragma("unroll") for (int m = 0; m < 4; ++m) _Pragma("unroll") for (int k = 0; k < 2; ++k) dst[m][k] = *(const LAS bf16x8*)(lds + PG8_SA(b, h) + aoff + m * 2048 + k * 1024); } while (0)
; #define PG8_LDB(dst, b, h) do { _Pragma("unroll") for (int n = 0; n < 2; ++n) _Pragma("unroll") for (int k = 0; k < 2; ++k) dst[n][k] = *(const LAS bf16x8*)(lds + PG8_SB(b, h) + boff + n * 2048 + k * 1024); } while (0)
; #define PG8_MMA(ai, bj, At, Bt) do { __builtin_amdgcn_s_setprio(1); _Pragma("unroll") for (int m = 0; m < 4; ++m) _Pragma("unroll") for (int n = 0; n < 2; ++n) _Pragma("unroll") for (int k = 0; k < 2; ++k) \
;         acc[ai][bj][m][n] = __builtin_amdgcn_mfma_f32_16x16x32_bf16(Bt[n][k], At[m][k], acc[ai][bj][m][n], 0, 0, 0); __builtin_amdgcn_s_setprio(0); } while (0)
; #define PG8_WAIT_V(n) asm volatile("s_waitcnt vmcnt(" #n ")" ::: "memory")
; #define PG8_WAIT_L(n) asm volatile("s_waitcnt lgkmcnt(" #n ")" ::: "memory")
; #define PG8_BAR __builtin_amdgcn_s_barrier()
; #define PG8_SCHED __builtin_amdgcn_sched_barrier(0)
; template <class Epi, class Sched, bool ALIGN_EPI>
; __device__ __forceinline__ void gemm_phase(LAS unsigned char* lds, const Gemm g, const Sched& S, const Epi& E) {
;     ...
;             PG8_WAIT_V(8); PG8_WAIT_L(0); PG8_BAR; PG8_MMA(1, 0, At, B0); PG8_MMA(1, 1, At, B1); PG8_BAR; PG8_SCHED;
;             PG8_LDB(B0, 1, 0); PG8_LDB(B1, 1, 1); PG8_SCHED; PG8_LDA(At, 1, 0); PG8_STAGE(PG8_SA(0, 1), a2 + hA, voffA);
;             PG8_WAIT_V(8); PG8_WAIT_L(0); PG8_BAR; PG8_MMA(0, 0, At, B0); PG8_MMA(0, 1, At, B1); PG8_BAR; PG8_SCHED;
;             PG8_LDA(At, 1, 1); PG8_STAGE(PG8_SB(1, 0), b3, voffB); PG8_STAGE(PG8_SB(1, 1), b3 + hB, voffB); PG8_STAGE(PG8_SA(1, 0), a3, voffA);
	s_waitcnt lgkmcnt(0)
	v_mfma_f32_16x16x32_bf16 v[60:63], v[144:147], v[184:187], v[60:63]
	v_mfma_f32_16x16x32_bf16 v[56:59], v[160:163], v[184:187], v[56:59]
	v_mfma_f32_16x16x32_bf16 v[44:47], v[144:147], v[192:195], v[44:47]
	v_mfma_f32_16x16x32_bf16 v[40:43], v[160:163], v[192:195], v[40:43]
	v_mfma_f32_16x16x32_bf16 v[28:31], v[144:147], v[200:203], v[28:31]
	v_mfma_f32_16x16x32_bf16 v[24:27], v[160:163], v[200:203], v[24:27]
	v_mfma_f32_16x16x32_bf16 v[12:15], v[144:147], v[208:211], v[12:15]
	v_mfma_f32_16x16x32_bf16 v[8:11], v[160:163], v[208:211], v[8:11]
	v_mfma_f32_16x16x32_bf16 v[60:63], v[156:159], v[188:191], v[60:63]
	v_mfma_f32_16x16x32_bf16 v[56:59], v[164:167], v[188:191], v[56:59]
	v_mfma_f32_16x16x32_bf16 v[44:47], v[156:159], v[196:199], v[44:47]
	v_mfma_f32_16x16x32_bf16 v[40:43], v[164:167], v[196:199], v[40:43]
	v_mfma_f32_16x16x32_bf16 v[28:31], v[156:159], v[204:207], v[28:31]
	v_mfma_f32_16x16x32_bf16 v[24:27], v[164:167], v[204:207], v[24:27]
	v_mfma_f32_16x16x32_bf16 v[12:15], v[156:159], v[212:215], v[12:15]
	v_mfma_f32_16x16x32_bf16 v[8:11], v[164:167], v[212:215], v[8:11]
	v_mfma_f32_16x16x32_bf16 v[52:55], v[168:171], v[184:187], v[52:55]
	v_mfma_f32_16x16x32_bf16 v[48:51], v[176:179], v[184:187], v[48:51]
	v_mfma_f32_16x16x32_bf16 v[36:39], v[168:171], v[192:195], v[36:39]
	v_mfma_f32_16x16x32_bf16 v[32:35], v[176:179], v[192:195], v[32:35]
	v_mfma_f32_16x16x32_bf16 v[20:23], v[168:171], v[200:203], v[20:23]
	v_mfma_f32_16x16x32_bf16 v[16:19], v[176:179], v[200:203], v[16:19]
	v_mfma_f32_16x16x32_bf16 v[4:7], v[168:171], v[208:211], v[4:7]
	v_mfma_f32_16x16x32_bf16 v[0:3], v[176:179], v[208:211], v[0:3]
	v_mfma_f32_16x16x32_bf16 v[52:55], v[172:175], v[188:191], v[52:55]
	v_mfma_f32_16x16x32_bf16 v[48:51], v[180:183], v[188:191], v[48:51]
	v_mfma_f32_16x16x32_bf16 v[36:39], v[172:175], v[196:199], v[36:39]
	v_mfma_f32_16x16x32_bf16 v[32:35], v[180:183], v[196:199], v[32:35]
	v_mfma_f32_16x16x32_bf16 v[20:23], v[172:175], v[204:207], v[20:23]
	v_mfma_f32_16x16x32_bf16 v[16:19], v[180:183], v[204:207], v[16:19]
	v_mfma_f32_16x16x32_bf16 v[4:7], v[172:175], v[212:215], v[4:7]
	v_mfma_f32_16x16x32_bf16 v[0:3], v[180:183], v[212:215], v[0:3]
	s_barrier
	s_add_i32 s18, 0, 0x18000
	v_add_u32_e32 v155, s18, v149
	s_add_i32 s19, 0, 0x1c000
	ds_read_b128 v[144:147], v155
	ds_read_b128 v[156:159], v155 offset:1024
	ds_read_b128 v[160:163], v155 offset:2048
	ds_read_b128 v[164:167], v155 offset:3072
	v_add_u32_e32 v155, s19, v149
	ds_read_b128 v[168:171], v155
	ds_read_b128 v[172:175], v155 offset:1024
	ds_read_b128 v[176:179], v155 offset:2048
	ds_read_b128 v[180:183], v155 offset:3072
	s_add_u32 s46, s62, 0x160000
	s_addc_u32 s47, s63, 0
	s_mov_b32 m0, s68
	v_lshl_add_u64 v[226:227], s[46:47], 0, v[128:129]
	ds_read_b128 v[184:187], v153 offset:32768
	ds_read_b128 v[188:191], v153 offset:33792
	ds_read_b128 v[192:195], v153 offset:34816
	ds_read_b128 v[196:199], v153 offset:35840
	ds_read_b128 v[200:203], v153 offset:36864
	ds_read_b128 v[204:207], v153 offset:37888
	ds_read_b128 v[208:211], v153 offset:38912
	ds_read_b128 v[212:215], v153 offset:39936
	global_load_lds_dwordx4 v[226:227], off
	v_lshl_add_u64 v[226:227], s[46:47], 0, v[132:133]
	s_mov_b32 m0, s69
	s_nop 0
	global_load_lds_dwordx4 v[226:227], off
	s_waitcnt vmcnt(8)
	s_waitcnt lgkmcnt(0)
	s_barrier
	s_waitcnt lgkmcnt(0)
	v_mfma_f32_16x16x32_bf16 v[124:127], v[144:147], v[184:187], v[124:127]
	v_mfma_f32_16x16x32_bf16 v[120:123], v[160:163], v[184:187], v[120:123]
	v_mfma_f32_16x16x32_bf16 v[108:111], v[144:147], v[192:195], v[108:111]
	v_mfma_f32_16x16x32_bf16 v[104:107], v[160:163], v[192:195], v[104:107]
	v_mfma_f32_16x16x32_bf16 v[92:95], v[144:147], v[200:203], v[92:95]
	v_mfma_f32_16x16x32_bf16 v[88:91], v[160:163], v[200:203], v[88:91]
	v_mfma_f32_16x16x32_bf16 v[76:79], v[144:147], v[208:211], v[76:79]
	v_mfma_f32_16x16x32_bf16 v[72:75], v[160:163], v[208:211], v[72:75]
	v_mfma_f32_16x16x32_bf16 v[124:127], v[156:159], v[188:191], v[124:127]
	v_mfma_f32_16x16x32_bf16 v[120:123], v[164:167], v[188:191], v[120:123]
	v_mfma_f32_16x16x32_bf16 v[108:111], v[156:159], v[196:199], v[108:111]
	v_mfma_f32_16x16x32_bf16 v[104:107], v[164:167], v[196:199], v[104:107]
	v_mfma_f32_16x16x32_bf16 v[92:95], v[156:159], v[204:207], v[92:95]
	v_mfma_f32_16x16x32_bf16 v[88:91], v[164:167], v[204:207], v[88:91]
	v_mfma_f32_16x16x32_bf16 v[76:79], v[156:159], v[212:215], v[76:79]
	v_mfma_f32_16x16x32_bf16 v[72:75], v[164:167], v[212:215], v[72:75]
	v_mfma_f32_16x16x32_bf16 v[116:119], v[168:171], v[184:187], v[116:119]
	v_mfma_f32_16x16x32_bf16 v[112:115], v[176:179], v[184:187], v[112:115]
	v_mfma_f32_16x16x32_bf16 v[100:103], v[168:171], v[192:195], v[100:103]
	v_mfma_f32_16x16x32_bf16 v[96:99], v[176:179], v[192:195], v[96:99]
	v_mfma_f32_16x16x32_bf16 v[84:87], v[168:171], v[200:203], v[84:87]
	v_mfma_f32_16x16x32_bf16 v[80:83], v[176:179], v[200:203], v[80:83]
	v_mfma_f32_16x16x32_bf16 v[68:71], v[168:171], v[208:211], v[68:71]
	v_mfma_f32_16x16x32_bf16 v[64:67], v[176:179], v[208:211], v[64:67]
	v_mfma_f32_16x16x32_bf16 v[116:119], v[172:175], v[188:191], v[116:119]
	v_mfma_f32_16x16x32_bf16 v[112:115], v[180:183], v[188:191], v[112:115]
	v_mfma_f32_16x16x32_bf16 v[100:103], v[172:175], v[196:199], v[100:103]
	v_mfma_f32_16x16x32_bf16 v[96:99], v[180:183], v[196:199], v[96:99]
	v_mfma_f32_16x16x32_bf16 v[84:87], v[172:175], v[204:207], v[84:87]
	v_mfma_f32_16x16x32_bf16 v[80:83], v[180:183], v[204:207], v[80:83]
	v_mfma_f32_16x16x32_bf16 v[68:71], v[172:175], v[212:215], v[68:71]
	v_mfma_f32_16x16x32_bf16 v[64:67], v[180:183], v[212:215], v[64:67]
	s_barrier
; #define PG8_STAGE(bufoff, gbase, voff) do { _Pragma("unroll") for (int _i = 0; _i < 2; ++_i) \
;         __builtin_amdgcn_global_load_lds((const unsigned*)((const char*)(gbase) + (voff)[_i]), (LAS unsigned*)(lds + (bufoff) + ldsw + _i * 8192), 16, 0, 0); } while (0)
; #define PG8_LDA(dst, b, h) do { _Pragma("unroll") for (int m = 0; m < 4; ++m) _Pragma("unroll") for (int k = 0; k < 2; ++k) dst[m][k] = *(const LAS bf16x8*)(lds + PG8_SA(b, h) + aoff + m * 2048 + k * 1024); } while (0)
; #define PG8_MMA(ai, bj, At, Bt) do { __builtin_amdgcn_s_setprio(1); _Pragma("unroll") for (int m = 0; m < 4; ++m) _Pragma("unroll") for (int n = 0; n < 2; ++n) _Pragma("unroll") for (int k = 0; k < 2; ++k) \
;         acc[ai][bj][m][n] = __builtin_amdgcn_mfma_f32_16x16x32_bf16(Bt[n][k], At[m][k], acc[ai][bj][m][n], 0, 0, 0); __builtin_amdgcn_s_setprio(0); } while (0)
; #define PG8_WAIT_V(n) asm volatile("s_waitcnt vmcnt(" #n ")" ::: "memory")
; #define PG8_WAIT_L(n) asm volatile("s_waitcnt lgkmcnt(" #n ")" ::: "memory")
; #define PG8_BAR __builtin_amdgcn_s_barrier()
; #define PG8_SCHED __builtin_amdgcn_sched_barrier(0)
; template <class Epi, class Sched, bool ALIGN_EPI>
; __device__ __forceinline__ void gemm_phase(LAS unsigned char* lds, const Gemm g, const Sched& S, const Epi& E) {
;     ...
;             PG8_LDA(At, 1, 1); PG8_STAGE(PG8_SB(1, 0), b3, voffB); PG8_STAGE(PG8_SB(1, 1), b3 + hB, voffB); PG8_STAGE(PG8_SA(1, 0), a3, voffA);
;             PG8_WAIT_V(8); PG8_WAIT_L(0); PG8_BAR; PG8_MMA(1, 0, At, B0); PG8_MMA(1, 1, At, B1); PG8_BAR; PG8_SCHED;
;         }
	s_add_i32 s18, s18, s65
	v_lshl_add_u64 v[216:217], v[216:217], 0, s[24:25]
	s_mov_b32 m0, s18
	ds_read_b128 v[184:187], v153 offset:49152
	ds_read_b128 v[188:191], v153 offset:50176
	ds_read_b128 v[192:195], v153 offset:51200
	ds_read_b128 v[196:199], v153 offset:52224
	ds_read_b128 v[200:203], v153 offset:53248
	ds_read_b128 v[204:207], v153 offset:54272
	ds_read_b128 v[208:211], v153 offset:55296
	ds_read_b128 v[212:215], v153 offset:56320
	global_load_lds_dwordx4 v[216:217], off
	s_add_i32 m0, s18, 0x2000
	s_add_u32 s46, s60, 0x160080
	v_lshl_add_u64 v[216:217], v[218:219], 0, s[24:25]
	s_addc_u32 s47, s61, 0
	s_add_i32 s18, s19, s65
	global_load_lds_dwordx4 v[216:217], off
	v_lshl_add_u64 v[216:217], s[46:47], 0, v[130:131]
	s_mov_b32 m0, s18
	s_nop 0
	global_load_lds_dwordx4 v[216:217], off
	v_lshl_add_u64 v[216:217], s[46:47], 0, v[134:135]
	s_add_i32 m0, s18, 0x2000
	s_nop 0
	global_load_lds_dwordx4 v[216:217], off
	v_lshl_add_u64 v[216:217], v[222:223], 0, s[24:25]
	s_mov_b32 m0, s71
	s_nop 0
	global_load_lds_dwordx4 v[216:217], off
	v_lshl_add_u64 v[216:217], v[224:225], 0, s[24:25]
	s_mov_b32 m0, s72
	s_nop 0
	global_load_lds_dwordx4 v[216:217], off
	s_waitcnt vmcnt(8)
	s_waitcnt lgkmcnt(0)
	s_barrier
	s_waitcnt lgkmcnt(0)
	v_mfma_f32_16x16x32_bf16 v[60:63], v[144:147], v[184:187], v[60:63]
	v_mfma_f32_16x16x32_bf16 v[56:59], v[160:163], v[184:187], v[56:59]
	v_mfma_f32_16x16x32_bf16 v[44:47], v[144:147], v[192:195], v[44:47]
	v_mfma_f32_16x16x32_bf16 v[40:43], v[160:163], v[192:195], v[40:43]
	v_mfma_f32_16x16x32_bf16 v[28:31], v[144:147], v[200:203], v[28:31]
	v_mfma_f32_16x16x32_bf16 v[24:27], v[160:163], v[200:203], v[24:27]
	v_mfma_f32_16x16x32_bf16 v[12:15], v[144:147], v[208:211], v[12:15]
	v_mfma_f32_16x16x32_bf16 v[8:11], v[160:163], v[208:211], v[8:11]
	v_mfma_f32_16x16x32_bf16 v[60:63], v[156:159], v[188:191], v[60:63]
	v_mfma_f32_16x16x32_bf16 v[56:59], v[164:167], v[188:191], v[56:59]
	v_mfma_f32_16x16x32_bf16 v[44:47], v[156:159], v[196:199], v[44:47]
	v_mfma_f32_16x16x32_bf16 v[40:43], v[164:167], v[196:199], v[40:43]
	v_mfma_f32_16x16x32_bf16 v[28:31], v[156:159], v[204:207], v[28:31]
	v_mfma_f32_16x16x32_bf16 v[24:27], v[164:167], v[204:207], v[24:27]
	v_mfma_f32_16x16x32_bf16 v[12:15], v[156:159], v[212:215], v[12:15]
	v_mfma_f32_16x16x32_bf16 v[8:11], v[164:167], v[212:215], v[8:11]
	v_mfma_f32_16x16x32_bf16 v[52:55], v[168:171], v[184:187], v[52:55]
	v_mfma_f32_16x16x32_bf16 v[48:51], v[176:179], v[184:187], v[48:51]
	v_mfma_f32_16x16x32_bf16 v[36:39], v[168:171], v[192:195], v[36:39]
	v_mfma_f32_16x16x32_bf16 v[32:35], v[176:179], v[192:195], v[32:35]
	v_mfma_f32_16x16x32_bf16 v[20:23], v[168:171], v[200:203], v[20:23]
	v_mfma_f32_16x16x32_bf16 v[16:19], v[176:179], v[200:203], v[16:19]
	v_mfma_f32_16x16x32_bf16 v[4:7], v[168:171], v[208:211], v[4:7]
	v_mfma_f32_16x16x32_bf16 v[0:3], v[176:179], v[208:211], v[0:3]
	v_mfma_f32_16x16x32_bf16 v[52:55], v[172:175], v[188:191], v[52:55]
	v_mfma_f32_16x16x32_bf16 v[48:51], v[180:183], v[188:191], v[48:51]
	v_mfma_f32_16x16x32_bf16 v[36:39], v[172:175], v[196:199], v[36:39]
	v_mfma_f32_16x16x32_bf16 v[32:35], v[180:183], v[196:199], v[32:35]
	v_mfma_f32_16x16x32_bf16 v[20:23], v[172:175], v[204:207], v[20:23]
	v_mfma_f32_16x16x32_bf16 v[16:19], v[180:183], v[204:207], v[16:19]
	v_mfma_f32_16x16x32_bf16 v[4:7], v[172:175], v[212:215], v[4:7]
	v_mfma_f32_16x16x32_bf16 v[0:3], v[180:183], v[212:215], v[0:3]
	s_barrier
	s_add_i32 s84, s84, 2
	s_add_u32 s42, s42, 0x100
	s_addc_u32 s43, s43, 0
	s_add_u32 s44, s44, 0x100
	s_addc_u32 s45, s45, 0
	s_cmpk_gt_u32 s84, 0x55
	s_cbranch_scc0 .LBB0_361
	s_and_b64 vcc, exec, s[26:27]
	s_cbranch_vccz .LBB0_364
	s_barrier

; #define PG8_STAGE(bufoff, gbase, voff) do { _Pragma("unroll") for (int _i = 0; _i < 2; ++_i) \
;         __builtin_amdgcn_global_load_lds((const unsigned*)((const char*)(gbase) + (voff)[_i]), (LAS unsigned*)(lds + (bufoff) + ldsw + _i * 8192), 16, 0, 0); } while (0)
; #define PG8_LDA(dst, b, h) do { _Pragma("unroll") for (int m = 0; m < 4; ++m) _Pragma("unroll") for (int k = 0; k < 2; ++k) dst[m][k] = *(const LAS bf16x8*)(lds + PG8_SA(b, h) + aoff + m * 2048 + k * 1024); } while (0)
; #define PG8_LDB(dst, b, h) do { _Pragma("unroll") for (int n = 0; n < 2; ++n) _Pragma("unroll") for (int k = 0; k < 2; ++k) dst[n][k] = *(const LAS bf16x8*)(lds + PG8_SB(b, h) + boff + n * 2048 + k * 1024); } while (0)
; #define PG8_MMA(ai, bj, At, Bt) do { __builtin_amdgcn_s_setprio(1); _Pragma("unroll") for (int m = 0; m < 4; ++m) _Pragma("unroll") for (int n = 0; n < 2; ++n) _Pragma("unroll") for (int k = 0; k < 2; ++k) \
;         acc[ai][bj][m][n] = __builtin_amdgcn_mfma_f32_16x16x32_bf16(Bt[n][k], At[m][k], acc[ai][bj][m][n], 0, 0, 0); __builtin_amdgcn_s_setprio(0); } while (0)
; #define PG8_WAIT_V(n) asm volatile("s_waitcnt vmcnt(" #n ")" ::: "memory")
; #define PG8_WAIT_L(n) asm volatile("s_waitcnt lgkmcnt(" #n ")" ::: "memory")
; #define PG8_BAR __builtin_amdgcn_s_barrier()
; #define PG8_SCHED __builtin_amdgcn_sched_barrier(0)
; template <class Epi, class Sched, bool ALIGN_EPI>
; __device__ __forceinline__ void gemm_phase(LAS unsigned char* lds, const Gemm g, const Sched& S, const Epi& E) {
;     ...
;         for (int t = 0; t < nt; t += 2) {
;             const bool last = (t == nt - 2);
;             const char* a1 = cA + (size_t)(t + 1) * kstep;
;             const char* a2 = last ? nA : cA + (size_t)(t + 2) * kstep; const char* b2 = last ? nB : cB + (size_t)(t + 2) * kstep;
;             const char* a3 = a2 + kstep; const char* b3 = b2 + kstep;
;             PG8_LDB(B0, 0, 0); PG8_LDB(B1, 0, 1); PG8_SCHED; PG8_LDA(At, 0, 0); PG8_STAGE(PG8_SA(1, 1), a1 + hA, voffA);
;             PG8_WAIT_V(8); PG8_WAIT_L(0); PG8_BAR; PG8_MMA(0, 0, At, B0); PG8_MMA(0, 1, At, B1); PG8_BAR; PG8_SCHED;
;             PG8_LDA(At, 0, 1); PG8_STAGE(PG8_SB(0, 0), b2, voffB); PG8_STAGE(PG8_SB(0, 1), b2 + hB, voffB); PG8_STAGE(PG8_SA(0, 0), a2, voffA);
;             PG8_WAIT_V(8); PG8_WAIT_L(0); PG8_BAR; PG8_MMA(1, 0, At, B0); PG8_MMA(1, 1, At, B1); PG8_BAR; PG8_SCHED;
.LBB0_466:
	ds_read_b128 v[128:131], v173
	ds_read_b128 v[132:135], v173 offset:1024
	ds_read_b128 v[160:163], v173 offset:2048
	ds_read_b128 v[168:171], v173 offset:3072
	ds_read_b128 v[176:179], v175
	s_waitcnt lgkmcnt(0)
	ds_read_b128 v[182:185], v175 offset:1024
	ds_read_b128 v[186:189], v175 offset:2048
	ds_read_b128 v[190:193], v175 offset:3072
	s_add_u32 s18, s6, 0xfff80080
	s_addc_u32 s19, s7, -1
	s_cmp_eq_u32 s46, 28
	s_cselect_b32 s83, vcc_lo, s19
	s_cselect_b32 s82, vcc_hi, s18
	s_cselect_b32 s81, s75, s45
	s_cselect_b32 s80, s87, s44
	v_lshl_add_u64 v[156:157], s[6:7], 0, v[148:149]
	s_add_i32 m0, s61, 0xc000
	ds_read_b128 v[194:197], v181
	ds_read_b128 v[198:201], v181 offset:1024
	ds_read_b128 v[202:205], v181 offset:2048
	ds_read_b128 v[206:209], v181 offset:3072
	ds_read_b128 v[210:213], v181 offset:4096
	ds_read_b128 v[214:217], v181 offset:5120
	ds_read_b128 v[224:227], v181 offset:6144
	ds_read_b128 v[228:231], v181 offset:7168
	global_load_lds_dwordx4 v[156:157], off
	v_lshl_add_u64 v[156:157], s[6:7], 0, v[150:151]
	s_add_i32 m0, s61, 0xe000
	s_nop 0
	global_load_lds_dwordx4 v[156:157], off
	s_waitcnt vmcnt(8)
	s_waitcnt lgkmcnt(0)
	s_barrier
	s_waitcnt lgkmcnt(0)
	v_mfma_f32_16x16x32_bf16 v[124:127], v[128:131], v[194:197], v[124:127]
	v_mfma_f32_16x16x32_bf16 v[116:119], v[160:163], v[194:197], v[116:119]
	v_mfma_f32_16x16x32_bf16 v[108:111], v[128:131], v[202:205], v[108:111]
	v_mfma_f32_16x16x32_bf16 v[100:103], v[160:163], v[202:205], v[100:103]
	v_mfma_f32_16x16x32_bf16 v[92:95], v[128:131], v[210:213], v[92:95]
	v_mfma_f32_16x16x32_bf16 v[84:87], v[160:163], v[210:213], v[84:87]
	v_mfma_f32_16x16x32_bf16 v[76:79], v[128:131], v[224:227], v[76:79]
	v_mfma_f32_16x16x32_bf16 v[68:71], v[160:163], v[224:227], v[68:71]
	v_mfma_f32_16x16x32_bf16 v[124:127], v[132:135], v[198:201], v[124:127]
	v_mfma_f32_16x16x32_bf16 v[116:119], v[168:171], v[198:201], v[116:119]
	v_mfma_f32_16x16x32_bf16 v[108:111], v[132:135], v[206:209], v[108:111]
	v_mfma_f32_16x16x32_bf16 v[100:103], v[168:171], v[206:209], v[100:103]
	v_mfma_f32_16x16x32_bf16 v[92:95], v[132:135], v[214:217], v[92:95]
	v_mfma_f32_16x16x32_bf16 v[84:87], v[168:171], v[214:217], v[84:87]
	v_mfma_f32_16x16x32_bf16 v[76:79], v[132:135], v[228:231], v[76:79]
	v_mfma_f32_16x16x32_bf16 v[68:71], v[168:171], v[228:231], v[68:71]
	v_mfma_f32_16x16x32_bf16 v[120:123], v[176:179], v[194:197], v[120:123]
	v_mfma_f32_16x16x32_bf16 v[112:115], v[186:189], v[194:197], v[112:115]
	v_mfma_f32_16x16x32_bf16 v[104:107], v[176:179], v[202:205], v[104:107]
	v_mfma_f32_16x16x32_bf16 v[96:99], v[186:189], v[202:205], v[96:99]
	v_mfma_f32_16x16x32_bf16 v[88:91], v[176:179], v[210:213], v[88:91]
	v_mfma_f32_16x16x32_bf16 v[80:83], v[186:189], v[210:213], v[80:83]
	v_mfma_f32_16x16x32_bf16 v[72:75], v[176:179], v[224:227], v[72:75]
	v_mfma_f32_16x16x32_bf16 v[64:67], v[186:189], v[224:227], v[64:67]
	v_mfma_f32_16x16x32_bf16 v[120:123], v[182:185], v[198:201], v[120:123]
	v_mfma_f32_16x16x32_bf16 v[112:115], v[190:193], v[198:201], v[112:115]
	v_mfma_f32_16x16x32_bf16 v[104:107], v[182:185], v[206:209], v[104:107]
	v_mfma_f32_16x16x32_bf16 v[96:99], v[190:193], v[206:209], v[96:99]
	v_mfma_f32_16x16x32_bf16 v[88:91], v[182:185], v[214:217], v[88:91]
	v_mfma_f32_16x16x32_bf16 v[80:83], v[190:193], v[214:217], v[80:83]
	v_mfma_f32_16x16x32_bf16 v[72:75], v[182:185], v[228:231], v[72:75]
	v_mfma_f32_16x16x32_bf16 v[64:67], v[190:193], v[228:231], v[64:67]
	s_barrier
	s_add_i32 s18, s92, s59
	v_lshl_add_u64 v[156:157], s[80:81], 0, v[138:139]
	s_mov_b32 m0, s18
	ds_read_b128 v[194:197], v181 offset:16384
	ds_read_b128 v[198:201], v181 offset:17408
	ds_read_b128 v[202:205], v181 offset:18432
	ds_read_b128 v[206:209], v181 offset:19456
	ds_read_b128 v[210:213], v181 offset:20480
	ds_read_b128 v[214:217], v181 offset:21504
	ds_read_b128 v[224:227], v181 offset:22528
	ds_read_b128 v[228:231], v181 offset:23552
	global_load_lds_dwordx4 v[156:157], off
	s_add_i32 m0, s18, 0x2000
	s_add_u32 s18, s80, 0x80000
	v_lshl_add_u64 v[218:219], s[80:81], 0, v[142:143]
	s_addc_u32 s19, s81, 0
	s_add_i32 s47, s93, s59
	global_load_lds_dwordx4 v[218:219], off
	v_lshl_add_u64 v[232:233], s[18:19], 0, v[138:139]
	s_mov_b32 m0, s47
	v_lshl_add_u64 v[234:235], s[82:83], 0, v[140:141]
	global_load_lds_dwordx4 v[232:233], off
	v_lshl_add_u64 v[232:233], s[18:19], 0, v[142:143]
	s_add_i32 m0, s47, 0x2000
	s_nop 0
	global_load_lds_dwordx4 v[232:233], off
	v_lshl_add_u64 v[232:233], s[82:83], 0, v[136:137]
	s_mov_b32 m0, s61
	s_nop 0
	global_load_lds_dwordx4 v[232:233], off
	s_mov_b32 m0, s63
	s_nop 0
	global_load_lds_dwordx4 v[234:235], off
	s_waitcnt vmcnt(8)
	s_waitcnt lgkmcnt(0)
	s_barrier
; #define PG8_STAGE(bufoff, gbase, voff) do { _Pragma("unroll") for (int _i = 0; _i < 2; ++_i) \
;         __builtin_amdgcn_global_load_lds((const unsigned*)((const char*)(gbase) + (voff)[_i]), (LAS unsigned*)(lds + (bufoff) + ldsw + _i * 8192), 16, 0, 0); } while (0)
; #define PG8_LDA(dst, b, h) do { _Pragma("unroll") for (int m = 0; m < 4; ++m) _Pragma("unroll") for (int k = 0; k < 2; ++k) dst[m][k] = *(const LAS bf16x8*)(lds + PG8_SA(b, h) + aoff + m * 2048 + k * 1024); } while (0)
; #define PG8_LDB(dst, b, h) do { _Pragma("unroll") for (int n = 0; n < 2; ++n) _Pragma("unroll") for (int k = 0; k < 2; ++k) dst[n][k] = *(const LAS bf16x8*)(lds + PG8_SB(b, h) + boff + n * 2048 + k * 1024); } while (0)
; #define PG8_MMA(ai, bj, At, Bt) do { __builtin_amdgcn_s_setprio(1); _Pragma("unroll") for (int m = 0; m < 4; ++m) _Pragma("unroll") for (int n = 0; n < 2; ++n) _Pragma("unroll") for (int k = 0; k < 2; ++k) \
;         acc[ai][bj][m][n] = __builtin_amdgcn_mfma_f32_16x16x32_bf16(Bt[n][k], At[m][k], acc[ai][bj][m][n], 0, 0, 0); __builtin_amdgcn_s_setprio(0); } while (0)
; #define PG8_WAIT_V(n) asm volatile("s_waitcnt vmcnt(" #n ")" ::: "memory")
; #define PG8_WAIT_L(n) asm volatile("s_waitcnt lgkmcnt(" #n ")" ::: "memory")
; #define PG8_BAR __builtin_amdgcn_s_barrier()
; #define PG8_SCHED __builtin_amdgcn_sched_barrier(0)
; template <class Epi, class Sched, bool ALIGN_EPI>
; __device__ __forceinline__ void gemm_phase(LAS unsigned char* lds, const Gemm g, const Sched& S, const Epi& E) {
;     ...
;             PG8_WAIT_V(8); PG8_WAIT_L(0); PG8_BAR; PG8_MMA(1, 0, At, B0); PG8_MMA(1, 1, At, B1); PG8_BAR; PG8_SCHED;
;             PG8_LDB(B0, 1, 0); PG8_LDB(B1, 1, 1); PG8_SCHED; PG8_LDA(At, 1, 0); PG8_STAGE(PG8_SA(0, 1), a2 + hA, voffA);
;             PG8_WAIT_V(8); PG8_WAIT_L(0); PG8_BAR; PG8_MMA(0, 0, At, B0); PG8_MMA(0, 1, At, B1); PG8_BAR; PG8_SCHED;
;             PG8_LDA(At, 1, 1); PG8_STAGE(PG8_SB(1, 0), b3, voffB); PG8_STAGE(PG8_SB(1, 1), b3 + hB, voffB); PG8_STAGE(PG8_SA(1, 0), a3, voffA);
	s_waitcnt lgkmcnt(0)
	v_mfma_f32_16x16x32_bf16 v[60:63], v[128:131], v[194:197], v[60:63]
	v_mfma_f32_16x16x32_bf16 v[52:55], v[160:163], v[194:197], v[52:55]
	v_mfma_f32_16x16x32_bf16 v[44:47], v[128:131], v[202:205], v[44:47]
	v_mfma_f32_16x16x32_bf16 v[36:39], v[160:163], v[202:205], v[36:39]
	v_mfma_f32_16x16x32_bf16 v[28:31], v[128:131], v[210:213], v[28:31]
	v_mfma_f32_16x16x32_bf16 v[20:23], v[160:163], v[210:213], v[20:23]
	v_mfma_f32_16x16x32_bf16 v[12:15], v[128:131], v[224:227], v[12:15]
	v_mfma_f32_16x16x32_bf16 v[4:7], v[160:163], v[224:227], v[4:7]
	v_mfma_f32_16x16x32_bf16 v[60:63], v[132:135], v[198:201], v[60:63]
	v_mfma_f32_16x16x32_bf16 v[52:55], v[168:171], v[198:201], v[52:55]
	v_mfma_f32_16x16x32_bf16 v[44:47], v[132:135], v[206:209], v[44:47]
	v_mfma_f32_16x16x32_bf16 v[36:39], v[168:171], v[206:209], v[36:39]
	v_mfma_f32_16x16x32_bf16 v[28:31], v[132:135], v[214:217], v[28:31]
	v_mfma_f32_16x16x32_bf16 v[20:23], v[168:171], v[214:217], v[20:23]
	v_mfma_f32_16x16x32_bf16 v[12:15], v[132:135], v[228:231], v[12:15]
	v_mfma_f32_16x16x32_bf16 v[4:7], v[168:171], v[228:231], v[4:7]
	v_mfma_f32_16x16x32_bf16 v[56:59], v[176:179], v[194:197], v[56:59]
	v_mfma_f32_16x16x32_bf16 v[48:51], v[186:189], v[194:197], v[48:51]
	v_mfma_f32_16x16x32_bf16 v[40:43], v[176:179], v[202:205], v[40:43]
	v_mfma_f32_16x16x32_bf16 v[32:35], v[186:189], v[202:205], v[32:35]
	v_mfma_f32_16x16x32_bf16 v[24:27], v[176:179], v[210:213], v[24:27]
	v_mfma_f32_16x16x32_bf16 v[16:19], v[186:189], v[210:213], v[16:19]
	v_mfma_f32_16x16x32_bf16 v[8:11], v[176:179], v[224:227], v[8:11]
	v_mfma_f32_16x16x32_bf16 v[0:3], v[186:189], v[224:227], v[0:3]
	v_mfma_f32_16x16x32_bf16 v[56:59], v[182:185], v[198:201], v[56:59]
	v_mfma_f32_16x16x32_bf16 v[48:51], v[190:193], v[198:201], v[48:51]
	v_mfma_f32_16x16x32_bf16 v[40:43], v[182:185], v[206:209], v[40:43]
	v_mfma_f32_16x16x32_bf16 v[32:35], v[190:193], v[206:209], v[32:35]
	v_mfma_f32_16x16x32_bf16 v[24:27], v[182:185], v[214:217], v[24:27]
	v_mfma_f32_16x16x32_bf16 v[16:19], v[190:193], v[214:217], v[16:19]
	v_mfma_f32_16x16x32_bf16 v[8:11], v[182:185], v[228:231], v[8:11]
	v_mfma_f32_16x16x32_bf16 v[0:3], v[190:193], v[228:231], v[0:3]
	s_barrier
	s_add_i32 s47, 0, 0x18000
	v_add_u32_e32 v145, s47, v165
	s_add_i32 s33, 0, 0x1c000
	ds_read_b128 v[128:131], v145
	ds_read_b128 v[132:135], v145 offset:1024
	ds_read_b128 v[160:163], v145 offset:2048
	ds_read_b128 v[168:171], v145 offset:3072
	v_add_u32_e32 v145, s33, v165
	ds_read_b128 v[176:179], v145
	ds_read_b128 v[182:185], v145 offset:1024
	ds_read_b128 v[186:189], v145 offset:2048
	ds_read_b128 v[190:193], v145 offset:3072
	s_add_u32 s18, s82, 0x80000
	s_addc_u32 s19, s83, 0
	s_mov_b32 m0, s65
	v_lshl_add_u64 v[236:237], s[18:19], 0, v[136:137]
	ds_read_b128 v[194:197], v181 offset:32768
	ds_read_b128 v[198:201], v181 offset:33792
	ds_read_b128 v[202:205], v181 offset:34816
	ds_read_b128 v[206:209], v181 offset:35840
	ds_read_b128 v[210:213], v181 offset:36864
	ds_read_b128 v[214:217], v181 offset:37888
	ds_read_b128 v[224:227], v181 offset:38912
	ds_read_b128 v[228:231], v181 offset:39936
	global_load_lds_dwordx4 v[236:237], off
	v_lshl_add_u64 v[236:237], s[18:19], 0, v[140:141]
	s_mov_b32 m0, s67
	s_nop 0
	global_load_lds_dwordx4 v[236:237], off
	s_waitcnt vmcnt(8)
	s_waitcnt lgkmcnt(0)
	s_barrier
	s_waitcnt lgkmcnt(0)
	v_mfma_f32_16x16x32_bf16 v[124:127], v[128:131], v[194:197], v[124:127]
	v_mfma_f32_16x16x32_bf16 v[116:119], v[160:163], v[194:197], v[116:119]
	v_mfma_f32_16x16x32_bf16 v[108:111], v[128:131], v[202:205], v[108:111]
	v_mfma_f32_16x16x32_bf16 v[100:103], v[160:163], v[202:205], v[100:103]
	v_mfma_f32_16x16x32_bf16 v[92:95], v[128:131], v[210:213], v[92:95]
	v_mfma_f32_16x16x32_bf16 v[84:87], v[160:163], v[210:213], v[84:87]
	v_mfma_f32_16x16x32_bf16 v[76:79], v[128:131], v[224:227], v[76:79]
	v_mfma_f32_16x16x32_bf16 v[68:71], v[160:163], v[224:227], v[68:71]
	v_mfma_f32_16x16x32_bf16 v[124:127], v[132:135], v[198:201], v[124:127]
	v_mfma_f32_16x16x32_bf16 v[116:119], v[168:171], v[198:201], v[116:119]
	v_mfma_f32_16x16x32_bf16 v[108:111], v[132:135], v[206:209], v[108:111]
	v_mfma_f32_16x16x32_bf16 v[100:103], v[168:171], v[206:209], v[100:103]
	v_mfma_f32_16x16x32_bf16 v[92:95], v[132:135], v[214:217], v[92:95]
	v_mfma_f32_16x16x32_bf16 v[84:87], v[168:171], v[214:217], v[84:87]
	v_mfma_f32_16x16x32_bf16 v[76:79], v[132:135], v[228:231], v[76:79]
	v_mfma_f32_16x16x32_bf16 v[68:71], v[168:171], v[228:231], v[68:71]
	v_mfma_f32_16x16x32_bf16 v[120:123], v[176:179], v[194:197], v[120:123]
	v_mfma_f32_16x16x32_bf16 v[112:115], v[186:189], v[194:197], v[112:115]
	v_mfma_f32_16x16x32_bf16 v[104:107], v[176:179], v[202:205], v[104:107]
	v_mfma_f32_16x16x32_bf16 v[96:99], v[186:189], v[202:205], v[96:99]
	v_mfma_f32_16x16x32_bf16 v[88:91], v[176:179], v[210:213], v[88:91]
	v_mfma_f32_16x16x32_bf16 v[80:83], v[186:189], v[210:213], v[80:83]
	v_mfma_f32_16x16x32_bf16 v[72:75], v[176:179], v[224:227], v[72:75]
	v_mfma_f32_16x16x32_bf16 v[64:67], v[186:189], v[224:227], v[64:67]
	v_mfma_f32_16x16x32_bf16 v[120:123], v[182:185], v[198:201], v[120:123]
	v_mfma_f32_16x16x32_bf16 v[112:115], v[190:193], v[198:201], v[112:115]
	v_mfma_f32_16x16x32_bf16 v[104:107], v[182:185], v[206:209], v[104:107]
	v_mfma_f32_16x16x32_bf16 v[96:99], v[190:193], v[206:209], v[96:99]
	v_mfma_f32_16x16x32_bf16 v[88:91], v[182:185], v[214:217], v[88:91]
	v_mfma_f32_16x16x32_bf16 v[80:83], v[190:193], v[214:217], v[80:83]
	v_mfma_f32_16x16x32_bf16 v[72:75], v[182:185], v[228:231], v[72:75]
	v_mfma_f32_16x16x32_bf16 v[64:67], v[190:193], v[228:231], v[64:67]
	s_barrier
; #define PG8_STAGE(bufoff, gbase, voff) do { _Pragma("unroll") for (int _i = 0; _i < 2; ++_i) \
;         __builtin_amdgcn_global_load_lds((const unsigned*)((const char*)(gbase) + (voff)[_i]), (LAS unsigned*)(lds + (bufoff) + ldsw + _i * 8192), 16, 0, 0); } while (0)
; #define PG8_LDA(dst, b, h) do { _Pragma("unroll") for (int m = 0; m < 4; ++m) _Pragma("unroll") for (int k = 0; k < 2; ++k) dst[m][k] = *(const LAS bf16x8*)(lds + PG8_SA(b, h) + aoff + m * 2048 + k * 1024); } while (0)
; #define PG8_MMA(ai, bj, At, Bt) do { __builtin_amdgcn_s_setprio(1); _Pragma("unroll") for (int m = 0; m < 4; ++m) _Pragma("unroll") for (int n = 0; n < 2; ++n) _Pragma("unroll") for (int k = 0; k < 2; ++k) \
;         acc[ai][bj][m][n] = __builtin_amdgcn_mfma_f32_16x16x32_bf16(Bt[n][k], At[m][k], acc[ai][bj][m][n], 0, 0, 0); __builtin_amdgcn_s_setprio(0); } while (0)
; #define PG8_WAIT_V(n) asm volatile("s_waitcnt vmcnt(" #n ")" ::: "memory")
; #define PG8_WAIT_L(n) asm volatile("s_waitcnt lgkmcnt(" #n ")" ::: "memory")
; #define PG8_BAR __builtin_amdgcn_s_barrier()
; #define PG8_SCHED __builtin_amdgcn_sched_barrier(0)
; template <class Epi, class Sched, bool ALIGN_EPI>
; __device__ __forceinline__ void gemm_phase(LAS unsigned char* lds, const Gemm g, const Sched& S, const Epi& E) {
;     ...
;             PG8_LDA(At, 1, 1); PG8_STAGE(PG8_SB(1, 0), b3, voffB); PG8_STAGE(PG8_SB(1, 1), b3 + hB, voffB); PG8_STAGE(PG8_SA(1, 0), a3, voffA);
;             PG8_WAIT_V(8); PG8_WAIT_L(0); PG8_BAR; PG8_MMA(1, 0, At, B0); PG8_MMA(1, 1, At, B1); PG8_BAR; PG8_SCHED;
;         }
;         if constexpr (ALIGN_EPI) { if (wr == 0) PG8_BAR; }
	s_add_i32 s18, s47, s59
	v_lshl_add_u64 v[156:157], v[156:157], 0, s[40:41]
	s_mov_b32 m0, s18
	ds_read_b128 v[194:197], v181 offset:49152
	ds_read_b128 v[198:201], v181 offset:50176
	ds_read_b128 v[202:205], v181 offset:51200
	ds_read_b128 v[206:209], v181 offset:52224
	ds_read_b128 v[210:213], v181 offset:53248
	ds_read_b128 v[214:217], v181 offset:54272
	ds_read_b128 v[224:227], v181 offset:55296
	ds_read_b128 v[228:231], v181 offset:56320
	global_load_lds_dwordx4 v[156:157], off
	s_add_i32 m0, s18, 0x2000
	s_add_u32 s18, s80, 0x80080
	v_lshl_add_u64 v[156:157], v[218:219], 0, s[40:41]
	s_addc_u32 s19, s81, 0
	s_add_i32 s33, s33, s59
	global_load_lds_dwordx4 v[156:157], off
	v_lshl_add_u64 v[156:157], s[18:19], 0, v[138:139]
	s_mov_b32 m0, s33
	s_nop 0
	global_load_lds_dwordx4 v[156:157], off
	v_lshl_add_u64 v[156:157], s[18:19], 0, v[142:143]
	s_add_i32 m0, s33, 0x2000
	s_nop 0
	global_load_lds_dwordx4 v[156:157], off
	v_lshl_add_u64 v[156:157], v[232:233], 0, s[40:41]
	s_mov_b32 m0, s69
	s_nop 0
	global_load_lds_dwordx4 v[156:157], off
	v_lshl_add_u64 v[156:157], v[234:235], 0, s[40:41]
	s_mov_b32 m0, s71
	s_nop 0
	global_load_lds_dwordx4 v[156:157], off
	s_waitcnt vmcnt(8)
	s_waitcnt lgkmcnt(0)
	s_barrier
	s_waitcnt lgkmcnt(0)
	v_mfma_f32_16x16x32_bf16 v[60:63], v[128:131], v[194:197], v[60:63]
	v_mfma_f32_16x16x32_bf16 v[52:55], v[160:163], v[194:197], v[52:55]
	v_mfma_f32_16x16x32_bf16 v[44:47], v[128:131], v[202:205], v[44:47]
	v_mfma_f32_16x16x32_bf16 v[36:39], v[160:163], v[202:205], v[36:39]
	v_mfma_f32_16x16x32_bf16 v[28:31], v[128:131], v[210:213], v[28:31]
	v_mfma_f32_16x16x32_bf16 v[20:23], v[160:163], v[210:213], v[20:23]
	v_mfma_f32_16x16x32_bf16 v[12:15], v[128:131], v[224:227], v[12:15]
	v_mfma_f32_16x16x32_bf16 v[4:7], v[160:163], v[224:227], v[4:7]
	v_mfma_f32_16x16x32_bf16 v[60:63], v[132:135], v[198:201], v[60:63]
	v_mfma_f32_16x16x32_bf16 v[52:55], v[168:171], v[198:201], v[52:55]
	v_mfma_f32_16x16x32_bf16 v[44:47], v[132:135], v[206:209], v[44:47]
	v_mfma_f32_16x16x32_bf16 v[36:39], v[168:171], v[206:209], v[36:39]
	v_mfma_f32_16x16x32_bf16 v[28:31], v[132:135], v[214:217], v[28:31]
	v_mfma_f32_16x16x32_bf16 v[20:23], v[168:171], v[214:217], v[20:23]
	v_mfma_f32_16x16x32_bf16 v[12:15], v[132:135], v[228:231], v[12:15]
	v_mfma_f32_16x16x32_bf16 v[4:7], v[168:171], v[228:231], v[4:7]
	v_mfma_f32_16x16x32_bf16 v[56:59], v[176:179], v[194:197], v[56:59]
	v_mfma_f32_16x16x32_bf16 v[48:51], v[186:189], v[194:197], v[48:51]
	v_mfma_f32_16x16x32_bf16 v[40:43], v[176:179], v[202:205], v[40:43]
	v_mfma_f32_16x16x32_bf16 v[32:35], v[186:189], v[202:205], v[32:35]
	v_mfma_f32_16x16x32_bf16 v[24:27], v[176:179], v[210:213], v[24:27]
	v_mfma_f32_16x16x32_bf16 v[16:19], v[186:189], v[210:213], v[16:19]
	v_mfma_f32_16x16x32_bf16 v[8:11], v[176:179], v[224:227], v[8:11]
	v_mfma_f32_16x16x32_bf16 v[0:3], v[186:189], v[224:227], v[0:3]
	v_mfma_f32_16x16x32_bf16 v[56:59], v[182:185], v[198:201], v[56:59]
	v_mfma_f32_16x16x32_bf16 v[48:51], v[190:193], v[198:201], v[48:51]
	v_mfma_f32_16x16x32_bf16 v[40:43], v[182:185], v[206:209], v[40:43]
	v_mfma_f32_16x16x32_bf16 v[32:35], v[190:193], v[206:209], v[32:35]
	v_mfma_f32_16x16x32_bf16 v[24:27], v[182:185], v[214:217], v[24:27]
	v_mfma_f32_16x16x32_bf16 v[16:19], v[190:193], v[214:217], v[16:19]
	v_mfma_f32_16x16x32_bf16 v[8:11], v[182:185], v[228:231], v[8:11]
	v_mfma_f32_16x16x32_bf16 v[0:3], v[190:193], v[228:231], v[0:3]
	s_barrier
	s_add_i32 s46, s46, 2
	s_add_u32 s6, s6, 0x100
	s_addc_u32 s7, s7, 0
	s_add_u32 s44, s44, 0x100
	s_addc_u32 s45, s45, 0
	s_cmp_gt_u32 s46, 29
	s_cbranch_scc0 .LBB0_466
	s_and_b64 vcc, exec, s[42:43]
	s_cbranch_vccz .LBB0_469
	s_barrier

; #define LAS __attribute__((address_space(3)))
; __device__ __forceinline__ unsigned cvt_pk_bf16(float lo, float hi) { unsigned r; asm volatile("v_cvt_pk_bf16_f32 %0, %1, %2" : "=v"(r) : "v"(lo), "v"(hi)); return r; }
; __global__ void __launch_bounds__(NTHR, 2) fwd_megakernel(Args args) {
;     ...
;             __syncthreads();
; #pragma unroll
;             for (int rr = 0; rr < 4; ++rr) { const int r = wave * 4 + rr; f32x4 x[4]; float s = 0.f;
; #pragma unroll
;                 for (int j = 0; j < 4; ++j) { x[j] = *(const LAS f32x4*)(Os + r * CCH + j * 256 + 4 * lane); s += (x[j][0] + x[j][1]) + (x[j][2] + x[j][3]); }
;                 const float mean = wave_sum(s) * (1.0f / CCH); float q = 0.f;
;     ...
;                     u32x2 w; w.x = cvt_pk_bf16(y[0], y[1]); w.y = cvt_pk_bf16(y[2], y[3]); *(u32x2*)(Y + (size_t)(t0 + r) * D + j * 256 + 4 * lane) = w; }
.LBB0_562:
	s_waitcnt lgkmcnt(0)
	s_barrier
	global_load_dwordx4 v[204:207], v[26:27], off
	global_load_dwordx4 v[232:235], v[28:29], off
	global_load_dwordx4 v[208:211], v[26:27], off offset:1024
	global_load_dwordx4 v[236:239], v[28:29], off offset:1024
	global_load_dwordx4 v[212:215], v[26:27], off offset:2048
	global_load_dwordx4 v[240:243], v[28:29], off offset:2048
	global_load_dwordx4 v[228:231], v[26:27], off offset:3072
	global_load_dwordx4 v[0:3], v[28:29], off offset:3072
	global_load_dwordx4 v[4:7], v[30:31], off
	global_load_dwordx4 v[8:11], v[30:31], off offset:1024
	global_load_dwordx4 v[12:15], v[30:31], off offset:2048
	global_load_dwordx4 v[16:19], v[30:31], off offset:3072
	v_add_u32_e32 v98, s24, v219
	v_add_u32_e32 v99, s26, v219
	v_add_u32_e32 v100, s57, v219
	v_add_u32_e32 v101, s59, v219
	ds_read_b128 v[140:143], v98
	ds_read_b128 v[144:147], v98 offset:1024
	ds_read_b128 v[148:151], v98 offset:2048
	ds_read_b128 v[152:155], v98 offset:3072
	ds_read_b128 v[156:159], v99
	ds_read_b128 v[160:163], v99 offset:1024
	ds_read_b128 v[164:167], v99 offset:2048
	ds_read_b128 v[168:171], v99 offset:3072
	ds_read_b128 v[172:175], v100
	ds_read_b128 v[176:179], v100 offset:1024
	ds_read_b128 v[180:183], v100 offset:2048
	ds_read_b128 v[184:187], v100 offset:3072
	ds_read_b128 v[188:191], v101
	ds_read_b128 v[192:195], v101 offset:1024
	ds_read_b128 v[196:199], v101 offset:2048
	ds_read_b128 v[200:203], v101 offset:3072
	s_add_i32 s2, s56, s62
	s_ashr_i32 s3, s2, 31
	s_lshl_b64 s[2:3], s[2:3], 12
	v_lshl_add_u64 v[126:127], v[32:33], 0, s[2:3]
	s_add_i32 s2, s25, s62
	s_ashr_i32 s3, s2, 31
	s_lshl_b64 s[2:3], s[2:3], 12
	v_lshl_add_u64 v[128:129], v[32:33], 0, s[2:3]
	s_add_i32 s2, s27, s62
	s_ashr_i32 s3, s2, 31
	s_lshl_b64 s[2:3], s[2:3], 12
	v_lshl_add_u64 v[130:131], v[32:33], 0, s[2:3]
	s_add_i32 s2, s58, s62
	s_ashr_i32 s3, s2, 31
	s_lshl_b64 s[2:3], s[2:3], 12
	v_lshl_add_u64 v[132:133], v[32:33], 0, s[2:3]
	s_waitcnt lgkmcnt(0)
	v_add_f32_e32 v110, v140, v141
	v_add_f32_e32 v111, v142, v143
	v_add_f32_e32 v114, v156, v157
	v_add_f32_e32 v115, v158, v159
	v_add_f32_e32 v118, v172, v173
	v_add_f32_e32 v119, v174, v175
	v_add_f32_e32 v122, v188, v189
	v_add_f32_e32 v123, v190, v191
	v_add_f32_e32 v110, v110, v111
	v_add_f32_e32 v114, v114, v115
	v_add_f32_e32 v118, v118, v119
	v_add_f32_e32 v122, v122, v123
	v_mov_b32_e32 v94, v110
	v_mov_b32_e32 v95, v114
	v_mov_b32_e32 v96, v118
	v_mov_b32_e32 v97, v122
	v_add_f32_e32 v110, v144, v145
	v_add_f32_e32 v111, v146, v147
	v_add_f32_e32 v114, v160, v161
	v_add_f32_e32 v115, v162, v163
	v_add_f32_e32 v118, v176, v177
	v_add_f32_e32 v119, v178, v179
	v_add_f32_e32 v122, v192, v193
	v_add_f32_e32 v123, v194, v195
	v_add_f32_e32 v110, v110, v111
	v_add_f32_e32 v114, v114, v115
	v_add_f32_e32 v118, v118, v119
	v_add_f32_e32 v122, v122, v123
	v_add_f32_e32 v94, v94, v110
	v_add_f32_e32 v95, v95, v114
	v_add_f32_e32 v96, v96, v118
	v_add_f32_e32 v97, v97, v122
	v_add_f32_e32 v110, v148, v149
	v_add_f32_e32 v111, v150, v151
	v_add_f32_e32 v114, v164, v165
	v_add_f32_e32 v115, v166, v167
	v_add_f32_e32 v118, v180, v181
	v_add_f32_e32 v119, v182, v183
	v_add_f32_e32 v122, v196, v197
	v_add_f32_e32 v123, v198, v199
	v_add_f32_e32 v110, v110, v111
	v_add_f32_e32 v114, v114, v115
	v_add_f32_e32 v118, v118, v119
	v_add_f32_e32 v122, v122, v123
	v_add_f32_e32 v94, v94, v110
	v_add_f32_e32 v95, v95, v114
	v_add_f32_e32 v96, v96, v118
	v_add_f32_e32 v97, v97, v122
	v_add_f32_e32 v110, v152, v153
	v_add_f32_e32 v111, v154, v155
	v_add_f32_e32 v114, v168, v169
	v_add_f32_e32 v115, v170, v171
	v_add_f32_e32 v118, v184, v185
	v_add_f32_e32 v119, v186, v187
	v_add_f32_e32 v122, v200, v201
	v_add_f32_e32 v123, v202, v203
	v_add_f32_e32 v110, v110, v111
	v_add_f32_e32 v114, v114, v115
	v_add_f32_e32 v118, v118, v119
	v_add_f32_e32 v122, v122, v123
	v_add_f32_e32 v94, v94, v110
	v_add_f32_e32 v95, v95, v114
	v_add_f32_e32 v96, v96, v118
	v_add_f32_e32 v97, v97, v122
	ds_bpermute_b32 v98, v222, v94
	ds_bpermute_b32 v99, v222, v95
	ds_bpermute_b32 v100, v222, v96
	ds_bpermute_b32 v101, v222, v97
	s_waitcnt lgkmcnt(0)
	v_add_f32_e32 v94, v94, v98
	v_add_f32_e32 v95, v95, v99
	v_add_f32_e32 v96, v96, v100
	v_add_f32_e32 v97, v97, v101
	ds_bpermute_b32 v98, v223, v94
	ds_bpermute_b32 v99, v223, v95
	ds_bpermute_b32 v100, v223, v96
	ds_bpermute_b32 v101, v223, v97
	s_waitcnt lgkmcnt(0)
	v_add_f32_e32 v94, v94, v98
	v_add_f32_e32 v95, v95, v99
	v_add_f32_e32 v96, v96, v100
	v_add_f32_e32 v97, v97, v101
	ds_bpermute_b32 v98, v224, v94
	ds_bpermute_b32 v99, v224, v95
	ds_bpermute_b32 v100, v224, v96
	ds_bpermute_b32 v101, v224, v97
	s_waitcnt lgkmcnt(0)
	v_add_f32_e32 v94, v94, v98
	v_add_f32_e32 v95, v95, v99
	v_add_f32_e32 v96, v96, v100
	v_add_f32_e32 v97, v97, v101
	ds_bpermute_b32 v98, v225, v94
	ds_bpermute_b32 v99, v225, v95
	ds_bpermute_b32 v100, v225, v96
	ds_bpermute_b32 v101, v225, v97
	s_waitcnt lgkmcnt(0)
	v_add_f32_e32 v94, v94, v98
	v_add_f32_e32 v95, v95, v99
	v_add_f32_e32 v96, v96, v100
	v_add_f32_e32 v97, v97, v101
	ds_bpermute_b32 v98, v216, v94
	ds_bpermute_b32 v99, v216, v95
	ds_bpermute_b32 v100, v216, v96
	ds_bpermute_b32 v101, v216, v97
	s_waitcnt lgkmcnt(0)
	v_add_f32_e32 v94, v94, v98
	v_add_f32_e32 v95, v95, v99
	v_add_f32_e32 v96, v96, v100
	v_add_f32_e32 v97, v97, v101
	ds_bpermute_b32 v98, v217, v94
	ds_bpermute_b32 v99, v217, v95
	ds_bpermute_b32 v100, v217, v96
	ds_bpermute_b32 v101, v217, v97
	s_waitcnt lgkmcnt(0)
; __global__ void __launch_bounds__(NTHR, 2) fwd_megakernel(Args args) {
;     ...
;                 const float mean = wave_sum(s) * (1.0f / CCH); float q = 0.f;
; #pragma unroll
;                 for (int j = 0; j < 4; ++j) { x[j] = x[j] - mean; q += (x[j][0] * x[j][0] + x[j][1] * x[j][1]) + (x[j][2] * x[j][2] + x[j][3] * x[j][3]); }
	v_add_f32_e32 v94, v94, v98
	v_add_f32_e32 v95, v95, v99
	v_add_f32_e32 v96, v96, v100
	v_add_f32_e32 v97, v97, v101
	v_fmamk_f32 v140, v94, 0xba800000, v140
	v_fmamk_f32 v141, v94, 0xba800000, v141
	v_fmamk_f32 v142, v94, 0xba800000, v142
	v_fmamk_f32 v143, v94, 0xba800000, v143
	v_fmamk_f32 v144, v94, 0xba800000, v144
	v_fmamk_f32 v145, v94, 0xba800000, v145
	v_fmamk_f32 v146, v94, 0xba800000, v146
	v_fmamk_f32 v147, v94, 0xba800000, v147
	v_fmamk_f32 v148, v94, 0xba800000, v148
	v_fmamk_f32 v149, v94, 0xba800000, v149
	v_fmamk_f32 v150, v94, 0xba800000, v150
	v_fmamk_f32 v151, v94, 0xba800000, v151
	v_fmamk_f32 v152, v94, 0xba800000, v152
	v_fmamk_f32 v153, v94, 0xba800000, v153
	v_fmamk_f32 v154, v94, 0xba800000, v154
	v_fmamk_f32 v155, v94, 0xba800000, v155
	v_fmamk_f32 v156, v95, 0xba800000, v156
	v_fmamk_f32 v157, v95, 0xba800000, v157
	v_fmamk_f32 v158, v95, 0xba800000, v158
	v_fmamk_f32 v159, v95, 0xba800000, v159
	v_fmamk_f32 v160, v95, 0xba800000, v160
	v_fmamk_f32 v161, v95, 0xba800000, v161
	v_fmamk_f32 v162, v95, 0xba800000, v162
	v_fmamk_f32 v163, v95, 0xba800000, v163
	v_fmamk_f32 v164, v95, 0xba800000, v164
	v_fmamk_f32 v165, v95, 0xba800000, v165
	v_fmamk_f32 v166, v95, 0xba800000, v166
	v_fmamk_f32 v167, v95, 0xba800000, v167
	v_fmamk_f32 v168, v95, 0xba800000, v168
	v_fmamk_f32 v169, v95, 0xba800000, v169
	v_fmamk_f32 v170, v95, 0xba800000, v170
	v_fmamk_f32 v171, v95, 0xba800000, v171
	v_fmamk_f32 v172, v96, 0xba800000, v172
	v_fmamk_f32 v173, v96, 0xba800000, v173
	v_fmamk_f32 v174, v96, 0xba800000, v174
	v_fmamk_f32 v175, v96, 0xba800000, v175
	v_fmamk_f32 v176, v96, 0xba800000, v176
	v_fmamk_f32 v177, v96, 0xba800000, v177
	v_fmamk_f32 v178, v96, 0xba800000, v178
	v_fmamk_f32 v179, v96, 0xba800000, v179
	v_fmamk_f32 v180, v96, 0xba800000, v180
	v_fmamk_f32 v181, v96, 0xba800000, v181
	v_fmamk_f32 v182, v96, 0xba800000, v182
	v_fmamk_f32 v183, v96, 0xba800000, v183
	v_fmamk_f32 v184, v96, 0xba800000, v184
	v_fmamk_f32 v185, v96, 0xba800000, v185
	v_fmamk_f32 v186, v96, 0xba800000, v186
	v_fmamk_f32 v187, v96, 0xba800000, v187
	v_fmamk_f32 v188, v97, 0xba800000, v188
	v_fmamk_f32 v189, v97, 0xba800000, v189
	v_fmamk_f32 v190, v97, 0xba800000, v190
	v_fmamk_f32 v191, v97, 0xba800000, v191
	v_fmamk_f32 v192, v97, 0xba800000, v192
	v_fmamk_f32 v193, v97, 0xba800000, v193
	v_fmamk_f32 v194, v97, 0xba800000, v194
	v_fmamk_f32 v195, v97, 0xba800000, v195
	v_fmamk_f32 v196, v97, 0xba800000, v196
	v_fmamk_f32 v197, v97, 0xba800000, v197
	v_fmamk_f32 v198, v97, 0xba800000, v198
	v_fmamk_f32 v199, v97, 0xba800000, v199
	v_fmamk_f32 v200, v97, 0xba800000, v200
	v_fmamk_f32 v201, v97, 0xba800000, v201
	v_fmamk_f32 v202, v97, 0xba800000, v202
	v_fmamk_f32 v203, v97, 0xba800000, v203
	v_mul_f32_e32 v110, v140, v140
	v_mul_f32_e32 v111, v142, v142
	v_mul_f32_e32 v114, v156, v156
	v_mul_f32_e32 v115, v158, v158
	v_mul_f32_e32 v118, v172, v172
	v_mul_f32_e32 v119, v174, v174
	v_mul_f32_e32 v122, v188, v188
	v_mul_f32_e32 v123, v190, v190
	v_fmac_f32_e32 v110, v141, v141
	v_fmac_f32_e32 v111, v143, v143
	v_fmac_f32_e32 v114, v157, v157
	v_fmac_f32_e32 v115, v159, v159
	v_fmac_f32_e32 v118, v173, v173
	v_fmac_f32_e32 v119, v175, v175
	v_fmac_f32_e32 v122, v189, v189
	v_fmac_f32_e32 v123, v191, v191
	v_add_f32_e32 v110, v110, v111
	v_add_f32_e32 v114, v114, v115
	v_add_f32_e32 v118, v118, v119
	v_add_f32_e32 v122, v122, v123
	v_mov_b32_e32 v102, v110
	v_mov_b32_e32 v103, v114
	v_mov_b32_e32 v104, v118
	v_mov_b32_e32 v105, v122
	v_mul_f32_e32 v110, v144, v144
	v_mul_f32_e32 v111, v146, v146
	v_mul_f32_e32 v114, v160, v160
	v_mul_f32_e32 v115, v162, v162
	v_mul_f32_e32 v118, v176, v176
	v_mul_f32_e32 v119, v178, v178
	v_mul_f32_e32 v122, v192, v192
	v_mul_f32_e32 v123, v194, v194
	v_fmac_f32_e32 v110, v145, v145
	v_fmac_f32_e32 v111, v147, v147
	v_fmac_f32_e32 v114, v161, v161
	v_fmac_f32_e32 v115, v163, v163
	v_fmac_f32_e32 v118, v177, v177
	v_fmac_f32_e32 v119, v179, v179
	v_fmac_f32_e32 v122, v193, v193
	v_fmac_f32_e32 v123, v195, v195
	v_add_f32_e32 v110, v110, v111
	v_add_f32_e32 v114, v114, v115
	v_add_f32_e32 v118, v118, v119
	v_add_f32_e32 v122, v122, v123
	v_add_f32_e32 v102, v102, v110
	v_add_f32_e32 v103, v103, v114
	v_add_f32_e32 v104, v104, v118
	v_add_f32_e32 v105, v105, v122
	v_mul_f32_e32 v110, v148, v148
	v_mul_f32_e32 v111, v150, v150
	v_mul_f32_e32 v114, v164, v164
	v_mul_f32_e32 v115, v166, v166
	v_mul_f32_e32 v118, v180, v180
	v_mul_f32_e32 v119, v182, v182
	v_mul_f32_e32 v122, v196, v196
	v_mul_f32_e32 v123, v198, v198
	v_fmac_f32_e32 v110, v149, v149
	v_fmac_f32_e32 v111, v151, v151
	v_fmac_f32_e32 v114, v165, v165
	v_fmac_f32_e32 v115, v167, v167
	v_fmac_f32_e32 v118, v181, v181
	v_fmac_f32_e32 v119, v183, v183
	v_fmac_f32_e32 v122, v197, v197
	v_fmac_f32_e32 v123, v199, v199
	v_add_f32_e32 v110, v110, v111
	v_add_f32_e32 v114, v114, v115
	v_add_f32_e32 v118, v118, v119
	v_add_f32_e32 v122, v122, v123
	v_add_f32_e32 v102, v102, v110
	v_add_f32_e32 v103, v103, v114
	v_add_f32_e32 v104, v104, v118
	v_add_f32_e32 v105, v105, v122
	v_mul_f32_e32 v110, v152, v152
	v_mul_f32_e32 v111, v154, v154
	v_mul_f32_e32 v114, v168, v168
	v_mul_f32_e32 v115, v170, v170
	v_mul_f32_e32 v118, v184, v184
	v_mul_f32_e32 v119, v186, v186
	v_mul_f32_e32 v122, v200, v200
	v_mul_f32_e32 v123, v202, v202
	v_fmac_f32_e32 v110, v153, v153
	v_fmac_f32_e32 v111, v155, v155
	v_fmac_f32_e32 v114, v169, v169
	v_fmac_f32_e32 v115, v171, v171
	v_fmac_f32_e32 v118, v185, v185
	v_fmac_f32_e32 v119, v187, v187
	v_fmac_f32_e32 v122, v201, v201
	v_fmac_f32_e32 v123, v203, v203
	v_add_f32_e32 v110, v110, v111
	v_add_f32_e32 v114, v114, v115
	v_add_f32_e32 v118, v118, v119
	v_add_f32_e32 v122, v122, v123
	v_add_f32_e32 v102, v102, v110
	v_add_f32_e32 v103, v103, v114
	v_add_f32_e32 v104, v104, v118
	v_add_f32_e32 v105, v105, v122
	ds_bpermute_b32 v98, v222, v102
	ds_bpermute_b32 v99, v222, v103
	ds_bpermute_b32 v100, v222, v104
	ds_bpermute_b32 v101, v222, v105
	s_waitcnt lgkmcnt(0)
; __device__ __forceinline__ float sigmoidf_(float x) { return fast_rcp(1.0f + fast_exp2(-1.4426950408889634f * x)); }
; #define KIN(i) (*(const float* const __attribute__((address_space(4)))*)(kp + kz + 8 * (i)))
; __global__ void __launch_bounds__(NTHR, 2) fwd_megakernel(Args args) {
;     ...
;                 for (int j = 0; j < 4; ++j) { x[j] = x[j] - mean; q += (x[j][0] * x[j][0] + x[j][1] * x[j][1]) + (x[j][2] * x[j][2] + x[j][3] * x[j][3]); }
;                 const float rstd = rsqrtf(wave_sum(q) * (1.0f / CCH) + LN_EPS); float z2 = 0.f;
; #pragma unroll
;                 for (int j = 0; j < 4; ++j) { const f32x4 gg = *(const f32x4*)(KIN(I_CONV_LN_G) + j * 256 + 4 * lane), bb = *(const f32x4*)(KIN(I_CONV_LN_B) + j * 256 + 4 * lane);
;                     f32x4 y = x[j] * rstd * gg + bb;
; #pragma unroll
;                     for (int e = 0; e < 4; ++e) { y[e] = y[e] * sigmoidf_(y[e]); z2 += y[e] * y[e]; }
;                     x[j] = y; }
	v_add_f32_e32 v102, v102, v98
	v_add_f32_e32 v103, v103, v99
	v_add_f32_e32 v104, v104, v100
	v_add_f32_e32 v105, v105, v101
	ds_bpermute_b32 v98, v223, v102
	ds_bpermute_b32 v99, v223, v103
	ds_bpermute_b32 v100, v223, v104
	ds_bpermute_b32 v101, v223, v105
	s_waitcnt lgkmcnt(0)
	v_add_f32_e32 v102, v102, v98
	v_add_f32_e32 v103, v103, v99
	v_add_f32_e32 v104, v104, v100
	v_add_f32_e32 v105, v105, v101
	ds_bpermute_b32 v98, v224, v102
	ds_bpermute_b32 v99, v224, v103
	ds_bpermute_b32 v100, v224, v104
	ds_bpermute_b32 v101, v224, v105
	s_waitcnt lgkmcnt(0)
	v_add_f32_e32 v102, v102, v98
	v_add_f32_e32 v103, v103, v99
	v_add_f32_e32 v104, v104, v100
	v_add_f32_e32 v105, v105, v101
	ds_bpermute_b32 v98, v225, v102
	ds_bpermute_b32 v99, v225, v103
	ds_bpermute_b32 v100, v225, v104
	ds_bpermute_b32 v101, v225, v105
	s_waitcnt lgkmcnt(0)
	v_add_f32_e32 v102, v102, v98
	v_add_f32_e32 v103, v103, v99
	v_add_f32_e32 v104, v104, v100
	v_add_f32_e32 v105, v105, v101
	ds_bpermute_b32 v98, v216, v102
	ds_bpermute_b32 v99, v216, v103
	ds_bpermute_b32 v100, v216, v104
	ds_bpermute_b32 v101, v216, v105
	s_waitcnt lgkmcnt(0)
	v_add_f32_e32 v102, v102, v98
	v_add_f32_e32 v103, v103, v99
	v_add_f32_e32 v104, v104, v100
	v_add_f32_e32 v105, v105, v101
	ds_bpermute_b32 v98, v217, v102
	ds_bpermute_b32 v99, v217, v103
	ds_bpermute_b32 v100, v217, v104
	ds_bpermute_b32 v101, v217, v105
	s_waitcnt lgkmcnt(0)
	v_add_f32_e32 v102, v102, v98
	v_add_f32_e32 v103, v103, v99
	v_add_f32_e32 v104, v104, v100
	v_add_f32_e32 v105, v105, v101
	v_fmamk_f32 v106, v102, 0x3a800000, v226
	v_fmamk_f32 v107, v103, 0x3a800000, v226
	v_fmamk_f32 v108, v104, 0x3a800000, v226
	v_fmamk_f32 v109, v105, 0x3a800000, v226
	v_rsq_f32_e32 v106, v106
	v_rsq_f32_e32 v107, v107
	v_rsq_f32_e32 v108, v108
	v_rsq_f32_e32 v109, v109
	s_waitcnt vmcnt(0)
	v_mov_b32_e32 v102, 0
	v_mov_b32_e32 v103, 0
	v_mov_b32_e32 v104, 0
	v_mov_b32_e32 v105, 0
	v_mul_f32_e32 v140, v140, v106
	v_mul_f32_e32 v141, v141, v106
	v_mul_f32_e32 v142, v142, v106
	v_mul_f32_e32 v143, v143, v106
	v_mul_f32_e32 v156, v156, v107
	v_mul_f32_e32 v157, v157, v107
	v_mul_f32_e32 v158, v158, v107
	v_mul_f32_e32 v159, v159, v107
	v_mul_f32_e32 v172, v172, v108
	v_mul_f32_e32 v173, v173, v108
	v_mul_f32_e32 v174, v174, v108
	v_mul_f32_e32 v175, v175, v108
	v_mul_f32_e32 v188, v188, v109
	v_mul_f32_e32 v189, v189, v109
	v_mul_f32_e32 v190, v190, v109
	v_mul_f32_e32 v191, v191, v109
	v_fma_f32 v140, v140, v204, v232
	v_fma_f32 v141, v141, v205, v233
	v_fma_f32 v142, v142, v206, v234
	v_fma_f32 v143, v143, v207, v235
	v_fma_f32 v156, v156, v204, v232
	v_fma_f32 v157, v157, v205, v233
	v_fma_f32 v158, v158, v206, v234
	v_fma_f32 v159, v159, v207, v235
	v_fma_f32 v172, v172, v204, v232
	v_fma_f32 v173, v173, v205, v233
	v_fma_f32 v174, v174, v206, v234
	v_fma_f32 v175, v175, v207, v235
	v_fma_f32 v188, v188, v204, v232
	v_fma_f32 v189, v189, v205, v233
	v_fma_f32 v190, v190, v206, v234
	v_fma_f32 v191, v191, v207, v235
	v_mul_f32_e32 v110, 0xbfb8aa3b, v140
	v_mul_f32_e32 v111, 0xbfb8aa3b, v141
	v_mul_f32_e32 v112, 0xbfb8aa3b, v142
	v_mul_f32_e32 v113, 0xbfb8aa3b, v143
	v_mul_f32_e32 v114, 0xbfb8aa3b, v156
	v_mul_f32_e32 v115, 0xbfb8aa3b, v157
	v_mul_f32_e32 v116, 0xbfb8aa3b, v158
	v_mul_f32_e32 v117, 0xbfb8aa3b, v159
	v_mul_f32_e32 v118, 0xbfb8aa3b, v172
	v_mul_f32_e32 v119, 0xbfb8aa3b, v173
	v_mul_f32_e32 v120, 0xbfb8aa3b, v174
	v_mul_f32_e32 v121, 0xbfb8aa3b, v175
	v_mul_f32_e32 v122, 0xbfb8aa3b, v188
	v_mul_f32_e32 v123, 0xbfb8aa3b, v189
	v_mul_f32_e32 v124, 0xbfb8aa3b, v190
	v_mul_f32_e32 v125, 0xbfb8aa3b, v191
	v_exp_f32_e32 v110, v110
	v_exp_f32_e32 v111, v111
	v_exp_f32_e32 v112, v112
	v_exp_f32_e32 v113, v113
	v_exp_f32_e32 v114, v114
	v_exp_f32_e32 v115, v115
	v_exp_f32_e32 v116, v116
	v_exp_f32_e32 v117, v117
	v_exp_f32_e32 v118, v118
	v_exp_f32_e32 v119, v119
	v_exp_f32_e32 v120, v120
	v_exp_f32_e32 v121, v121
	v_exp_f32_e32 v122, v122
	v_exp_f32_e32 v123, v123
	v_exp_f32_e32 v124, v124
	v_exp_f32_e32 v125, v125
	v_add_f32_e32 v110, 1.0, v110
	v_add_f32_e32 v111, 1.0, v111
	v_add_f32_e32 v112, 1.0, v112
	v_add_f32_e32 v113, 1.0, v113
	v_add_f32_e32 v114, 1.0, v114
	v_add_f32_e32 v115, 1.0, v115
	v_add_f32_e32 v116, 1.0, v116
	v_add_f32_e32 v117, 1.0, v117
	v_add_f32_e32 v118, 1.0, v118
	v_add_f32_e32 v119, 1.0, v119
	v_add_f32_e32 v120, 1.0, v120
	v_add_f32_e32 v121, 1.0, v121
	v_add_f32_e32 v122, 1.0, v122
	v_add_f32_e32 v123, 1.0, v123
	v_add_f32_e32 v124, 1.0, v124
	v_add_f32_e32 v125, 1.0, v125
	v_rcp_f32_e32 v110, v110
	v_rcp_f32_e32 v111, v111
	v_rcp_f32_e32 v112, v112
	v_rcp_f32_e32 v113, v113
	v_rcp_f32_e32 v114, v114
	v_rcp_f32_e32 v115, v115
	v_rcp_f32_e32 v116, v116
	v_rcp_f32_e32 v117, v117
	v_rcp_f32_e32 v118, v118
	v_rcp_f32_e32 v119, v119
	v_rcp_f32_e32 v120, v120
	v_rcp_f32_e32 v121, v121
	v_rcp_f32_e32 v122, v122
	v_rcp_f32_e32 v123, v123
	v_rcp_f32_e32 v124, v124
	v_rcp_f32_e32 v125, v125
	v_mul_f32_e32 v140, v140, v110
	v_mul_f32_e32 v141, v141, v111
	v_mul_f32_e32 v142, v142, v112
	v_mul_f32_e32 v143, v143, v113
	v_mul_f32_e32 v156, v156, v114
	v_mul_f32_e32 v157, v157, v115
	v_mul_f32_e32 v158, v158, v116
	v_mul_f32_e32 v159, v159, v117
	v_mul_f32_e32 v172, v172, v118
	v_mul_f32_e32 v173, v173, v119
	v_mul_f32_e32 v174, v174, v120
	v_mul_f32_e32 v175, v175, v121
	v_mul_f32_e32 v188, v188, v122
	v_mul_f32_e32 v189, v189, v123
	v_mul_f32_e32 v190, v190, v124
	v_mul_f32_e32 v191, v191, v125
	v_fmac_f32_e32 v102, v140, v140
	v_fmac_f32_e32 v103, v156, v156
	v_fmac_f32_e32 v104, v172, v172
	v_fmac_f32_e32 v105, v188, v188
	v_fmac_f32_e32 v102, v141, v141
	v_fmac_f32_e32 v103, v157, v157
	v_fmac_f32_e32 v104, v173, v173
; __device__ __forceinline__ float sigmoidf_(float x) { return fast_rcp(1.0f + fast_exp2(-1.4426950408889634f * x)); }
; #define KIN(i) (*(const float* const __attribute__((address_space(4)))*)(kp + kz + 8 * (i)))
; __global__ void __launch_bounds__(NTHR, 2) fwd_megakernel(Args args) {
;     ...
;                 for (int j = 0; j < 4; ++j) { const f32x4 gg = *(const f32x4*)(KIN(I_CONV_LN_G) + j * 256 + 4 * lane), bb = *(const f32x4*)(KIN(I_CONV_LN_B) + j * 256 + 4 * lane);
;                     f32x4 y = x[j] * rstd * gg + bb;
; #pragma unroll
;                     for (int e = 0; e < 4; ++e) { y[e] = y[e] * sigmoidf_(y[e]); z2 += y[e] * y[e]; }
;                     x[j] = y; }
	v_fmac_f32_e32 v105, v189, v189
	v_fmac_f32_e32 v102, v142, v142
	v_fmac_f32_e32 v103, v158, v158
	v_fmac_f32_e32 v104, v174, v174
	v_fmac_f32_e32 v105, v190, v190
	v_fmac_f32_e32 v102, v143, v143
	v_fmac_f32_e32 v103, v159, v159
	v_fmac_f32_e32 v104, v175, v175
	v_fmac_f32_e32 v105, v191, v191
	v_mul_f32_e32 v144, v144, v106
	v_mul_f32_e32 v145, v145, v106
	v_mul_f32_e32 v146, v146, v106
	v_mul_f32_e32 v147, v147, v106
	v_mul_f32_e32 v160, v160, v107
	v_mul_f32_e32 v161, v161, v107
	v_mul_f32_e32 v162, v162, v107
	v_mul_f32_e32 v163, v163, v107
	v_mul_f32_e32 v176, v176, v108
	v_mul_f32_e32 v177, v177, v108
	v_mul_f32_e32 v178, v178, v108
	v_mul_f32_e32 v179, v179, v108
	v_mul_f32_e32 v192, v192, v109
	v_mul_f32_e32 v193, v193, v109
	v_mul_f32_e32 v194, v194, v109
	v_mul_f32_e32 v195, v195, v109
	v_fma_f32 v144, v144, v208, v236
	v_fma_f32 v145, v145, v209, v237
	v_fma_f32 v146, v146, v210, v238
	v_fma_f32 v147, v147, v211, v239
	v_fma_f32 v160, v160, v208, v236
	v_fma_f32 v161, v161, v209, v237
	v_fma_f32 v162, v162, v210, v238
	v_fma_f32 v163, v163, v211, v239
	v_fma_f32 v176, v176, v208, v236
	v_fma_f32 v177, v177, v209, v237
	v_fma_f32 v178, v178, v210, v238
	v_fma_f32 v179, v179, v211, v239
	v_fma_f32 v192, v192, v208, v236
	v_fma_f32 v193, v193, v209, v237
	v_fma_f32 v194, v194, v210, v238
	v_fma_f32 v195, v195, v211, v239
	v_mul_f32_e32 v110, 0xbfb8aa3b, v144
	v_mul_f32_e32 v111, 0xbfb8aa3b, v145
	v_mul_f32_e32 v112, 0xbfb8aa3b, v146
	v_mul_f32_e32 v113, 0xbfb8aa3b, v147
	v_mul_f32_e32 v114, 0xbfb8aa3b, v160
	v_mul_f32_e32 v115, 0xbfb8aa3b, v161
	v_mul_f32_e32 v116, 0xbfb8aa3b, v162
	v_mul_f32_e32 v117, 0xbfb8aa3b, v163
	v_mul_f32_e32 v118, 0xbfb8aa3b, v176
	v_mul_f32_e32 v119, 0xbfb8aa3b, v177
	v_mul_f32_e32 v120, 0xbfb8aa3b, v178
	v_mul_f32_e32 v121, 0xbfb8aa3b, v179
	v_mul_f32_e32 v122, 0xbfb8aa3b, v192
	v_mul_f32_e32 v123, 0xbfb8aa3b, v193
	v_mul_f32_e32 v124, 0xbfb8aa3b, v194
	v_mul_f32_e32 v125, 0xbfb8aa3b, v195
	v_exp_f32_e32 v110, v110
	v_exp_f32_e32 v111, v111
	v_exp_f32_e32 v112, v112
	v_exp_f32_e32 v113, v113
	v_exp_f32_e32 v114, v114
	v_exp_f32_e32 v115, v115
	v_exp_f32_e32 v116, v116
	v_exp_f32_e32 v117, v117
	v_exp_f32_e32 v118, v118
	v_exp_f32_e32 v119, v119
	v_exp_f32_e32 v120, v120
	v_exp_f32_e32 v121, v121
	v_exp_f32_e32 v122, v122
	v_exp_f32_e32 v123, v123
	v_exp_f32_e32 v124, v124
	v_exp_f32_e32 v125, v125
	v_add_f32_e32 v110, 1.0, v110
	v_add_f32_e32 v111, 1.0, v111
	v_add_f32_e32 v112, 1.0, v112
	v_add_f32_e32 v113, 1.0, v113
	v_add_f32_e32 v114, 1.0, v114
	v_add_f32_e32 v115, 1.0, v115
	v_add_f32_e32 v116, 1.0, v116
	v_add_f32_e32 v117, 1.0, v117
	v_add_f32_e32 v118, 1.0, v118
	v_add_f32_e32 v119, 1.0, v119
	v_add_f32_e32 v120, 1.0, v120
	v_add_f32_e32 v121, 1.0, v121
	v_add_f32_e32 v122, 1.0, v122
	v_add_f32_e32 v123, 1.0, v123
	v_add_f32_e32 v124, 1.0, v124
	v_add_f32_e32 v125, 1.0, v125
	v_rcp_f32_e32 v110, v110
	v_rcp_f32_e32 v111, v111
	v_rcp_f32_e32 v112, v112
	v_rcp_f32_e32 v113, v113
	v_rcp_f32_e32 v114, v114
	v_rcp_f32_e32 v115, v115
	v_rcp_f32_e32 v116, v116
	v_rcp_f32_e32 v117, v117
	v_rcp_f32_e32 v118, v118
	v_rcp_f32_e32 v119, v119
	v_rcp_f32_e32 v120, v120
	v_rcp_f32_e32 v121, v121
	v_rcp_f32_e32 v122, v122
	v_rcp_f32_e32 v123, v123
	v_rcp_f32_e32 v124, v124
	v_rcp_f32_e32 v125, v125
	v_mul_f32_e32 v144, v144, v110
	v_mul_f32_e32 v145, v145, v111
	v_mul_f32_e32 v146, v146, v112
	v_mul_f32_e32 v147, v147, v113
	v_mul_f32_e32 v160, v160, v114
	v_mul_f32_e32 v161, v161, v115
	v_mul_f32_e32 v162, v162, v116
	v_mul_f32_e32 v163, v163, v117
	v_mul_f32_e32 v176, v176, v118
	v_mul_f32_e32 v177, v177, v119
	v_mul_f32_e32 v178, v178, v120
	v_mul_f32_e32 v179, v179, v121
	v_mul_f32_e32 v192, v192, v122
	v_mul_f32_e32 v193, v193, v123
	v_mul_f32_e32 v194, v194, v124
	v_mul_f32_e32 v195, v195, v125
	v_fmac_f32_e32 v102, v144, v144
	v_fmac_f32_e32 v103, v160, v160
	v_fmac_f32_e32 v104, v176, v176
	v_fmac_f32_e32 v105, v192, v192
	v_fmac_f32_e32 v102, v145, v145
	v_fmac_f32_e32 v103, v161, v161
	v_fmac_f32_e32 v104, v177, v177
	v_fmac_f32_e32 v105, v193, v193
	v_fmac_f32_e32 v102, v146, v146
	v_fmac_f32_e32 v103, v162, v162
	v_fmac_f32_e32 v104, v178, v178
	v_fmac_f32_e32 v105, v194, v194
	v_fmac_f32_e32 v102, v147, v147
	v_fmac_f32_e32 v103, v163, v163
	v_fmac_f32_e32 v104, v179, v179
	v_fmac_f32_e32 v105, v195, v195
	v_mul_f32_e32 v148, v148, v106
	v_mul_f32_e32 v149, v149, v106
	v_mul_f32_e32 v150, v150, v106
	v_mul_f32_e32 v151, v151, v106
	v_mul_f32_e32 v164, v164, v107
	v_mul_f32_e32 v165, v165, v107
	v_mul_f32_e32 v166, v166, v107
	v_mul_f32_e32 v167, v167, v107
	v_mul_f32_e32 v180, v180, v108
	v_mul_f32_e32 v181, v181, v108
	v_mul_f32_e32 v182, v182, v108
	v_mul_f32_e32 v183, v183, v108
	v_mul_f32_e32 v196, v196, v109
	v_mul_f32_e32 v197, v197, v109
	v_mul_f32_e32 v198, v198, v109
	v_mul_f32_e32 v199, v199, v109
	v_fma_f32 v148, v148, v212, v240
	v_fma_f32 v149, v149, v213, v241
	v_fma_f32 v150, v150, v214, v242
	v_fma_f32 v151, v151, v215, v243
	v_fma_f32 v164, v164, v212, v240
	v_fma_f32 v165, v165, v213, v241
	v_fma_f32 v166, v166, v214, v242
	v_fma_f32 v167, v167, v215, v243
	v_fma_f32 v180, v180, v212, v240
	v_fma_f32 v181, v181, v213, v241
	v_fma_f32 v182, v182, v214, v242
	v_fma_f32 v183, v183, v215, v243
	v_fma_f32 v196, v196, v212, v240
	v_fma_f32 v197, v197, v213, v241
	v_fma_f32 v198, v198, v214, v242
	v_fma_f32 v199, v199, v215, v243
	v_mul_f32_e32 v110, 0xbfb8aa3b, v148
	v_mul_f32_e32 v111, 0xbfb8aa3b, v149
	v_mul_f32_e32 v112, 0xbfb8aa3b, v150
	v_mul_f32_e32 v113, 0xbfb8aa3b, v151
	v_mul_f32_e32 v114, 0xbfb8aa3b, v164
	v_mul_f32_e32 v115, 0xbfb8aa3b, v165
	v_mul_f32_e32 v116, 0xbfb8aa3b, v166
; __device__ __forceinline__ float sigmoidf_(float x) { return fast_rcp(1.0f + fast_exp2(-1.4426950408889634f * x)); }
; #define KIN(i) (*(const float* const __attribute__((address_space(4)))*)(kp + kz + 8 * (i)))
; __global__ void __launch_bounds__(NTHR, 2) fwd_megakernel(Args args) {
;     ...
;                 for (int j = 0; j < 4; ++j) { const f32x4 gg = *(const f32x4*)(KIN(I_CONV_LN_G) + j * 256 + 4 * lane), bb = *(const f32x4*)(KIN(I_CONV_LN_B) + j * 256 + 4 * lane);
;                     f32x4 y = x[j] * rstd * gg + bb;
; #pragma unroll
;                     for (int e = 0; e < 4; ++e) { y[e] = y[e] * sigmoidf_(y[e]); z2 += y[e] * y[e]; }
;                     x[j] = y; }
;                 const float r2 = rsqrtf(wave_sum(z2) * (1.0f / CCH) + RMS_EPS);
	v_mul_f32_e32 v117, 0xbfb8aa3b, v167
	v_mul_f32_e32 v118, 0xbfb8aa3b, v180
	v_mul_f32_e32 v119, 0xbfb8aa3b, v181
	v_mul_f32_e32 v120, 0xbfb8aa3b, v182
	v_mul_f32_e32 v121, 0xbfb8aa3b, v183
	v_mul_f32_e32 v122, 0xbfb8aa3b, v196
	v_mul_f32_e32 v123, 0xbfb8aa3b, v197
	v_mul_f32_e32 v124, 0xbfb8aa3b, v198
	v_mul_f32_e32 v125, 0xbfb8aa3b, v199
	v_exp_f32_e32 v110, v110
	v_exp_f32_e32 v111, v111
	v_exp_f32_e32 v112, v112
	v_exp_f32_e32 v113, v113
	v_exp_f32_e32 v114, v114
	v_exp_f32_e32 v115, v115
	v_exp_f32_e32 v116, v116
	v_exp_f32_e32 v117, v117
	v_exp_f32_e32 v118, v118
	v_exp_f32_e32 v119, v119
	v_exp_f32_e32 v120, v120
	v_exp_f32_e32 v121, v121
	v_exp_f32_e32 v122, v122
	v_exp_f32_e32 v123, v123
	v_exp_f32_e32 v124, v124
	v_exp_f32_e32 v125, v125
	v_add_f32_e32 v110, 1.0, v110
	v_add_f32_e32 v111, 1.0, v111
	v_add_f32_e32 v112, 1.0, v112
	v_add_f32_e32 v113, 1.0, v113
	v_add_f32_e32 v114, 1.0, v114
	v_add_f32_e32 v115, 1.0, v115
	v_add_f32_e32 v116, 1.0, v116
	v_add_f32_e32 v117, 1.0, v117
	v_add_f32_e32 v118, 1.0, v118
	v_add_f32_e32 v119, 1.0, v119
	v_add_f32_e32 v120, 1.0, v120
	v_add_f32_e32 v121, 1.0, v121
	v_add_f32_e32 v122, 1.0, v122
	v_add_f32_e32 v123, 1.0, v123
	v_add_f32_e32 v124, 1.0, v124
	v_add_f32_e32 v125, 1.0, v125
	v_rcp_f32_e32 v110, v110
	v_rcp_f32_e32 v111, v111
	v_rcp_f32_e32 v112, v112
	v_rcp_f32_e32 v113, v113
	v_rcp_f32_e32 v114, v114
	v_rcp_f32_e32 v115, v115
	v_rcp_f32_e32 v116, v116
	v_rcp_f32_e32 v117, v117
	v_rcp_f32_e32 v118, v118
	v_rcp_f32_e32 v119, v119
	v_rcp_f32_e32 v120, v120
	v_rcp_f32_e32 v121, v121
	v_rcp_f32_e32 v122, v122
	v_rcp_f32_e32 v123, v123
	v_rcp_f32_e32 v124, v124
	v_rcp_f32_e32 v125, v125
	v_mul_f32_e32 v148, v148, v110
	v_mul_f32_e32 v149, v149, v111
	v_mul_f32_e32 v150, v150, v112
	v_mul_f32_e32 v151, v151, v113
	v_mul_f32_e32 v164, v164, v114
	v_mul_f32_e32 v165, v165, v115
	v_mul_f32_e32 v166, v166, v116
	v_mul_f32_e32 v167, v167, v117
	v_mul_f32_e32 v180, v180, v118
	v_mul_f32_e32 v181, v181, v119
	v_mul_f32_e32 v182, v182, v120
	v_mul_f32_e32 v183, v183, v121
	v_mul_f32_e32 v196, v196, v122
	v_mul_f32_e32 v197, v197, v123
	v_mul_f32_e32 v198, v198, v124
	v_mul_f32_e32 v199, v199, v125
	v_fmac_f32_e32 v102, v148, v148
	v_fmac_f32_e32 v103, v164, v164
	v_fmac_f32_e32 v104, v180, v180
	v_fmac_f32_e32 v105, v196, v196
	v_fmac_f32_e32 v102, v149, v149
	v_fmac_f32_e32 v103, v165, v165
	v_fmac_f32_e32 v104, v181, v181
	v_fmac_f32_e32 v105, v197, v197
	v_fmac_f32_e32 v102, v150, v150
	v_fmac_f32_e32 v103, v166, v166
	v_fmac_f32_e32 v104, v182, v182
	v_fmac_f32_e32 v105, v198, v198
	v_fmac_f32_e32 v102, v151, v151
	v_fmac_f32_e32 v103, v167, v167
	v_fmac_f32_e32 v104, v183, v183
	v_fmac_f32_e32 v105, v199, v199
	v_mul_f32_e32 v152, v152, v106
	v_mul_f32_e32 v153, v153, v106
	v_mul_f32_e32 v154, v154, v106
	v_mul_f32_e32 v155, v155, v106
	v_mul_f32_e32 v168, v168, v107
	v_mul_f32_e32 v169, v169, v107
	v_mul_f32_e32 v170, v170, v107
	v_mul_f32_e32 v171, v171, v107
	v_mul_f32_e32 v184, v184, v108
	v_mul_f32_e32 v185, v185, v108
	v_mul_f32_e32 v186, v186, v108
	v_mul_f32_e32 v187, v187, v108
	v_mul_f32_e32 v200, v200, v109
	v_mul_f32_e32 v201, v201, v109
	v_mul_f32_e32 v202, v202, v109
	v_mul_f32_e32 v203, v203, v109
	v_fma_f32 v152, v152, v228, v0
	v_fma_f32 v153, v153, v229, v1
	v_fma_f32 v154, v154, v230, v2
	v_fma_f32 v155, v155, v231, v3
	v_fma_f32 v168, v168, v228, v0
	v_fma_f32 v169, v169, v229, v1
	v_fma_f32 v170, v170, v230, v2
	v_fma_f32 v171, v171, v231, v3
	v_fma_f32 v184, v184, v228, v0
	v_fma_f32 v185, v185, v229, v1
	v_fma_f32 v186, v186, v230, v2
	v_fma_f32 v187, v187, v231, v3
	v_fma_f32 v200, v200, v228, v0
	v_fma_f32 v201, v201, v229, v1
	v_fma_f32 v202, v202, v230, v2
	v_fma_f32 v203, v203, v231, v3
	v_mul_f32_e32 v110, 0xbfb8aa3b, v152
	v_mul_f32_e32 v111, 0xbfb8aa3b, v153
	v_mul_f32_e32 v112, 0xbfb8aa3b, v154
	v_mul_f32_e32 v113, 0xbfb8aa3b, v155
	v_mul_f32_e32 v114, 0xbfb8aa3b, v168
	v_mul_f32_e32 v115, 0xbfb8aa3b, v169
	v_mul_f32_e32 v116, 0xbfb8aa3b, v170
	v_mul_f32_e32 v117, 0xbfb8aa3b, v171
	v_mul_f32_e32 v118, 0xbfb8aa3b, v184
	v_mul_f32_e32 v119, 0xbfb8aa3b, v185
	v_mul_f32_e32 v120, 0xbfb8aa3b, v186
	v_mul_f32_e32 v121, 0xbfb8aa3b, v187
	v_mul_f32_e32 v122, 0xbfb8aa3b, v200
	v_mul_f32_e32 v123, 0xbfb8aa3b, v201
	v_mul_f32_e32 v124, 0xbfb8aa3b, v202
	v_mul_f32_e32 v125, 0xbfb8aa3b, v203
	v_exp_f32_e32 v110, v110
	v_exp_f32_e32 v111, v111
	v_exp_f32_e32 v112, v112
	v_exp_f32_e32 v113, v113
	v_exp_f32_e32 v114, v114
	v_exp_f32_e32 v115, v115
	v_exp_f32_e32 v116, v116
	v_exp_f32_e32 v117, v117
	v_exp_f32_e32 v118, v118
	v_exp_f32_e32 v119, v119
	v_exp_f32_e32 v120, v120
	v_exp_f32_e32 v121, v121
	v_exp_f32_e32 v122, v122
	v_exp_f32_e32 v123, v123
	v_exp_f32_e32 v124, v124
	v_exp_f32_e32 v125, v125
	v_add_f32_e32 v110, 1.0, v110
	v_add_f32_e32 v111, 1.0, v111
	v_add_f32_e32 v112, 1.0, v112
	v_add_f32_e32 v113, 1.0, v113
	v_add_f32_e32 v114, 1.0, v114
	v_add_f32_e32 v115, 1.0, v115
	v_add_f32_e32 v116, 1.0, v116
	v_add_f32_e32 v117, 1.0, v117
	v_add_f32_e32 v118, 1.0, v118
	v_add_f32_e32 v119, 1.0, v119
	v_add_f32_e32 v120, 1.0, v120
	v_add_f32_e32 v121, 1.0, v121
	v_add_f32_e32 v122, 1.0, v122
	v_add_f32_e32 v123, 1.0, v123
	v_add_f32_e32 v124, 1.0, v124
	v_add_f32_e32 v125, 1.0, v125
	v_rcp_f32_e32 v110, v110
	v_rcp_f32_e32 v111, v111
	v_rcp_f32_e32 v112, v112
	v_rcp_f32_e32 v113, v113
	v_rcp_f32_e32 v114, v114
	v_rcp_f32_e32 v115, v115
	v_rcp_f32_e32 v116, v116
	v_rcp_f32_e32 v117, v117
	v_rcp_f32_e32 v118, v118
	v_rcp_f32_e32 v119, v119
	v_rcp_f32_e32 v120, v120
	v_rcp_f32_e32 v121, v121
	v_rcp_f32_e32 v122, v122
	v_rcp_f32_e32 v123, v123
	v_rcp_f32_e32 v124, v124
	v_rcp_f32_e32 v125, v125
	v_mul_f32_e32 v152, v152, v110
	v_mul_f32_e32 v153, v153, v111
	v_mul_f32_e32 v154, v154, v112
	v_mul_f32_e32 v155, v155, v113
	v_mul_f32_e32 v168, v168, v114
	v_mul_f32_e32 v169, v169, v115
	v_mul_f32_e32 v170, v170, v116
	v_mul_f32_e32 v171, v171, v117
	v_mul_f32_e32 v184, v184, v118
	v_mul_f32_e32 v185, v185, v119
	v_mul_f32_e32 v186, v186, v120
	v_mul_f32_e32 v187, v187, v121
	v_mul_f32_e32 v200, v200, v122
	v_mul_f32_e32 v201, v201, v123
	v_mul_f32_e32 v202, v202, v124
	v_mul_f32_e32 v203, v203, v125
	v_fmac_f32_e32 v102, v152, v152
	v_fmac_f32_e32 v103, v168, v168
	v_fmac_f32_e32 v104, v184, v184
	v_fmac_f32_e32 v105, v200, v200
	v_fmac_f32_e32 v102, v153, v153
	v_fmac_f32_e32 v103, v169, v169
	v_fmac_f32_e32 v104, v185, v185
	v_fmac_f32_e32 v105, v201, v201
	v_fmac_f32_e32 v102, v154, v154
	v_fmac_f32_e32 v103, v170, v170
	v_fmac_f32_e32 v104, v186, v186
	v_fmac_f32_e32 v105, v202, v202
	v_fmac_f32_e32 v102, v155, v155
	v_fmac_f32_e32 v103, v171, v171
	v_fmac_f32_e32 v104, v187, v187
	v_fmac_f32_e32 v105, v203, v203
	ds_bpermute_b32 v98, v222, v102
	ds_bpermute_b32 v99, v222, v103
	ds_bpermute_b32 v100, v222, v104
	ds_bpermute_b32 v101, v222, v105
	s_waitcnt lgkmcnt(0)
; __global__ void __launch_bounds__(NTHR, 2) fwd_megakernel(Args args) {
;     ...
;                 const float r2 = rsqrtf(wave_sum(z2) * (1.0f / CCH) + RMS_EPS);
	v_add_f32_e32 v102, v102, v98
	v_add_f32_e32 v103, v103, v99
	v_add_f32_e32 v104, v104, v100
	v_add_f32_e32 v105, v105, v101
	ds_bpermute_b32 v98, v223, v102
	ds_bpermute_b32 v99, v223, v103
	ds_bpermute_b32 v100, v223, v104
	ds_bpermute_b32 v101, v223, v105
	s_waitcnt lgkmcnt(0)
	v_add_f32_e32 v102, v102, v98
	v_add_f32_e32 v103, v103, v99
	v_add_f32_e32 v104, v104, v100
	v_add_f32_e32 v105, v105, v101
	ds_bpermute_b32 v98, v224, v102
	ds_bpermute_b32 v99, v224, v103
	ds_bpermute_b32 v100, v224, v104
	ds_bpermute_b32 v101, v224, v105
	s_waitcnt lgkmcnt(0)
	v_add_f32_e32 v102, v102, v98
	v_add_f32_e32 v103, v103, v99
	v_add_f32_e32 v104, v104, v100
	v_add_f32_e32 v105, v105, v101
	ds_bpermute_b32 v98, v225, v102
	ds_bpermute_b32 v99, v225, v103
	ds_bpermute_b32 v100, v225, v104
	ds_bpermute_b32 v101, v225, v105
	s_waitcnt lgkmcnt(0)
	v_add_f32_e32 v102, v102, v98
	v_add_f32_e32 v103, v103, v99
	v_add_f32_e32 v104, v104, v100
	v_add_f32_e32 v105, v105, v101
	ds_bpermute_b32 v98, v216, v102
	ds_bpermute_b32 v99, v216, v103
	ds_bpermute_b32 v100, v216, v104
	ds_bpermute_b32 v101, v216, v105
	s_waitcnt lgkmcnt(0)
	v_add_f32_e32 v102, v102, v98
	v_add_f32_e32 v103, v103, v99
	v_add_f32_e32 v104, v104, v100
	v_add_f32_e32 v105, v105, v101
	ds_bpermute_b32 v98, v217, v102
	ds_bpermute_b32 v99, v217, v103
	ds_bpermute_b32 v100, v217, v104
	ds_bpermute_b32 v101, v217, v105
	s_waitcnt lgkmcnt(0)
; __device__ __forceinline__ unsigned cvt_pk_bf16(float lo, float hi) { unsigned r; asm volatile("v_cvt_pk_bf16_f32 %0, %1, %2" : "=v"(r) : "v"(lo), "v"(hi)); return r; }
; #define KIN(i) (*(const float* const __attribute__((address_space(4)))*)(kp + kz + 8 * (i)))
; __global__ void __launch_bounds__(NTHR, 2) fwd_megakernel(Args args) {
;     ...
;         for (int cu = bid; cu < T / 32; cu += G) {
;     ...
;                 const float r2 = rsqrtf(wave_sum(z2) * (1.0f / CCH) + RMS_EPS);
; #pragma unroll
;                 for (int j = 0; j < 4; ++j) { const f32x4 gg = *(const f32x4*)(KIN(I_OUT_NORM_CONV) + j * 256 + 4 * lane); const f32x4 y = x[j] * r2 * gg;
;                     u32x2 w; w.x = cvt_pk_bf16(y[0], y[1]); w.y = cvt_pk_bf16(y[2], y[3]); *(u32x2*)(Y + (size_t)(t0 + r) * D + j * 256 + 4 * lane) = w; }
;             }
;             __syncthreads();
;         }
	v_add_f32_e32 v102, v102, v98
	v_add_f32_e32 v103, v103, v99
	v_add_f32_e32 v104, v104, v100
	v_add_f32_e32 v105, v105, v101
	v_fmamk_f32 v106, v102, 0x3a800000, v227
	v_fmamk_f32 v107, v103, 0x3a800000, v227
	v_fmamk_f32 v108, v104, 0x3a800000, v227
	v_fmamk_f32 v109, v105, 0x3a800000, v227
	v_rsq_f32_e32 v106, v106
	v_rsq_f32_e32 v107, v107
	v_rsq_f32_e32 v108, v108
	v_rsq_f32_e32 v109, v109
	s_nop 0
	v_mul_f32_e32 v140, v140, v106
	v_mul_f32_e32 v141, v141, v106
	v_mul_f32_e32 v142, v142, v106
	v_mul_f32_e32 v143, v143, v106
	v_mul_f32_e32 v156, v156, v107
	v_mul_f32_e32 v157, v157, v107
	v_mul_f32_e32 v158, v158, v107
	v_mul_f32_e32 v159, v159, v107
	v_mul_f32_e32 v172, v172, v108
	v_mul_f32_e32 v173, v173, v108
	v_mul_f32_e32 v174, v174, v108
	v_mul_f32_e32 v175, v175, v108
	v_mul_f32_e32 v188, v188, v109
	v_mul_f32_e32 v189, v189, v109
	v_mul_f32_e32 v190, v190, v109
	v_mul_f32_e32 v191, v191, v109
	v_mul_f32_e32 v140, v140, v4
	v_mul_f32_e32 v141, v141, v5
	v_mul_f32_e32 v142, v142, v6
	v_mul_f32_e32 v143, v143, v7
	v_mul_f32_e32 v156, v156, v4
	v_mul_f32_e32 v157, v157, v5
	v_mul_f32_e32 v158, v158, v6
	v_mul_f32_e32 v159, v159, v7
	v_mul_f32_e32 v172, v172, v4
	v_mul_f32_e32 v173, v173, v5
	v_mul_f32_e32 v174, v174, v6
	v_mul_f32_e32 v175, v175, v7
	v_mul_f32_e32 v188, v188, v4
	v_mul_f32_e32 v189, v189, v5
	v_mul_f32_e32 v190, v190, v6
	v_mul_f32_e32 v191, v191, v7
	v_cvt_pk_bf16_f32 v134, v140, v141
	v_cvt_pk_bf16_f32 v135, v142, v143
	v_cvt_pk_bf16_f32 v136, v156, v157
	v_cvt_pk_bf16_f32 v137, v158, v159
	v_cvt_pk_bf16_f32 v242, v172, v173
	v_cvt_pk_bf16_f32 v243, v174, v175
	v_cvt_pk_bf16_f32 v244, v188, v189
	v_cvt_pk_bf16_f32 v245, v190, v191
	global_store_dwordx2 v[126:127], v[134:135], off
	global_store_dwordx2 v[128:129], v[136:137], off
	global_store_dwordx2 v[130:131], v[242:243], off
	global_store_dwordx2 v[132:133], v[244:245], off
	s_nop 1
	v_mul_f32_e32 v144, v144, v106
	v_mul_f32_e32 v145, v145, v106
	v_mul_f32_e32 v146, v146, v106
	v_mul_f32_e32 v147, v147, v106
	v_mul_f32_e32 v160, v160, v107
	v_mul_f32_e32 v161, v161, v107
	v_mul_f32_e32 v162, v162, v107
	v_mul_f32_e32 v163, v163, v107
	v_mul_f32_e32 v176, v176, v108
	v_mul_f32_e32 v177, v177, v108
	v_mul_f32_e32 v178, v178, v108
	v_mul_f32_e32 v179, v179, v108
	v_mul_f32_e32 v192, v192, v109
	v_mul_f32_e32 v193, v193, v109
	v_mul_f32_e32 v194, v194, v109
	v_mul_f32_e32 v195, v195, v109
	v_mul_f32_e32 v144, v144, v8
	v_mul_f32_e32 v145, v145, v9
	v_mul_f32_e32 v146, v146, v10
	v_mul_f32_e32 v147, v147, v11
	v_mul_f32_e32 v160, v160, v8
	v_mul_f32_e32 v161, v161, v9
	v_mul_f32_e32 v162, v162, v10
	v_mul_f32_e32 v163, v163, v11
	v_mul_f32_e32 v176, v176, v8
	v_mul_f32_e32 v177, v177, v9
	v_mul_f32_e32 v178, v178, v10
	v_mul_f32_e32 v179, v179, v11
	v_mul_f32_e32 v192, v192, v8
	v_mul_f32_e32 v193, v193, v9
	v_mul_f32_e32 v194, v194, v10
	v_mul_f32_e32 v195, v195, v11
	v_cvt_pk_bf16_f32 v134, v144, v145
	v_cvt_pk_bf16_f32 v135, v146, v147
	v_cvt_pk_bf16_f32 v136, v160, v161
	v_cvt_pk_bf16_f32 v137, v162, v163
	v_cvt_pk_bf16_f32 v242, v176, v177
	v_cvt_pk_bf16_f32 v243, v178, v179
	v_cvt_pk_bf16_f32 v244, v192, v193
	v_cvt_pk_bf16_f32 v245, v194, v195
	global_store_dwordx2 v[126:127], v[134:135], off offset:512
	global_store_dwordx2 v[128:129], v[136:137], off offset:512
	global_store_dwordx2 v[130:131], v[242:243], off offset:512
	global_store_dwordx2 v[132:133], v[244:245], off offset:512
	s_nop 1
	v_mul_f32_e32 v148, v148, v106
	v_mul_f32_e32 v149, v149, v106
	v_mul_f32_e32 v150, v150, v106
	v_mul_f32_e32 v151, v151, v106
	v_mul_f32_e32 v164, v164, v107
	v_mul_f32_e32 v165, v165, v107
	v_mul_f32_e32 v166, v166, v107
	v_mul_f32_e32 v167, v167, v107
	v_mul_f32_e32 v180, v180, v108
	v_mul_f32_e32 v181, v181, v108
	v_mul_f32_e32 v182, v182, v108
	v_mul_f32_e32 v183, v183, v108
	v_mul_f32_e32 v196, v196, v109
	v_mul_f32_e32 v197, v197, v109
	v_mul_f32_e32 v198, v198, v109
	v_mul_f32_e32 v199, v199, v109
	v_mul_f32_e32 v148, v148, v12
	v_mul_f32_e32 v149, v149, v13
	v_mul_f32_e32 v150, v150, v14
	v_mul_f32_e32 v151, v151, v15
	v_mul_f32_e32 v164, v164, v12
	v_mul_f32_e32 v165, v165, v13
	v_mul_f32_e32 v166, v166, v14
	v_mul_f32_e32 v167, v167, v15
	v_mul_f32_e32 v180, v180, v12
	v_mul_f32_e32 v181, v181, v13
	v_mul_f32_e32 v182, v182, v14
	v_mul_f32_e32 v183, v183, v15
	v_mul_f32_e32 v196, v196, v12
	v_mul_f32_e32 v197, v197, v13
	v_mul_f32_e32 v198, v198, v14
	v_mul_f32_e32 v199, v199, v15
	v_cvt_pk_bf16_f32 v134, v148, v149
	v_cvt_pk_bf16_f32 v135, v150, v151
	v_cvt_pk_bf16_f32 v136, v164, v165
	v_cvt_pk_bf16_f32 v137, v166, v167
	v_cvt_pk_bf16_f32 v242, v180, v181
	v_cvt_pk_bf16_f32 v243, v182, v183
	v_cvt_pk_bf16_f32 v244, v196, v197
	v_cvt_pk_bf16_f32 v245, v198, v199
	global_store_dwordx2 v[126:127], v[134:135], off offset:1024
	global_store_dwordx2 v[128:129], v[136:137], off offset:1024
	global_store_dwordx2 v[130:131], v[242:243], off offset:1024
	global_store_dwordx2 v[132:133], v[244:245], off offset:1024
	s_nop 1
	v_mul_f32_e32 v152, v152, v106
	v_mul_f32_e32 v153, v153, v106
	v_mul_f32_e32 v154, v154, v106
	v_mul_f32_e32 v155, v155, v106
	v_mul_f32_e32 v168, v168, v107
	v_mul_f32_e32 v169, v169, v107
	v_mul_f32_e32 v170, v170, v107
	v_mul_f32_e32 v171, v171, v107
	v_mul_f32_e32 v184, v184, v108
	v_mul_f32_e32 v185, v185, v108
	v_mul_f32_e32 v186, v186, v108
	v_mul_f32_e32 v187, v187, v108
	v_mul_f32_e32 v200, v200, v109
	v_mul_f32_e32 v201, v201, v109
	v_mul_f32_e32 v202, v202, v109
	v_mul_f32_e32 v203, v203, v109
	v_mul_f32_e32 v152, v152, v16
	v_mul_f32_e32 v153, v153, v17
	v_mul_f32_e32 v154, v154, v18
	v_mul_f32_e32 v155, v155, v19
	v_mul_f32_e32 v168, v168, v16
	v_mul_f32_e32 v169, v169, v17
	v_mul_f32_e32 v170, v170, v18
	v_mul_f32_e32 v171, v171, v19
	v_mul_f32_e32 v184, v184, v16
	v_mul_f32_e32 v185, v185, v17
	v_mul_f32_e32 v186, v186, v18
	v_mul_f32_e32 v187, v187, v19
	v_mul_f32_e32 v200, v200, v16
	v_mul_f32_e32 v201, v201, v17
	v_mul_f32_e32 v202, v202, v18
	v_mul_f32_e32 v203, v203, v19
	v_cvt_pk_bf16_f32 v134, v152, v153
	v_cvt_pk_bf16_f32 v135, v154, v155
	v_cvt_pk_bf16_f32 v136, v168, v169
	v_cvt_pk_bf16_f32 v137, v170, v171
	v_cvt_pk_bf16_f32 v242, v184, v185
	v_cvt_pk_bf16_f32 v243, v186, v187
	v_cvt_pk_bf16_f32 v244, v200, v201
	v_cvt_pk_bf16_f32 v245, v202, v203
	global_store_dwordx2 v[126:127], v[134:135], off offset:1536
	global_store_dwordx2 v[128:129], v[136:137], off offset:1536
	global_store_dwordx2 v[130:131], v[242:243], off offset:1536
	global_store_dwordx2 v[132:133], v[244:245], off offset:1536
	s_add_i32 s61, s61, s34
	s_cmpk_gt_i32 s61, 0xff
	s_barrier
	s_cbranch_scc1 .LBB0_657

; #define PG8_STAGE(bufoff, gbase, voff) do { _Pragma("unroll") for (int _i = 0; _i < 2; ++_i) \
;         __builtin_amdgcn_global_load_lds((const unsigned*)((const char*)(gbase) + (voff)[_i]), (LAS unsigned*)(lds + (bufoff) + ldsw + _i * 8192), 16, 0, 0); } while (0)
; #define PG8_LDA(dst, b, h) do { _Pragma("unroll") for (int m = 0; m < 4; ++m) _Pragma("unroll") for (int k = 0; k < 2; ++k) dst[m][k] = *(const LAS bf16x8*)(lds + PG8_SA(b, h) + aoff + m * 2048 + k * 1024); } while (0)
; #define PG8_LDB(dst, b, h) do { _Pragma("unroll") for (int n = 0; n < 2; ++n) _Pragma("unroll") for (int k = 0; k < 2; ++k) dst[n][k] = *(const LAS bf16x8*)(lds + PG8_SB(b, h) + boff + n * 2048 + k * 1024); } while (0)
; #define PG8_MMA(ai, bj, At, Bt) do { __builtin_amdgcn_s_setprio(1); _Pragma("unroll") for (int m = 0; m < 4; ++m) _Pragma("unroll") for (int n = 0; n < 2; ++n) _Pragma("unroll") for (int k = 0; k < 2; ++k) \
;         acc[ai][bj][m][n] = __builtin_amdgcn_mfma_f32_16x16x32_bf16(Bt[n][k], At[m][k], acc[ai][bj][m][n], 0, 0, 0); __builtin_amdgcn_s_setprio(0); } while (0)
; #define PG8_WAIT_V(n) asm volatile("s_waitcnt vmcnt(" #n ")" ::: "memory")
; #define PG8_WAIT_L(n) asm volatile("s_waitcnt lgkmcnt(" #n ")" ::: "memory")
; #define PG8_BAR __builtin_amdgcn_s_barrier()
; #define PG8_SCHED __builtin_amdgcn_sched_barrier(0)
; template <class Epi, class Sched, bool ALIGN_EPI>
; __device__ __forceinline__ void gemm_phase(LAS unsigned char* lds, const Gemm g, const Sched& S, const Epi& E) {
;     ...
;             const bool last = (t == nt - 2);
;             const char* a1 = cA + (size_t)(t + 1) * kstep;
;             const char* a2 = last ? nA : cA + (size_t)(t + 2) * kstep; const char* b2 = last ? nB : cB + (size_t)(t + 2) * kstep;
;             const char* a3 = a2 + kstep; const char* b3 = b2 + kstep;
;             PG8_LDB(B0, 0, 0); PG8_LDB(B1, 0, 1); PG8_SCHED; PG8_LDA(At, 0, 0); PG8_STAGE(PG8_SA(1, 1), a1 + hA, voffA);
;             PG8_WAIT_V(8); PG8_WAIT_L(0); PG8_BAR; PG8_MMA(0, 0, At, B0); PG8_MMA(0, 1, At, B1); PG8_BAR; PG8_SCHED;
;             PG8_LDA(At, 0, 1); PG8_STAGE(PG8_SB(0, 0), b2, voffB); PG8_STAGE(PG8_SB(0, 1), b2 + hB, voffB); PG8_STAGE(PG8_SA(0, 0), a2, voffA);
;             PG8_WAIT_V(8); PG8_WAIT_L(0); PG8_BAR; PG8_MMA(1, 0, At, B0); PG8_MMA(1, 1, At, B1); PG8_BAR; PG8_SCHED;
.LBB0_845:
	ds_read_b128 v[144:147], v151
	ds_read_b128 v[156:159], v151 offset:1024
	ds_read_b128 v[160:163], v151 offset:2048
	ds_read_b128 v[164:167], v151 offset:3072
	ds_read_b128 v[168:171], v152
	ds_read_b128 v[172:175], v152 offset:1024
	ds_read_b128 v[176:179], v152 offset:2048
	ds_read_b128 v[180:183], v152 offset:3072
	s_add_u32 s18, s58, 0xfff80080
	s_addc_u32 s19, s59, -1
	s_cmp_eq_u32 s46, 28
	s_cselect_b32 s63, s81, s19
	s_cselect_b32 s62, s82, s18
	s_cselect_b32 s61, s41, s45
	s_cselect_b32 s60, s83, s44
	v_lshl_add_u64 v[216:217], s[58:59], 0, v[136:137]
	s_add_i32 m0, s66, 0xc000
	ds_read_b128 v[184:187], v153
	ds_read_b128 v[188:191], v153 offset:1024
	ds_read_b128 v[192:195], v153 offset:2048
	ds_read_b128 v[196:199], v153 offset:3072
	ds_read_b128 v[200:203], v153 offset:4096
	ds_read_b128 v[204:207], v153 offset:5120
	ds_read_b128 v[208:211], v153 offset:6144
	ds_read_b128 v[212:215], v153 offset:7168
	global_load_lds_dwordx4 v[216:217], off
	v_lshl_add_u64 v[216:217], s[58:59], 0, v[138:139]
	s_add_i32 m0, s66, 0xe000
	s_nop 0
	global_load_lds_dwordx4 v[216:217], off
	s_waitcnt vmcnt(8)
	s_waitcnt lgkmcnt(0)
	s_barrier
	s_waitcnt lgkmcnt(0)
	v_mfma_f32_16x16x32_bf16 v[124:127], v[144:147], v[184:187], v[124:127]
	v_mfma_f32_16x16x32_bf16 v[120:123], v[160:163], v[184:187], v[120:123]
	v_mfma_f32_16x16x32_bf16 v[108:111], v[144:147], v[192:195], v[108:111]
	v_mfma_f32_16x16x32_bf16 v[104:107], v[160:163], v[192:195], v[104:107]
	v_mfma_f32_16x16x32_bf16 v[92:95], v[144:147], v[200:203], v[92:95]
	v_mfma_f32_16x16x32_bf16 v[88:91], v[160:163], v[200:203], v[88:91]
	v_mfma_f32_16x16x32_bf16 v[76:79], v[144:147], v[208:211], v[76:79]
	v_mfma_f32_16x16x32_bf16 v[72:75], v[160:163], v[208:211], v[72:75]
	v_mfma_f32_16x16x32_bf16 v[124:127], v[156:159], v[188:191], v[124:127]
	v_mfma_f32_16x16x32_bf16 v[120:123], v[164:167], v[188:191], v[120:123]
	v_mfma_f32_16x16x32_bf16 v[108:111], v[156:159], v[196:199], v[108:111]
	v_mfma_f32_16x16x32_bf16 v[104:107], v[164:167], v[196:199], v[104:107]
	v_mfma_f32_16x16x32_bf16 v[92:95], v[156:159], v[204:207], v[92:95]
	v_mfma_f32_16x16x32_bf16 v[88:91], v[164:167], v[204:207], v[88:91]
	v_mfma_f32_16x16x32_bf16 v[76:79], v[156:159], v[212:215], v[76:79]
	v_mfma_f32_16x16x32_bf16 v[72:75], v[164:167], v[212:215], v[72:75]
	v_mfma_f32_16x16x32_bf16 v[116:119], v[168:171], v[184:187], v[116:119]
	v_mfma_f32_16x16x32_bf16 v[112:115], v[176:179], v[184:187], v[112:115]
	v_mfma_f32_16x16x32_bf16 v[100:103], v[168:171], v[192:195], v[100:103]
	v_mfma_f32_16x16x32_bf16 v[96:99], v[176:179], v[192:195], v[96:99]
	v_mfma_f32_16x16x32_bf16 v[84:87], v[168:171], v[200:203], v[84:87]
	v_mfma_f32_16x16x32_bf16 v[80:83], v[176:179], v[200:203], v[80:83]
	v_mfma_f32_16x16x32_bf16 v[68:71], v[168:171], v[208:211], v[68:71]
	v_mfma_f32_16x16x32_bf16 v[64:67], v[176:179], v[208:211], v[64:67]
	v_mfma_f32_16x16x32_bf16 v[116:119], v[172:175], v[188:191], v[116:119]
	v_mfma_f32_16x16x32_bf16 v[112:115], v[180:183], v[188:191], v[112:115]
	v_mfma_f32_16x16x32_bf16 v[100:103], v[172:175], v[196:199], v[100:103]
	v_mfma_f32_16x16x32_bf16 v[96:99], v[180:183], v[196:199], v[96:99]
	v_mfma_f32_16x16x32_bf16 v[84:87], v[172:175], v[204:207], v[84:87]
	v_mfma_f32_16x16x32_bf16 v[80:83], v[180:183], v[204:207], v[80:83]
	v_mfma_f32_16x16x32_bf16 v[68:71], v[172:175], v[212:215], v[68:71]
	v_mfma_f32_16x16x32_bf16 v[64:67], v[180:183], v[212:215], v[64:67]
	s_barrier
	s_add_i32 s18, s76, s65
	v_lshl_add_u64 v[216:217], s[60:61], 0, v[130:131]
	s_mov_b32 m0, s18
	ds_read_b128 v[184:187], v153 offset:16384
	ds_read_b128 v[188:191], v153 offset:17408
	ds_read_b128 v[192:195], v153 offset:18432
	ds_read_b128 v[196:199], v153 offset:19456
	ds_read_b128 v[200:203], v153 offset:20480
	ds_read_b128 v[204:207], v153 offset:21504
	ds_read_b128 v[208:211], v153 offset:22528
	ds_read_b128 v[212:215], v153 offset:23552
	global_load_lds_dwordx4 v[216:217], off
	s_add_i32 m0, s18, 0x2000
	s_add_u32 s18, s60, 0x80000
	v_lshl_add_u64 v[218:219], s[60:61], 0, v[134:135]
	s_addc_u32 s19, s61, 0
	s_add_i32 s33, s77, s65
	global_load_lds_dwordx4 v[218:219], off
	v_lshl_add_u64 v[222:223], s[18:19], 0, v[130:131]
	s_mov_b32 m0, s33
	v_lshl_add_u64 v[224:225], s[62:63], 0, v[132:133]
	global_load_lds_dwordx4 v[222:223], off
	v_lshl_add_u64 v[222:223], s[18:19], 0, v[134:135]
	s_add_i32 m0, s33, 0x2000
	s_nop 0
	global_load_lds_dwordx4 v[222:223], off
	v_lshl_add_u64 v[222:223], s[62:63], 0, v[128:129]
	s_mov_b32 m0, s66
	s_nop 0
	global_load_lds_dwordx4 v[222:223], off
	s_mov_b32 m0, s67
	s_nop 0
	global_load_lds_dwordx4 v[224:225], off
	s_waitcnt vmcnt(8)
	s_waitcnt lgkmcnt(0)
	s_barrier
; #define PG8_STAGE(bufoff, gbase, voff) do { _Pragma("unroll") for (int _i = 0; _i < 2; ++_i) \
;         __builtin_amdgcn_global_load_lds((const unsigned*)((const char*)(gbase) + (voff)[_i]), (LAS unsigned*)(lds + (bufoff) + ldsw + _i * 8192), 16, 0, 0); } while (0)
; #define PG8_LDA(dst, b, h) do { _Pragma("unroll") for (int m = 0; m < 4; ++m) _Pragma("unroll") for (int k = 0; k < 2; ++k) dst[m][k] = *(const LAS bf16x8*)(lds + PG8_SA(b, h) + aoff + m * 2048 + k * 1024); } while (0)
; #define PG8_LDB(dst, b, h) do { _Pragma("unroll") for (int n = 0; n < 2; ++n) _Pragma("unroll") for (int k = 0; k < 2; ++k) dst[n][k] = *(const LAS bf16x8*)(lds + PG8_SB(b, h) + boff + n * 2048 + k * 1024); } while (0)
; #define PG8_MMA(ai, bj, At, Bt) do { __builtin_amdgcn_s_setprio(1); _Pragma("unroll") for (int m = 0; m < 4; ++m) _Pragma("unroll") for (int n = 0; n < 2; ++n) _Pragma("unroll") for (int k = 0; k < 2; ++k) \
;         acc[ai][bj][m][n] = __builtin_amdgcn_mfma_f32_16x16x32_bf16(Bt[n][k], At[m][k], acc[ai][bj][m][n], 0, 0, 0); __builtin_amdgcn_s_setprio(0); } while (0)
; #define PG8_WAIT_V(n) asm volatile("s_waitcnt vmcnt(" #n ")" ::: "memory")
; #define PG8_WAIT_L(n) asm volatile("s_waitcnt lgkmcnt(" #n ")" ::: "memory")
; #define PG8_BAR __builtin_amdgcn_s_barrier()
; #define PG8_SCHED __builtin_amdgcn_sched_barrier(0)
; template <class Epi, class Sched, bool ALIGN_EPI>
; __device__ __forceinline__ void gemm_phase(LAS unsigned char* lds, const Gemm g, const Sched& S, const Epi& E) {
;     ...
;             PG8_WAIT_V(8); PG8_WAIT_L(0); PG8_BAR; PG8_MMA(1, 0, At, B0); PG8_MMA(1, 1, At, B1); PG8_BAR; PG8_SCHED;
;             PG8_LDB(B0, 1, 0); PG8_LDB(B1, 1, 1); PG8_SCHED; PG8_LDA(At, 1, 0); PG8_STAGE(PG8_SA(0, 1), a2 + hA, voffA);
;             PG8_WAIT_V(8); PG8_WAIT_L(0); PG8_BAR; PG8_MMA(0, 0, At, B0); PG8_MMA(0, 1, At, B1); PG8_BAR; PG8_SCHED;
	s_waitcnt lgkmcnt(0)
	v_mfma_f32_16x16x32_bf16 v[60:63], v[144:147], v[184:187], v[60:63]
	v_mfma_f32_16x16x32_bf16 v[56:59], v[160:163], v[184:187], v[56:59]
	v_mfma_f32_16x16x32_bf16 v[44:47], v[144:147], v[192:195], v[44:47]
	v_mfma_f32_16x16x32_bf16 v[40:43], v[160:163], v[192:195], v[40:43]
	v_mfma_f32_16x16x32_bf16 v[28:31], v[144:147], v[200:203], v[28:31]
	v_mfma_f32_16x16x32_bf16 v[24:27], v[160:163], v[200:203], v[24:27]
	v_mfma_f32_16x16x32_bf16 v[12:15], v[144:147], v[208:211], v[12:15]
	v_mfma_f32_16x16x32_bf16 v[8:11], v[160:163], v[208:211], v[8:11]
	v_mfma_f32_16x16x32_bf16 v[60:63], v[156:159], v[188:191], v[60:63]
	v_mfma_f32_16x16x32_bf16 v[56:59], v[164:167], v[188:191], v[56:59]
	v_mfma_f32_16x16x32_bf16 v[44:47], v[156:159], v[196:199], v[44:47]
	v_mfma_f32_16x16x32_bf16 v[40:43], v[164:167], v[196:199], v[40:43]
	v_mfma_f32_16x16x32_bf16 v[28:31], v[156:159], v[204:207], v[28:31]
	v_mfma_f32_16x16x32_bf16 v[24:27], v[164:167], v[204:207], v[24:27]
	v_mfma_f32_16x16x32_bf16 v[12:15], v[156:159], v[212:215], v[12:15]
	v_mfma_f32_16x16x32_bf16 v[8:11], v[164:167], v[212:215], v[8:11]
	v_mfma_f32_16x16x32_bf16 v[52:55], v[168:171], v[184:187], v[52:55]
	v_mfma_f32_16x16x32_bf16 v[48:51], v[176:179], v[184:187], v[48:51]
	v_mfma_f32_16x16x32_bf16 v[36:39], v[168:171], v[192:195], v[36:39]
	v_mfma_f32_16x16x32_bf16 v[32:35], v[176:179], v[192:195], v[32:35]
	v_mfma_f32_16x16x32_bf16 v[20:23], v[168:171], v[200:203], v[20:23]
	v_mfma_f32_16x16x32_bf16 v[16:19], v[176:179], v[200:203], v[16:19]
	v_mfma_f32_16x16x32_bf16 v[4:7], v[168:171], v[208:211], v[4:7]
	v_mfma_f32_16x16x32_bf16 v[0:3], v[176:179], v[208:211], v[0:3]
	v_mfma_f32_16x16x32_bf16 v[52:55], v[172:175], v[188:191], v[52:55]
	v_mfma_f32_16x16x32_bf16 v[48:51], v[180:183], v[188:191], v[48:51]
	v_mfma_f32_16x16x32_bf16 v[36:39], v[172:175], v[196:199], v[36:39]
	v_mfma_f32_16x16x32_bf16 v[32:35], v[180:183], v[196:199], v[32:35]
	v_mfma_f32_16x16x32_bf16 v[20:23], v[172:175], v[204:207], v[20:23]
	v_mfma_f32_16x16x32_bf16 v[16:19], v[180:183], v[204:207], v[16:19]
	v_mfma_f32_16x16x32_bf16 v[4:7], v[172:175], v[212:215], v[4:7]
	v_mfma_f32_16x16x32_bf16 v[0:3], v[180:183], v[212:215], v[0:3]
	s_barrier
	s_add_i32 s33, 0, 0x18000
	v_add_u32_e32 v155, s33, v149
	s_add_i32 s47, 0, 0x1c000
	ds_read_b128 v[144:147], v155
	ds_read_b128 v[156:159], v155 offset:1024
	ds_read_b128 v[160:163], v155 offset:2048
	ds_read_b128 v[164:167], v155 offset:3072
	v_add_u32_e32 v155, s47, v149
	ds_read_b128 v[168:171], v155
	ds_read_b128 v[172:175], v155 offset:1024
	ds_read_b128 v[176:179], v155 offset:2048
	ds_read_b128 v[180:183], v155 offset:3072
	s_add_u32 s18, s62, 0x80000
	s_addc_u32 s19, s63, 0
	s_mov_b32 m0, s68
	v_lshl_add_u64 v[226:227], s[18:19], 0, v[128:129]
	ds_read_b128 v[184:187], v153 offset:32768
	ds_read_b128 v[188:191], v153 offset:33792
	ds_read_b128 v[192:195], v153 offset:34816
	ds_read_b128 v[196:199], v153 offset:35840
	ds_read_b128 v[200:203], v153 offset:36864
	ds_read_b128 v[204:207], v153 offset:37888
	ds_read_b128 v[208:211], v153 offset:38912
	ds_read_b128 v[212:215], v153 offset:39936
	global_load_lds_dwordx4 v[226:227], off
	v_lshl_add_u64 v[226:227], s[18:19], 0, v[132:133]
	s_mov_b32 m0, s69
	s_nop 0
	global_load_lds_dwordx4 v[226:227], off
	s_waitcnt vmcnt(8)
	s_waitcnt lgkmcnt(0)
	s_barrier
	s_waitcnt lgkmcnt(0)
	v_mfma_f32_16x16x32_bf16 v[124:127], v[144:147], v[184:187], v[124:127]
	v_mfma_f32_16x16x32_bf16 v[120:123], v[160:163], v[184:187], v[120:123]
	v_mfma_f32_16x16x32_bf16 v[108:111], v[144:147], v[192:195], v[108:111]
	v_mfma_f32_16x16x32_bf16 v[104:107], v[160:163], v[192:195], v[104:107]
	v_mfma_f32_16x16x32_bf16 v[92:95], v[144:147], v[200:203], v[92:95]
	v_mfma_f32_16x16x32_bf16 v[88:91], v[160:163], v[200:203], v[88:91]
	v_mfma_f32_16x16x32_bf16 v[76:79], v[144:147], v[208:211], v[76:79]
	v_mfma_f32_16x16x32_bf16 v[72:75], v[160:163], v[208:211], v[72:75]
	v_mfma_f32_16x16x32_bf16 v[124:127], v[156:159], v[188:191], v[124:127]
	v_mfma_f32_16x16x32_bf16 v[120:123], v[164:167], v[188:191], v[120:123]
	v_mfma_f32_16x16x32_bf16 v[108:111], v[156:159], v[196:199], v[108:111]
	v_mfma_f32_16x16x32_bf16 v[104:107], v[164:167], v[196:199], v[104:107]
	v_mfma_f32_16x16x32_bf16 v[92:95], v[156:159], v[204:207], v[92:95]
	v_mfma_f32_16x16x32_bf16 v[88:91], v[164:167], v[204:207], v[88:91]
	v_mfma_f32_16x16x32_bf16 v[76:79], v[156:159], v[212:215], v[76:79]
	v_mfma_f32_16x16x32_bf16 v[72:75], v[164:167], v[212:215], v[72:75]
	v_mfma_f32_16x16x32_bf16 v[116:119], v[168:171], v[184:187], v[116:119]
	v_mfma_f32_16x16x32_bf16 v[112:115], v[176:179], v[184:187], v[112:115]
	v_mfma_f32_16x16x32_bf16 v[100:103], v[168:171], v[192:195], v[100:103]
	v_mfma_f32_16x16x32_bf16 v[96:99], v[176:179], v[192:195], v[96:99]
	v_mfma_f32_16x16x32_bf16 v[84:87], v[168:171], v[200:203], v[84:87]
	v_mfma_f32_16x16x32_bf16 v[80:83], v[176:179], v[200:203], v[80:83]
	v_mfma_f32_16x16x32_bf16 v[68:71], v[168:171], v[208:211], v[68:71]
	v_mfma_f32_16x16x32_bf16 v[64:67], v[176:179], v[208:211], v[64:67]
	v_mfma_f32_16x16x32_bf16 v[116:119], v[172:175], v[188:191], v[116:119]
	v_mfma_f32_16x16x32_bf16 v[112:115], v[180:183], v[188:191], v[112:115]
	v_mfma_f32_16x16x32_bf16 v[100:103], v[172:175], v[196:199], v[100:103]
	v_mfma_f32_16x16x32_bf16 v[96:99], v[180:183], v[196:199], v[96:99]
	v_mfma_f32_16x16x32_bf16 v[84:87], v[172:175], v[204:207], v[84:87]
	v_mfma_f32_16x16x32_bf16 v[80:83], v[180:183], v[204:207], v[80:83]
	v_mfma_f32_16x16x32_bf16 v[68:71], v[172:175], v[212:215], v[68:71]
	v_mfma_f32_16x16x32_bf16 v[64:67], v[180:183], v[212:215], v[64:67]
	s_barrier
; #define PG8_STAGE(bufoff, gbase, voff) do { _Pragma("unroll") for (int _i = 0; _i < 2; ++_i) \
;         __builtin_amdgcn_global_load_lds((const unsigned*)((const char*)(gbase) + (voff)[_i]), (LAS unsigned*)(lds + (bufoff) + ldsw + _i * 8192), 16, 0, 0); } while (0)
; #define PG8_LDA(dst, b, h) do { _Pragma("unroll") for (int m = 0; m < 4; ++m) _Pragma("unroll") for (int k = 0; k < 2; ++k) dst[m][k] = *(const LAS bf16x8*)(lds + PG8_SA(b, h) + aoff + m * 2048 + k * 1024); } while (0)
; #define PG8_MMA(ai, bj, At, Bt) do { __builtin_amdgcn_s_setprio(1); _Pragma("unroll") for (int m = 0; m < 4; ++m) _Pragma("unroll") for (int n = 0; n < 2; ++n) _Pragma("unroll") for (int k = 0; k < 2; ++k) \
;         acc[ai][bj][m][n] = __builtin_amdgcn_mfma_f32_16x16x32_bf16(Bt[n][k], At[m][k], acc[ai][bj][m][n], 0, 0, 0); __builtin_amdgcn_s_setprio(0); } while (0)
; #define PG8_WAIT_V(n) asm volatile("s_waitcnt vmcnt(" #n ")" ::: "memory")
; #define PG8_WAIT_L(n) asm volatile("s_waitcnt lgkmcnt(" #n ")" ::: "memory")
; #define PG8_BAR __builtin_amdgcn_s_barrier()
; #define PG8_SCHED __builtin_amdgcn_sched_barrier(0)
; template <class Epi, class Sched, bool ALIGN_EPI>
; __device__ __forceinline__ void gemm_phase(LAS unsigned char* lds, const Gemm g, const Sched& S, const Epi& E) {
;     ...
;             PG8_LDA(At, 1, 1); PG8_STAGE(PG8_SB(1, 0), b3, voffB); PG8_STAGE(PG8_SB(1, 1), b3 + hB, voffB); PG8_STAGE(PG8_SA(1, 0), a3, voffA);
;             PG8_WAIT_V(8); PG8_WAIT_L(0); PG8_BAR; PG8_MMA(1, 0, At, B0); PG8_MMA(1, 1, At, B1); PG8_BAR; PG8_SCHED;
;         }
;         if constexpr (ALIGN_EPI) { if (wr == 0) PG8_BAR; }
	s_add_i32 s18, s33, s65
	v_lshl_add_u64 v[216:217], v[216:217], 0, s[26:27]
	s_mov_b32 m0, s18
	ds_read_b128 v[184:187], v153 offset:49152
	ds_read_b128 v[188:191], v153 offset:50176
	ds_read_b128 v[192:195], v153 offset:51200
	ds_read_b128 v[196:199], v153 offset:52224
	ds_read_b128 v[200:203], v153 offset:53248
	ds_read_b128 v[204:207], v153 offset:54272
	ds_read_b128 v[208:211], v153 offset:55296
	ds_read_b128 v[212:215], v153 offset:56320
	global_load_lds_dwordx4 v[216:217], off
	s_add_i32 m0, s18, 0x2000
	s_add_u32 s18, s60, 0x80080
	v_lshl_add_u64 v[216:217], v[218:219], 0, s[26:27]
	s_addc_u32 s19, s61, 0
	s_add_i32 s33, s47, s65
	global_load_lds_dwordx4 v[216:217], off
	v_lshl_add_u64 v[216:217], s[18:19], 0, v[130:131]
	s_mov_b32 m0, s33
	s_nop 0
	global_load_lds_dwordx4 v[216:217], off
	v_lshl_add_u64 v[216:217], s[18:19], 0, v[134:135]
	s_add_i32 m0, s33, 0x2000
	s_nop 0
	global_load_lds_dwordx4 v[216:217], off
	v_lshl_add_u64 v[216:217], v[222:223], 0, s[26:27]
	s_mov_b32 m0, s71
	s_nop 0
	global_load_lds_dwordx4 v[216:217], off
	v_lshl_add_u64 v[216:217], v[224:225], 0, s[26:27]
	s_mov_b32 m0, s72
	s_nop 0
	global_load_lds_dwordx4 v[216:217], off
	s_waitcnt vmcnt(8)
	s_waitcnt lgkmcnt(0)
	s_barrier
	s_waitcnt lgkmcnt(0)
	v_mfma_f32_16x16x32_bf16 v[60:63], v[144:147], v[184:187], v[60:63]
	v_mfma_f32_16x16x32_bf16 v[56:59], v[160:163], v[184:187], v[56:59]
	v_mfma_f32_16x16x32_bf16 v[44:47], v[144:147], v[192:195], v[44:47]
	v_mfma_f32_16x16x32_bf16 v[40:43], v[160:163], v[192:195], v[40:43]
	v_mfma_f32_16x16x32_bf16 v[28:31], v[144:147], v[200:203], v[28:31]
	v_mfma_f32_16x16x32_bf16 v[24:27], v[160:163], v[200:203], v[24:27]
	v_mfma_f32_16x16x32_bf16 v[12:15], v[144:147], v[208:211], v[12:15]
	v_mfma_f32_16x16x32_bf16 v[8:11], v[160:163], v[208:211], v[8:11]
	v_mfma_f32_16x16x32_bf16 v[60:63], v[156:159], v[188:191], v[60:63]
	v_mfma_f32_16x16x32_bf16 v[56:59], v[164:167], v[188:191], v[56:59]
	v_mfma_f32_16x16x32_bf16 v[44:47], v[156:159], v[196:199], v[44:47]
	v_mfma_f32_16x16x32_bf16 v[40:43], v[164:167], v[196:199], v[40:43]
	v_mfma_f32_16x16x32_bf16 v[28:31], v[156:159], v[204:207], v[28:31]
	v_mfma_f32_16x16x32_bf16 v[24:27], v[164:167], v[204:207], v[24:27]
	v_mfma_f32_16x16x32_bf16 v[12:15], v[156:159], v[212:215], v[12:15]
	v_mfma_f32_16x16x32_bf16 v[8:11], v[164:167], v[212:215], v[8:11]
	v_mfma_f32_16x16x32_bf16 v[52:55], v[168:171], v[184:187], v[52:55]
	v_mfma_f32_16x16x32_bf16 v[48:51], v[176:179], v[184:187], v[48:51]
	v_mfma_f32_16x16x32_bf16 v[36:39], v[168:171], v[192:195], v[36:39]
	v_mfma_f32_16x16x32_bf16 v[32:35], v[176:179], v[192:195], v[32:35]
	v_mfma_f32_16x16x32_bf16 v[20:23], v[168:171], v[200:203], v[20:23]
	v_mfma_f32_16x16x32_bf16 v[16:19], v[176:179], v[200:203], v[16:19]
	v_mfma_f32_16x16x32_bf16 v[4:7], v[168:171], v[208:211], v[4:7]
	v_mfma_f32_16x16x32_bf16 v[0:3], v[176:179], v[208:211], v[0:3]
	v_mfma_f32_16x16x32_bf16 v[52:55], v[172:175], v[188:191], v[52:55]
	v_mfma_f32_16x16x32_bf16 v[48:51], v[180:183], v[188:191], v[48:51]
	v_mfma_f32_16x16x32_bf16 v[36:39], v[172:175], v[196:199], v[36:39]
	v_mfma_f32_16x16x32_bf16 v[32:35], v[180:183], v[196:199], v[32:35]
	v_mfma_f32_16x16x32_bf16 v[20:23], v[172:175], v[204:207], v[20:23]
	v_mfma_f32_16x16x32_bf16 v[16:19], v[180:183], v[204:207], v[16:19]
	v_mfma_f32_16x16x32_bf16 v[4:7], v[172:175], v[212:215], v[4:7]
	v_mfma_f32_16x16x32_bf16 v[0:3], v[180:183], v[212:215], v[0:3]
	s_barrier
	s_add_i32 s46, s46, 2
	s_add_u32 s58, s58, 0x100
	s_addc_u32 s59, s59, 0
	s_add_u32 s44, s44, 0x100
	s_addc_u32 s45, s45, 0
	s_cmp_gt_u32 s46, 29
	s_cbranch_scc0 .LBB0_845
	s_and_b64 vcc, exec, s[38:39]
	s_cbranch_vccz .LBB0_848
	s_barrier

; #define PG8_STAGE(bufoff, gbase, voff) do { _Pragma("unroll") for (int _i = 0; _i < 2; ++_i) \
;         __builtin_amdgcn_global_load_lds((const unsigned*)((const char*)(gbase) + (voff)[_i]), (LAS unsigned*)(lds + (bufoff) + ldsw + _i * 8192), 16, 0, 0); } while (0)
; #define PG8_LDA(dst, b, h) do { _Pragma("unroll") for (int m = 0; m < 4; ++m) _Pragma("unroll") for (int k = 0; k < 2; ++k) dst[m][k] = *(const LAS bf16x8*)(lds + PG8_SA(b, h) + aoff + m * 2048 + k * 1024); } while (0)
; #define PG8_LDB(dst, b, h) do { _Pragma("unroll") for (int n = 0; n < 2; ++n) _Pragma("unroll") for (int k = 0; k < 2; ++k) dst[n][k] = *(const LAS bf16x8*)(lds + PG8_SB(b, h) + boff + n * 2048 + k * 1024); } while (0)
; #define PG8_MMA(ai, bj, At, Bt) do { __builtin_amdgcn_s_setprio(1); _Pragma("unroll") for (int m = 0; m < 4; ++m) _Pragma("unroll") for (int n = 0; n < 2; ++n) _Pragma("unroll") for (int k = 0; k < 2; ++k) \
;         acc[ai][bj][m][n] = __builtin_amdgcn_mfma_f32_16x16x32_bf16(Bt[n][k], At[m][k], acc[ai][bj][m][n], 0, 0, 0); __builtin_amdgcn_s_setprio(0); } while (0)
; #define PG8_WAIT_V(n) asm volatile("s_waitcnt vmcnt(" #n ")" ::: "memory")
; #define PG8_WAIT_L(n) asm volatile("s_waitcnt lgkmcnt(" #n ")" ::: "memory")
; #define PG8_BAR __builtin_amdgcn_s_barrier()
; #define PG8_SCHED __builtin_amdgcn_sched_barrier(0)
; template <class Epi, class Sched, bool ALIGN_EPI>
; __device__ __forceinline__ void gemm_phase(LAS unsigned char* lds, const Gemm g, const Sched& S, const Epi& E) {
;     ...
;             const bool last = (t == nt - 2);
;             const char* a1 = cA + (size_t)(t + 1) * kstep;
;             const char* a2 = last ? nA : cA + (size_t)(t + 2) * kstep; const char* b2 = last ? nB : cB + (size_t)(t + 2) * kstep;
;             const char* a3 = a2 + kstep; const char* b3 = b2 + kstep;
;             PG8_LDB(B0, 0, 0); PG8_LDB(B1, 0, 1); PG8_SCHED; PG8_LDA(At, 0, 0); PG8_STAGE(PG8_SA(1, 1), a1 + hA, voffA);
;             PG8_WAIT_V(8); PG8_WAIT_L(0); PG8_BAR; PG8_MMA(0, 0, At, B0); PG8_MMA(0, 1, At, B1); PG8_BAR; PG8_SCHED;
;             PG8_LDA(At, 0, 1); PG8_STAGE(PG8_SB(0, 0), b2, voffB); PG8_STAGE(PG8_SB(0, 1), b2 + hB, voffB); PG8_STAGE(PG8_SA(0, 0), a2, voffA);
;             PG8_WAIT_V(8); PG8_WAIT_L(0); PG8_BAR; PG8_MMA(1, 0, At, B0); PG8_MMA(1, 1, At, B1); PG8_BAR; PG8_SCHED;
.LBB0_926:
	ds_read_b128 v[156:159], v150
	ds_read_b128 v[166:169], v150 offset:1024
	ds_read_b128 v[170:173], v150 offset:2048
	ds_read_b128 v[174:177], v150 offset:3072
	ds_read_b128 v[178:181], v151
	ds_read_b128 v[182:185], v151 offset:1024
	ds_read_b128 v[186:189], v151 offset:2048
	ds_read_b128 v[190:193], v151 offset:3072
	s_add_i32 s94, s62, 2
	s_add_u32 s18, s60, 0xf3a80080
	s_addc_u32 s19, s61, -1
	s_cmp_lg_u32 s68, s62
	s_cselect_b32 s18, s18, 0
	s_cselect_b32 s19, s19, 0
	s_add_u32 s64, s58, s18
	s_addc_u32 s65, s59, s19
	s_add_u32 s62, s56, s18
	s_addc_u32 s63, s57, s19
	s_mov_b32 m0, s44
	v_lshl_add_u64 v[160:161], v[146:147], 0, s[60:61]
	ds_read_b128 v[194:197], v152
	ds_read_b128 v[198:201], v152 offset:1024
	ds_read_b128 v[202:205], v152 offset:2048
	ds_read_b128 v[206:209], v152 offset:3072
	ds_read_b128 v[210:213], v152 offset:4096
	ds_read_b128 v[214:217], v152 offset:5120
	ds_read_b128 v[222:225], v152 offset:6144
	ds_read_b128 v[226:229], v152 offset:7168
	global_load_lds_dwordx4 v[160:161], off
	v_lshl_add_u64 v[160:161], v[148:149], 0, s[60:61]
	s_mov_b32 m0, s45
	s_nop 0
	global_load_lds_dwordx4 v[160:161], off
	s_waitcnt vmcnt(8)
	s_waitcnt lgkmcnt(0)
	s_barrier
	s_waitcnt lgkmcnt(0)
	v_mfma_f32_16x16x32_bf16 v[124:127], v[156:159], v[194:197], v[124:127]
	v_mfma_f32_16x16x32_bf16 v[120:123], v[170:173], v[194:197], v[120:123]
	v_mfma_f32_16x16x32_bf16 v[108:111], v[156:159], v[202:205], v[108:111]
	v_mfma_f32_16x16x32_bf16 v[104:107], v[170:173], v[202:205], v[104:107]
	v_mfma_f32_16x16x32_bf16 v[92:95], v[156:159], v[210:213], v[92:95]
	v_mfma_f32_16x16x32_bf16 v[88:91], v[170:173], v[210:213], v[88:91]
	v_mfma_f32_16x16x32_bf16 v[76:79], v[156:159], v[222:225], v[76:79]
	v_mfma_f32_16x16x32_bf16 v[72:75], v[170:173], v[222:225], v[72:75]
	v_mfma_f32_16x16x32_bf16 v[124:127], v[166:169], v[198:201], v[124:127]
	v_mfma_f32_16x16x32_bf16 v[120:123], v[174:177], v[198:201], v[120:123]
	v_mfma_f32_16x16x32_bf16 v[108:111], v[166:169], v[206:209], v[108:111]
	v_mfma_f32_16x16x32_bf16 v[104:107], v[174:177], v[206:209], v[104:107]
	v_mfma_f32_16x16x32_bf16 v[92:95], v[166:169], v[214:217], v[92:95]
	v_mfma_f32_16x16x32_bf16 v[88:91], v[174:177], v[214:217], v[88:91]
	v_mfma_f32_16x16x32_bf16 v[76:79], v[166:169], v[226:229], v[76:79]
	v_mfma_f32_16x16x32_bf16 v[72:75], v[174:177], v[226:229], v[72:75]
	v_mfma_f32_16x16x32_bf16 v[116:119], v[178:181], v[194:197], v[116:119]
	v_mfma_f32_16x16x32_bf16 v[112:115], v[186:189], v[194:197], v[112:115]
	v_mfma_f32_16x16x32_bf16 v[100:103], v[178:181], v[202:205], v[100:103]
	v_mfma_f32_16x16x32_bf16 v[96:99], v[186:189], v[202:205], v[96:99]
	v_mfma_f32_16x16x32_bf16 v[84:87], v[178:181], v[210:213], v[84:87]
	v_mfma_f32_16x16x32_bf16 v[80:83], v[186:189], v[210:213], v[80:83]
	v_mfma_f32_16x16x32_bf16 v[68:71], v[178:181], v[222:225], v[68:71]
	v_mfma_f32_16x16x32_bf16 v[64:67], v[186:189], v[222:225], v[64:67]
	v_mfma_f32_16x16x32_bf16 v[116:119], v[182:185], v[198:201], v[116:119]
	v_mfma_f32_16x16x32_bf16 v[112:115], v[190:193], v[198:201], v[112:115]
	v_mfma_f32_16x16x32_bf16 v[100:103], v[182:185], v[206:209], v[100:103]
	v_mfma_f32_16x16x32_bf16 v[96:99], v[190:193], v[206:209], v[96:99]
	v_mfma_f32_16x16x32_bf16 v[84:87], v[182:185], v[214:217], v[84:87]
	v_mfma_f32_16x16x32_bf16 v[80:83], v[190:193], v[214:217], v[80:83]
	v_mfma_f32_16x16x32_bf16 v[68:71], v[182:185], v[226:229], v[68:71]
	v_mfma_f32_16x16x32_bf16 v[64:67], v[190:193], v[226:229], v[64:67]
	s_barrier
	s_mov_b32 m0, s46
	v_lshl_add_u64 v[160:161], s[62:63], 0, v[130:131]
	s_add_u32 s18, s62, 0x80000
	ds_read_b128 v[194:197], v152 offset:16384
	ds_read_b128 v[198:201], v152 offset:17408
	ds_read_b128 v[202:205], v152 offset:18432
	ds_read_b128 v[206:209], v152 offset:19456
	ds_read_b128 v[210:213], v152 offset:20480
	ds_read_b128 v[214:217], v152 offset:21504
	ds_read_b128 v[222:225], v152 offset:22528
	ds_read_b128 v[226:229], v152 offset:23552
	global_load_lds_dwordx4 v[160:161], off
	v_lshl_add_u64 v[218:219], s[62:63], 0, v[134:135]
	s_mov_b32 m0, s47
	s_addc_u32 s19, s63, 0
	global_load_lds_dwordx4 v[218:219], off
	v_lshl_add_u64 v[230:231], s[18:19], 0, v[130:131]
	s_mov_b32 m0, s92
	v_lshl_add_u64 v[232:233], s[64:65], 0, v[132:133]
	global_load_lds_dwordx4 v[230:231], off
	v_lshl_add_u64 v[230:231], s[18:19], 0, v[134:135]
	s_mov_b32 m0, s93
	s_nop 0
	global_load_lds_dwordx4 v[230:231], off
	v_lshl_add_u64 v[230:231], s[64:65], 0, v[128:129]
	s_mov_b32 m0, s22
	s_nop 0
	global_load_lds_dwordx4 v[230:231], off
	s_mov_b32 m0, s87
	s_nop 0
	global_load_lds_dwordx4 v[232:233], off
	s_waitcnt vmcnt(8)
	s_waitcnt lgkmcnt(0)
	s_barrier
; #define PG8_STAGE(bufoff, gbase, voff) do { _Pragma("unroll") for (int _i = 0; _i < 2; ++_i) \
;         __builtin_amdgcn_global_load_lds((const unsigned*)((const char*)(gbase) + (voff)[_i]), (LAS unsigned*)(lds + (bufoff) + ldsw + _i * 8192), 16, 0, 0); } while (0)
; #define PG8_LDA(dst, b, h) do { _Pragma("unroll") for (int m = 0; m < 4; ++m) _Pragma("unroll") for (int k = 0; k < 2; ++k) dst[m][k] = *(const LAS bf16x8*)(lds + PG8_SA(b, h) + aoff + m * 2048 + k * 1024); } while (0)
; #define PG8_LDB(dst, b, h) do { _Pragma("unroll") for (int n = 0; n < 2; ++n) _Pragma("unroll") for (int k = 0; k < 2; ++k) dst[n][k] = *(const LAS bf16x8*)(lds + PG8_SB(b, h) + boff + n * 2048 + k * 1024); } while (0)
; #define PG8_MMA(ai, bj, At, Bt) do { __builtin_amdgcn_s_setprio(1); _Pragma("unroll") for (int m = 0; m < 4; ++m) _Pragma("unroll") for (int n = 0; n < 2; ++n) _Pragma("unroll") for (int k = 0; k < 2; ++k) \
;         acc[ai][bj][m][n] = __builtin_amdgcn_mfma_f32_16x16x32_bf16(Bt[n][k], At[m][k], acc[ai][bj][m][n], 0, 0, 0); __builtin_amdgcn_s_setprio(0); } while (0)
; #define PG8_WAIT_V(n) asm volatile("s_waitcnt vmcnt(" #n ")" ::: "memory")
; #define PG8_WAIT_L(n) asm volatile("s_waitcnt lgkmcnt(" #n ")" ::: "memory")
; #define PG8_BAR __builtin_amdgcn_s_barrier()
; #define PG8_SCHED __builtin_amdgcn_sched_barrier(0)
; template <class Epi, class Sched, bool ALIGN_EPI>
; __device__ __forceinline__ void gemm_phase(LAS unsigned char* lds, const Gemm g, const Sched& S, const Epi& E) {
;     ...
;             PG8_WAIT_V(8); PG8_WAIT_L(0); PG8_BAR; PG8_MMA(1, 0, At, B0); PG8_MMA(1, 1, At, B1); PG8_BAR; PG8_SCHED;
;             PG8_LDB(B0, 1, 0); PG8_LDB(B1, 1, 1); PG8_SCHED; PG8_LDA(At, 1, 0); PG8_STAGE(PG8_SA(0, 1), a2 + hA, voffA);
;             PG8_WAIT_V(8); PG8_WAIT_L(0); PG8_BAR; PG8_MMA(0, 0, At, B0); PG8_MMA(0, 1, At, B1); PG8_BAR; PG8_SCHED;
	s_waitcnt lgkmcnt(0)
	v_mfma_f32_16x16x32_bf16 v[60:63], v[156:159], v[194:197], v[60:63]
	v_mfma_f32_16x16x32_bf16 v[56:59], v[170:173], v[194:197], v[56:59]
	v_mfma_f32_16x16x32_bf16 v[44:47], v[156:159], v[202:205], v[44:47]
	v_mfma_f32_16x16x32_bf16 v[40:43], v[170:173], v[202:205], v[40:43]
	v_mfma_f32_16x16x32_bf16 v[28:31], v[156:159], v[210:213], v[28:31]
	v_mfma_f32_16x16x32_bf16 v[24:27], v[170:173], v[210:213], v[24:27]
	v_mfma_f32_16x16x32_bf16 v[12:15], v[156:159], v[222:225], v[12:15]
	v_mfma_f32_16x16x32_bf16 v[8:11], v[170:173], v[222:225], v[8:11]
	v_mfma_f32_16x16x32_bf16 v[60:63], v[166:169], v[198:201], v[60:63]
	v_mfma_f32_16x16x32_bf16 v[56:59], v[174:177], v[198:201], v[56:59]
	v_mfma_f32_16x16x32_bf16 v[44:47], v[166:169], v[206:209], v[44:47]
	v_mfma_f32_16x16x32_bf16 v[40:43], v[174:177], v[206:209], v[40:43]
	v_mfma_f32_16x16x32_bf16 v[28:31], v[166:169], v[214:217], v[28:31]
	v_mfma_f32_16x16x32_bf16 v[24:27], v[174:177], v[214:217], v[24:27]
	v_mfma_f32_16x16x32_bf16 v[12:15], v[166:169], v[226:229], v[12:15]
	v_mfma_f32_16x16x32_bf16 v[8:11], v[174:177], v[226:229], v[8:11]
	v_mfma_f32_16x16x32_bf16 v[52:55], v[178:181], v[194:197], v[52:55]
	v_mfma_f32_16x16x32_bf16 v[48:51], v[186:189], v[194:197], v[48:51]
	v_mfma_f32_16x16x32_bf16 v[36:39], v[178:181], v[202:205], v[36:39]
	v_mfma_f32_16x16x32_bf16 v[32:35], v[186:189], v[202:205], v[32:35]
	v_mfma_f32_16x16x32_bf16 v[20:23], v[178:181], v[210:213], v[20:23]
	v_mfma_f32_16x16x32_bf16 v[16:19], v[186:189], v[210:213], v[16:19]
	v_mfma_f32_16x16x32_bf16 v[4:7], v[178:181], v[222:225], v[4:7]
	v_mfma_f32_16x16x32_bf16 v[0:3], v[186:189], v[222:225], v[0:3]
	v_mfma_f32_16x16x32_bf16 v[52:55], v[182:185], v[198:201], v[52:55]
	v_mfma_f32_16x16x32_bf16 v[48:51], v[190:193], v[198:201], v[48:51]
	v_mfma_f32_16x16x32_bf16 v[36:39], v[182:185], v[206:209], v[36:39]
	v_mfma_f32_16x16x32_bf16 v[32:35], v[190:193], v[206:209], v[32:35]
	v_mfma_f32_16x16x32_bf16 v[20:23], v[182:185], v[214:217], v[20:23]
	v_mfma_f32_16x16x32_bf16 v[16:19], v[190:193], v[214:217], v[16:19]
	v_mfma_f32_16x16x32_bf16 v[4:7], v[182:185], v[226:229], v[4:7]
	v_mfma_f32_16x16x32_bf16 v[0:3], v[190:193], v[226:229], v[0:3]
	s_barrier
	ds_read_b128 v[156:159], v153
	ds_read_b128 v[166:169], v153 offset:1024
	ds_read_b128 v[170:173], v153 offset:2048
	ds_read_b128 v[174:177], v153 offset:3072
	ds_read_b128 v[178:181], v154
	ds_read_b128 v[182:185], v154 offset:1024
	ds_read_b128 v[186:189], v154 offset:2048
	ds_read_b128 v[190:193], v154 offset:3072
	s_add_u32 s18, s64, 0x80000
	s_addc_u32 s19, s65, 0
	s_mov_b32 m0, s88
	v_lshl_add_u64 v[234:235], s[18:19], 0, v[128:129]
	ds_read_b128 v[194:197], v152 offset:32768
	ds_read_b128 v[198:201], v152 offset:33792
	ds_read_b128 v[202:205], v152 offset:34816
	ds_read_b128 v[206:209], v152 offset:35840
	ds_read_b128 v[210:213], v152 offset:36864
	ds_read_b128 v[214:217], v152 offset:37888
	ds_read_b128 v[222:225], v152 offset:38912
	ds_read_b128 v[226:229], v152 offset:39936
	global_load_lds_dwordx4 v[234:235], off
	v_lshl_add_u64 v[234:235], s[18:19], 0, v[132:133]
	s_mov_b32 m0, s89
	s_nop 0
	global_load_lds_dwordx4 v[234:235], off
	s_waitcnt vmcnt(8)
	s_waitcnt lgkmcnt(0)
	s_barrier
	s_waitcnt lgkmcnt(0)
	v_mfma_f32_16x16x32_bf16 v[124:127], v[156:159], v[194:197], v[124:127]
	v_mfma_f32_16x16x32_bf16 v[120:123], v[170:173], v[194:197], v[120:123]
	v_mfma_f32_16x16x32_bf16 v[108:111], v[156:159], v[202:205], v[108:111]
	v_mfma_f32_16x16x32_bf16 v[104:107], v[170:173], v[202:205], v[104:107]
	v_mfma_f32_16x16x32_bf16 v[92:95], v[156:159], v[210:213], v[92:95]
	v_mfma_f32_16x16x32_bf16 v[88:91], v[170:173], v[210:213], v[88:91]
	v_mfma_f32_16x16x32_bf16 v[76:79], v[156:159], v[222:225], v[76:79]
	v_mfma_f32_16x16x32_bf16 v[72:75], v[170:173], v[222:225], v[72:75]
	v_mfma_f32_16x16x32_bf16 v[124:127], v[166:169], v[198:201], v[124:127]
	v_mfma_f32_16x16x32_bf16 v[120:123], v[174:177], v[198:201], v[120:123]
	v_mfma_f32_16x16x32_bf16 v[108:111], v[166:169], v[206:209], v[108:111]
	v_mfma_f32_16x16x32_bf16 v[104:107], v[174:177], v[206:209], v[104:107]
	v_mfma_f32_16x16x32_bf16 v[92:95], v[166:169], v[214:217], v[92:95]
	v_mfma_f32_16x16x32_bf16 v[88:91], v[174:177], v[214:217], v[88:91]
	v_mfma_f32_16x16x32_bf16 v[76:79], v[166:169], v[226:229], v[76:79]
	v_mfma_f32_16x16x32_bf16 v[72:75], v[174:177], v[226:229], v[72:75]
	v_mfma_f32_16x16x32_bf16 v[116:119], v[178:181], v[194:197], v[116:119]
	v_mfma_f32_16x16x32_bf16 v[112:115], v[186:189], v[194:197], v[112:115]
	v_mfma_f32_16x16x32_bf16 v[100:103], v[178:181], v[202:205], v[100:103]
	v_mfma_f32_16x16x32_bf16 v[96:99], v[186:189], v[202:205], v[96:99]
	v_mfma_f32_16x16x32_bf16 v[84:87], v[178:181], v[210:213], v[84:87]
	v_mfma_f32_16x16x32_bf16 v[80:83], v[186:189], v[210:213], v[80:83]
	v_mfma_f32_16x16x32_bf16 v[68:71], v[178:181], v[222:225], v[68:71]
	v_mfma_f32_16x16x32_bf16 v[64:67], v[186:189], v[222:225], v[64:67]
	v_mfma_f32_16x16x32_bf16 v[116:119], v[182:185], v[198:201], v[116:119]
	v_mfma_f32_16x16x32_bf16 v[112:115], v[190:193], v[198:201], v[112:115]
	v_mfma_f32_16x16x32_bf16 v[100:103], v[182:185], v[206:209], v[100:103]
	v_mfma_f32_16x16x32_bf16 v[96:99], v[190:193], v[206:209], v[96:99]
	v_mfma_f32_16x16x32_bf16 v[84:87], v[182:185], v[214:217], v[84:87]
	v_mfma_f32_16x16x32_bf16 v[80:83], v[190:193], v[214:217], v[80:83]
	v_mfma_f32_16x16x32_bf16 v[68:71], v[182:185], v[226:229], v[68:71]
	v_mfma_f32_16x16x32_bf16 v[64:67], v[190:193], v[226:229], v[64:67]
	s_barrier
; #define PG8_STAGE(bufoff, gbase, voff) do { _Pragma("unroll") for (int _i = 0; _i < 2; ++_i) \
;         __builtin_amdgcn_global_load_lds((const unsigned*)((const char*)(gbase) + (voff)[_i]), (LAS unsigned*)(lds + (bufoff) + ldsw + _i * 8192), 16, 0, 0); } while (0)
; #define PG8_LDA(dst, b, h) do { _Pragma("unroll") for (int m = 0; m < 4; ++m) _Pragma("unroll") for (int k = 0; k < 2; ++k) dst[m][k] = *(const LAS bf16x8*)(lds + PG8_SA(b, h) + aoff + m * 2048 + k * 1024); } while (0)
; #define PG8_MMA(ai, bj, At, Bt) do { __builtin_amdgcn_s_setprio(1); _Pragma("unroll") for (int m = 0; m < 4; ++m) _Pragma("unroll") for (int n = 0; n < 2; ++n) _Pragma("unroll") for (int k = 0; k < 2; ++k) \
;         acc[ai][bj][m][n] = __builtin_amdgcn_mfma_f32_16x16x32_bf16(Bt[n][k], At[m][k], acc[ai][bj][m][n], 0, 0, 0); __builtin_amdgcn_s_setprio(0); } while (0)
; #define PG8_WAIT_V(n) asm volatile("s_waitcnt vmcnt(" #n ")" ::: "memory")
; #define PG8_WAIT_L(n) asm volatile("s_waitcnt lgkmcnt(" #n ")" ::: "memory")
; #define PG8_BAR __builtin_amdgcn_s_barrier()
; #define PG8_SCHED __builtin_amdgcn_sched_barrier(0)
; template <class Epi, class Sched, bool ALIGN_EPI>
; __device__ __forceinline__ void gemm_phase(LAS unsigned char* lds, const Gemm g, const Sched& S, const Epi& E) {
;     ...
;             PG8_LDA(At, 1, 1); PG8_STAGE(PG8_SB(1, 0), b3, voffB); PG8_STAGE(PG8_SB(1, 1), b3 + hB, voffB); PG8_STAGE(PG8_SA(1, 0), a3, voffA);
;             PG8_WAIT_V(8); PG8_WAIT_L(0); PG8_BAR; PG8_MMA(1, 0, At, B0); PG8_MMA(1, 1, At, B1); PG8_BAR; PG8_SCHED;
;         }
;         if constexpr (ALIGN_EPI) { if (wr == 0) PG8_BAR; }
	s_add_i32 s18, s74, s84
	v_lshl_add_u64 v[160:161], v[160:161], 0, s[24:25]
	s_mov_b32 m0, s18
	ds_read_b128 v[194:197], v152 offset:49152
	ds_read_b128 v[198:201], v152 offset:50176
	ds_read_b128 v[202:205], v152 offset:51200
	ds_read_b128 v[206:209], v152 offset:52224
	ds_read_b128 v[210:213], v152 offset:53248
	ds_read_b128 v[214:217], v152 offset:54272
	ds_read_b128 v[222:225], v152 offset:55296
	ds_read_b128 v[226:229], v152 offset:56320
	global_load_lds_dwordx4 v[160:161], off
	s_add_i32 m0, s18, 0x2000
	s_add_u32 s18, s62, 0x80080
	v_lshl_add_u64 v[160:161], v[218:219], 0, s[24:25]
	s_addc_u32 s19, s63, 0
	s_add_i32 s33, s75, s84
	global_load_lds_dwordx4 v[160:161], off
	v_lshl_add_u64 v[160:161], s[18:19], 0, v[130:131]
	s_mov_b32 m0, s33
	s_nop 0
	global_load_lds_dwordx4 v[160:161], off
	v_lshl_add_u64 v[160:161], s[18:19], 0, v[134:135]
	s_add_i32 m0, s33, 0x2000
	s_nop 0
	global_load_lds_dwordx4 v[160:161], off
	v_lshl_add_u64 v[160:161], v[230:231], 0, s[24:25]
	s_mov_b32 m0, s90
	s_nop 0
	global_load_lds_dwordx4 v[160:161], off
	v_lshl_add_u64 v[160:161], v[232:233], 0, s[24:25]
	s_mov_b32 m0, s91
	s_nop 0
	global_load_lds_dwordx4 v[160:161], off
	s_waitcnt vmcnt(8)
	s_waitcnt lgkmcnt(0)
	s_barrier
	s_waitcnt lgkmcnt(0)
	v_mfma_f32_16x16x32_bf16 v[60:63], v[156:159], v[194:197], v[60:63]
	v_mfma_f32_16x16x32_bf16 v[56:59], v[170:173], v[194:197], v[56:59]
	v_mfma_f32_16x16x32_bf16 v[44:47], v[156:159], v[202:205], v[44:47]
	v_mfma_f32_16x16x32_bf16 v[40:43], v[170:173], v[202:205], v[40:43]
	v_mfma_f32_16x16x32_bf16 v[28:31], v[156:159], v[210:213], v[28:31]
	v_mfma_f32_16x16x32_bf16 v[24:27], v[170:173], v[210:213], v[24:27]
	v_mfma_f32_16x16x32_bf16 v[12:15], v[156:159], v[222:225], v[12:15]
	v_mfma_f32_16x16x32_bf16 v[8:11], v[170:173], v[222:225], v[8:11]
	v_mfma_f32_16x16x32_bf16 v[60:63], v[166:169], v[198:201], v[60:63]
	v_mfma_f32_16x16x32_bf16 v[56:59], v[174:177], v[198:201], v[56:59]
	v_mfma_f32_16x16x32_bf16 v[44:47], v[166:169], v[206:209], v[44:47]
	v_mfma_f32_16x16x32_bf16 v[40:43], v[174:177], v[206:209], v[40:43]
	v_mfma_f32_16x16x32_bf16 v[28:31], v[166:169], v[214:217], v[28:31]
	v_mfma_f32_16x16x32_bf16 v[24:27], v[174:177], v[214:217], v[24:27]
	v_mfma_f32_16x16x32_bf16 v[12:15], v[166:169], v[226:229], v[12:15]
	v_mfma_f32_16x16x32_bf16 v[8:11], v[174:177], v[226:229], v[8:11]
	v_mfma_f32_16x16x32_bf16 v[52:55], v[178:181], v[194:197], v[52:55]
	v_mfma_f32_16x16x32_bf16 v[48:51], v[186:189], v[194:197], v[48:51]
	v_mfma_f32_16x16x32_bf16 v[36:39], v[178:181], v[202:205], v[36:39]
	v_mfma_f32_16x16x32_bf16 v[32:35], v[186:189], v[202:205], v[32:35]
	v_mfma_f32_16x16x32_bf16 v[20:23], v[178:181], v[210:213], v[20:23]
	v_mfma_f32_16x16x32_bf16 v[16:19], v[186:189], v[210:213], v[16:19]
	v_mfma_f32_16x16x32_bf16 v[4:7], v[178:181], v[222:225], v[4:7]
	v_mfma_f32_16x16x32_bf16 v[0:3], v[186:189], v[222:225], v[0:3]
	v_mfma_f32_16x16x32_bf16 v[52:55], v[182:185], v[198:201], v[52:55]
	v_mfma_f32_16x16x32_bf16 v[48:51], v[190:193], v[198:201], v[48:51]
	v_mfma_f32_16x16x32_bf16 v[36:39], v[182:185], v[206:209], v[36:39]
	v_mfma_f32_16x16x32_bf16 v[32:35], v[190:193], v[206:209], v[32:35]
	v_mfma_f32_16x16x32_bf16 v[20:23], v[182:185], v[214:217], v[20:23]
	v_mfma_f32_16x16x32_bf16 v[16:19], v[190:193], v[214:217], v[16:19]
	v_mfma_f32_16x16x32_bf16 v[4:7], v[182:185], v[226:229], v[4:7]
	v_mfma_f32_16x16x32_bf16 v[0:3], v[190:193], v[226:229], v[0:3]
	s_barrier
	s_add_u32 s60, s60, 0x100
	s_addc_u32 s61, s61, 0
	s_cmp_lt_i32 s94, s27
	s_mov_b32 s62, s94
	s_cbranch_scc1 .LBB0_926
	v_readlane_b32 s92, v254, 6
	v_readlane_b32 s93, v254, 7

; #define PG8_STAGE(bufoff, gbase, voff) do { _Pragma("unroll") for (int _i = 0; _i < 2; ++_i) \
;         __builtin_amdgcn_global_load_lds((const unsigned*)((const char*)(gbase) + (voff)[_i]), (LAS unsigned*)(lds + (bufoff) + ldsw + _i * 8192), 16, 0, 0); } while (0)
; #define PG8_LDA(dst, b, h) do { _Pragma("unroll") for (int m = 0; m < 4; ++m) _Pragma("unroll") for (int k = 0; k < 2; ++k) dst[m][k] = *(const LAS bf16x8*)(lds + PG8_SA(b, h) + aoff + m * 2048 + k * 1024); } while (0)
; #define PG8_LDB(dst, b, h) do { _Pragma("unroll") for (int n = 0; n < 2; ++n) _Pragma("unroll") for (int k = 0; k < 2; ++k) dst[n][k] = *(const LAS bf16x8*)(lds + PG8_SB(b, h) + boff + n * 2048 + k * 1024); } while (0)
; #define PG8_MMA(ai, bj, At, Bt) do { __builtin_amdgcn_s_setprio(1); _Pragma("unroll") for (int m = 0; m < 4; ++m) _Pragma("unroll") for (int n = 0; n < 2; ++n) _Pragma("unroll") for (int k = 0; k < 2; ++k) \
;         acc[ai][bj][m][n] = __builtin_amdgcn_mfma_f32_16x16x32_bf16(Bt[n][k], At[m][k], acc[ai][bj][m][n], 0, 0, 0); __builtin_amdgcn_s_setprio(0); } while (0)
; #define PG8_WAIT_V(n) asm volatile("s_waitcnt vmcnt(" #n ")" ::: "memory")
; #define PG8_WAIT_L(n) asm volatile("s_waitcnt lgkmcnt(" #n ")" ::: "memory")
; #define PG8_BAR __builtin_amdgcn_s_barrier()
; #define PG8_SCHED __builtin_amdgcn_sched_barrier(0)
; template <class Epi, class Sched, bool ALIGN_EPI>
; __device__ __forceinline__ void gemm_phase(LAS unsigned char* lds, const Gemm g, const Sched& S, const Epi& E) {
;     ...
;             const bool last = (t == nt - 2);
;             const char* a1 = cA + (size_t)(t + 1) * kstep;
;             const char* a2 = last ? nA : cA + (size_t)(t + 2) * kstep; const char* b2 = last ? nB : cB + (size_t)(t + 2) * kstep;
;             const char* a3 = a2 + kstep; const char* b3 = b2 + kstep;
;             PG8_LDB(B0, 0, 0); PG8_LDB(B1, 0, 1); PG8_SCHED; PG8_LDA(At, 0, 0); PG8_STAGE(PG8_SA(1, 1), a1 + hA, voffA);
;             PG8_WAIT_V(8); PG8_WAIT_L(0); PG8_BAR; PG8_MMA(0, 0, At, B0); PG8_MMA(0, 1, At, B1); PG8_BAR; PG8_SCHED;
;             PG8_LDA(At, 0, 1); PG8_STAGE(PG8_SB(0, 0), b2, voffB); PG8_STAGE(PG8_SB(0, 1), b2 + hB, voffB); PG8_STAGE(PG8_SA(0, 0), a2, voffA);
;             PG8_WAIT_V(8); PG8_WAIT_L(0); PG8_BAR; PG8_MMA(1, 0, At, B0); PG8_MMA(1, 1, At, B1); PG8_BAR; PG8_SCHED;
.LBB0_955:
	ds_read_b128 v[156:159], v152
	ds_read_b128 v[160:163], v152 offset:1024
	ds_read_b128 v[164:167], v152 offset:2048
	ds_read_b128 v[168:171], v152 offset:3072
	ds_read_b128 v[172:175], v153
	ds_read_b128 v[176:179], v153 offset:1024
	ds_read_b128 v[180:183], v153 offset:2048
	ds_read_b128 v[184:187], v153 offset:3072
	s_add_i32 s75, s40, 2
	s_add_u32 s18, s38, 0xf4b80080
	s_addc_u32 s19, s39, -1
	s_cmp_lg_u32 s57, s40
	s_cselect_b32 s18, s18, 0
	s_cselect_b32 s19, s19, 0
	s_add_u32 s42, s26, s18
	s_addc_u32 s43, s27, s19
	s_add_u32 s40, s24, s18
	s_addc_u32 s41, s25, s19
	s_mov_b32 m0, s4
	v_lshl_add_u64 v[222:223], v[142:143], 0, s[38:39]
	ds_read_b128 v[188:191], v151
	ds_read_b128 v[192:195], v151 offset:1024
	ds_read_b128 v[196:199], v151 offset:2048
	ds_read_b128 v[200:203], v151 offset:3072
	ds_read_b128 v[204:207], v151 offset:4096
	ds_read_b128 v[208:211], v151 offset:5120
	ds_read_b128 v[212:215], v151 offset:6144
	ds_read_b128 v[216:219], v151 offset:7168
	global_load_lds_dwordx4 v[222:223], off
	v_lshl_add_u64 v[222:223], v[144:145], 0, s[38:39]
	s_mov_b32 m0, s44
	s_nop 0
	global_load_lds_dwordx4 v[222:223], off
	s_waitcnt vmcnt(8)
	s_waitcnt lgkmcnt(0)
	s_barrier
	s_waitcnt lgkmcnt(0)
	v_mfma_f32_16x16x32_bf16 v[124:127], v[156:159], v[188:191], v[124:127]
	v_mfma_f32_16x16x32_bf16 v[120:123], v[164:167], v[188:191], v[120:123]
	v_mfma_f32_16x16x32_bf16 v[108:111], v[156:159], v[196:199], v[108:111]
	v_mfma_f32_16x16x32_bf16 v[104:107], v[164:167], v[196:199], v[104:107]
	v_mfma_f32_16x16x32_bf16 v[92:95], v[156:159], v[204:207], v[92:95]
	v_mfma_f32_16x16x32_bf16 v[88:91], v[164:167], v[204:207], v[88:91]
	v_mfma_f32_16x16x32_bf16 v[76:79], v[156:159], v[212:215], v[76:79]
	v_mfma_f32_16x16x32_bf16 v[72:75], v[164:167], v[212:215], v[72:75]
	v_mfma_f32_16x16x32_bf16 v[124:127], v[160:163], v[192:195], v[124:127]
	v_mfma_f32_16x16x32_bf16 v[120:123], v[168:171], v[192:195], v[120:123]
	v_mfma_f32_16x16x32_bf16 v[108:111], v[160:163], v[200:203], v[108:111]
	v_mfma_f32_16x16x32_bf16 v[104:107], v[168:171], v[200:203], v[104:107]
	v_mfma_f32_16x16x32_bf16 v[92:95], v[160:163], v[208:211], v[92:95]
	v_mfma_f32_16x16x32_bf16 v[88:91], v[168:171], v[208:211], v[88:91]
	v_mfma_f32_16x16x32_bf16 v[76:79], v[160:163], v[216:219], v[76:79]
	v_mfma_f32_16x16x32_bf16 v[72:75], v[168:171], v[216:219], v[72:75]
	v_mfma_f32_16x16x32_bf16 v[116:119], v[172:175], v[188:191], v[116:119]
	v_mfma_f32_16x16x32_bf16 v[112:115], v[180:183], v[188:191], v[112:115]
	v_mfma_f32_16x16x32_bf16 v[100:103], v[172:175], v[196:199], v[100:103]
	v_mfma_f32_16x16x32_bf16 v[96:99], v[180:183], v[196:199], v[96:99]
	v_mfma_f32_16x16x32_bf16 v[84:87], v[172:175], v[204:207], v[84:87]
	v_mfma_f32_16x16x32_bf16 v[80:83], v[180:183], v[204:207], v[80:83]
	v_mfma_f32_16x16x32_bf16 v[68:71], v[172:175], v[212:215], v[68:71]
	v_mfma_f32_16x16x32_bf16 v[64:67], v[180:183], v[212:215], v[64:67]
	v_mfma_f32_16x16x32_bf16 v[116:119], v[176:179], v[192:195], v[116:119]
	v_mfma_f32_16x16x32_bf16 v[112:115], v[184:187], v[192:195], v[112:115]
	v_mfma_f32_16x16x32_bf16 v[100:103], v[176:179], v[200:203], v[100:103]
	v_mfma_f32_16x16x32_bf16 v[96:99], v[184:187], v[200:203], v[96:99]
	v_mfma_f32_16x16x32_bf16 v[84:87], v[176:179], v[208:211], v[84:87]
	v_mfma_f32_16x16x32_bf16 v[80:83], v[184:187], v[208:211], v[80:83]
	v_mfma_f32_16x16x32_bf16 v[68:71], v[176:179], v[216:219], v[68:71]
	v_mfma_f32_16x16x32_bf16 v[64:67], v[184:187], v[216:219], v[64:67]
	s_barrier
	s_mov_b32 m0, s45
	v_lshl_add_u64 v[222:223], s[40:41], 0, v[130:131]
	s_add_u32 s18, s40, 0x100000
	ds_read_b128 v[188:191], v151 offset:16384
	ds_read_b128 v[192:195], v151 offset:17408
	ds_read_b128 v[196:199], v151 offset:18432
	ds_read_b128 v[200:203], v151 offset:19456
	ds_read_b128 v[204:207], v151 offset:20480
	ds_read_b128 v[208:211], v151 offset:21504
	ds_read_b128 v[212:215], v151 offset:22528
	ds_read_b128 v[216:219], v151 offset:23552
	global_load_lds_dwordx4 v[222:223], off
	v_lshl_add_u64 v[224:225], s[40:41], 0, v[134:135]
	s_mov_b32 m0, s46
	s_addc_u32 s19, s41, 0
	global_load_lds_dwordx4 v[224:225], off
	v_lshl_add_u64 v[226:227], s[18:19], 0, v[130:131]
	s_mov_b32 m0, s47
	v_lshl_add_u64 v[228:229], s[42:43], 0, v[132:133]
	global_load_lds_dwordx4 v[226:227], off
	v_lshl_add_u64 v[226:227], s[18:19], 0, v[134:135]
	s_mov_b32 m0, s74
	s_nop 0
	global_load_lds_dwordx4 v[226:227], off
	v_lshl_add_u64 v[226:227], s[42:43], 0, v[128:129]
	s_mov_b32 m0, s23
	s_nop 0
	global_load_lds_dwordx4 v[226:227], off
	s_mov_b32 m0, s67
	s_nop 0
	global_load_lds_dwordx4 v[228:229], off
	s_waitcnt vmcnt(8)
	s_waitcnt lgkmcnt(0)
	s_barrier
; #define PG8_STAGE(bufoff, gbase, voff) do { _Pragma("unroll") for (int _i = 0; _i < 2; ++_i) \
;         __builtin_amdgcn_global_load_lds((const unsigned*)((const char*)(gbase) + (voff)[_i]), (LAS unsigned*)(lds + (bufoff) + ldsw + _i * 8192), 16, 0, 0); } while (0)
; #define PG8_LDA(dst, b, h) do { _Pragma("unroll") for (int m = 0; m < 4; ++m) _Pragma("unroll") for (int k = 0; k < 2; ++k) dst[m][k] = *(const LAS bf16x8*)(lds + PG8_SA(b, h) + aoff + m * 2048 + k * 1024); } while (0)
; #define PG8_LDB(dst, b, h) do { _Pragma("unroll") for (int n = 0; n < 2; ++n) _Pragma("unroll") for (int k = 0; k < 2; ++k) dst[n][k] = *(const LAS bf16x8*)(lds + PG8_SB(b, h) + boff + n * 2048 + k * 1024); } while (0)
; #define PG8_MMA(ai, bj, At, Bt) do { __builtin_amdgcn_s_setprio(1); _Pragma("unroll") for (int m = 0; m < 4; ++m) _Pragma("unroll") for (int n = 0; n < 2; ++n) _Pragma("unroll") for (int k = 0; k < 2; ++k) \
;         acc[ai][bj][m][n] = __builtin_amdgcn_mfma_f32_16x16x32_bf16(Bt[n][k], At[m][k], acc[ai][bj][m][n], 0, 0, 0); __builtin_amdgcn_s_setprio(0); } while (0)
; #define PG8_WAIT_V(n) asm volatile("s_waitcnt vmcnt(" #n ")" ::: "memory")
; #define PG8_WAIT_L(n) asm volatile("s_waitcnt lgkmcnt(" #n ")" ::: "memory")
; #define PG8_BAR __builtin_amdgcn_s_barrier()
; #define PG8_SCHED __builtin_amdgcn_sched_barrier(0)
; template <class Epi, class Sched, bool ALIGN_EPI>
; __device__ __forceinline__ void gemm_phase(LAS unsigned char* lds, const Gemm g, const Sched& S, const Epi& E) {
;     ...
;             PG8_WAIT_V(8); PG8_WAIT_L(0); PG8_BAR; PG8_MMA(1, 0, At, B0); PG8_MMA(1, 1, At, B1); PG8_BAR; PG8_SCHED;
;             PG8_LDB(B0, 1, 0); PG8_LDB(B1, 1, 1); PG8_SCHED; PG8_LDA(At, 1, 0); PG8_STAGE(PG8_SA(0, 1), a2 + hA, voffA);
;             PG8_WAIT_V(8); PG8_WAIT_L(0); PG8_BAR; PG8_MMA(0, 0, At, B0); PG8_MMA(0, 1, At, B1); PG8_BAR; PG8_SCHED;
	s_waitcnt lgkmcnt(0)
	v_mfma_f32_16x16x32_bf16 v[60:63], v[156:159], v[188:191], v[60:63]
	v_mfma_f32_16x16x32_bf16 v[56:59], v[164:167], v[188:191], v[56:59]
	v_mfma_f32_16x16x32_bf16 v[44:47], v[156:159], v[196:199], v[44:47]
	v_mfma_f32_16x16x32_bf16 v[40:43], v[164:167], v[196:199], v[40:43]
	v_mfma_f32_16x16x32_bf16 v[28:31], v[156:159], v[204:207], v[28:31]
	v_mfma_f32_16x16x32_bf16 v[24:27], v[164:167], v[204:207], v[24:27]
	v_mfma_f32_16x16x32_bf16 v[12:15], v[156:159], v[212:215], v[12:15]
	v_mfma_f32_16x16x32_bf16 v[8:11], v[164:167], v[212:215], v[8:11]
	v_mfma_f32_16x16x32_bf16 v[60:63], v[160:163], v[192:195], v[60:63]
	v_mfma_f32_16x16x32_bf16 v[56:59], v[168:171], v[192:195], v[56:59]
	v_mfma_f32_16x16x32_bf16 v[44:47], v[160:163], v[200:203], v[44:47]
	v_mfma_f32_16x16x32_bf16 v[40:43], v[168:171], v[200:203], v[40:43]
	v_mfma_f32_16x16x32_bf16 v[28:31], v[160:163], v[208:211], v[28:31]
	v_mfma_f32_16x16x32_bf16 v[24:27], v[168:171], v[208:211], v[24:27]
	v_mfma_f32_16x16x32_bf16 v[12:15], v[160:163], v[216:219], v[12:15]
	v_mfma_f32_16x16x32_bf16 v[8:11], v[168:171], v[216:219], v[8:11]
	v_mfma_f32_16x16x32_bf16 v[52:55], v[172:175], v[188:191], v[52:55]
	v_mfma_f32_16x16x32_bf16 v[48:51], v[180:183], v[188:191], v[48:51]
	v_mfma_f32_16x16x32_bf16 v[36:39], v[172:175], v[196:199], v[36:39]
	v_mfma_f32_16x16x32_bf16 v[32:35], v[180:183], v[196:199], v[32:35]
	v_mfma_f32_16x16x32_bf16 v[20:23], v[172:175], v[204:207], v[20:23]
	v_mfma_f32_16x16x32_bf16 v[16:19], v[180:183], v[204:207], v[16:19]
	v_mfma_f32_16x16x32_bf16 v[4:7], v[172:175], v[212:215], v[4:7]
	v_mfma_f32_16x16x32_bf16 v[0:3], v[180:183], v[212:215], v[0:3]
	v_mfma_f32_16x16x32_bf16 v[52:55], v[176:179], v[192:195], v[52:55]
	v_mfma_f32_16x16x32_bf16 v[48:51], v[184:187], v[192:195], v[48:51]
	v_mfma_f32_16x16x32_bf16 v[36:39], v[176:179], v[200:203], v[36:39]
	v_mfma_f32_16x16x32_bf16 v[32:35], v[184:187], v[200:203], v[32:35]
	v_mfma_f32_16x16x32_bf16 v[20:23], v[176:179], v[208:211], v[20:23]
	v_mfma_f32_16x16x32_bf16 v[16:19], v[184:187], v[208:211], v[16:19]
	v_mfma_f32_16x16x32_bf16 v[4:7], v[176:179], v[216:219], v[4:7]
	v_mfma_f32_16x16x32_bf16 v[0:3], v[184:187], v[216:219], v[0:3]
	s_barrier
	s_add_i32 s33, 0, 0x1c000
	v_add_u32_e32 v155, s33, v150
	ds_read_b128 v[156:159], v154
	ds_read_b128 v[160:163], v154 offset:1024
	ds_read_b128 v[164:167], v154 offset:2048
	ds_read_b128 v[168:171], v154 offset:3072
	ds_read_b128 v[172:175], v155
	ds_read_b128 v[176:179], v155 offset:1024
	ds_read_b128 v[180:183], v155 offset:2048
	ds_read_b128 v[184:187], v155 offset:3072
	s_add_u32 s18, s42, 0x80000
	s_addc_u32 s19, s43, 0
	s_mov_b32 m0, s68
	v_lshl_add_u64 v[230:231], s[18:19], 0, v[128:129]
	ds_read_b128 v[188:191], v151 offset:32768
	ds_read_b128 v[192:195], v151 offset:33792
	ds_read_b128 v[196:199], v151 offset:34816
	ds_read_b128 v[200:203], v151 offset:35840
	ds_read_b128 v[204:207], v151 offset:36864
	ds_read_b128 v[208:211], v151 offset:37888
	ds_read_b128 v[212:215], v151 offset:38912
	ds_read_b128 v[216:219], v151 offset:39936
	global_load_lds_dwordx4 v[230:231], off
	v_lshl_add_u64 v[230:231], s[18:19], 0, v[132:133]
	s_mov_b32 m0, s69
	s_nop 0
	global_load_lds_dwordx4 v[230:231], off
	s_waitcnt vmcnt(8)
	s_waitcnt lgkmcnt(0)
	s_barrier
	s_waitcnt lgkmcnt(0)
	v_mfma_f32_16x16x32_bf16 v[124:127], v[156:159], v[188:191], v[124:127]
	v_mfma_f32_16x16x32_bf16 v[120:123], v[164:167], v[188:191], v[120:123]
	v_mfma_f32_16x16x32_bf16 v[108:111], v[156:159], v[196:199], v[108:111]
	v_mfma_f32_16x16x32_bf16 v[104:107], v[164:167], v[196:199], v[104:107]
	v_mfma_f32_16x16x32_bf16 v[92:95], v[156:159], v[204:207], v[92:95]
	v_mfma_f32_16x16x32_bf16 v[88:91], v[164:167], v[204:207], v[88:91]
	v_mfma_f32_16x16x32_bf16 v[76:79], v[156:159], v[212:215], v[76:79]
	v_mfma_f32_16x16x32_bf16 v[72:75], v[164:167], v[212:215], v[72:75]
	v_mfma_f32_16x16x32_bf16 v[124:127], v[160:163], v[192:195], v[124:127]
	v_mfma_f32_16x16x32_bf16 v[120:123], v[168:171], v[192:195], v[120:123]
	v_mfma_f32_16x16x32_bf16 v[108:111], v[160:163], v[200:203], v[108:111]
	v_mfma_f32_16x16x32_bf16 v[104:107], v[168:171], v[200:203], v[104:107]
	v_mfma_f32_16x16x32_bf16 v[92:95], v[160:163], v[208:211], v[92:95]
	v_mfma_f32_16x16x32_bf16 v[88:91], v[168:171], v[208:211], v[88:91]
	v_mfma_f32_16x16x32_bf16 v[76:79], v[160:163], v[216:219], v[76:79]
	v_mfma_f32_16x16x32_bf16 v[72:75], v[168:171], v[216:219], v[72:75]
	v_mfma_f32_16x16x32_bf16 v[116:119], v[172:175], v[188:191], v[116:119]
	v_mfma_f32_16x16x32_bf16 v[112:115], v[180:183], v[188:191], v[112:115]
	v_mfma_f32_16x16x32_bf16 v[100:103], v[172:175], v[196:199], v[100:103]
	v_mfma_f32_16x16x32_bf16 v[96:99], v[180:183], v[196:199], v[96:99]
	v_mfma_f32_16x16x32_bf16 v[84:87], v[172:175], v[204:207], v[84:87]
	v_mfma_f32_16x16x32_bf16 v[80:83], v[180:183], v[204:207], v[80:83]
	v_mfma_f32_16x16x32_bf16 v[68:71], v[172:175], v[212:215], v[68:71]
	v_mfma_f32_16x16x32_bf16 v[64:67], v[180:183], v[212:215], v[64:67]
	v_mfma_f32_16x16x32_bf16 v[116:119], v[176:179], v[192:195], v[116:119]
	v_mfma_f32_16x16x32_bf16 v[112:115], v[184:187], v[192:195], v[112:115]
	v_mfma_f32_16x16x32_bf16 v[100:103], v[176:179], v[200:203], v[100:103]
	v_mfma_f32_16x16x32_bf16 v[96:99], v[184:187], v[200:203], v[96:99]
	v_mfma_f32_16x16x32_bf16 v[84:87], v[176:179], v[208:211], v[84:87]
	v_mfma_f32_16x16x32_bf16 v[80:83], v[184:187], v[208:211], v[80:83]
	v_mfma_f32_16x16x32_bf16 v[68:71], v[176:179], v[216:219], v[68:71]
	v_mfma_f32_16x16x32_bf16 v[64:67], v[184:187], v[216:219], v[64:67]
	s_barrier
; #define PG8_STAGE(bufoff, gbase, voff) do { _Pragma("unroll") for (int _i = 0; _i < 2; ++_i) \
;         __builtin_amdgcn_global_load_lds((const unsigned*)((const char*)(gbase) + (voff)[_i]), (LAS unsigned*)(lds + (bufoff) + ldsw + _i * 8192), 16, 0, 0); } while (0)
; #define PG8_LDA(dst, b, h) do { _Pragma("unroll") for (int m = 0; m < 4; ++m) _Pragma("unroll") for (int k = 0; k < 2; ++k) dst[m][k] = *(const LAS bf16x8*)(lds + PG8_SA(b, h) + aoff + m * 2048 + k * 1024); } while (0)
; #define PG8_MMA(ai, bj, At, Bt) do { __builtin_amdgcn_s_setprio(1); _Pragma("unroll") for (int m = 0; m < 4; ++m) _Pragma("unroll") for (int n = 0; n < 2; ++n) _Pragma("unroll") for (int k = 0; k < 2; ++k) \
;         acc[ai][bj][m][n] = __builtin_amdgcn_mfma_f32_16x16x32_bf16(Bt[n][k], At[m][k], acc[ai][bj][m][n], 0, 0, 0); __builtin_amdgcn_s_setprio(0); } while (0)
; #define PG8_WAIT_V(n) asm volatile("s_waitcnt vmcnt(" #n ")" ::: "memory")
; #define PG8_WAIT_L(n) asm volatile("s_waitcnt lgkmcnt(" #n ")" ::: "memory")
; #define PG8_BAR __builtin_amdgcn_s_barrier()
; #define PG8_SCHED __builtin_amdgcn_sched_barrier(0)
; template <class Epi, class Sched, bool ALIGN_EPI>
; __device__ __forceinline__ void gemm_phase(LAS unsigned char* lds, const Gemm g, const Sched& S, const Epi& E) {
;     ...
;             PG8_LDA(At, 1, 1); PG8_STAGE(PG8_SB(1, 0), b3, voffB); PG8_STAGE(PG8_SB(1, 1), b3 + hB, voffB); PG8_STAGE(PG8_SA(1, 0), a3, voffA);
;             PG8_WAIT_V(8); PG8_WAIT_L(0); PG8_BAR; PG8_MMA(1, 0, At, B0); PG8_MMA(1, 1, At, B1); PG8_BAR; PG8_SCHED;
;         }
;         if constexpr (ALIGN_EPI) { if (wr == 0) PG8_BAR; }
	s_add_i32 s18, s61, s11
	v_lshl_add_u64 v[222:223], v[222:223], 0, s[6:7]
	s_mov_b32 m0, s18
	ds_read_b128 v[188:191], v151 offset:49152
	ds_read_b128 v[192:195], v151 offset:50176
	ds_read_b128 v[196:199], v151 offset:51200
	ds_read_b128 v[200:203], v151 offset:52224
	ds_read_b128 v[204:207], v151 offset:53248
	ds_read_b128 v[208:211], v151 offset:54272
	ds_read_b128 v[212:215], v151 offset:55296
	ds_read_b128 v[216:219], v151 offset:56320
	global_load_lds_dwordx4 v[222:223], off
	s_add_i32 m0, s18, 0x2000
	s_add_u32 s18, s40, 0x100080
	v_lshl_add_u64 v[222:223], v[224:225], 0, s[6:7]
	s_addc_u32 s19, s41, 0
	s_add_i32 s33, s33, s11
	global_load_lds_dwordx4 v[222:223], off
	v_lshl_add_u64 v[222:223], s[18:19], 0, v[130:131]
	s_mov_b32 m0, s33
	s_nop 0
	global_load_lds_dwordx4 v[222:223], off
	v_lshl_add_u64 v[222:223], s[18:19], 0, v[134:135]
	s_add_i32 m0, s33, 0x2000
	s_nop 0
	global_load_lds_dwordx4 v[222:223], off
	v_lshl_add_u64 v[222:223], v[226:227], 0, s[6:7]
	s_mov_b32 m0, s70
	s_nop 0
	global_load_lds_dwordx4 v[222:223], off
	v_lshl_add_u64 v[222:223], v[228:229], 0, s[6:7]
	s_mov_b32 m0, s71
	s_nop 0
	global_load_lds_dwordx4 v[222:223], off
	s_waitcnt vmcnt(8)
	s_waitcnt lgkmcnt(0)
	s_barrier
	s_waitcnt lgkmcnt(0)
	v_mfma_f32_16x16x32_bf16 v[60:63], v[156:159], v[188:191], v[60:63]
	v_mfma_f32_16x16x32_bf16 v[56:59], v[164:167], v[188:191], v[56:59]
	v_mfma_f32_16x16x32_bf16 v[44:47], v[156:159], v[196:199], v[44:47]
	v_mfma_f32_16x16x32_bf16 v[40:43], v[164:167], v[196:199], v[40:43]
	v_mfma_f32_16x16x32_bf16 v[28:31], v[156:159], v[204:207], v[28:31]
	v_mfma_f32_16x16x32_bf16 v[24:27], v[164:167], v[204:207], v[24:27]
	v_mfma_f32_16x16x32_bf16 v[12:15], v[156:159], v[212:215], v[12:15]
	v_mfma_f32_16x16x32_bf16 v[8:11], v[164:167], v[212:215], v[8:11]
	v_mfma_f32_16x16x32_bf16 v[60:63], v[160:163], v[192:195], v[60:63]
	v_mfma_f32_16x16x32_bf16 v[56:59], v[168:171], v[192:195], v[56:59]
	v_mfma_f32_16x16x32_bf16 v[44:47], v[160:163], v[200:203], v[44:47]
	v_mfma_f32_16x16x32_bf16 v[40:43], v[168:171], v[200:203], v[40:43]
	v_mfma_f32_16x16x32_bf16 v[28:31], v[160:163], v[208:211], v[28:31]
	v_mfma_f32_16x16x32_bf16 v[24:27], v[168:171], v[208:211], v[24:27]
	v_mfma_f32_16x16x32_bf16 v[12:15], v[160:163], v[216:219], v[12:15]
	v_mfma_f32_16x16x32_bf16 v[8:11], v[168:171], v[216:219], v[8:11]
	v_mfma_f32_16x16x32_bf16 v[52:55], v[172:175], v[188:191], v[52:55]
	v_mfma_f32_16x16x32_bf16 v[48:51], v[180:183], v[188:191], v[48:51]
	v_mfma_f32_16x16x32_bf16 v[36:39], v[172:175], v[196:199], v[36:39]
	v_mfma_f32_16x16x32_bf16 v[32:35], v[180:183], v[196:199], v[32:35]
	v_mfma_f32_16x16x32_bf16 v[20:23], v[172:175], v[204:207], v[20:23]
	v_mfma_f32_16x16x32_bf16 v[16:19], v[180:183], v[204:207], v[16:19]
	v_mfma_f32_16x16x32_bf16 v[4:7], v[172:175], v[212:215], v[4:7]
	v_mfma_f32_16x16x32_bf16 v[0:3], v[180:183], v[212:215], v[0:3]
	v_mfma_f32_16x16x32_bf16 v[52:55], v[176:179], v[192:195], v[52:55]
	v_mfma_f32_16x16x32_bf16 v[48:51], v[184:187], v[192:195], v[48:51]
	v_mfma_f32_16x16x32_bf16 v[36:39], v[176:179], v[200:203], v[36:39]
	v_mfma_f32_16x16x32_bf16 v[32:35], v[184:187], v[200:203], v[32:35]
	v_mfma_f32_16x16x32_bf16 v[20:23], v[176:179], v[208:211], v[20:23]
	v_mfma_f32_16x16x32_bf16 v[16:19], v[184:187], v[208:211], v[16:19]
	v_mfma_f32_16x16x32_bf16 v[4:7], v[176:179], v[216:219], v[4:7]
	v_mfma_f32_16x16x32_bf16 v[0:3], v[184:187], v[216:219], v[0:3]
	s_barrier
	s_add_u32 s38, s38, 0x100
	s_addc_u32 s39, s39, 0
	s_cmp_ge_i32 s75, s56
	s_mov_b32 s40, s75
	s_cbranch_scc0 .LBB0_955

; #define PG8_STAGE(bufoff, gbase, voff) do { _Pragma("unroll") for (int _i = 0; _i < 2; ++_i) \
;         __builtin_amdgcn_global_load_lds((const unsigned*)((const char*)(gbase) + (voff)[_i]), (LAS unsigned*)(lds + (bufoff) + ldsw + _i * 8192), 16, 0, 0); } while (0)
; #define PG8_LDA(dst, b, h) do { _Pragma("unroll") for (int m = 0; m < 4; ++m) _Pragma("unroll") for (int k = 0; k < 2; ++k) dst[m][k] = *(const LAS bf16x8*)(lds + PG8_SA(b, h) + aoff + m * 2048 + k * 1024); } while (0)
; #define PG8_LDB(dst, b, h) do { _Pragma("unroll") for (int n = 0; n < 2; ++n) _Pragma("unroll") for (int k = 0; k < 2; ++k) dst[n][k] = *(const LAS bf16x8*)(lds + PG8_SB(b, h) + boff + n * 2048 + k * 1024); } while (0)
; #define PG8_MMA(ai, bj, At, Bt) do { __builtin_amdgcn_s_setprio(1); _Pragma("unroll") for (int m = 0; m < 4; ++m) _Pragma("unroll") for (int n = 0; n < 2; ++n) _Pragma("unroll") for (int k = 0; k < 2; ++k) \
;         acc[ai][bj][m][n] = __builtin_amdgcn_mfma_f32_16x16x32_bf16(Bt[n][k], At[m][k], acc[ai][bj][m][n], 0, 0, 0); __builtin_amdgcn_s_setprio(0); } while (0)
; #define PG8_WAIT_V(n) asm volatile("s_waitcnt vmcnt(" #n ")" ::: "memory")
; #define PG8_WAIT_L(n) asm volatile("s_waitcnt lgkmcnt(" #n ")" ::: "memory")
; #define PG8_BAR __builtin_amdgcn_s_barrier()
; #define PG8_SCHED __builtin_amdgcn_sched_barrier(0)
; template <class Epi, class Sched, bool ALIGN_EPI>
; __device__ __forceinline__ void gemm_phase(LAS unsigned char* lds, const Gemm g, const Sched& S, const Epi& E) {
;     ...
;             const bool last = (t == nt - 2);
;             const char* a1 = cA + (size_t)(t + 1) * kstep;
;             const char* a2 = last ? nA : cA + (size_t)(t + 2) * kstep; const char* b2 = last ? nB : cB + (size_t)(t + 2) * kstep;
;             const char* a3 = a2 + kstep; const char* b3 = b2 + kstep;
;             PG8_LDB(B0, 0, 0); PG8_LDB(B1, 0, 1); PG8_SCHED; PG8_LDA(At, 0, 0); PG8_STAGE(PG8_SA(1, 1), a1 + hA, voffA);
;             PG8_WAIT_V(8); PG8_WAIT_L(0); PG8_BAR; PG8_MMA(0, 0, At, B0); PG8_MMA(0, 1, At, B1); PG8_BAR; PG8_SCHED;
;             PG8_LDA(At, 0, 1); PG8_STAGE(PG8_SB(0, 0), b2, voffB); PG8_STAGE(PG8_SB(0, 1), b2 + hB, voffB); PG8_STAGE(PG8_SA(0, 0), a2, voffA);
;             PG8_WAIT_V(8); PG8_WAIT_L(0); PG8_BAR; PG8_MMA(1, 0, At, B0); PG8_MMA(1, 1, At, B1); PG8_BAR; PG8_SCHED;
.LBB0_1065:
	ds_read_b128 v[144:147], v151
	ds_read_b128 v[156:159], v151 offset:1024
	ds_read_b128 v[160:163], v151 offset:2048
	ds_read_b128 v[164:167], v151 offset:3072
	ds_read_b128 v[168:171], v152
	ds_read_b128 v[172:175], v152 offset:1024
	ds_read_b128 v[176:179], v152 offset:2048
	ds_read_b128 v[180:183], v152 offset:3072
	s_add_i32 s47, s46, 2
	s_add_u32 s18, s52, 0xfffc0080
	s_addc_u32 s19, s53, -1
	s_cmp_eq_u32 s68, s46
	s_cselect_b32 s57, s11, s19
	s_cselect_b32 s56, s39, s18
	s_cselect_b32 s55, s80, s45
	s_cselect_b32 s54, s81, s44
	v_lshl_add_u64 v[216:217], s[52:53], 0, v[136:137]
	s_add_i32 m0, s60, 0xc000
	ds_read_b128 v[184:187], v153
	ds_read_b128 v[188:191], v153 offset:1024
	ds_read_b128 v[192:195], v153 offset:2048
	ds_read_b128 v[196:199], v153 offset:3072
	ds_read_b128 v[200:203], v153 offset:4096
	ds_read_b128 v[204:207], v153 offset:5120
	ds_read_b128 v[208:211], v153 offset:6144
	ds_read_b128 v[212:215], v153 offset:7168
	global_load_lds_dwordx4 v[216:217], off
	v_lshl_add_u64 v[216:217], s[52:53], 0, v[138:139]
	s_add_i32 m0, s60, 0xe000
	s_nop 0
	global_load_lds_dwordx4 v[216:217], off
	s_waitcnt vmcnt(8)
	s_waitcnt lgkmcnt(0)
	s_barrier
	s_waitcnt lgkmcnt(0)
	v_mfma_f32_16x16x32_bf16 v[124:127], v[144:147], v[184:187], v[124:127]
	v_mfma_f32_16x16x32_bf16 v[120:123], v[160:163], v[184:187], v[120:123]
	v_mfma_f32_16x16x32_bf16 v[108:111], v[144:147], v[192:195], v[108:111]
	v_mfma_f32_16x16x32_bf16 v[104:107], v[160:163], v[192:195], v[104:107]
	v_mfma_f32_16x16x32_bf16 v[92:95], v[144:147], v[200:203], v[92:95]
	v_mfma_f32_16x16x32_bf16 v[88:91], v[160:163], v[200:203], v[88:91]
	v_mfma_f32_16x16x32_bf16 v[76:79], v[144:147], v[208:211], v[76:79]
	v_mfma_f32_16x16x32_bf16 v[72:75], v[160:163], v[208:211], v[72:75]
	v_mfma_f32_16x16x32_bf16 v[124:127], v[156:159], v[188:191], v[124:127]
	v_mfma_f32_16x16x32_bf16 v[120:123], v[164:167], v[188:191], v[120:123]
	v_mfma_f32_16x16x32_bf16 v[108:111], v[156:159], v[196:199], v[108:111]
	v_mfma_f32_16x16x32_bf16 v[104:107], v[164:167], v[196:199], v[104:107]
	v_mfma_f32_16x16x32_bf16 v[92:95], v[156:159], v[204:207], v[92:95]
	v_mfma_f32_16x16x32_bf16 v[88:91], v[164:167], v[204:207], v[88:91]
	v_mfma_f32_16x16x32_bf16 v[76:79], v[156:159], v[212:215], v[76:79]
	v_mfma_f32_16x16x32_bf16 v[72:75], v[164:167], v[212:215], v[72:75]
	v_mfma_f32_16x16x32_bf16 v[116:119], v[168:171], v[184:187], v[116:119]
	v_mfma_f32_16x16x32_bf16 v[112:115], v[176:179], v[184:187], v[112:115]
	v_mfma_f32_16x16x32_bf16 v[100:103], v[168:171], v[192:195], v[100:103]
	v_mfma_f32_16x16x32_bf16 v[96:99], v[176:179], v[192:195], v[96:99]
	v_mfma_f32_16x16x32_bf16 v[84:87], v[168:171], v[200:203], v[84:87]
	v_mfma_f32_16x16x32_bf16 v[80:83], v[176:179], v[200:203], v[80:83]
	v_mfma_f32_16x16x32_bf16 v[68:71], v[168:171], v[208:211], v[68:71]
	v_mfma_f32_16x16x32_bf16 v[64:67], v[176:179], v[208:211], v[64:67]
	v_mfma_f32_16x16x32_bf16 v[116:119], v[172:175], v[188:191], v[116:119]
	v_mfma_f32_16x16x32_bf16 v[112:115], v[180:183], v[188:191], v[112:115]
	v_mfma_f32_16x16x32_bf16 v[100:103], v[172:175], v[196:199], v[100:103]
	v_mfma_f32_16x16x32_bf16 v[96:99], v[180:183], v[196:199], v[96:99]
	v_mfma_f32_16x16x32_bf16 v[84:87], v[172:175], v[204:207], v[84:87]
	v_mfma_f32_16x16x32_bf16 v[80:83], v[180:183], v[204:207], v[80:83]
	v_mfma_f32_16x16x32_bf16 v[68:71], v[172:175], v[212:215], v[68:71]
	v_mfma_f32_16x16x32_bf16 v[64:67], v[180:183], v[212:215], v[64:67]
	s_barrier
	s_add_i32 s18, s74, s59
	v_lshl_add_u64 v[216:217], s[54:55], 0, v[130:131]
	s_mov_b32 m0, s18
	ds_read_b128 v[184:187], v153 offset:16384
	ds_read_b128 v[188:191], v153 offset:17408
	ds_read_b128 v[192:195], v153 offset:18432
	ds_read_b128 v[196:199], v153 offset:19456
	ds_read_b128 v[200:203], v153 offset:20480
	ds_read_b128 v[204:207], v153 offset:21504
	ds_read_b128 v[208:211], v153 offset:22528
	ds_read_b128 v[212:215], v153 offset:23552
	global_load_lds_dwordx4 v[216:217], off
	s_add_i32 m0, s18, 0x2000
	s_add_u32 s18, s54, 0x40000
	v_lshl_add_u64 v[218:219], s[54:55], 0, v[134:135]
	s_addc_u32 s19, s55, 0
	s_add_i32 s33, s75, s59
	global_load_lds_dwordx4 v[218:219], off
	v_lshl_add_u64 v[222:223], s[18:19], 0, v[130:131]
	s_mov_b32 m0, s33
	v_lshl_add_u64 v[224:225], s[56:57], 0, v[132:133]
	global_load_lds_dwordx4 v[222:223], off
	v_lshl_add_u64 v[222:223], s[18:19], 0, v[134:135]
	s_add_i32 m0, s33, 0x2000
	s_nop 0
	global_load_lds_dwordx4 v[222:223], off
	v_lshl_add_u64 v[222:223], s[56:57], 0, v[128:129]
	s_mov_b32 m0, s60
	s_nop 0
	global_load_lds_dwordx4 v[222:223], off
	s_mov_b32 m0, s61
	s_nop 0
	global_load_lds_dwordx4 v[224:225], off
	s_waitcnt vmcnt(8)
	s_waitcnt lgkmcnt(0)
	s_barrier
; #define PG8_STAGE(bufoff, gbase, voff) do { _Pragma("unroll") for (int _i = 0; _i < 2; ++_i) \
;         __builtin_amdgcn_global_load_lds((const unsigned*)((const char*)(gbase) + (voff)[_i]), (LAS unsigned*)(lds + (bufoff) + ldsw + _i * 8192), 16, 0, 0); } while (0)
; #define PG8_LDA(dst, b, h) do { _Pragma("unroll") for (int m = 0; m < 4; ++m) _Pragma("unroll") for (int k = 0; k < 2; ++k) dst[m][k] = *(const LAS bf16x8*)(lds + PG8_SA(b, h) + aoff + m * 2048 + k * 1024); } while (0)
; #define PG8_LDB(dst, b, h) do { _Pragma("unroll") for (int n = 0; n < 2; ++n) _Pragma("unroll") for (int k = 0; k < 2; ++k) dst[n][k] = *(const LAS bf16x8*)(lds + PG8_SB(b, h) + boff + n * 2048 + k * 1024); } while (0)
; #define PG8_MMA(ai, bj, At, Bt) do { __builtin_amdgcn_s_setprio(1); _Pragma("unroll") for (int m = 0; m < 4; ++m) _Pragma("unroll") for (int n = 0; n < 2; ++n) _Pragma("unroll") for (int k = 0; k < 2; ++k) \
;         acc[ai][bj][m][n] = __builtin_amdgcn_mfma_f32_16x16x32_bf16(Bt[n][k], At[m][k], acc[ai][bj][m][n], 0, 0, 0); __builtin_amdgcn_s_setprio(0); } while (0)
; #define PG8_WAIT_V(n) asm volatile("s_waitcnt vmcnt(" #n ")" ::: "memory")
; #define PG8_WAIT_L(n) asm volatile("s_waitcnt lgkmcnt(" #n ")" ::: "memory")
; #define PG8_BAR __builtin_amdgcn_s_barrier()
; #define PG8_SCHED __builtin_amdgcn_sched_barrier(0)
; template <class Epi, class Sched, bool ALIGN_EPI>
; __device__ __forceinline__ void gemm_phase(LAS unsigned char* lds, const Gemm g, const Sched& S, const Epi& E) {
;     ...
;             PG8_WAIT_V(8); PG8_WAIT_L(0); PG8_BAR; PG8_MMA(1, 0, At, B0); PG8_MMA(1, 1, At, B1); PG8_BAR; PG8_SCHED;
;             PG8_LDB(B0, 1, 0); PG8_LDB(B1, 1, 1); PG8_SCHED; PG8_LDA(At, 1, 0); PG8_STAGE(PG8_SA(0, 1), a2 + hA, voffA);
;             PG8_WAIT_V(8); PG8_WAIT_L(0); PG8_BAR; PG8_MMA(0, 0, At, B0); PG8_MMA(0, 1, At, B1); PG8_BAR; PG8_SCHED;
	s_waitcnt lgkmcnt(0)
	v_mfma_f32_16x16x32_bf16 v[60:63], v[144:147], v[184:187], v[60:63]
	v_mfma_f32_16x16x32_bf16 v[56:59], v[160:163], v[184:187], v[56:59]
	v_mfma_f32_16x16x32_bf16 v[44:47], v[144:147], v[192:195], v[44:47]
	v_mfma_f32_16x16x32_bf16 v[40:43], v[160:163], v[192:195], v[40:43]
	v_mfma_f32_16x16x32_bf16 v[28:31], v[144:147], v[200:203], v[28:31]
	v_mfma_f32_16x16x32_bf16 v[24:27], v[160:163], v[200:203], v[24:27]
	v_mfma_f32_16x16x32_bf16 v[12:15], v[144:147], v[208:211], v[12:15]
	v_mfma_f32_16x16x32_bf16 v[8:11], v[160:163], v[208:211], v[8:11]
	v_mfma_f32_16x16x32_bf16 v[60:63], v[156:159], v[188:191], v[60:63]
	v_mfma_f32_16x16x32_bf16 v[56:59], v[164:167], v[188:191], v[56:59]
	v_mfma_f32_16x16x32_bf16 v[44:47], v[156:159], v[196:199], v[44:47]
	v_mfma_f32_16x16x32_bf16 v[40:43], v[164:167], v[196:199], v[40:43]
	v_mfma_f32_16x16x32_bf16 v[28:31], v[156:159], v[204:207], v[28:31]
	v_mfma_f32_16x16x32_bf16 v[24:27], v[164:167], v[204:207], v[24:27]
	v_mfma_f32_16x16x32_bf16 v[12:15], v[156:159], v[212:215], v[12:15]
	v_mfma_f32_16x16x32_bf16 v[8:11], v[164:167], v[212:215], v[8:11]
	v_mfma_f32_16x16x32_bf16 v[52:55], v[168:171], v[184:187], v[52:55]
	v_mfma_f32_16x16x32_bf16 v[48:51], v[176:179], v[184:187], v[48:51]
	v_mfma_f32_16x16x32_bf16 v[36:39], v[168:171], v[192:195], v[36:39]
	v_mfma_f32_16x16x32_bf16 v[32:35], v[176:179], v[192:195], v[32:35]
	v_mfma_f32_16x16x32_bf16 v[20:23], v[168:171], v[200:203], v[20:23]
	v_mfma_f32_16x16x32_bf16 v[16:19], v[176:179], v[200:203], v[16:19]
	v_mfma_f32_16x16x32_bf16 v[4:7], v[168:171], v[208:211], v[4:7]
	v_mfma_f32_16x16x32_bf16 v[0:3], v[176:179], v[208:211], v[0:3]
	v_mfma_f32_16x16x32_bf16 v[52:55], v[172:175], v[188:191], v[52:55]
	v_mfma_f32_16x16x32_bf16 v[48:51], v[180:183], v[188:191], v[48:51]
	v_mfma_f32_16x16x32_bf16 v[36:39], v[172:175], v[196:199], v[36:39]
	v_mfma_f32_16x16x32_bf16 v[32:35], v[180:183], v[196:199], v[32:35]
	v_mfma_f32_16x16x32_bf16 v[20:23], v[172:175], v[204:207], v[20:23]
	v_mfma_f32_16x16x32_bf16 v[16:19], v[180:183], v[204:207], v[16:19]
	v_mfma_f32_16x16x32_bf16 v[4:7], v[172:175], v[212:215], v[4:7]
	v_mfma_f32_16x16x32_bf16 v[0:3], v[180:183], v[212:215], v[0:3]
	s_barrier
	s_add_i32 s33, 0, 0x18000
	v_add_u32_e32 v155, s33, v149
	s_add_i32 s46, 0, 0x1c000
	ds_read_b128 v[144:147], v155
	ds_read_b128 v[156:159], v155 offset:1024
	ds_read_b128 v[160:163], v155 offset:2048
	ds_read_b128 v[164:167], v155 offset:3072
	v_add_u32_e32 v155, s46, v149
	ds_read_b128 v[168:171], v155
	ds_read_b128 v[172:175], v155 offset:1024
	ds_read_b128 v[176:179], v155 offset:2048
	ds_read_b128 v[180:183], v155 offset:3072
	s_add_u32 s18, s56, 0x40000
	s_addc_u32 s19, s57, 0
	s_mov_b32 m0, s62
	v_lshl_add_u64 v[226:227], s[18:19], 0, v[128:129]
	ds_read_b128 v[184:187], v153 offset:32768
	ds_read_b128 v[188:191], v153 offset:33792
	ds_read_b128 v[192:195], v153 offset:34816
	ds_read_b128 v[196:199], v153 offset:35840
	ds_read_b128 v[200:203], v153 offset:36864
	ds_read_b128 v[204:207], v153 offset:37888
	ds_read_b128 v[208:211], v153 offset:38912
	ds_read_b128 v[212:215], v153 offset:39936
	global_load_lds_dwordx4 v[226:227], off
	v_lshl_add_u64 v[226:227], s[18:19], 0, v[132:133]
	s_mov_b32 m0, s63
	s_nop 0
	global_load_lds_dwordx4 v[226:227], off
	s_waitcnt vmcnt(8)
	s_waitcnt lgkmcnt(0)
	s_barrier
	s_waitcnt lgkmcnt(0)
	v_mfma_f32_16x16x32_bf16 v[124:127], v[144:147], v[184:187], v[124:127]
	v_mfma_f32_16x16x32_bf16 v[120:123], v[160:163], v[184:187], v[120:123]
	v_mfma_f32_16x16x32_bf16 v[108:111], v[144:147], v[192:195], v[108:111]
	v_mfma_f32_16x16x32_bf16 v[104:107], v[160:163], v[192:195], v[104:107]
	v_mfma_f32_16x16x32_bf16 v[92:95], v[144:147], v[200:203], v[92:95]
	v_mfma_f32_16x16x32_bf16 v[88:91], v[160:163], v[200:203], v[88:91]
	v_mfma_f32_16x16x32_bf16 v[76:79], v[144:147], v[208:211], v[76:79]
	v_mfma_f32_16x16x32_bf16 v[72:75], v[160:163], v[208:211], v[72:75]
	v_mfma_f32_16x16x32_bf16 v[124:127], v[156:159], v[188:191], v[124:127]
	v_mfma_f32_16x16x32_bf16 v[120:123], v[164:167], v[188:191], v[120:123]
	v_mfma_f32_16x16x32_bf16 v[108:111], v[156:159], v[196:199], v[108:111]
	v_mfma_f32_16x16x32_bf16 v[104:107], v[164:167], v[196:199], v[104:107]
	v_mfma_f32_16x16x32_bf16 v[92:95], v[156:159], v[204:207], v[92:95]
	v_mfma_f32_16x16x32_bf16 v[88:91], v[164:167], v[204:207], v[88:91]
	v_mfma_f32_16x16x32_bf16 v[76:79], v[156:159], v[212:215], v[76:79]
	v_mfma_f32_16x16x32_bf16 v[72:75], v[164:167], v[212:215], v[72:75]
	v_mfma_f32_16x16x32_bf16 v[116:119], v[168:171], v[184:187], v[116:119]
	v_mfma_f32_16x16x32_bf16 v[112:115], v[176:179], v[184:187], v[112:115]
	v_mfma_f32_16x16x32_bf16 v[100:103], v[168:171], v[192:195], v[100:103]
	v_mfma_f32_16x16x32_bf16 v[96:99], v[176:179], v[192:195], v[96:99]
	v_mfma_f32_16x16x32_bf16 v[84:87], v[168:171], v[200:203], v[84:87]
	v_mfma_f32_16x16x32_bf16 v[80:83], v[176:179], v[200:203], v[80:83]
	v_mfma_f32_16x16x32_bf16 v[68:71], v[168:171], v[208:211], v[68:71]
	v_mfma_f32_16x16x32_bf16 v[64:67], v[176:179], v[208:211], v[64:67]
	v_mfma_f32_16x16x32_bf16 v[116:119], v[172:175], v[188:191], v[116:119]
	v_mfma_f32_16x16x32_bf16 v[112:115], v[180:183], v[188:191], v[112:115]
	v_mfma_f32_16x16x32_bf16 v[100:103], v[172:175], v[196:199], v[100:103]
	v_mfma_f32_16x16x32_bf16 v[96:99], v[180:183], v[196:199], v[96:99]
	v_mfma_f32_16x16x32_bf16 v[84:87], v[172:175], v[204:207], v[84:87]
	v_mfma_f32_16x16x32_bf16 v[80:83], v[180:183], v[204:207], v[80:83]
	v_mfma_f32_16x16x32_bf16 v[68:71], v[172:175], v[212:215], v[68:71]
	v_mfma_f32_16x16x32_bf16 v[64:67], v[180:183], v[212:215], v[64:67]
	s_barrier
; #define PG8_STAGE(bufoff, gbase, voff) do { _Pragma("unroll") for (int _i = 0; _i < 2; ++_i) \
;         __builtin_amdgcn_global_load_lds((const unsigned*)((const char*)(gbase) + (voff)[_i]), (LAS unsigned*)(lds + (bufoff) + ldsw + _i * 8192), 16, 0, 0); } while (0)
; #define PG8_LDA(dst, b, h) do { _Pragma("unroll") for (int m = 0; m < 4; ++m) _Pragma("unroll") for (int k = 0; k < 2; ++k) dst[m][k] = *(const LAS bf16x8*)(lds + PG8_SA(b, h) + aoff + m * 2048 + k * 1024); } while (0)
; #define PG8_MMA(ai, bj, At, Bt) do { __builtin_amdgcn_s_setprio(1); _Pragma("unroll") for (int m = 0; m < 4; ++m) _Pragma("unroll") for (int n = 0; n < 2; ++n) _Pragma("unroll") for (int k = 0; k < 2; ++k) \
;         acc[ai][bj][m][n] = __builtin_amdgcn_mfma_f32_16x16x32_bf16(Bt[n][k], At[m][k], acc[ai][bj][m][n], 0, 0, 0); __builtin_amdgcn_s_setprio(0); } while (0)
; #define PG8_WAIT_V(n) asm volatile("s_waitcnt vmcnt(" #n ")" ::: "memory")
; #define PG8_WAIT_L(n) asm volatile("s_waitcnt lgkmcnt(" #n ")" ::: "memory")
; #define PG8_BAR __builtin_amdgcn_s_barrier()
; #define PG8_SCHED __builtin_amdgcn_sched_barrier(0)
; template <class Epi, class Sched, bool ALIGN_EPI>
; __device__ __forceinline__ void gemm_phase(LAS unsigned char* lds, const Gemm g, const Sched& S, const Epi& E) {
;     ...
;             PG8_LDA(At, 1, 1); PG8_STAGE(PG8_SB(1, 0), b3, voffB); PG8_STAGE(PG8_SB(1, 1), b3 + hB, voffB); PG8_STAGE(PG8_SA(1, 0), a3, voffA);
;             PG8_WAIT_V(8); PG8_WAIT_L(0); PG8_BAR; PG8_MMA(1, 0, At, B0); PG8_MMA(1, 1, At, B1); PG8_BAR; PG8_SCHED;
;         }
;         if constexpr (ALIGN_EPI) { if (wr == 0) PG8_BAR; }
	s_add_i32 s18, s33, s59
	v_lshl_add_u64 v[216:217], v[216:217], 0, s[24:25]
	s_mov_b32 m0, s18
	ds_read_b128 v[184:187], v153 offset:49152
	ds_read_b128 v[188:191], v153 offset:50176
	ds_read_b128 v[192:195], v153 offset:51200
	ds_read_b128 v[196:199], v153 offset:52224
	ds_read_b128 v[200:203], v153 offset:53248
	ds_read_b128 v[204:207], v153 offset:54272
	ds_read_b128 v[208:211], v153 offset:55296
	ds_read_b128 v[212:215], v153 offset:56320
	global_load_lds_dwordx4 v[216:217], off
	s_add_i32 m0, s18, 0x2000
	s_add_u32 s18, s54, 0x40080
	v_lshl_add_u64 v[216:217], v[218:219], 0, s[24:25]
	s_addc_u32 s19, s55, 0
	s_add_i32 s33, s46, s59
	global_load_lds_dwordx4 v[216:217], off
	v_lshl_add_u64 v[216:217], s[18:19], 0, v[130:131]
	s_mov_b32 m0, s33
	s_nop 0
	global_load_lds_dwordx4 v[216:217], off
	v_lshl_add_u64 v[216:217], s[18:19], 0, v[134:135]
	s_add_i32 m0, s33, 0x2000
	s_nop 0
	global_load_lds_dwordx4 v[216:217], off
	v_lshl_add_u64 v[216:217], v[222:223], 0, s[24:25]
	s_mov_b32 m0, s66
	s_nop 0
	global_load_lds_dwordx4 v[216:217], off
	v_lshl_add_u64 v[216:217], v[224:225], 0, s[24:25]
	s_mov_b32 m0, s67
	s_nop 0
	global_load_lds_dwordx4 v[216:217], off
	s_waitcnt vmcnt(8)
	s_waitcnt lgkmcnt(0)
	s_barrier
	s_waitcnt lgkmcnt(0)
	v_mfma_f32_16x16x32_bf16 v[60:63], v[144:147], v[184:187], v[60:63]
	v_mfma_f32_16x16x32_bf16 v[56:59], v[160:163], v[184:187], v[56:59]
	v_mfma_f32_16x16x32_bf16 v[44:47], v[144:147], v[192:195], v[44:47]
	v_mfma_f32_16x16x32_bf16 v[40:43], v[160:163], v[192:195], v[40:43]
	v_mfma_f32_16x16x32_bf16 v[28:31], v[144:147], v[200:203], v[28:31]
	v_mfma_f32_16x16x32_bf16 v[24:27], v[160:163], v[200:203], v[24:27]
	v_mfma_f32_16x16x32_bf16 v[12:15], v[144:147], v[208:211], v[12:15]
	v_mfma_f32_16x16x32_bf16 v[8:11], v[160:163], v[208:211], v[8:11]
	v_mfma_f32_16x16x32_bf16 v[60:63], v[156:159], v[188:191], v[60:63]
	v_mfma_f32_16x16x32_bf16 v[56:59], v[164:167], v[188:191], v[56:59]
	v_mfma_f32_16x16x32_bf16 v[44:47], v[156:159], v[196:199], v[44:47]
	v_mfma_f32_16x16x32_bf16 v[40:43], v[164:167], v[196:199], v[40:43]
	v_mfma_f32_16x16x32_bf16 v[28:31], v[156:159], v[204:207], v[28:31]
	v_mfma_f32_16x16x32_bf16 v[24:27], v[164:167], v[204:207], v[24:27]
	v_mfma_f32_16x16x32_bf16 v[12:15], v[156:159], v[212:215], v[12:15]
	v_mfma_f32_16x16x32_bf16 v[8:11], v[164:167], v[212:215], v[8:11]
	v_mfma_f32_16x16x32_bf16 v[52:55], v[168:171], v[184:187], v[52:55]
	v_mfma_f32_16x16x32_bf16 v[48:51], v[176:179], v[184:187], v[48:51]
	v_mfma_f32_16x16x32_bf16 v[36:39], v[168:171], v[192:195], v[36:39]
	v_mfma_f32_16x16x32_bf16 v[32:35], v[176:179], v[192:195], v[32:35]
	v_mfma_f32_16x16x32_bf16 v[20:23], v[168:171], v[200:203], v[20:23]
	v_mfma_f32_16x16x32_bf16 v[16:19], v[176:179], v[200:203], v[16:19]
	v_mfma_f32_16x16x32_bf16 v[4:7], v[168:171], v[208:211], v[4:7]
	v_mfma_f32_16x16x32_bf16 v[0:3], v[176:179], v[208:211], v[0:3]
	v_mfma_f32_16x16x32_bf16 v[52:55], v[172:175], v[188:191], v[52:55]
	v_mfma_f32_16x16x32_bf16 v[48:51], v[180:183], v[188:191], v[48:51]
	v_mfma_f32_16x16x32_bf16 v[36:39], v[172:175], v[196:199], v[36:39]
	v_mfma_f32_16x16x32_bf16 v[32:35], v[180:183], v[196:199], v[32:35]
	v_mfma_f32_16x16x32_bf16 v[20:23], v[172:175], v[204:207], v[20:23]
	v_mfma_f32_16x16x32_bf16 v[16:19], v[180:183], v[204:207], v[16:19]
	v_mfma_f32_16x16x32_bf16 v[4:7], v[172:175], v[212:215], v[4:7]
	v_mfma_f32_16x16x32_bf16 v[0:3], v[180:183], v[212:215], v[0:3]
	s_barrier
	s_add_u32 s52, s52, 0x100
	s_addc_u32 s53, s53, 0
	s_add_u32 s44, s44, 0x100
	s_addc_u32 s45, s45, 0
	s_cmp_ge_i32 s47, s65
	s_mov_b32 s46, s47
	s_cbranch_scc0 .LBB0_1065

; #define PG8_STAGE(bufoff, gbase, voff) do { _Pragma("unroll") for (int _i = 0; _i < 2; ++_i) \
;         __builtin_amdgcn_global_load_lds((const unsigned*)((const char*)(gbase) + (voff)[_i]), (LAS unsigned*)(lds + (bufoff) + ldsw + _i * 8192), 16, 0, 0); } while (0)
; #define PG8_LDA(dst, b, h) do { _Pragma("unroll") for (int m = 0; m < 4; ++m) _Pragma("unroll") for (int k = 0; k < 2; ++k) dst[m][k] = *(const LAS bf16x8*)(lds + PG8_SA(b, h) + aoff + m * 2048 + k * 1024); } while (0)
; #define PG8_LDB(dst, b, h) do { _Pragma("unroll") for (int n = 0; n < 2; ++n) _Pragma("unroll") for (int k = 0; k < 2; ++k) dst[n][k] = *(const LAS bf16x8*)(lds + PG8_SB(b, h) + boff + n * 2048 + k * 1024); } while (0)
; #define PG8_MMA(ai, bj, At, Bt) do { __builtin_amdgcn_s_setprio(1); _Pragma("unroll") for (int m = 0; m < 4; ++m) _Pragma("unroll") for (int n = 0; n < 2; ++n) _Pragma("unroll") for (int k = 0; k < 2; ++k) \
;         acc[ai][bj][m][n] = __builtin_amdgcn_mfma_f32_16x16x32_bf16(Bt[n][k], At[m][k], acc[ai][bj][m][n], 0, 0, 0); __builtin_amdgcn_s_setprio(0); } while (0)
; #define PG8_WAIT_V(n) asm volatile("s_waitcnt vmcnt(" #n ")" ::: "memory")
; #define PG8_WAIT_L(n) asm volatile("s_waitcnt lgkmcnt(" #n ")" ::: "memory")
; #define PG8_BAR __builtin_amdgcn_s_barrier()
; #define PG8_SCHED __builtin_amdgcn_sched_barrier(0)
; template <class Epi, class Sched, bool ALIGN_EPI>
; __device__ __forceinline__ void gemm_phase(LAS unsigned char* lds, const Gemm g, const Sched& S, const Epi& E) {
;     ...
;             const bool last = (t == nt - 2);
;             const char* a1 = cA + (size_t)(t + 1) * kstep;
;             const char* a2 = last ? nA : cA + (size_t)(t + 2) * kstep; const char* b2 = last ? nB : cB + (size_t)(t + 2) * kstep;
;             const char* a3 = a2 + kstep; const char* b3 = b2 + kstep;
;             PG8_LDB(B0, 0, 0); PG8_LDB(B1, 0, 1); PG8_SCHED; PG8_LDA(At, 0, 0); PG8_STAGE(PG8_SA(1, 1), a1 + hA, voffA);
;             PG8_WAIT_V(8); PG8_WAIT_L(0); PG8_BAR; PG8_MMA(0, 0, At, B0); PG8_MMA(0, 1, At, B1); PG8_BAR; PG8_SCHED;
;             PG8_LDA(At, 0, 1); PG8_STAGE(PG8_SB(0, 0), b2, voffB); PG8_STAGE(PG8_SB(0, 1), b2 + hB, voffB); PG8_STAGE(PG8_SA(0, 0), a2, voffA);
;             PG8_WAIT_V(8); PG8_WAIT_L(0); PG8_BAR; PG8_MMA(1, 0, At, B0); PG8_MMA(1, 1, At, B1); PG8_BAR; PG8_SCHED;
.LBB0_1148:
	ds_read_b128 v[128:131], v184
	ds_read_b128 v[132:135], v184 offset:1024
	ds_read_b128 v[136:139], v184 offset:2048
	ds_read_b128 v[140:143], v184 offset:3072
	ds_read_b128 v[162:165], v185
	ds_read_b128 v[166:169], v185 offset:1024
	ds_read_b128 v[170:173], v185 offset:2048
	ds_read_b128 v[174:177], v185 offset:3072
	s_add_u32 s6, s4, 0xfff80080
	s_addc_u32 s7, s5, -1
	s_cmp_eq_u32 s46, 28
	s_cselect_b32 s55, s74, s7
	s_cselect_b32 s54, s75, s6
	s_cselect_b32 s7, s41, s45
	s_cselect_b32 s6, s76, s44
	v_lshl_add_u64 v[178:179], s[4:5], 0, v[154:155]
	s_add_i32 m0, s58, 0xc000
	ds_read_b128 v[188:191], v186
	ds_read_b128 v[192:195], v186 offset:1024
	ds_read_b128 v[196:199], v186 offset:2048
	ds_read_b128 v[200:203], v186 offset:3072
	ds_read_b128 v[204:207], v186 offset:4096
	ds_read_b128 v[208:211], v186 offset:5120
	ds_read_b128 v[212:215], v186 offset:6144
	ds_read_b128 v[216:219], v186 offset:7168
	global_load_lds_dwordx4 v[178:179], off
	v_lshl_add_u64 v[178:179], s[4:5], 0, v[156:157]
	s_add_i32 m0, s58, 0xe000
	s_nop 0
	global_load_lds_dwordx4 v[178:179], off
	s_waitcnt vmcnt(8)
	s_waitcnt lgkmcnt(0)
	s_barrier
	s_waitcnt lgkmcnt(0)
	v_mfma_f32_16x16x32_bf16 v[124:127], v[128:131], v[188:191], v[124:127]
	v_mfma_f32_16x16x32_bf16 v[116:119], v[136:139], v[188:191], v[116:119]
	v_mfma_f32_16x16x32_bf16 v[108:111], v[128:131], v[196:199], v[108:111]
	v_mfma_f32_16x16x32_bf16 v[100:103], v[136:139], v[196:199], v[100:103]
	v_mfma_f32_16x16x32_bf16 v[92:95], v[128:131], v[204:207], v[92:95]
	v_mfma_f32_16x16x32_bf16 v[84:87], v[136:139], v[204:207], v[84:87]
	v_mfma_f32_16x16x32_bf16 v[76:79], v[128:131], v[212:215], v[76:79]
	v_mfma_f32_16x16x32_bf16 v[68:71], v[136:139], v[212:215], v[68:71]
	v_mfma_f32_16x16x32_bf16 v[124:127], v[132:135], v[192:195], v[124:127]
	v_mfma_f32_16x16x32_bf16 v[116:119], v[140:143], v[192:195], v[116:119]
	v_mfma_f32_16x16x32_bf16 v[108:111], v[132:135], v[200:203], v[108:111]
	v_mfma_f32_16x16x32_bf16 v[100:103], v[140:143], v[200:203], v[100:103]
	v_mfma_f32_16x16x32_bf16 v[92:95], v[132:135], v[208:211], v[92:95]
	v_mfma_f32_16x16x32_bf16 v[84:87], v[140:143], v[208:211], v[84:87]
	v_mfma_f32_16x16x32_bf16 v[76:79], v[132:135], v[216:219], v[76:79]
	v_mfma_f32_16x16x32_bf16 v[68:71], v[140:143], v[216:219], v[68:71]
	v_mfma_f32_16x16x32_bf16 v[120:123], v[162:165], v[188:191], v[120:123]
	v_mfma_f32_16x16x32_bf16 v[112:115], v[170:173], v[188:191], v[112:115]
	v_mfma_f32_16x16x32_bf16 v[104:107], v[162:165], v[196:199], v[104:107]
	v_mfma_f32_16x16x32_bf16 v[96:99], v[170:173], v[196:199], v[96:99]
	v_mfma_f32_16x16x32_bf16 v[88:91], v[162:165], v[204:207], v[88:91]
	v_mfma_f32_16x16x32_bf16 v[80:83], v[170:173], v[204:207], v[80:83]
	v_mfma_f32_16x16x32_bf16 v[72:75], v[162:165], v[212:215], v[72:75]
	v_mfma_f32_16x16x32_bf16 v[64:67], v[170:173], v[212:215], v[64:67]
	v_mfma_f32_16x16x32_bf16 v[120:123], v[166:169], v[192:195], v[120:123]
	v_mfma_f32_16x16x32_bf16 v[112:115], v[174:177], v[192:195], v[112:115]
	v_mfma_f32_16x16x32_bf16 v[104:107], v[166:169], v[200:203], v[104:107]
	v_mfma_f32_16x16x32_bf16 v[96:99], v[174:177], v[200:203], v[96:99]
	v_mfma_f32_16x16x32_bf16 v[88:91], v[166:169], v[208:211], v[88:91]
	v_mfma_f32_16x16x32_bf16 v[80:83], v[174:177], v[208:211], v[80:83]
	v_mfma_f32_16x16x32_bf16 v[72:75], v[166:169], v[216:219], v[72:75]
	v_mfma_f32_16x16x32_bf16 v[64:67], v[174:177], v[216:219], v[64:67]
	s_barrier
	s_add_i32 s18, s66, s39
	v_lshl_add_u64 v[178:179], s[6:7], 0, v[148:149]
	s_mov_b32 m0, s18
	ds_read_b128 v[188:191], v186 offset:16384
	ds_read_b128 v[192:195], v186 offset:17408
	ds_read_b128 v[196:199], v186 offset:18432
	ds_read_b128 v[200:203], v186 offset:19456
	ds_read_b128 v[204:207], v186 offset:20480
	ds_read_b128 v[208:211], v186 offset:21504
	ds_read_b128 v[212:215], v186 offset:22528
	ds_read_b128 v[216:219], v186 offset:23552
	global_load_lds_dwordx4 v[178:179], off
	s_add_i32 m0, s18, 0x2000
	s_add_u32 s18, s6, 0x80000
	v_lshl_add_u64 v[222:223], s[6:7], 0, v[144:145]
	s_addc_u32 s19, s7, 0
	s_add_i32 s33, s67, s39
	global_load_lds_dwordx4 v[222:223], off
	v_lshl_add_u64 v[224:225], s[18:19], 0, v[148:149]
	s_mov_b32 m0, s33
	v_lshl_add_u64 v[226:227], s[54:55], 0, v[146:147]
	global_load_lds_dwordx4 v[224:225], off
	v_lshl_add_u64 v[224:225], s[18:19], 0, v[144:145]
	s_add_i32 m0, s33, 0x2000
	s_nop 0
	global_load_lds_dwordx4 v[224:225], off
	v_lshl_add_u64 v[224:225], s[54:55], 0, v[150:151]
	s_mov_b32 m0, s58
	s_nop 0
	global_load_lds_dwordx4 v[224:225], off
	s_mov_b32 m0, s59
	s_nop 0
	global_load_lds_dwordx4 v[226:227], off
	s_waitcnt vmcnt(8)
	s_waitcnt lgkmcnt(0)
	s_barrier
; #define PG8_STAGE(bufoff, gbase, voff) do { _Pragma("unroll") for (int _i = 0; _i < 2; ++_i) \
;         __builtin_amdgcn_global_load_lds((const unsigned*)((const char*)(gbase) + (voff)[_i]), (LAS unsigned*)(lds + (bufoff) + ldsw + _i * 8192), 16, 0, 0); } while (0)
; #define PG8_LDA(dst, b, h) do { _Pragma("unroll") for (int m = 0; m < 4; ++m) _Pragma("unroll") for (int k = 0; k < 2; ++k) dst[m][k] = *(const LAS bf16x8*)(lds + PG8_SA(b, h) + aoff + m * 2048 + k * 1024); } while (0)
; #define PG8_LDB(dst, b, h) do { _Pragma("unroll") for (int n = 0; n < 2; ++n) _Pragma("unroll") for (int k = 0; k < 2; ++k) dst[n][k] = *(const LAS bf16x8*)(lds + PG8_SB(b, h) + boff + n * 2048 + k * 1024); } while (0)
; #define PG8_MMA(ai, bj, At, Bt) do { __builtin_amdgcn_s_setprio(1); _Pragma("unroll") for (int m = 0; m < 4; ++m) _Pragma("unroll") for (int n = 0; n < 2; ++n) _Pragma("unroll") for (int k = 0; k < 2; ++k) \
;         acc[ai][bj][m][n] = __builtin_amdgcn_mfma_f32_16x16x32_bf16(Bt[n][k], At[m][k], acc[ai][bj][m][n], 0, 0, 0); __builtin_amdgcn_s_setprio(0); } while (0)
; #define PG8_WAIT_V(n) asm volatile("s_waitcnt vmcnt(" #n ")" ::: "memory")
; #define PG8_WAIT_L(n) asm volatile("s_waitcnt lgkmcnt(" #n ")" ::: "memory")
; #define PG8_BAR __builtin_amdgcn_s_barrier()
; #define PG8_SCHED __builtin_amdgcn_sched_barrier(0)
; template <class Epi, class Sched, bool ALIGN_EPI>
; __device__ __forceinline__ void gemm_phase(LAS unsigned char* lds, const Gemm g, const Sched& S, const Epi& E) {
;     ...
;             PG8_WAIT_V(8); PG8_WAIT_L(0); PG8_BAR; PG8_MMA(1, 0, At, B0); PG8_MMA(1, 1, At, B1); PG8_BAR; PG8_SCHED;
;             PG8_LDB(B0, 1, 0); PG8_LDB(B1, 1, 1); PG8_SCHED; PG8_LDA(At, 1, 0); PG8_STAGE(PG8_SA(0, 1), a2 + hA, voffA);
;             PG8_WAIT_V(8); PG8_WAIT_L(0); PG8_BAR; PG8_MMA(0, 0, At, B0); PG8_MMA(0, 1, At, B1); PG8_BAR; PG8_SCHED;
	s_waitcnt lgkmcnt(0)
	v_mfma_f32_16x16x32_bf16 v[60:63], v[128:131], v[188:191], v[60:63]
	v_mfma_f32_16x16x32_bf16 v[52:55], v[136:139], v[188:191], v[52:55]
	v_mfma_f32_16x16x32_bf16 v[44:47], v[128:131], v[196:199], v[44:47]
	v_mfma_f32_16x16x32_bf16 v[36:39], v[136:139], v[196:199], v[36:39]
	v_mfma_f32_16x16x32_bf16 v[28:31], v[128:131], v[204:207], v[28:31]
	v_mfma_f32_16x16x32_bf16 v[20:23], v[136:139], v[204:207], v[20:23]
	v_mfma_f32_16x16x32_bf16 v[12:15], v[128:131], v[212:215], v[12:15]
	v_mfma_f32_16x16x32_bf16 v[4:7], v[136:139], v[212:215], v[4:7]
	v_mfma_f32_16x16x32_bf16 v[60:63], v[132:135], v[192:195], v[60:63]
	v_mfma_f32_16x16x32_bf16 v[52:55], v[140:143], v[192:195], v[52:55]
	v_mfma_f32_16x16x32_bf16 v[44:47], v[132:135], v[200:203], v[44:47]
	v_mfma_f32_16x16x32_bf16 v[36:39], v[140:143], v[200:203], v[36:39]
	v_mfma_f32_16x16x32_bf16 v[28:31], v[132:135], v[208:211], v[28:31]
	v_mfma_f32_16x16x32_bf16 v[20:23], v[140:143], v[208:211], v[20:23]
	v_mfma_f32_16x16x32_bf16 v[12:15], v[132:135], v[216:219], v[12:15]
	v_mfma_f32_16x16x32_bf16 v[4:7], v[140:143], v[216:219], v[4:7]
	v_mfma_f32_16x16x32_bf16 v[56:59], v[162:165], v[188:191], v[56:59]
	v_mfma_f32_16x16x32_bf16 v[48:51], v[170:173], v[188:191], v[48:51]
	v_mfma_f32_16x16x32_bf16 v[40:43], v[162:165], v[196:199], v[40:43]
	v_mfma_f32_16x16x32_bf16 v[32:35], v[170:173], v[196:199], v[32:35]
	v_mfma_f32_16x16x32_bf16 v[24:27], v[162:165], v[204:207], v[24:27]
	v_mfma_f32_16x16x32_bf16 v[16:19], v[170:173], v[204:207], v[16:19]
	v_mfma_f32_16x16x32_bf16 v[8:11], v[162:165], v[212:215], v[8:11]
	v_mfma_f32_16x16x32_bf16 v[0:3], v[170:173], v[212:215], v[0:3]
	v_mfma_f32_16x16x32_bf16 v[56:59], v[166:169], v[192:195], v[56:59]
	v_mfma_f32_16x16x32_bf16 v[48:51], v[174:177], v[192:195], v[48:51]
	v_mfma_f32_16x16x32_bf16 v[40:43], v[166:169], v[200:203], v[40:43]
	v_mfma_f32_16x16x32_bf16 v[32:35], v[174:177], v[200:203], v[32:35]
	v_mfma_f32_16x16x32_bf16 v[24:27], v[166:169], v[208:211], v[24:27]
	v_mfma_f32_16x16x32_bf16 v[16:19], v[174:177], v[208:211], v[16:19]
	v_mfma_f32_16x16x32_bf16 v[8:11], v[166:169], v[216:219], v[8:11]
	v_mfma_f32_16x16x32_bf16 v[0:3], v[174:177], v[216:219], v[0:3]
	s_barrier
	s_add_i32 s33, 0, 0x18000
	s_add_i32 s47, 0, 0x1c000
	v_add_u32_e32 v140, s33, v182
	v_add_u32_e32 v174, s47, v182
	ds_read_b128 v[128:131], v140
	ds_read_b128 v[132:135], v140 offset:1024
	ds_read_b128 v[136:139], v140 offset:2048
	ds_read_b128 v[140:143], v140 offset:3072
	ds_read_b128 v[162:165], v174
	ds_read_b128 v[166:169], v174 offset:1024
	ds_read_b128 v[170:173], v174 offset:2048
	ds_read_b128 v[174:177], v174 offset:3072
	s_add_u32 s18, s54, 0x80000
	s_addc_u32 s19, s55, 0
	s_mov_b32 m0, s60
	v_lshl_add_u64 v[228:229], s[18:19], 0, v[150:151]
	ds_read_b128 v[188:191], v186 offset:32768
	ds_read_b128 v[192:195], v186 offset:33792
	ds_read_b128 v[196:199], v186 offset:34816
	ds_read_b128 v[200:203], v186 offset:35840
	ds_read_b128 v[204:207], v186 offset:36864
	ds_read_b128 v[208:211], v186 offset:37888
	ds_read_b128 v[212:215], v186 offset:38912
	ds_read_b128 v[216:219], v186 offset:39936
	global_load_lds_dwordx4 v[228:229], off
	v_lshl_add_u64 v[228:229], s[18:19], 0, v[146:147]
	s_mov_b32 m0, s61
	s_nop 0
	global_load_lds_dwordx4 v[228:229], off
	s_waitcnt vmcnt(8)
	s_waitcnt lgkmcnt(0)
	s_barrier
	s_waitcnt lgkmcnt(0)
	v_mfma_f32_16x16x32_bf16 v[124:127], v[128:131], v[188:191], v[124:127]
	v_mfma_f32_16x16x32_bf16 v[116:119], v[136:139], v[188:191], v[116:119]
	v_mfma_f32_16x16x32_bf16 v[108:111], v[128:131], v[196:199], v[108:111]
	v_mfma_f32_16x16x32_bf16 v[100:103], v[136:139], v[196:199], v[100:103]
	v_mfma_f32_16x16x32_bf16 v[92:95], v[128:131], v[204:207], v[92:95]
	v_mfma_f32_16x16x32_bf16 v[84:87], v[136:139], v[204:207], v[84:87]
	v_mfma_f32_16x16x32_bf16 v[76:79], v[128:131], v[212:215], v[76:79]
	v_mfma_f32_16x16x32_bf16 v[68:71], v[136:139], v[212:215], v[68:71]
	v_mfma_f32_16x16x32_bf16 v[124:127], v[132:135], v[192:195], v[124:127]
	v_mfma_f32_16x16x32_bf16 v[116:119], v[140:143], v[192:195], v[116:119]
	v_mfma_f32_16x16x32_bf16 v[108:111], v[132:135], v[200:203], v[108:111]
	v_mfma_f32_16x16x32_bf16 v[100:103], v[140:143], v[200:203], v[100:103]
	v_mfma_f32_16x16x32_bf16 v[92:95], v[132:135], v[208:211], v[92:95]
	v_mfma_f32_16x16x32_bf16 v[84:87], v[140:143], v[208:211], v[84:87]
	v_mfma_f32_16x16x32_bf16 v[76:79], v[132:135], v[216:219], v[76:79]
	v_mfma_f32_16x16x32_bf16 v[68:71], v[140:143], v[216:219], v[68:71]
	v_mfma_f32_16x16x32_bf16 v[120:123], v[162:165], v[188:191], v[120:123]
	v_mfma_f32_16x16x32_bf16 v[112:115], v[170:173], v[188:191], v[112:115]
	v_mfma_f32_16x16x32_bf16 v[104:107], v[162:165], v[196:199], v[104:107]
	v_mfma_f32_16x16x32_bf16 v[96:99], v[170:173], v[196:199], v[96:99]
	v_mfma_f32_16x16x32_bf16 v[88:91], v[162:165], v[204:207], v[88:91]
	v_mfma_f32_16x16x32_bf16 v[80:83], v[170:173], v[204:207], v[80:83]
	v_mfma_f32_16x16x32_bf16 v[72:75], v[162:165], v[212:215], v[72:75]
	v_mfma_f32_16x16x32_bf16 v[64:67], v[170:173], v[212:215], v[64:67]
	v_mfma_f32_16x16x32_bf16 v[120:123], v[166:169], v[192:195], v[120:123]
	v_mfma_f32_16x16x32_bf16 v[112:115], v[174:177], v[192:195], v[112:115]
	v_mfma_f32_16x16x32_bf16 v[104:107], v[166:169], v[200:203], v[104:107]
	v_mfma_f32_16x16x32_bf16 v[96:99], v[174:177], v[200:203], v[96:99]
	v_mfma_f32_16x16x32_bf16 v[88:91], v[166:169], v[208:211], v[88:91]
	v_mfma_f32_16x16x32_bf16 v[80:83], v[174:177], v[208:211], v[80:83]
	v_mfma_f32_16x16x32_bf16 v[72:75], v[166:169], v[216:219], v[72:75]
	v_mfma_f32_16x16x32_bf16 v[64:67], v[174:177], v[216:219], v[64:67]
	s_barrier
; #define PG8_STAGE(bufoff, gbase, voff) do { _Pragma("unroll") for (int _i = 0; _i < 2; ++_i) \
;         __builtin_amdgcn_global_load_lds((const unsigned*)((const char*)(gbase) + (voff)[_i]), (LAS unsigned*)(lds + (bufoff) + ldsw + _i * 8192), 16, 0, 0); } while (0)
; #define PG8_LDA(dst, b, h) do { _Pragma("unroll") for (int m = 0; m < 4; ++m) _Pragma("unroll") for (int k = 0; k < 2; ++k) dst[m][k] = *(const LAS bf16x8*)(lds + PG8_SA(b, h) + aoff + m * 2048 + k * 1024); } while (0)
; #define PG8_MMA(ai, bj, At, Bt) do { __builtin_amdgcn_s_setprio(1); _Pragma("unroll") for (int m = 0; m < 4; ++m) _Pragma("unroll") for (int n = 0; n < 2; ++n) _Pragma("unroll") for (int k = 0; k < 2; ++k) \
;         acc[ai][bj][m][n] = __builtin_amdgcn_mfma_f32_16x16x32_bf16(Bt[n][k], At[m][k], acc[ai][bj][m][n], 0, 0, 0); __builtin_amdgcn_s_setprio(0); } while (0)
; #define PG8_WAIT_V(n) asm volatile("s_waitcnt vmcnt(" #n ")" ::: "memory")
; #define PG8_WAIT_L(n) asm volatile("s_waitcnt lgkmcnt(" #n ")" ::: "memory")
; #define PG8_BAR __builtin_amdgcn_s_barrier()
; #define PG8_SCHED __builtin_amdgcn_sched_barrier(0)
; template <class Epi, class Sched, bool ALIGN_EPI>
; __device__ __forceinline__ void gemm_phase(LAS unsigned char* lds, const Gemm g, const Sched& S, const Epi& E) {
;     ...
;             PG8_LDA(At, 1, 1); PG8_STAGE(PG8_SB(1, 0), b3, voffB); PG8_STAGE(PG8_SB(1, 1), b3 + hB, voffB); PG8_STAGE(PG8_SA(1, 0), a3, voffA);
;             PG8_WAIT_V(8); PG8_WAIT_L(0); PG8_BAR; PG8_MMA(1, 0, At, B0); PG8_MMA(1, 1, At, B1); PG8_BAR; PG8_SCHED;
;         }
;         if constexpr (ALIGN_EPI) { if (wr == 0) PG8_BAR; }
	s_add_i32 s18, s33, s39
	v_lshl_add_u64 v[178:179], v[178:179], 0, s[26:27]
	s_mov_b32 m0, s18
	ds_read_b128 v[188:191], v186 offset:49152
	ds_read_b128 v[192:195], v186 offset:50176
	ds_read_b128 v[196:199], v186 offset:51200
	ds_read_b128 v[200:203], v186 offset:52224
	ds_read_b128 v[204:207], v186 offset:53248
	ds_read_b128 v[208:211], v186 offset:54272
	ds_read_b128 v[212:215], v186 offset:55296
	ds_read_b128 v[216:219], v186 offset:56320
	global_load_lds_dwordx4 v[178:179], off
	s_add_i32 m0, s18, 0x2000
	s_add_u32 s6, s6, 0x80080
	v_lshl_add_u64 v[178:179], v[222:223], 0, s[26:27]
	s_addc_u32 s7, s7, 0
	s_add_i32 s18, s47, s39
	global_load_lds_dwordx4 v[178:179], off
	v_lshl_add_u64 v[178:179], s[6:7], 0, v[148:149]
	s_mov_b32 m0, s18
	s_nop 0
	global_load_lds_dwordx4 v[178:179], off
	v_lshl_add_u64 v[178:179], s[6:7], 0, v[144:145]
	s_add_i32 m0, s18, 0x2000
	s_nop 0
	global_load_lds_dwordx4 v[178:179], off
	v_lshl_add_u64 v[178:179], v[224:225], 0, s[26:27]
	s_mov_b32 m0, s62
	s_nop 0
	global_load_lds_dwordx4 v[178:179], off
	v_lshl_add_u64 v[178:179], v[226:227], 0, s[26:27]
	s_mov_b32 m0, s63
	s_nop 0
	global_load_lds_dwordx4 v[178:179], off
	s_waitcnt vmcnt(8)
	s_waitcnt lgkmcnt(0)
	s_barrier
	s_waitcnt lgkmcnt(0)
	v_mfma_f32_16x16x32_bf16 v[60:63], v[128:131], v[188:191], v[60:63]
	v_mfma_f32_16x16x32_bf16 v[52:55], v[136:139], v[188:191], v[52:55]
	v_mfma_f32_16x16x32_bf16 v[44:47], v[128:131], v[196:199], v[44:47]
	v_mfma_f32_16x16x32_bf16 v[36:39], v[136:139], v[196:199], v[36:39]
	v_mfma_f32_16x16x32_bf16 v[28:31], v[128:131], v[204:207], v[28:31]
	v_mfma_f32_16x16x32_bf16 v[20:23], v[136:139], v[204:207], v[20:23]
	v_mfma_f32_16x16x32_bf16 v[12:15], v[128:131], v[212:215], v[12:15]
	v_mfma_f32_16x16x32_bf16 v[4:7], v[136:139], v[212:215], v[4:7]
	v_mfma_f32_16x16x32_bf16 v[60:63], v[132:135], v[192:195], v[60:63]
	v_mfma_f32_16x16x32_bf16 v[52:55], v[140:143], v[192:195], v[52:55]
	v_mfma_f32_16x16x32_bf16 v[44:47], v[132:135], v[200:203], v[44:47]
	v_mfma_f32_16x16x32_bf16 v[36:39], v[140:143], v[200:203], v[36:39]
	v_mfma_f32_16x16x32_bf16 v[28:31], v[132:135], v[208:211], v[28:31]
	v_mfma_f32_16x16x32_bf16 v[20:23], v[140:143], v[208:211], v[20:23]
	v_mfma_f32_16x16x32_bf16 v[12:15], v[132:135], v[216:219], v[12:15]
	v_mfma_f32_16x16x32_bf16 v[4:7], v[140:143], v[216:219], v[4:7]
	v_mfma_f32_16x16x32_bf16 v[56:59], v[162:165], v[188:191], v[56:59]
	v_mfma_f32_16x16x32_bf16 v[48:51], v[170:173], v[188:191], v[48:51]
	v_mfma_f32_16x16x32_bf16 v[40:43], v[162:165], v[196:199], v[40:43]
	v_mfma_f32_16x16x32_bf16 v[32:35], v[170:173], v[196:199], v[32:35]
	v_mfma_f32_16x16x32_bf16 v[24:27], v[162:165], v[204:207], v[24:27]
	v_mfma_f32_16x16x32_bf16 v[16:19], v[170:173], v[204:207], v[16:19]
	v_mfma_f32_16x16x32_bf16 v[8:11], v[162:165], v[212:215], v[8:11]
	v_mfma_f32_16x16x32_bf16 v[0:3], v[170:173], v[212:215], v[0:3]
	v_mfma_f32_16x16x32_bf16 v[56:59], v[166:169], v[192:195], v[56:59]
	v_mfma_f32_16x16x32_bf16 v[48:51], v[174:177], v[192:195], v[48:51]
	v_mfma_f32_16x16x32_bf16 v[40:43], v[166:169], v[200:203], v[40:43]
	v_mfma_f32_16x16x32_bf16 v[32:35], v[174:177], v[200:203], v[32:35]
	v_mfma_f32_16x16x32_bf16 v[24:27], v[166:169], v[208:211], v[24:27]
	v_mfma_f32_16x16x32_bf16 v[16:19], v[174:177], v[208:211], v[16:19]
	v_mfma_f32_16x16x32_bf16 v[8:11], v[166:169], v[216:219], v[8:11]
	v_mfma_f32_16x16x32_bf16 v[0:3], v[174:177], v[216:219], v[0:3]
	s_barrier
	s_add_i32 s46, s46, 2
	s_add_u32 s4, s4, 0x100
	s_addc_u32 s5, s5, 0
	s_add_u32 s44, s44, 0x100
	s_addc_u32 s45, s45, 0
	s_cmp_gt_u32 s46, 29
	s_cbranch_scc0 .LBB0_1148
	s_and_b64 vcc, exec, s[30:31]
	s_cbranch_vccz .LBB0_1151
	s_barrier

; #define PG8_STAGE(bufoff, gbase, voff) do { _Pragma("unroll") for (int _i = 0; _i < 2; ++_i) \
;         __builtin_amdgcn_global_load_lds((const unsigned*)((const char*)(gbase) + (voff)[_i]), (LAS unsigned*)(lds + (bufoff) + ldsw + _i * 8192), 16, 0, 0); } while (0)
; #define PG8_LDA(dst, b, h) do { _Pragma("unroll") for (int m = 0; m < 4; ++m) _Pragma("unroll") for (int k = 0; k < 2; ++k) dst[m][k] = *(const LAS bf16x8*)(lds + PG8_SA(b, h) + aoff + m * 2048 + k * 1024); } while (0)
; #define PG8_LDB(dst, b, h) do { _Pragma("unroll") for (int n = 0; n < 2; ++n) _Pragma("unroll") for (int k = 0; k < 2; ++k) dst[n][k] = *(const LAS bf16x8*)(lds + PG8_SB(b, h) + boff + n * 2048 + k * 1024); } while (0)
; #define PG8_MMA(ai, bj, At, Bt) do { __builtin_amdgcn_s_setprio(1); _Pragma("unroll") for (int m = 0; m < 4; ++m) _Pragma("unroll") for (int n = 0; n < 2; ++n) _Pragma("unroll") for (int k = 0; k < 2; ++k) \
;         acc[ai][bj][m][n] = __builtin_amdgcn_mfma_f32_16x16x32_bf16(Bt[n][k], At[m][k], acc[ai][bj][m][n], 0, 0, 0); __builtin_amdgcn_s_setprio(0); } while (0)
; #define PG8_WAIT_V(n) asm volatile("s_waitcnt vmcnt(" #n ")" ::: "memory")
; #define PG8_WAIT_L(n) asm volatile("s_waitcnt lgkmcnt(" #n ")" ::: "memory")
; #define PG8_BAR __builtin_amdgcn_s_barrier()
; #define PG8_SCHED __builtin_amdgcn_sched_barrier(0)
; template <class Epi, class Sched, bool ALIGN_EPI>
; __device__ __forceinline__ void gemm_phase(LAS unsigned char* lds, const Gemm g, const Sched& S, const Epi& E) {
;     ...
;             const bool last = (t == nt - 2);
;             const char* a1 = cA + (size_t)(t + 1) * kstep;
;             const char* a2 = last ? nA : cA + (size_t)(t + 2) * kstep; const char* b2 = last ? nB : cB + (size_t)(t + 2) * kstep;
;             const char* a3 = a2 + kstep; const char* b3 = b2 + kstep;
;             PG8_LDB(B0, 0, 0); PG8_LDB(B1, 0, 1); PG8_SCHED; PG8_LDA(At, 0, 0); PG8_STAGE(PG8_SA(1, 1), a1 + hA, voffA);
;             PG8_WAIT_V(8); PG8_WAIT_L(0); PG8_BAR; PG8_MMA(0, 0, At, B0); PG8_MMA(0, 1, At, B1); PG8_BAR; PG8_SCHED;
;             PG8_LDA(At, 0, 1); PG8_STAGE(PG8_SB(0, 0), b2, voffB); PG8_STAGE(PG8_SB(0, 1), b2 + hB, voffB); PG8_STAGE(PG8_SA(0, 0), a2, voffA);
;             PG8_WAIT_V(8); PG8_WAIT_L(0); PG8_BAR; PG8_MMA(1, 0, At, B0); PG8_MMA(1, 1, At, B1); PG8_BAR; PG8_SCHED;
.LBB0_1234:
	ds_read_b128 v[144:147], v151
	ds_read_b128 v[156:159], v151 offset:1024
	ds_read_b128 v[160:163], v151 offset:2048
	ds_read_b128 v[164:167], v151 offset:3072
	ds_read_b128 v[168:171], v152
	ds_read_b128 v[172:175], v152 offset:1024
	ds_read_b128 v[176:179], v152 offset:2048
	ds_read_b128 v[180:183], v152 offset:3072
	s_add_u32 s18, s38, 0xffea0080
	s_addc_u32 s19, s39, -1
	s_cmpk_eq_i32 s46, 0x54
	s_cselect_b32 s43, s70, s19
	s_cselect_b32 s42, s71, s18
	s_cselect_b32 s41, s27, s45
	s_cselect_b32 s40, s72, s44
	v_lshl_add_u64 v[216:217], s[38:39], 0, v[136:137]
	s_add_i32 m0, s55, 0xc000
	ds_read_b128 v[184:187], v153
	ds_read_b128 v[188:191], v153 offset:1024
	ds_read_b128 v[192:195], v153 offset:2048
	ds_read_b128 v[196:199], v153 offset:3072
	ds_read_b128 v[200:203], v153 offset:4096
	ds_read_b128 v[204:207], v153 offset:5120
	ds_read_b128 v[208:211], v153 offset:6144
	ds_read_b128 v[212:215], v153 offset:7168
	global_load_lds_dwordx4 v[216:217], off
	v_lshl_add_u64 v[216:217], s[38:39], 0, v[138:139]
	s_add_i32 m0, s55, 0xe000
	s_nop 0
	global_load_lds_dwordx4 v[216:217], off
	s_waitcnt vmcnt(8)
	s_waitcnt lgkmcnt(0)
	s_barrier
	s_waitcnt lgkmcnt(0)
	v_mfma_f32_16x16x32_bf16 v[124:127], v[144:147], v[184:187], v[124:127]
	v_mfma_f32_16x16x32_bf16 v[120:123], v[160:163], v[184:187], v[120:123]
	v_mfma_f32_16x16x32_bf16 v[108:111], v[144:147], v[192:195], v[108:111]
	v_mfma_f32_16x16x32_bf16 v[104:107], v[160:163], v[192:195], v[104:107]
	v_mfma_f32_16x16x32_bf16 v[92:95], v[144:147], v[200:203], v[92:95]
	v_mfma_f32_16x16x32_bf16 v[88:91], v[160:163], v[200:203], v[88:91]
	v_mfma_f32_16x16x32_bf16 v[76:79], v[144:147], v[208:211], v[76:79]
	v_mfma_f32_16x16x32_bf16 v[72:75], v[160:163], v[208:211], v[72:75]
	v_mfma_f32_16x16x32_bf16 v[124:127], v[156:159], v[188:191], v[124:127]
	v_mfma_f32_16x16x32_bf16 v[120:123], v[164:167], v[188:191], v[120:123]
	v_mfma_f32_16x16x32_bf16 v[108:111], v[156:159], v[196:199], v[108:111]
	v_mfma_f32_16x16x32_bf16 v[104:107], v[164:167], v[196:199], v[104:107]
	v_mfma_f32_16x16x32_bf16 v[92:95], v[156:159], v[204:207], v[92:95]
	v_mfma_f32_16x16x32_bf16 v[88:91], v[164:167], v[204:207], v[88:91]
	v_mfma_f32_16x16x32_bf16 v[76:79], v[156:159], v[212:215], v[76:79]
	v_mfma_f32_16x16x32_bf16 v[72:75], v[164:167], v[212:215], v[72:75]
	v_mfma_f32_16x16x32_bf16 v[116:119], v[168:171], v[184:187], v[116:119]
	v_mfma_f32_16x16x32_bf16 v[112:115], v[176:179], v[184:187], v[112:115]
	v_mfma_f32_16x16x32_bf16 v[100:103], v[168:171], v[192:195], v[100:103]
	v_mfma_f32_16x16x32_bf16 v[96:99], v[176:179], v[192:195], v[96:99]
	v_mfma_f32_16x16x32_bf16 v[84:87], v[168:171], v[200:203], v[84:87]
	v_mfma_f32_16x16x32_bf16 v[80:83], v[176:179], v[200:203], v[80:83]
	v_mfma_f32_16x16x32_bf16 v[68:71], v[168:171], v[208:211], v[68:71]
	v_mfma_f32_16x16x32_bf16 v[64:67], v[176:179], v[208:211], v[64:67]
	v_mfma_f32_16x16x32_bf16 v[116:119], v[172:175], v[188:191], v[116:119]
	v_mfma_f32_16x16x32_bf16 v[112:115], v[180:183], v[188:191], v[112:115]
	v_mfma_f32_16x16x32_bf16 v[100:103], v[172:175], v[196:199], v[100:103]
	v_mfma_f32_16x16x32_bf16 v[96:99], v[180:183], v[196:199], v[96:99]
	v_mfma_f32_16x16x32_bf16 v[84:87], v[172:175], v[204:207], v[84:87]
	v_mfma_f32_16x16x32_bf16 v[80:83], v[180:183], v[204:207], v[80:83]
	v_mfma_f32_16x16x32_bf16 v[68:71], v[172:175], v[212:215], v[68:71]
	v_mfma_f32_16x16x32_bf16 v[64:67], v[180:183], v[212:215], v[64:67]
	s_barrier
	s_add_i32 s18, s65, s54
	v_lshl_add_u64 v[216:217], s[40:41], 0, v[130:131]
	s_mov_b32 m0, s18
	ds_read_b128 v[184:187], v153 offset:16384
	ds_read_b128 v[188:191], v153 offset:17408
	ds_read_b128 v[192:195], v153 offset:18432
	ds_read_b128 v[196:199], v153 offset:19456
	ds_read_b128 v[200:203], v153 offset:20480
	ds_read_b128 v[204:207], v153 offset:21504
	ds_read_b128 v[208:211], v153 offset:22528
	ds_read_b128 v[212:215], v153 offset:23552
	global_load_lds_dwordx4 v[216:217], off
	s_add_i32 m0, s18, 0x2000
	s_add_u32 s18, s40, 0x160000
	v_lshl_add_u64 v[218:219], s[40:41], 0, v[134:135]
	s_addc_u32 s19, s41, 0
	s_add_i32 s33, s66, s54
	global_load_lds_dwordx4 v[218:219], off
	v_lshl_add_u64 v[222:223], s[18:19], 0, v[130:131]
	s_mov_b32 m0, s33
	v_lshl_add_u64 v[224:225], s[42:43], 0, v[132:133]
	global_load_lds_dwordx4 v[222:223], off
	v_lshl_add_u64 v[222:223], s[18:19], 0, v[134:135]
	s_add_i32 m0, s33, 0x2000
	s_nop 0
	global_load_lds_dwordx4 v[222:223], off
	v_lshl_add_u64 v[222:223], s[42:43], 0, v[128:129]
	s_mov_b32 m0, s55
	s_nop 0
	global_load_lds_dwordx4 v[222:223], off
	s_mov_b32 m0, s56
	s_nop 0
	global_load_lds_dwordx4 v[224:225], off
	s_waitcnt vmcnt(8)
	s_waitcnt lgkmcnt(0)
	s_barrier
; #define PG8_STAGE(bufoff, gbase, voff) do { _Pragma("unroll") for (int _i = 0; _i < 2; ++_i) \
;         __builtin_amdgcn_global_load_lds((const unsigned*)((const char*)(gbase) + (voff)[_i]), (LAS unsigned*)(lds + (bufoff) + ldsw + _i * 8192), 16, 0, 0); } while (0)
; #define PG8_LDA(dst, b, h) do { _Pragma("unroll") for (int m = 0; m < 4; ++m) _Pragma("unroll") for (int k = 0; k < 2; ++k) dst[m][k] = *(const LAS bf16x8*)(lds + PG8_SA(b, h) + aoff + m * 2048 + k * 1024); } while (0)
; #define PG8_LDB(dst, b, h) do { _Pragma("unroll") for (int n = 0; n < 2; ++n) _Pragma("unroll") for (int k = 0; k < 2; ++k) dst[n][k] = *(const LAS bf16x8*)(lds + PG8_SB(b, h) + boff + n * 2048 + k * 1024); } while (0)
; #define PG8_MMA(ai, bj, At, Bt) do { __builtin_amdgcn_s_setprio(1); _Pragma("unroll") for (int m = 0; m < 4; ++m) _Pragma("unroll") for (int n = 0; n < 2; ++n) _Pragma("unroll") for (int k = 0; k < 2; ++k) \
;         acc[ai][bj][m][n] = __builtin_amdgcn_mfma_f32_16x16x32_bf16(Bt[n][k], At[m][k], acc[ai][bj][m][n], 0, 0, 0); __builtin_amdgcn_s_setprio(0); } while (0)
; #define PG8_WAIT_V(n) asm volatile("s_waitcnt vmcnt(" #n ")" ::: "memory")
; #define PG8_WAIT_L(n) asm volatile("s_waitcnt lgkmcnt(" #n ")" ::: "memory")
; #define PG8_BAR __builtin_amdgcn_s_barrier()
; #define PG8_SCHED __builtin_amdgcn_sched_barrier(0)
; template <class Epi, class Sched, bool ALIGN_EPI>
; __device__ __forceinline__ void gemm_phase(LAS unsigned char* lds, const Gemm g, const Sched& S, const Epi& E) {
;     ...
;             PG8_WAIT_V(8); PG8_WAIT_L(0); PG8_BAR; PG8_MMA(1, 0, At, B0); PG8_MMA(1, 1, At, B1); PG8_BAR; PG8_SCHED;
;             PG8_LDB(B0, 1, 0); PG8_LDB(B1, 1, 1); PG8_SCHED; PG8_LDA(At, 1, 0); PG8_STAGE(PG8_SA(0, 1), a2 + hA, voffA);
;             PG8_WAIT_V(8); PG8_WAIT_L(0); PG8_BAR; PG8_MMA(0, 0, At, B0); PG8_MMA(0, 1, At, B1); PG8_BAR; PG8_SCHED;
	s_waitcnt lgkmcnt(0)
	v_mfma_f32_16x16x32_bf16 v[60:63], v[144:147], v[184:187], v[60:63]
	v_mfma_f32_16x16x32_bf16 v[56:59], v[160:163], v[184:187], v[56:59]
	v_mfma_f32_16x16x32_bf16 v[44:47], v[144:147], v[192:195], v[44:47]
	v_mfma_f32_16x16x32_bf16 v[40:43], v[160:163], v[192:195], v[40:43]
	v_mfma_f32_16x16x32_bf16 v[28:31], v[144:147], v[200:203], v[28:31]
	v_mfma_f32_16x16x32_bf16 v[24:27], v[160:163], v[200:203], v[24:27]
	v_mfma_f32_16x16x32_bf16 v[12:15], v[144:147], v[208:211], v[12:15]
	v_mfma_f32_16x16x32_bf16 v[8:11], v[160:163], v[208:211], v[8:11]
	v_mfma_f32_16x16x32_bf16 v[60:63], v[156:159], v[188:191], v[60:63]
	v_mfma_f32_16x16x32_bf16 v[56:59], v[164:167], v[188:191], v[56:59]
	v_mfma_f32_16x16x32_bf16 v[44:47], v[156:159], v[196:199], v[44:47]
	v_mfma_f32_16x16x32_bf16 v[40:43], v[164:167], v[196:199], v[40:43]
	v_mfma_f32_16x16x32_bf16 v[28:31], v[156:159], v[204:207], v[28:31]
	v_mfma_f32_16x16x32_bf16 v[24:27], v[164:167], v[204:207], v[24:27]
	v_mfma_f32_16x16x32_bf16 v[12:15], v[156:159], v[212:215], v[12:15]
	v_mfma_f32_16x16x32_bf16 v[8:11], v[164:167], v[212:215], v[8:11]
	v_mfma_f32_16x16x32_bf16 v[52:55], v[168:171], v[184:187], v[52:55]
	v_mfma_f32_16x16x32_bf16 v[48:51], v[176:179], v[184:187], v[48:51]
	v_mfma_f32_16x16x32_bf16 v[36:39], v[168:171], v[192:195], v[36:39]
	v_mfma_f32_16x16x32_bf16 v[32:35], v[176:179], v[192:195], v[32:35]
	v_mfma_f32_16x16x32_bf16 v[20:23], v[168:171], v[200:203], v[20:23]
	v_mfma_f32_16x16x32_bf16 v[16:19], v[176:179], v[200:203], v[16:19]
	v_mfma_f32_16x16x32_bf16 v[4:7], v[168:171], v[208:211], v[4:7]
	v_mfma_f32_16x16x32_bf16 v[0:3], v[176:179], v[208:211], v[0:3]
	v_mfma_f32_16x16x32_bf16 v[52:55], v[172:175], v[188:191], v[52:55]
	v_mfma_f32_16x16x32_bf16 v[48:51], v[180:183], v[188:191], v[48:51]
	v_mfma_f32_16x16x32_bf16 v[36:39], v[172:175], v[196:199], v[36:39]
	v_mfma_f32_16x16x32_bf16 v[32:35], v[180:183], v[196:199], v[32:35]
	v_mfma_f32_16x16x32_bf16 v[20:23], v[172:175], v[204:207], v[20:23]
	v_mfma_f32_16x16x32_bf16 v[16:19], v[180:183], v[204:207], v[16:19]
	v_mfma_f32_16x16x32_bf16 v[4:7], v[172:175], v[212:215], v[4:7]
	v_mfma_f32_16x16x32_bf16 v[0:3], v[180:183], v[212:215], v[0:3]
	s_barrier
	s_add_i32 s33, 0, 0x18000
	v_add_u32_e32 v155, s33, v149
	s_add_i32 s47, 0, 0x1c000
	ds_read_b128 v[144:147], v155
	ds_read_b128 v[156:159], v155 offset:1024
	ds_read_b128 v[160:163], v155 offset:2048
	ds_read_b128 v[164:167], v155 offset:3072
	v_add_u32_e32 v155, s47, v149
	ds_read_b128 v[168:171], v155
	ds_read_b128 v[172:175], v155 offset:1024
	ds_read_b128 v[176:179], v155 offset:2048
	ds_read_b128 v[180:183], v155 offset:3072
	s_add_u32 s18, s42, 0x160000
	s_addc_u32 s19, s43, 0
	s_mov_b32 m0, s57
	v_lshl_add_u64 v[226:227], s[18:19], 0, v[128:129]
	ds_read_b128 v[184:187], v153 offset:32768
	ds_read_b128 v[188:191], v153 offset:33792
	ds_read_b128 v[192:195], v153 offset:34816
	ds_read_b128 v[196:199], v153 offset:35840
	ds_read_b128 v[200:203], v153 offset:36864
	ds_read_b128 v[204:207], v153 offset:37888
	ds_read_b128 v[208:211], v153 offset:38912
	ds_read_b128 v[212:215], v153 offset:39936
	global_load_lds_dwordx4 v[226:227], off
	v_lshl_add_u64 v[226:227], s[18:19], 0, v[132:133]
	s_mov_b32 m0, s58
	s_nop 0
	global_load_lds_dwordx4 v[226:227], off
	s_waitcnt vmcnt(8)
	s_waitcnt lgkmcnt(0)
	s_barrier
	s_waitcnt lgkmcnt(0)
	v_mfma_f32_16x16x32_bf16 v[124:127], v[144:147], v[184:187], v[124:127]
	v_mfma_f32_16x16x32_bf16 v[120:123], v[160:163], v[184:187], v[120:123]
	v_mfma_f32_16x16x32_bf16 v[108:111], v[144:147], v[192:195], v[108:111]
	v_mfma_f32_16x16x32_bf16 v[104:107], v[160:163], v[192:195], v[104:107]
	v_mfma_f32_16x16x32_bf16 v[92:95], v[144:147], v[200:203], v[92:95]
	v_mfma_f32_16x16x32_bf16 v[88:91], v[160:163], v[200:203], v[88:91]
	v_mfma_f32_16x16x32_bf16 v[76:79], v[144:147], v[208:211], v[76:79]
	v_mfma_f32_16x16x32_bf16 v[72:75], v[160:163], v[208:211], v[72:75]
	v_mfma_f32_16x16x32_bf16 v[124:127], v[156:159], v[188:191], v[124:127]
	v_mfma_f32_16x16x32_bf16 v[120:123], v[164:167], v[188:191], v[120:123]
	v_mfma_f32_16x16x32_bf16 v[108:111], v[156:159], v[196:199], v[108:111]
	v_mfma_f32_16x16x32_bf16 v[104:107], v[164:167], v[196:199], v[104:107]
	v_mfma_f32_16x16x32_bf16 v[92:95], v[156:159], v[204:207], v[92:95]
	v_mfma_f32_16x16x32_bf16 v[88:91], v[164:167], v[204:207], v[88:91]
	v_mfma_f32_16x16x32_bf16 v[76:79], v[156:159], v[212:215], v[76:79]
	v_mfma_f32_16x16x32_bf16 v[72:75], v[164:167], v[212:215], v[72:75]
	v_mfma_f32_16x16x32_bf16 v[116:119], v[168:171], v[184:187], v[116:119]
	v_mfma_f32_16x16x32_bf16 v[112:115], v[176:179], v[184:187], v[112:115]
	v_mfma_f32_16x16x32_bf16 v[100:103], v[168:171], v[192:195], v[100:103]
	v_mfma_f32_16x16x32_bf16 v[96:99], v[176:179], v[192:195], v[96:99]
	v_mfma_f32_16x16x32_bf16 v[84:87], v[168:171], v[200:203], v[84:87]
	v_mfma_f32_16x16x32_bf16 v[80:83], v[176:179], v[200:203], v[80:83]
	v_mfma_f32_16x16x32_bf16 v[68:71], v[168:171], v[208:211], v[68:71]
	v_mfma_f32_16x16x32_bf16 v[64:67], v[176:179], v[208:211], v[64:67]
	v_mfma_f32_16x16x32_bf16 v[116:119], v[172:175], v[188:191], v[116:119]
	v_mfma_f32_16x16x32_bf16 v[112:115], v[180:183], v[188:191], v[112:115]
	v_mfma_f32_16x16x32_bf16 v[100:103], v[172:175], v[196:199], v[100:103]
	v_mfma_f32_16x16x32_bf16 v[96:99], v[180:183], v[196:199], v[96:99]
	v_mfma_f32_16x16x32_bf16 v[84:87], v[172:175], v[204:207], v[84:87]
	v_mfma_f32_16x16x32_bf16 v[80:83], v[180:183], v[204:207], v[80:83]
	v_mfma_f32_16x16x32_bf16 v[68:71], v[172:175], v[212:215], v[68:71]
	v_mfma_f32_16x16x32_bf16 v[64:67], v[180:183], v[212:215], v[64:67]
	s_barrier
; #define PG8_STAGE(bufoff, gbase, voff) do { _Pragma("unroll") for (int _i = 0; _i < 2; ++_i) \
;         __builtin_amdgcn_global_load_lds((const unsigned*)((const char*)(gbase) + (voff)[_i]), (LAS unsigned*)(lds + (bufoff) + ldsw + _i * 8192), 16, 0, 0); } while (0)
; #define PG8_LDA(dst, b, h) do { _Pragma("unroll") for (int m = 0; m < 4; ++m) _Pragma("unroll") for (int k = 0; k < 2; ++k) dst[m][k] = *(const LAS bf16x8*)(lds + PG8_SA(b, h) + aoff + m * 2048 + k * 1024); } while (0)
; #define PG8_MMA(ai, bj, At, Bt) do { __builtin_amdgcn_s_setprio(1); _Pragma("unroll") for (int m = 0; m < 4; ++m) _Pragma("unroll") for (int n = 0; n < 2; ++n) _Pragma("unroll") for (int k = 0; k < 2; ++k) \
;         acc[ai][bj][m][n] = __builtin_amdgcn_mfma_f32_16x16x32_bf16(Bt[n][k], At[m][k], acc[ai][bj][m][n], 0, 0, 0); __builtin_amdgcn_s_setprio(0); } while (0)
; #define PG8_WAIT_V(n) asm volatile("s_waitcnt vmcnt(" #n ")" ::: "memory")
; #define PG8_WAIT_L(n) asm volatile("s_waitcnt lgkmcnt(" #n ")" ::: "memory")
; #define PG8_BAR __builtin_amdgcn_s_barrier()
; #define PG8_SCHED __builtin_amdgcn_sched_barrier(0)
; template <class Epi, class Sched, bool ALIGN_EPI>
; __device__ __forceinline__ void gemm_phase(LAS unsigned char* lds, const Gemm g, const Sched& S, const Epi& E) {
;     ...
;             PG8_LDA(At, 1, 1); PG8_STAGE(PG8_SB(1, 0), b3, voffB); PG8_STAGE(PG8_SB(1, 1), b3 + hB, voffB); PG8_STAGE(PG8_SA(1, 0), a3, voffA);
;             PG8_WAIT_V(8); PG8_WAIT_L(0); PG8_BAR; PG8_MMA(1, 0, At, B0); PG8_MMA(1, 1, At, B1); PG8_BAR; PG8_SCHED;
;         }
;         if constexpr (ALIGN_EPI) { if (wr == 0) PG8_BAR; }
	s_add_i32 s18, s33, s54
	v_lshl_add_u64 v[216:217], v[216:217], 0, s[22:23]
	s_mov_b32 m0, s18
	ds_read_b128 v[184:187], v153 offset:49152
	ds_read_b128 v[188:191], v153 offset:50176
	ds_read_b128 v[192:195], v153 offset:51200
	ds_read_b128 v[196:199], v153 offset:52224
	ds_read_b128 v[200:203], v153 offset:53248
	ds_read_b128 v[204:207], v153 offset:54272
	ds_read_b128 v[208:211], v153 offset:55296
	ds_read_b128 v[212:215], v153 offset:56320
	global_load_lds_dwordx4 v[216:217], off
	s_add_i32 m0, s18, 0x2000
	s_add_u32 s18, s40, 0x160080
	v_lshl_add_u64 v[216:217], v[218:219], 0, s[22:23]
	s_addc_u32 s19, s41, 0
	s_add_i32 s33, s47, s54
	global_load_lds_dwordx4 v[216:217], off
	v_lshl_add_u64 v[216:217], s[18:19], 0, v[130:131]
	s_mov_b32 m0, s33
	s_nop 0
	global_load_lds_dwordx4 v[216:217], off
	v_lshl_add_u64 v[216:217], s[18:19], 0, v[134:135]
	s_add_i32 m0, s33, 0x2000
	s_nop 0
	global_load_lds_dwordx4 v[216:217], off
	v_lshl_add_u64 v[216:217], v[222:223], 0, s[22:23]
	s_mov_b32 m0, s60
	s_nop 0
	global_load_lds_dwordx4 v[216:217], off
	v_lshl_add_u64 v[216:217], v[224:225], 0, s[22:23]
	s_mov_b32 m0, s61
	s_nop 0
	global_load_lds_dwordx4 v[216:217], off
	s_waitcnt vmcnt(8)
	s_waitcnt lgkmcnt(0)
	s_barrier
	s_waitcnt lgkmcnt(0)
	v_mfma_f32_16x16x32_bf16 v[60:63], v[144:147], v[184:187], v[60:63]
	v_mfma_f32_16x16x32_bf16 v[56:59], v[160:163], v[184:187], v[56:59]
	v_mfma_f32_16x16x32_bf16 v[44:47], v[144:147], v[192:195], v[44:47]
	v_mfma_f32_16x16x32_bf16 v[40:43], v[160:163], v[192:195], v[40:43]
	v_mfma_f32_16x16x32_bf16 v[28:31], v[144:147], v[200:203], v[28:31]
	v_mfma_f32_16x16x32_bf16 v[24:27], v[160:163], v[200:203], v[24:27]
	v_mfma_f32_16x16x32_bf16 v[12:15], v[144:147], v[208:211], v[12:15]
	v_mfma_f32_16x16x32_bf16 v[8:11], v[160:163], v[208:211], v[8:11]
	v_mfma_f32_16x16x32_bf16 v[60:63], v[156:159], v[188:191], v[60:63]
	v_mfma_f32_16x16x32_bf16 v[56:59], v[164:167], v[188:191], v[56:59]
	v_mfma_f32_16x16x32_bf16 v[44:47], v[156:159], v[196:199], v[44:47]
	v_mfma_f32_16x16x32_bf16 v[40:43], v[164:167], v[196:199], v[40:43]
	v_mfma_f32_16x16x32_bf16 v[28:31], v[156:159], v[204:207], v[28:31]
	v_mfma_f32_16x16x32_bf16 v[24:27], v[164:167], v[204:207], v[24:27]
	v_mfma_f32_16x16x32_bf16 v[12:15], v[156:159], v[212:215], v[12:15]
	v_mfma_f32_16x16x32_bf16 v[8:11], v[164:167], v[212:215], v[8:11]
	v_mfma_f32_16x16x32_bf16 v[52:55], v[168:171], v[184:187], v[52:55]
	v_mfma_f32_16x16x32_bf16 v[48:51], v[176:179], v[184:187], v[48:51]
	v_mfma_f32_16x16x32_bf16 v[36:39], v[168:171], v[192:195], v[36:39]
	v_mfma_f32_16x16x32_bf16 v[32:35], v[176:179], v[192:195], v[32:35]
	v_mfma_f32_16x16x32_bf16 v[20:23], v[168:171], v[200:203], v[20:23]
	v_mfma_f32_16x16x32_bf16 v[16:19], v[176:179], v[200:203], v[16:19]
	v_mfma_f32_16x16x32_bf16 v[4:7], v[168:171], v[208:211], v[4:7]
	v_mfma_f32_16x16x32_bf16 v[0:3], v[176:179], v[208:211], v[0:3]
	v_mfma_f32_16x16x32_bf16 v[52:55], v[172:175], v[188:191], v[52:55]
	v_mfma_f32_16x16x32_bf16 v[48:51], v[180:183], v[188:191], v[48:51]
	v_mfma_f32_16x16x32_bf16 v[36:39], v[172:175], v[196:199], v[36:39]
	v_mfma_f32_16x16x32_bf16 v[32:35], v[180:183], v[196:199], v[32:35]
	v_mfma_f32_16x16x32_bf16 v[20:23], v[172:175], v[204:207], v[20:23]
	v_mfma_f32_16x16x32_bf16 v[16:19], v[180:183], v[204:207], v[16:19]
	v_mfma_f32_16x16x32_bf16 v[4:7], v[172:175], v[212:215], v[4:7]
	v_mfma_f32_16x16x32_bf16 v[0:3], v[180:183], v[212:215], v[0:3]
	s_barrier
	s_add_i32 s46, s46, 2
	s_add_u32 s38, s38, 0x100
	s_addc_u32 s39, s39, 0
	s_add_u32 s44, s44, 0x100
	s_addc_u32 s45, s45, 0
	s_cmpk_gt_u32 s46, 0x55
	s_cbranch_scc0 .LBB0_1234
	s_and_b64 vcc, exec, s[24:25]
	s_cbranch_vccz .LBB0_1237
	s_barrier

; #define PG8_STAGE(bufoff, gbase, voff) do { _Pragma("unroll") for (int _i = 0; _i < 2; ++_i) \
;         __builtin_amdgcn_global_load_lds((const unsigned*)((const char*)(gbase) + (voff)[_i]), (LAS unsigned*)(lds + (bufoff) + ldsw + _i * 8192), 16, 0, 0); } while (0)
; #define PG8_LDA(dst, b, h) do { _Pragma("unroll") for (int m = 0; m < 4; ++m) _Pragma("unroll") for (int k = 0; k < 2; ++k) dst[m][k] = *(const LAS bf16x8*)(lds + PG8_SA(b, h) + aoff + m * 2048 + k * 1024); } while (0)
; #define PG8_LDB(dst, b, h) do { _Pragma("unroll") for (int n = 0; n < 2; ++n) _Pragma("unroll") for (int k = 0; k < 2; ++k) dst[n][k] = *(const LAS bf16x8*)(lds + PG8_SB(b, h) + boff + n * 2048 + k * 1024); } while (0)
; #define PG8_MMA(ai, bj, At, Bt) do { __builtin_amdgcn_s_setprio(1); _Pragma("unroll") for (int m = 0; m < 4; ++m) _Pragma("unroll") for (int n = 0; n < 2; ++n) _Pragma("unroll") for (int k = 0; k < 2; ++k) \
;         acc[ai][bj][m][n] = __builtin_amdgcn_mfma_f32_16x16x32_bf16(Bt[n][k], At[m][k], acc[ai][bj][m][n], 0, 0, 0); __builtin_amdgcn_s_setprio(0); } while (0)
; #define PG8_WAIT_V(n) asm volatile("s_waitcnt vmcnt(" #n ")" ::: "memory")
; #define PG8_WAIT_L(n) asm volatile("s_waitcnt lgkmcnt(" #n ")" ::: "memory")
; #define PG8_BAR __builtin_amdgcn_s_barrier()
; #define PG8_SCHED __builtin_amdgcn_sched_barrier(0)
; template <class Epi, class Sched, bool ALIGN_EPI>
; __device__ __forceinline__ void gemm_phase(LAS unsigned char* lds, const Gemm g, const Sched& S, const Epi& E) {
;     ...
;             const bool last = (t == nt - 2);
;             const char* a1 = cA + (size_t)(t + 1) * kstep;
;             const char* a2 = last ? nA : cA + (size_t)(t + 2) * kstep; const char* b2 = last ? nB : cB + (size_t)(t + 2) * kstep;
;             const char* a3 = a2 + kstep; const char* b3 = b2 + kstep;
;             PG8_LDB(B0, 0, 0); PG8_LDB(B1, 0, 1); PG8_SCHED; PG8_LDA(At, 0, 0); PG8_STAGE(PG8_SA(1, 1), a1 + hA, voffA);
;             PG8_WAIT_V(8); PG8_WAIT_L(0); PG8_BAR; PG8_MMA(0, 0, At, B0); PG8_MMA(0, 1, At, B1); PG8_BAR; PG8_SCHED;
;             PG8_LDA(At, 0, 1); PG8_STAGE(PG8_SB(0, 0), b2, voffB); PG8_STAGE(PG8_SB(0, 1), b2 + hB, voffB); PG8_STAGE(PG8_SA(0, 0), a2, voffA);
;             PG8_WAIT_V(8); PG8_WAIT_L(0); PG8_BAR; PG8_MMA(1, 0, At, B0); PG8_MMA(1, 1, At, B1); PG8_BAR; PG8_SCHED;
.LBB0_1278:
	ds_read_b128 v[146:149], v186
	ds_read_b128 v[150:153], v186 offset:1024
	ds_read_b128 v[154:157], v186 offset:2048
	ds_read_b128 v[192:195], v186 offset:3072
	ds_read_b128 v[196:199], v187
	ds_read_b128 v[200:203], v187 offset:1024
	ds_read_b128 v[204:207], v187 offset:2048
	ds_read_b128 v[208:211], v187 offset:3072
	s_add_u32 s18, s54, 0xffea0080
	s_addc_u32 s19, s55, -1
	s_cmpk_eq_i32 s46, 0x54
	s_cselect_b32 s59, s11, s19
	s_cselect_b32 s58, s39, s18
	s_cselect_b32 s57, s41, s45
	s_cselect_b32 s56, s78, s44
	v_lshl_add_u64 v[158:159], s[54:55], 0, v[138:139]
	s_add_i32 m0, s61, 0xc000
	ds_read_b128 v[212:215], v188
	ds_read_b128 v[216:219], v188 offset:1024
	ds_read_b128 v[222:225], v188 offset:2048
	ds_read_b128 v[226:229], v188 offset:3072
	ds_read_b128 v[230:233], v188 offset:4096
	ds_read_b128 v[234:237], v188 offset:5120
	ds_read_b128 v[238:241], v188 offset:6144
	ds_read_b128 v[242:245], v188 offset:7168
	global_load_lds_dwordx4 v[158:159], off
	v_lshl_add_u64 v[158:159], s[54:55], 0, v[140:141]
	s_add_i32 m0, s61, 0xe000
	s_nop 0
	global_load_lds_dwordx4 v[158:159], off
	s_waitcnt vmcnt(8)
	s_waitcnt lgkmcnt(0)
	s_barrier
	s_waitcnt lgkmcnt(0)
	v_mfma_f32_16x16x32_bf16 v[124:127], v[146:149], v[212:215], v[124:127]
	v_mfma_f32_16x16x32_bf16 v[120:123], v[154:157], v[212:215], v[120:123]
	v_mfma_f32_16x16x32_bf16 v[108:111], v[146:149], v[222:225], v[108:111]
	v_mfma_f32_16x16x32_bf16 v[104:107], v[154:157], v[222:225], v[104:107]
	v_mfma_f32_16x16x32_bf16 v[92:95], v[146:149], v[230:233], v[92:95]
	v_mfma_f32_16x16x32_bf16 v[88:91], v[154:157], v[230:233], v[88:91]
	v_mfma_f32_16x16x32_bf16 v[76:79], v[146:149], v[238:241], v[76:79]
	v_mfma_f32_16x16x32_bf16 v[72:75], v[154:157], v[238:241], v[72:75]
	v_mfma_f32_16x16x32_bf16 v[124:127], v[150:153], v[216:219], v[124:127]
	v_mfma_f32_16x16x32_bf16 v[120:123], v[192:195], v[216:219], v[120:123]
	v_mfma_f32_16x16x32_bf16 v[108:111], v[150:153], v[226:229], v[108:111]
	v_mfma_f32_16x16x32_bf16 v[104:107], v[192:195], v[226:229], v[104:107]
	v_mfma_f32_16x16x32_bf16 v[92:95], v[150:153], v[234:237], v[92:95]
	v_mfma_f32_16x16x32_bf16 v[88:91], v[192:195], v[234:237], v[88:91]
	v_mfma_f32_16x16x32_bf16 v[76:79], v[150:153], v[242:245], v[76:79]
	v_mfma_f32_16x16x32_bf16 v[72:75], v[192:195], v[242:245], v[72:75]
	v_mfma_f32_16x16x32_bf16 v[116:119], v[196:199], v[212:215], v[116:119]
	v_mfma_f32_16x16x32_bf16 v[112:115], v[204:207], v[212:215], v[112:115]
	v_mfma_f32_16x16x32_bf16 v[100:103], v[196:199], v[222:225], v[100:103]
	v_mfma_f32_16x16x32_bf16 v[96:99], v[204:207], v[222:225], v[96:99]
	v_mfma_f32_16x16x32_bf16 v[84:87], v[196:199], v[230:233], v[84:87]
	v_mfma_f32_16x16x32_bf16 v[80:83], v[204:207], v[230:233], v[80:83]
	v_mfma_f32_16x16x32_bf16 v[68:71], v[196:199], v[238:241], v[68:71]
	v_mfma_f32_16x16x32_bf16 v[64:67], v[204:207], v[238:241], v[64:67]
	v_mfma_f32_16x16x32_bf16 v[116:119], v[200:203], v[216:219], v[116:119]
	v_mfma_f32_16x16x32_bf16 v[112:115], v[208:211], v[216:219], v[112:115]
	v_mfma_f32_16x16x32_bf16 v[100:103], v[200:203], v[226:229], v[100:103]
	v_mfma_f32_16x16x32_bf16 v[96:99], v[208:211], v[226:229], v[96:99]
	v_mfma_f32_16x16x32_bf16 v[84:87], v[200:203], v[234:237], v[84:87]
	v_mfma_f32_16x16x32_bf16 v[80:83], v[208:211], v[234:237], v[80:83]
	v_mfma_f32_16x16x32_bf16 v[68:71], v[200:203], v[242:245], v[68:71]
	v_mfma_f32_16x16x32_bf16 v[64:67], v[208:211], v[242:245], v[64:67]
	s_barrier
	s_add_i32 s18, s71, s60
	v_lshl_add_u64 v[158:159], s[56:57], 0, v[130:131]
	s_mov_b32 m0, s18
	ds_read_b128 v[212:215], v188 offset:16384
	ds_read_b128 v[216:219], v188 offset:17408
	ds_read_b128 v[222:225], v188 offset:18432
	ds_read_b128 v[226:229], v188 offset:19456
	ds_read_b128 v[230:233], v188 offset:20480
	ds_read_b128 v[234:237], v188 offset:21504
	ds_read_b128 v[238:241], v188 offset:22528
	ds_read_b128 v[242:245], v188 offset:23552
	global_load_lds_dwordx4 v[158:159], off
	s_add_i32 m0, s18, 0x2000
	s_add_u32 s18, s56, 0x160000
	v_lshl_add_u64 v[246:247], s[56:57], 0, v[134:135]
	s_addc_u32 s19, s57, 0
	s_add_i32 s33, s72, s60
	global_load_lds_dwordx4 v[246:247], off
	v_lshl_add_u64 v[248:249], s[18:19], 0, v[130:131]
	s_mov_b32 m0, s33
	v_lshl_add_u64 v[250:251], s[58:59], 0, v[132:133]
	global_load_lds_dwordx4 v[248:249], off
	v_lshl_add_u64 v[248:249], s[18:19], 0, v[134:135]
	s_add_i32 m0, s33, 0x2000
	s_nop 0
	global_load_lds_dwordx4 v[248:249], off
	v_lshl_add_u64 v[248:249], s[58:59], 0, v[128:129]
	s_mov_b32 m0, s61
	s_nop 0
	global_load_lds_dwordx4 v[248:249], off
	s_mov_b32 m0, s62
	s_nop 0
	global_load_lds_dwordx4 v[250:251], off
	s_waitcnt vmcnt(8)
	s_waitcnt lgkmcnt(0)
	s_barrier
; #define PG8_STAGE(bufoff, gbase, voff) do { _Pragma("unroll") for (int _i = 0; _i < 2; ++_i) \
;         __builtin_amdgcn_global_load_lds((const unsigned*)((const char*)(gbase) + (voff)[_i]), (LAS unsigned*)(lds + (bufoff) + ldsw + _i * 8192), 16, 0, 0); } while (0)
; #define PG8_LDA(dst, b, h) do { _Pragma("unroll") for (int m = 0; m < 4; ++m) _Pragma("unroll") for (int k = 0; k < 2; ++k) dst[m][k] = *(const LAS bf16x8*)(lds + PG8_SA(b, h) + aoff + m * 2048 + k * 1024); } while (0)
; #define PG8_LDB(dst, b, h) do { _Pragma("unroll") for (int n = 0; n < 2; ++n) _Pragma("unroll") for (int k = 0; k < 2; ++k) dst[n][k] = *(const LAS bf16x8*)(lds + PG8_SB(b, h) + boff + n * 2048 + k * 1024); } while (0)
; #define PG8_MMA(ai, bj, At, Bt) do { __builtin_amdgcn_s_setprio(1); _Pragma("unroll") for (int m = 0; m < 4; ++m) _Pragma("unroll") for (int n = 0; n < 2; ++n) _Pragma("unroll") for (int k = 0; k < 2; ++k) \
;         acc[ai][bj][m][n] = __builtin_amdgcn_mfma_f32_16x16x32_bf16(Bt[n][k], At[m][k], acc[ai][bj][m][n], 0, 0, 0); __builtin_amdgcn_s_setprio(0); } while (0)
; #define PG8_WAIT_V(n) asm volatile("s_waitcnt vmcnt(" #n ")" ::: "memory")
; #define PG8_WAIT_L(n) asm volatile("s_waitcnt lgkmcnt(" #n ")" ::: "memory")
; #define PG8_BAR __builtin_amdgcn_s_barrier()
; #define PG8_SCHED __builtin_amdgcn_sched_barrier(0)
; template <class Epi, class Sched, bool ALIGN_EPI>
; __device__ __forceinline__ void gemm_phase(LAS unsigned char* lds, const Gemm g, const Sched& S, const Epi& E) {
;     ...
;             PG8_WAIT_V(8); PG8_WAIT_L(0); PG8_BAR; PG8_MMA(1, 0, At, B0); PG8_MMA(1, 1, At, B1); PG8_BAR; PG8_SCHED;
;             PG8_LDB(B0, 1, 0); PG8_LDB(B1, 1, 1); PG8_SCHED; PG8_LDA(At, 1, 0); PG8_STAGE(PG8_SA(0, 1), a2 + hA, voffA);
;             PG8_WAIT_V(8); PG8_WAIT_L(0); PG8_BAR; PG8_MMA(0, 0, At, B0); PG8_MMA(0, 1, At, B1); PG8_BAR; PG8_SCHED;
	s_waitcnt lgkmcnt(0)
	v_mfma_f32_16x16x32_bf16 v[60:63], v[146:149], v[212:215], v[60:63]
	v_mfma_f32_16x16x32_bf16 v[56:59], v[154:157], v[212:215], v[56:59]
	v_mfma_f32_16x16x32_bf16 v[44:47], v[146:149], v[222:225], v[44:47]
	v_mfma_f32_16x16x32_bf16 v[40:43], v[154:157], v[222:225], v[40:43]
	v_mfma_f32_16x16x32_bf16 v[28:31], v[146:149], v[230:233], v[28:31]
	v_mfma_f32_16x16x32_bf16 v[24:27], v[154:157], v[230:233], v[24:27]
	v_mfma_f32_16x16x32_bf16 v[12:15], v[146:149], v[238:241], v[12:15]
	v_mfma_f32_16x16x32_bf16 v[8:11], v[154:157], v[238:241], v[8:11]
	v_mfma_f32_16x16x32_bf16 v[60:63], v[150:153], v[216:219], v[60:63]
	v_mfma_f32_16x16x32_bf16 v[56:59], v[192:195], v[216:219], v[56:59]
	v_mfma_f32_16x16x32_bf16 v[44:47], v[150:153], v[226:229], v[44:47]
	v_mfma_f32_16x16x32_bf16 v[40:43], v[192:195], v[226:229], v[40:43]
	v_mfma_f32_16x16x32_bf16 v[28:31], v[150:153], v[234:237], v[28:31]
	v_mfma_f32_16x16x32_bf16 v[24:27], v[192:195], v[234:237], v[24:27]
	v_mfma_f32_16x16x32_bf16 v[12:15], v[150:153], v[242:245], v[12:15]
	v_mfma_f32_16x16x32_bf16 v[8:11], v[192:195], v[242:245], v[8:11]
	v_mfma_f32_16x16x32_bf16 v[52:55], v[196:199], v[212:215], v[52:55]
	v_mfma_f32_16x16x32_bf16 v[48:51], v[204:207], v[212:215], v[48:51]
	v_mfma_f32_16x16x32_bf16 v[36:39], v[196:199], v[222:225], v[36:39]
	v_mfma_f32_16x16x32_bf16 v[32:35], v[204:207], v[222:225], v[32:35]
	v_mfma_f32_16x16x32_bf16 v[20:23], v[196:199], v[230:233], v[20:23]
	v_mfma_f32_16x16x32_bf16 v[16:19], v[204:207], v[230:233], v[16:19]
	v_mfma_f32_16x16x32_bf16 v[4:7], v[196:199], v[238:241], v[4:7]
	v_mfma_f32_16x16x32_bf16 v[0:3], v[204:207], v[238:241], v[0:3]
	v_mfma_f32_16x16x32_bf16 v[52:55], v[200:203], v[216:219], v[52:55]
	v_mfma_f32_16x16x32_bf16 v[48:51], v[208:211], v[216:219], v[48:51]
	v_mfma_f32_16x16x32_bf16 v[36:39], v[200:203], v[226:229], v[36:39]
	v_mfma_f32_16x16x32_bf16 v[32:35], v[208:211], v[226:229], v[32:35]
	v_mfma_f32_16x16x32_bf16 v[20:23], v[200:203], v[234:237], v[20:23]
	v_mfma_f32_16x16x32_bf16 v[16:19], v[208:211], v[234:237], v[16:19]
	v_mfma_f32_16x16x32_bf16 v[4:7], v[200:203], v[242:245], v[4:7]
	v_mfma_f32_16x16x32_bf16 v[0:3], v[208:211], v[242:245], v[0:3]
	s_barrier
	s_add_i32 s33, 0, 0x18000
	v_add_u32_e32 v136, s33, v163
	s_add_i32 s47, 0, 0x1c000
	ds_read_b128 v[146:149], v136
	ds_read_b128 v[150:153], v136 offset:1024
	ds_read_b128 v[154:157], v136 offset:2048
	ds_read_b128 v[192:195], v136 offset:3072
	v_add_u32_e32 v136, s47, v163
	ds_read_b128 v[196:199], v136
	ds_read_b128 v[200:203], v136 offset:1024
	ds_read_b128 v[204:207], v136 offset:2048
	ds_read_b128 v[208:211], v136 offset:3072
	s_add_u32 s18, s58, 0x160000
	s_addc_u32 s19, s59, 0
	s_mov_b32 m0, s63
	v_lshl_add_u64 v[252:253], s[18:19], 0, v[128:129]
	ds_read_b128 v[212:215], v188 offset:32768
	ds_read_b128 v[216:219], v188 offset:33792
	ds_read_b128 v[222:225], v188 offset:34816
	ds_read_b128 v[226:229], v188 offset:35840
	ds_read_b128 v[230:233], v188 offset:36864
	ds_read_b128 v[234:237], v188 offset:37888
	ds_read_b128 v[238:241], v188 offset:38912
	ds_read_b128 v[242:245], v188 offset:39936
	global_load_lds_dwordx4 v[252:253], off
	v_lshl_add_u64 v[252:253], s[18:19], 0, v[132:133]
	s_mov_b32 m0, s64
	s_nop 0
	global_load_lds_dwordx4 v[252:253], off
	s_waitcnt vmcnt(8)
	s_waitcnt lgkmcnt(0)
	s_barrier
	s_waitcnt lgkmcnt(0)
	v_mfma_f32_16x16x32_bf16 v[124:127], v[146:149], v[212:215], v[124:127]
	v_mfma_f32_16x16x32_bf16 v[120:123], v[154:157], v[212:215], v[120:123]
	v_mfma_f32_16x16x32_bf16 v[108:111], v[146:149], v[222:225], v[108:111]
	v_mfma_f32_16x16x32_bf16 v[104:107], v[154:157], v[222:225], v[104:107]
	v_mfma_f32_16x16x32_bf16 v[92:95], v[146:149], v[230:233], v[92:95]
	v_mfma_f32_16x16x32_bf16 v[88:91], v[154:157], v[230:233], v[88:91]
	v_mfma_f32_16x16x32_bf16 v[76:79], v[146:149], v[238:241], v[76:79]
	v_mfma_f32_16x16x32_bf16 v[72:75], v[154:157], v[238:241], v[72:75]
	v_mfma_f32_16x16x32_bf16 v[124:127], v[150:153], v[216:219], v[124:127]
	v_mfma_f32_16x16x32_bf16 v[120:123], v[192:195], v[216:219], v[120:123]
	v_mfma_f32_16x16x32_bf16 v[108:111], v[150:153], v[226:229], v[108:111]
	v_mfma_f32_16x16x32_bf16 v[104:107], v[192:195], v[226:229], v[104:107]
	v_mfma_f32_16x16x32_bf16 v[92:95], v[150:153], v[234:237], v[92:95]
	v_mfma_f32_16x16x32_bf16 v[88:91], v[192:195], v[234:237], v[88:91]
	v_mfma_f32_16x16x32_bf16 v[76:79], v[150:153], v[242:245], v[76:79]
	v_mfma_f32_16x16x32_bf16 v[72:75], v[192:195], v[242:245], v[72:75]
	v_mfma_f32_16x16x32_bf16 v[116:119], v[196:199], v[212:215], v[116:119]
	v_mfma_f32_16x16x32_bf16 v[112:115], v[204:207], v[212:215], v[112:115]
	v_mfma_f32_16x16x32_bf16 v[100:103], v[196:199], v[222:225], v[100:103]
	v_mfma_f32_16x16x32_bf16 v[96:99], v[204:207], v[222:225], v[96:99]
	v_mfma_f32_16x16x32_bf16 v[84:87], v[196:199], v[230:233], v[84:87]
	v_mfma_f32_16x16x32_bf16 v[80:83], v[204:207], v[230:233], v[80:83]
	v_mfma_f32_16x16x32_bf16 v[68:71], v[196:199], v[238:241], v[68:71]
	v_mfma_f32_16x16x32_bf16 v[64:67], v[204:207], v[238:241], v[64:67]
	v_mfma_f32_16x16x32_bf16 v[116:119], v[200:203], v[216:219], v[116:119]
	v_mfma_f32_16x16x32_bf16 v[112:115], v[208:211], v[216:219], v[112:115]
	v_mfma_f32_16x16x32_bf16 v[100:103], v[200:203], v[226:229], v[100:103]
	v_mfma_f32_16x16x32_bf16 v[96:99], v[208:211], v[226:229], v[96:99]
	v_mfma_f32_16x16x32_bf16 v[84:87], v[200:203], v[234:237], v[84:87]
	v_mfma_f32_16x16x32_bf16 v[80:83], v[208:211], v[234:237], v[80:83]
	v_mfma_f32_16x16x32_bf16 v[68:71], v[200:203], v[242:245], v[68:71]
	v_mfma_f32_16x16x32_bf16 v[64:67], v[208:211], v[242:245], v[64:67]
	s_barrier
; #define PG8_STAGE(bufoff, gbase, voff) do { _Pragma("unroll") for (int _i = 0; _i < 2; ++_i) \
;         __builtin_amdgcn_global_load_lds((const unsigned*)((const char*)(gbase) + (voff)[_i]), (LAS unsigned*)(lds + (bufoff) + ldsw + _i * 8192), 16, 0, 0); } while (0)
; #define PG8_LDA(dst, b, h) do { _Pragma("unroll") for (int m = 0; m < 4; ++m) _Pragma("unroll") for (int k = 0; k < 2; ++k) dst[m][k] = *(const LAS bf16x8*)(lds + PG8_SA(b, h) + aoff + m * 2048 + k * 1024); } while (0)
; #define PG8_MMA(ai, bj, At, Bt) do { __builtin_amdgcn_s_setprio(1); _Pragma("unroll") for (int m = 0; m < 4; ++m) _Pragma("unroll") for (int n = 0; n < 2; ++n) _Pragma("unroll") for (int k = 0; k < 2; ++k) \
;         acc[ai][bj][m][n] = __builtin_amdgcn_mfma_f32_16x16x32_bf16(Bt[n][k], At[m][k], acc[ai][bj][m][n], 0, 0, 0); __builtin_amdgcn_s_setprio(0); } while (0)
; #define PG8_WAIT_V(n) asm volatile("s_waitcnt vmcnt(" #n ")" ::: "memory")
; #define PG8_WAIT_L(n) asm volatile("s_waitcnt lgkmcnt(" #n ")" ::: "memory")
; #define PG8_BAR __builtin_amdgcn_s_barrier()
; #define PG8_SCHED __builtin_amdgcn_sched_barrier(0)
; template <class Epi, class Sched, bool ALIGN_EPI>
; __device__ __forceinline__ void gemm_phase(LAS unsigned char* lds, const Gemm g, const Sched& S, const Epi& E) {
;     ...
;             PG8_LDA(At, 1, 1); PG8_STAGE(PG8_SB(1, 0), b3, voffB); PG8_STAGE(PG8_SB(1, 1), b3 + hB, voffB); PG8_STAGE(PG8_SA(1, 0), a3, voffA);
;             PG8_WAIT_V(8); PG8_WAIT_L(0); PG8_BAR; PG8_MMA(1, 0, At, B0); PG8_MMA(1, 1, At, B1); PG8_BAR; PG8_SCHED;
;         }
;         if constexpr (ALIGN_EPI) { if (wr == 0) PG8_BAR; }
	s_add_i32 s18, s33, s60
	v_lshl_add_u64 v[158:159], v[158:159], 0, s[30:31]
	s_mov_b32 m0, s18
	ds_read_b128 v[212:215], v188 offset:49152
	ds_read_b128 v[216:219], v188 offset:50176
	ds_read_b128 v[222:225], v188 offset:51200
	ds_read_b128 v[226:229], v188 offset:52224
	ds_read_b128 v[230:233], v188 offset:53248
	ds_read_b128 v[234:237], v188 offset:54272
	ds_read_b128 v[238:241], v188 offset:55296
	ds_read_b128 v[242:245], v188 offset:56320
	global_load_lds_dwordx4 v[158:159], off
	s_add_i32 m0, s18, 0x2000
	s_add_u32 s18, s56, 0x160080
	v_lshl_add_u64 v[158:159], v[246:247], 0, s[30:31]
	s_addc_u32 s19, s57, 0
	s_add_i32 s33, s47, s60
	global_load_lds_dwordx4 v[158:159], off
	v_lshl_add_u64 v[158:159], s[18:19], 0, v[130:131]
	s_mov_b32 m0, s33
	s_nop 0
	global_load_lds_dwordx4 v[158:159], off
	v_lshl_add_u64 v[158:159], s[18:19], 0, v[134:135]
	s_add_i32 m0, s33, 0x2000
	s_nop 0
	global_load_lds_dwordx4 v[158:159], off
	v_lshl_add_u64 v[158:159], v[248:249], 0, s[30:31]
	s_mov_b32 m0, s68
	s_nop 0
	global_load_lds_dwordx4 v[158:159], off
	v_lshl_add_u64 v[158:159], v[250:251], 0, s[30:31]
	s_mov_b32 m0, s69
	s_nop 0
	global_load_lds_dwordx4 v[158:159], off
	s_waitcnt vmcnt(8)
	s_waitcnt lgkmcnt(0)
	s_barrier
	s_waitcnt lgkmcnt(0)
	v_mfma_f32_16x16x32_bf16 v[60:63], v[146:149], v[212:215], v[60:63]
	v_mfma_f32_16x16x32_bf16 v[56:59], v[154:157], v[212:215], v[56:59]
	v_mfma_f32_16x16x32_bf16 v[44:47], v[146:149], v[222:225], v[44:47]
	v_mfma_f32_16x16x32_bf16 v[40:43], v[154:157], v[222:225], v[40:43]
	v_mfma_f32_16x16x32_bf16 v[28:31], v[146:149], v[230:233], v[28:31]
	v_mfma_f32_16x16x32_bf16 v[24:27], v[154:157], v[230:233], v[24:27]
	v_mfma_f32_16x16x32_bf16 v[12:15], v[146:149], v[238:241], v[12:15]
	v_mfma_f32_16x16x32_bf16 v[8:11], v[154:157], v[238:241], v[8:11]
	v_mfma_f32_16x16x32_bf16 v[60:63], v[150:153], v[216:219], v[60:63]
	v_mfma_f32_16x16x32_bf16 v[56:59], v[192:195], v[216:219], v[56:59]
	v_mfma_f32_16x16x32_bf16 v[44:47], v[150:153], v[226:229], v[44:47]
	v_mfma_f32_16x16x32_bf16 v[40:43], v[192:195], v[226:229], v[40:43]
	v_mfma_f32_16x16x32_bf16 v[28:31], v[150:153], v[234:237], v[28:31]
	v_mfma_f32_16x16x32_bf16 v[24:27], v[192:195], v[234:237], v[24:27]
	v_mfma_f32_16x16x32_bf16 v[12:15], v[150:153], v[242:245], v[12:15]
	v_mfma_f32_16x16x32_bf16 v[8:11], v[192:195], v[242:245], v[8:11]
	v_mfma_f32_16x16x32_bf16 v[52:55], v[196:199], v[212:215], v[52:55]
	v_mfma_f32_16x16x32_bf16 v[48:51], v[204:207], v[212:215], v[48:51]
	v_mfma_f32_16x16x32_bf16 v[36:39], v[196:199], v[222:225], v[36:39]
	v_mfma_f32_16x16x32_bf16 v[32:35], v[204:207], v[222:225], v[32:35]
	v_mfma_f32_16x16x32_bf16 v[20:23], v[196:199], v[230:233], v[20:23]
	v_mfma_f32_16x16x32_bf16 v[16:19], v[204:207], v[230:233], v[16:19]
	v_mfma_f32_16x16x32_bf16 v[4:7], v[196:199], v[238:241], v[4:7]
	v_mfma_f32_16x16x32_bf16 v[0:3], v[204:207], v[238:241], v[0:3]
	v_mfma_f32_16x16x32_bf16 v[52:55], v[200:203], v[216:219], v[52:55]
	v_mfma_f32_16x16x32_bf16 v[48:51], v[208:211], v[216:219], v[48:51]
	v_mfma_f32_16x16x32_bf16 v[36:39], v[200:203], v[226:229], v[36:39]
	v_mfma_f32_16x16x32_bf16 v[32:35], v[208:211], v[226:229], v[32:35]
	v_mfma_f32_16x16x32_bf16 v[20:23], v[200:203], v[234:237], v[20:23]
	v_mfma_f32_16x16x32_bf16 v[16:19], v[208:211], v[234:237], v[16:19]
	v_mfma_f32_16x16x32_bf16 v[4:7], v[200:203], v[242:245], v[4:7]
	v_mfma_f32_16x16x32_bf16 v[0:3], v[208:211], v[242:245], v[0:3]
	s_barrier
	s_add_i32 s46, s46, 2
	s_add_u32 s54, s54, 0x100
	s_addc_u32 s55, s55, 0
	s_add_u32 s44, s44, 0x100
	s_addc_u32 s45, s45, 0
	s_cmpk_gt_u32 s46, 0x55
	s_cbranch_scc0 .LBB0_1278
	s_and_b64 vcc, exec, s[36:37]
	s_cbranch_vccz .LBB0_1281
	s_barrier
